# GEMM epilogue dwordx4 stores made write-through (sc1) so the grid-sync L2 writeback is short
# speedup vs baseline: 1.0141x; 1.0141x over previous
; #define GCOMPUTE(AS, BS) GCOMPUTE_KS(AS, BS, 0) GCOMPUTE_KS(AS, BS, 1)
; template <int EPI>
; DI void gemm_phase(const P& p, int l, const u16* __restrict__ A, const u16* __restrict__ Bt, int mpx, char* lds) {
;     ...
;   __syncthreads();
;   __builtin_amdgcn_sched_barrier(0);
;   GCOMPUTE(As1, Bs1)
;   __builtin_amdgcn_sched_barrier(0);
;   }
;   __syncthreads();
;   GSTORE(As0, Bs0)
.Lgemm_out_exit:
	v_mfma_f32_16x16x32_bf16 v[134:137], v[246:249], v[162:165], v[134:137]
	v_mfma_f32_16x16x32_bf16 v[138:141], v[246:249], v[166:169], v[138:141]
	v_mfma_f32_16x16x32_bf16 v[142:145], v[246:249], v[170:173], v[142:145]
	v_mfma_f32_16x16x32_bf16 v[146:149], v[246:249], v[174:177], v[146:149]
	v_mfma_f32_16x16x32_bf16 v[150:153], v[250:253], v[162:165], v[150:153]
	v_mfma_f32_16x16x32_bf16 v[154:157], v[250:253], v[166:169], v[154:157]
	v_mfma_f32_16x16x32_bf16 v[158:161], v[250:253], v[170:173], v[158:161]
	v_mfma_f32_16x16x32_bf16 v[2:5], v[250:253], v[174:177], v[2:5]
	s_barrier
	ds_read_b128 v[162:165], v231
	ds_read_b128 v[166:169], v230
	ds_read_b128 v[170:173], v230 offset:2048
	ds_read_b128 v[174:177], v230 offset:4096
	ds_read_b128 v[178:181], v230 offset:6144
	s_waitcnt lgkmcnt(3)
	v_mfma_f32_16x16x32_bf16 v[6:9], v[162:165], v[166:169], v[6:9]
	s_waitcnt lgkmcnt(2)
	v_mfma_f32_16x16x32_bf16 v[10:13], v[162:165], v[170:173], v[10:13]
	s_waitcnt lgkmcnt(1)
	v_mfma_f32_16x16x32_bf16 v[14:17], v[162:165], v[174:177], v[14:17]
	s_waitcnt lgkmcnt(0)
	v_mfma_f32_16x16x32_bf16 v[22:25], v[162:165], v[178:181], v[22:25]
	ds_read_b128 v[162:165], v231 offset:2048
	s_waitcnt lgkmcnt(0)
	v_mfma_f32_16x16x32_bf16 v[26:29], v[162:165], v[166:169], v[26:29]
	v_mfma_f32_16x16x32_bf16 v[30:33], v[162:165], v[170:173], v[30:33]
	v_mfma_f32_16x16x32_bf16 v[34:37], v[162:165], v[174:177], v[34:37]
	v_mfma_f32_16x16x32_bf16 v[38:41], v[162:165], v[178:181], v[38:41]
	ds_read_b128 v[162:165], v231 offset:4096
	s_waitcnt lgkmcnt(0)
	v_mfma_f32_16x16x32_bf16 v[42:45], v[162:165], v[166:169], v[42:45]
	v_mfma_f32_16x16x32_bf16 v[46:49], v[162:165], v[170:173], v[46:49]
	v_mfma_f32_16x16x32_bf16 v[50:53], v[162:165], v[174:177], v[50:53]
	v_mfma_f32_16x16x32_bf16 v[54:57], v[162:165], v[178:181], v[54:57]
	ds_read_b128 v[162:165], v231 offset:6144
	s_waitcnt lgkmcnt(0)
	v_mfma_f32_16x16x32_bf16 v[58:61], v[162:165], v[166:169], v[58:61]
	v_mfma_f32_16x16x32_bf16 v[62:65], v[162:165], v[170:173], v[62:65]
	v_mfma_f32_16x16x32_bf16 v[66:69], v[162:165], v[174:177], v[66:69]
	v_mfma_f32_16x16x32_bf16 v[162:165], v[162:165], v[178:181], v[70:73]
	s_nop 2
	ds_read_b128 v[70:73], v231 offset:8192
	s_waitcnt lgkmcnt(0)
	v_mfma_f32_16x16x32_bf16 v[182:185], v[70:73], v[166:169], v[74:77]
	s_nop 2
	ds_read_b128 v[74:77], v233
	v_mfma_f32_16x16x32_bf16 v[186:189], v[70:73], v[170:173], v[78:81]
	v_mfma_f32_16x16x32_bf16 v[190:193], v[70:73], v[174:177], v[82:85]
	v_mfma_f32_16x16x32_bf16 v[212:215], v[70:73], v[178:181], v[114:117]
	ds_read_b128 v[70:73], v231 offset:10240
	s_waitcnt lgkmcnt(0)
	v_mfma_f32_16x16x32_bf16 v[216:219], v[70:73], v[166:169], v[118:121]
	v_mfma_f32_16x16x32_bf16 v[220:223], v[70:73], v[170:173], v[122:125]
	v_mfma_f32_16x16x32_bf16 v[234:237], v[70:73], v[174:177], v[126:129]
	v_mfma_f32_16x16x32_bf16 v[238:241], v[70:73], v[178:181], v[130:133]
	ds_read_b128 v[70:73], v231 offset:12288
	s_waitcnt lgkmcnt(0)
	v_mfma_f32_16x16x32_bf16 v[242:245], v[70:73], v[166:169], v[134:137]
	v_mfma_f32_16x16x32_bf16 v[246:249], v[70:73], v[170:173], v[138:141]
	v_mfma_f32_16x16x32_bf16 v[250:253], v[70:73], v[174:177], v[142:145]
	v_mfma_f32_16x16x32_bf16 v[208:211], v[70:73], v[178:181], v[146:149]
	ds_read_b128 v[70:73], v231 offset:14336
	s_waitcnt lgkmcnt(0)
	v_mfma_f32_16x16x32_bf16 v[178:181], v[70:73], v[178:181], v[2:5]
	s_nop 2
	ds_read_b128 v[2:5], v232
	s_waitcnt lgkmcnt(0)
	v_mfma_f32_16x16x32_bf16 v[146:149], v[74:77], v[2:5], v[6:9]
	s_nop 2
	ds_read_b128 v[6:9], v232 offset:2048
	v_mfma_f32_16x16x32_bf16 v[170:173], v[70:73], v[170:173], v[154:157]
	s_waitcnt lgkmcnt(0)
	v_mfma_f32_16x16x32_bf16 v[154:157], v[74:77], v[6:9], v[10:13]
	s_nop 2
	ds_read_b128 v[10:13], v232 offset:4096
	v_mfma_f32_16x16x32_bf16 v[166:169], v[70:73], v[166:169], v[150:153]
	s_waitcnt lgkmcnt(0)
	v_mfma_f32_16x16x32_bf16 v[150:153], v[74:77], v[10:13], v[14:17]
	s_nop 2
	ds_read_b128 v[14:17], v232 offset:6144
	v_mfma_f32_16x16x32_bf16 v[174:177], v[70:73], v[174:177], v[158:161]
	s_waitcnt lgkmcnt(0)
	v_mfma_f32_16x16x32_bf16 v[158:161], v[74:77], v[14:17], v[22:25]
	s_nop 2
	ds_read_b128 v[22:25], v233 offset:2048
	s_waitcnt lgkmcnt(0)
	v_mfma_f32_16x16x32_bf16 v[138:141], v[22:25], v[2:5], v[26:29]
	s_nop 2
	ds_read_b128 v[26:29], v233 offset:12288
	v_mfma_f32_16x16x32_bf16 v[142:145], v[22:25], v[6:9], v[30:33]
	v_mfma_f32_16x16x32_bf16 v[130:133], v[22:25], v[10:13], v[34:37]
	v_mfma_f32_16x16x32_bf16 v[134:137], v[22:25], v[14:17], v[38:41]
	ds_read_b128 v[22:25], v233 offset:4096
	s_waitcnt lgkmcnt(0)
	v_mfma_f32_16x16x32_bf16 v[122:125], v[22:25], v[2:5], v[42:45]
	v_mfma_f32_16x16x32_bf16 v[126:129], v[22:25], v[6:9], v[46:49]
	v_mfma_f32_16x16x32_bf16 v[114:117], v[22:25], v[10:13], v[50:53]
	v_mfma_f32_16x16x32_bf16 v[118:121], v[22:25], v[14:17], v[54:57]
	ds_read_b128 v[22:25], v233 offset:6144
	s_waitcnt lgkmcnt(0)
	v_mfma_f32_16x16x32_bf16 v[78:81], v[22:25], v[2:5], v[58:61]
	v_mfma_f32_16x16x32_bf16 v[82:85], v[22:25], v[6:9], v[62:65]
	v_mfma_f32_16x16x32_bf16 v[70:73], v[22:25], v[10:13], v[66:69]
	v_mfma_f32_16x16x32_bf16 v[74:77], v[22:25], v[14:17], v[162:165]
	ds_read_b128 v[22:25], v233 offset:8192
	s_nop 1
	ds_read_b128 v[162:165], v233 offset:14336
	s_waitcnt lgkmcnt(1)
	v_mfma_f32_16x16x32_bf16 v[62:65], v[22:25], v[2:5], v[182:185]
	v_mfma_f32_16x16x32_bf16 v[66:69], v[22:25], v[6:9], v[186:189]
	v_mfma_f32_16x16x32_bf16 v[54:57], v[22:25], v[10:13], v[190:193]
	v_mfma_f32_16x16x32_bf16 v[58:61], v[22:25], v[14:17], v[212:215]
	ds_read_b128 v[22:25], v233 offset:10240
	s_waitcnt lgkmcnt(0)
	v_mfma_f32_16x16x32_bf16 v[46:49], v[22:25], v[2:5], v[216:219]
	v_mfma_f32_16x16x32_bf16 v[50:53], v[22:25], v[6:9], v[220:223]
	v_mfma_f32_16x16x32_bf16 v[38:41], v[22:25], v[10:13], v[234:237]
	v_mfma_f32_16x16x32_bf16 v[42:45], v[22:25], v[14:17], v[238:241]
	v_mfma_f32_16x16x32_bf16 v[30:33], v[26:29], v[2:5], v[242:245]
	v_mfma_f32_16x16x32_bf16 v[34:37], v[26:29], v[6:9], v[246:249]
	v_mfma_f32_16x16x32_bf16 v[22:25], v[26:29], v[10:13], v[250:253]
	v_mfma_f32_16x16x32_bf16 v[26:29], v[26:29], v[14:17], v[208:211]
	v_mfma_f32_16x16x32_bf16 v[166:169], v[162:165], v[2:5], v[166:169]
	v_mfma_f32_16x16x32_bf16 v[170:173], v[162:165], v[6:9], v[170:173]
	v_mfma_f32_16x16x32_bf16 v[2:5], v[162:165], v[10:13], v[174:177]
	v_mfma_f32_16x16x32_bf16 v[6:9], v[162:165], v[14:17], v[178:181]
	v_mov_b32_e32 v14, v195
	s_barrier
; template <int EPI>
; DI void gemm_phase(const P& p, int l, const u16* __restrict__ A, const u16* __restrict__ Bt, int mpx, char* lds) {
;     ...
;   if constexpr (EPI == 1) {
;     const float alpha = 1.4142135623730951f;
;     float* Cw = (float*)(lds + 65536) + w * (16 * 68);
;     const int mr = m0 < MLAT ? (m0 >> 11) : 16;
;     const int colw = n0 + wn * 64;
;     const float* gate = p.mod + (size_t)(l * 17 + mr) * 3072 + 2048 + colw;
;     const float* xr = ((l == 0) ? (m0 < MLAT ? p.x + (size_t)m0 * 1024 : p.ctx + (size_t)(m0 - MLAT) * 1024)
;                                 : p.out + (size_t)m0 * 1024) + (size_t)(wm * 128) * 1024 + colw;
;     float* Z = (float*)p.slab + (size_t)(m0 + wm * 128) * 1024 + colw;
;     const int c4 = (lane & 15) * 4, rr0 = lane >> 4;
;     const float4 gt = *(const float4*)(gate + c4);
;     float4 xn[4];
; #pragma unroll
;     for (int i = 0; i < 4; ++i) xn[i] = *(const float4*)(xr + (size_t)(rr0 + 4 * i) * 1024 + c4);
; #pragma unroll
;     for (int mi = 0; mi < 8; ++mi) {
;       float4 xv[4];
; #pragma unroll
;       for (int i = 0; i < 4; ++i) xv[i] = xn[i];
;       if (mi < 7) {
; #pragma unroll
;         for (int i = 0; i < 4; ++i) xn[i] = *(const float4*)(xr + (size_t)((mi + 1) * 16 + rr0 + 4 * i) * 1024 + c4);
;       }
; #pragma unroll
;       for (int ni = 0; ni < 4; ++ni)
; #pragma unroll
;         for (int j = 0; j < 4; ++j) Cw[(g * 4 + j) * 68 + ni * 16 + r] = acc[mi][ni][j];
;       __builtin_amdgcn_fence(__ATOMIC_RELEASE, "wavefront");
; #pragma unroll
;       for (int i = 0; i < 4; ++i) {
;         const int row = rr0 + 4 * i;
;         const float4 a = *(const float4*)&Cw[row * 68 + c4];
;         float4 z;
;         z.x = alpha * xv[i].x + gt.x * a.x;
;         z.y = alpha * xv[i].y + gt.y * a.y;
;         z.z = alpha * xv[i].z + gt.z * a.z;
;         z.w = alpha * xv[i].w + gt.w * a.w;
;         *(float4*)(Z + (size_t)(mi * 16 + row) * 1024 + c4) = z;
	s_waitcnt vmcnt(7)
	ds_write_b128 v198, v[18:21]
	s_waitcnt vmcnt(5)
	ds_write_b128 v198, v[86:89] offset:8192
	s_waitcnt vmcnt(4)
	ds_write_b128 v198, v[90:93] offset:16384
	s_waitcnt vmcnt(3)
	ds_write_b128 v198, v[94:97] offset:24576
	ds_write_b128 v198, v[98:101] offset:32768
	s_waitcnt vmcnt(2)
	ds_write_b128 v198, v[102:105] offset:40960
	s_waitcnt vmcnt(1)
	ds_write_b128 v198, v[106:109] offset:49152
	s_waitcnt vmcnt(0)
	ds_write_b128 v198, v[110:113] offset:57344
	s_movk_i32 s2, 0x1100
	v_lshrrev_b32_e32 v0, 6, v14
	v_mul_lo_u32 v19, v0, s2
	s_min_i32 s2, s60, 0x8000
	s_lshr_b32 s2, s2, 11
	s_mul_i32 s46, s50, 17
	v_and_b32_e32 v0, 0xc0, v14
	s_add_i32 s2, s2, s46
	v_readlane_b32 s64, v255, 28
	v_or_b32_e32 v0, s61, v0
	s_mul_hi_i32 s47, s2, 0x3000
	s_mulk_i32 s2, 0x3000
	v_readlane_b32 s66, v255, 30
	v_readlane_b32 s67, v255, 31
	s_add_u32 s46, s66, s2
	v_lshlrev_b64 v[10:11], 2, v[0:1]
	v_mov_b32_e32 v0, 0x8000
	s_addc_u32 s47, s67, s47
	v_sub_co_u32_e32 v0, vcc, s60, v0
	v_lshl_add_u64 v[12:13], s[46:47], 0, v[10:11]
	s_and_b64 s[46:47], vcc, exec
	v_readfirstlane_b32 s2, v0
	s_cselect_b32 s2, s60, s2
	s_cselect_b32 s48, 0, 16
	s_and_b64 s[46:47], s[0:1], exec
	s_cselect_b32 s46, s48, 0x88
	s_cselect_b32 s2, s2, s60
	s_add_u32 s46, s96, s46
	s_addc_u32 s47, s97, 0
	s_load_dwordx2 s[46:47], s[46:47], 0x0
	v_ashrrev_i32_e32 v0, 1, v14
	v_and_b32_e32 v18, 15, v14
	v_bfe_u32 v88, v14, 4, 2
	s_lshl_b64 s[48:49], s[2:3], 12
	v_and_b32_e32 v14, 0xffffff80, v0
	s_waitcnt lgkmcnt(0)
	s_add_u32 s46, s46, s48
	v_ashrrev_i32_e32 v15, 31, v14
	s_addc_u32 s47, s47, s49
	v_lshlrev_b64 v[16:17], 12, v[14:15]
	v_lshl_add_u64 v[16:17], s[46:47], 0, v[16:17]
	v_add_u32_e32 v14, s60, v14
	v_lshl_add_u64 v[16:17], v[16:17], 0, v[10:11]
	v_ashrrev_i32_e32 v15, 31, v14
	v_lshlrev_b32_e32 v0, 4, v18
	v_lshlrev_b64 v[14:15], 12, v[14:15]
	v_lshlrev_b32_e32 v20, 2, v18
	v_lshl_add_u64 v[16:17], v[16:17], 0, v[0:1]
	v_lshlrev_b32_e32 v86, 12, v88
	v_mov_b32_e32 v87, v1
	v_lshl_add_u64 v[14:15], s[18:19], 0, v[14:15]
	v_lshl_add_u64 v[162:163], v[16:17], 0, v[86:87]
	v_add3_u32 v16, s78, v19, v20
	s_movk_i32 s2, 0x440
	v_lshl_add_u64 v[12:13], v[12:13], 0, v[0:1]
	v_lshl_add_u64 v[10:11], v[14:15], 0, v[10:11]
	v_mad_u32_u24 v165, v88, s2, v16
	s_movk_i32 s2, 0x2000
	v_lshl_add_u64 v[14:15], v[10:11], 0, v[0:1]
	v_add_co_u32_e32 v10, vcc, s2, v12
	ds_write2_b32 v165, v146, v154 offset1:16
	ds_write2_b32 v165, v147, v155 offset0:68 offset1:84
	ds_write2_b32 v165, v148, v156 offset0:136 offset1:152
	ds_write2_b32 v165, v149, v157 offset0:204 offset1:220
	ds_write2_b32 v165, v150, v158 offset0:32 offset1:48
	ds_write2_b32 v165, v151, v159 offset0:100 offset1:116
	ds_write2_b32 v165, v152, v160 offset0:168 offset1:184
	ds_write2_b32 v165, v153, v161 offset0:236 offset1:252
	v_addc_co_u32_e32 v11, vcc, 0, v13, vcc
	v_mad_u32_u24 v17, v18, 12, v16
	global_load_dwordx4 v[18:21], v[10:11], off
	s_nop 0
	global_load_dwordx4 v[10:13], v[162:163], off
	v_or_b32_e32 v0, 4, v88
	v_add_co_u32_e32 v16, vcc, s94, v162
	v_mad_u32_u24 v164, v88, s79, v17
	v_mad_u32_u24 v158, v0, s79, v17
	v_addc_co_u32_e32 v17, vcc, 0, v163, vcc
	global_load_dwordx4 v[102:105], v[16:17], off
	v_add_co_u32_e32 v16, vcc, s21, v162
	v_lshlrev_b32_e32 v0, 12, v0
	s_nop 0
	v_addc_co_u32_e32 v17, vcc, 0, v163, vcc
	global_load_dwordx4 v[94:97], v[16:17], off
	v_lshl_add_u64 v[156:157], v[14:15], 0, v[0:1]
	v_or_b32_e32 v0, 0x8000, v86
	v_lshl_add_u64 v[154:155], v[14:15], 0, v[0:1]
	v_or_b32_e32 v0, 0xc000, v86
	s_mov_b32 s2, 0xc000
	v_lshl_add_u64 v[152:153], v[14:15], 0, v[86:87]
	v_lshl_add_u64 v[150:151], v[14:15], 0, v[0:1]
	v_add_co_u32_e32 v14, vcc, s2, v162
	s_mov_b32 s2, 0x14000
	s_nop 0
	v_addc_co_u32_e32 v15, vcc, 0, v163, vcc
	global_load_dwordx4 v[86:89], v[14:15], off
	v_add_co_u32_e32 v14, vcc, s85, v162
	s_mov_b32 s46, 0x30000
	s_nop 0
	v_addc_co_u32_e32 v15, vcc, 0, v163, vcc
	global_load_dwordx4 v[146:149], v[14:15], off
	v_add_co_u32_e32 v14, vcc, s2, v162
	s_mov_b32 s2, 0x18000
	s_nop 0
	v_addc_co_u32_e32 v15, vcc, 0, v163, vcc
	global_load_dwordx4 v[106:109], v[14:15], off
	v_add_co_u32_e32 v14, vcc, s2, v162
	s_mov_b32 s2, 0x1c000
	s_nop 0
	v_addc_co_u32_e32 v15, vcc, 0, v163, vcc
	global_load_dwordx4 v[98:101], v[14:15], off
	v_add_co_u32_e32 v14, vcc, s2, v162
	s_mov_b32 s2, 0x24000
	s_nop 0
	v_addc_co_u32_e32 v15, vcc, 0, v163, vcc
	global_load_dwordx4 v[90:93], v[14:15], off
	ds_read_b128 v[14:17], v164
	s_mov_b32 s60, s58
	s_mov_b32 s61, s59
	s_mov_b64 s[48:49], s[42:43]
	v_readlane_b32 s65, v255, 29
	v_readlane_b32 s68, v255, 32
	v_readlane_b32 s69, v255, 33
	v_readlane_b32 s70, v255, 34
	v_readlane_b32 s71, v255, 35
	s_waitcnt vmcnt(8) lgkmcnt(0)
	v_pk_mul_f32 v[14:15], v[18:19], v[14:15]
	s_waitcnt vmcnt(7)
	v_pk_fma_f32 v[10:11], v[10:11], s[34:35], v[14:15] op_sel_hi:[1,0,1]
	v_pk_mul_f32 v[14:15], v[20:21], v[16:17]
	s_nop 0
	v_pk_fma_f32 v[12:13], v[12:13], s[34:35], v[14:15] op_sel_hi:[1,0,1]
	global_store_dwordx4 v[152:153], v[10:13], off sc1
	ds_read_b128 v[10:13], v158
	s_waitcnt lgkmcnt(0)
	v_pk_mul_f32 v[10:11], v[18:19], v[10:11]
	v_pk_mul_f32 v[12:13], v[20:21], v[12:13]
	s_waitcnt vmcnt(7)
	v_pk_fma_f32 v[10:11], v[102:103], s[34:35], v[10:11] op_sel_hi:[1,0,1]
	v_pk_fma_f32 v[12:13], v[104:105], s[34:35], v[12:13] op_sel_hi:[1,0,1]
	global_store_dwordx4 v[156:157], v[10:13], off sc1
	ds_read_b128 v[10:13], v158 offset:1088
	s_waitcnt lgkmcnt(0)
	v_pk_mul_f32 v[10:11], v[18:19], v[10:11]
	v_pk_mul_f32 v[12:13], v[20:21], v[12:13]
	s_waitcnt vmcnt(7)
; template <int EPI>
; DI void gemm_phase(const P& p, int l, const u16* __restrict__ A, const u16* __restrict__ Bt, int mpx, char* lds) {
;     ...
;     for (int mi = 0; mi < 8; ++mi) {
;       float4 xv[4];
; #pragma unroll
;       for (int i = 0; i < 4; ++i) xv[i] = xn[i];
;       if (mi < 7) {
; #pragma unroll
;         for (int i = 0; i < 4; ++i) xn[i] = *(const float4*)(xr + (size_t)((mi + 1) * 16 + rr0 + 4 * i) * 1024 + c4);
;       }
; #pragma unroll
;       for (int ni = 0; ni < 4; ++ni)
; #pragma unroll
;         for (int j = 0; j < 4; ++j) Cw[(g * 4 + j) * 68 + ni * 16 + r] = acc[mi][ni][j];
;       __builtin_amdgcn_fence(__ATOMIC_RELEASE, "wavefront");
; #pragma unroll
;       for (int i = 0; i < 4; ++i) {
;         const int row = rr0 + 4 * i;
;         const float4 a = *(const float4*)&Cw[row * 68 + c4];
;         float4 z;
;         z.x = alpha * xv[i].x + gt.x * a.x;
;         z.y = alpha * xv[i].y + gt.y * a.y;
;         z.z = alpha * xv[i].z + gt.z * a.z;
;         z.w = alpha * xv[i].w + gt.w * a.w;
;         *(float4*)(Z + (size_t)(mi * 16 + row) * 1024 + c4) = z;
;       }
;       __builtin_amdgcn_fence(__ATOMIC_RELEASE, "wavefront");
	v_pk_fma_f32 v[10:11], v[94:95], s[34:35], v[10:11] op_sel_hi:[1,0,1]
	v_pk_fma_f32 v[12:13], v[96:97], s[34:35], v[12:13] op_sel_hi:[1,0,1]
	global_store_dwordx4 v[154:155], v[10:13], off sc1
	ds_read_b128 v[10:13], v158 offset:2176
	s_waitcnt lgkmcnt(0)
	v_pk_mul_f32 v[10:11], v[18:19], v[10:11]
	v_pk_mul_f32 v[12:13], v[20:21], v[12:13]
	s_waitcnt vmcnt(7)
	v_pk_fma_f32 v[10:11], v[86:87], s[34:35], v[10:11] op_sel_hi:[1,0,1]
	v_pk_fma_f32 v[12:13], v[88:89], s[34:35], v[12:13] op_sel_hi:[1,0,1]
	global_store_dwordx4 v[150:151], v[10:13], off sc1
	ds_write2_b32 v165, v138, v142 offset1:16
	ds_write2_b32 v165, v139, v143 offset0:68 offset1:84
	ds_write2_b32 v165, v140, v144 offset0:136 offset1:152
	ds_write2_b32 v165, v141, v145 offset0:204 offset1:220
	ds_write2_b32 v165, v130, v134 offset0:32 offset1:48
	ds_write2_b32 v165, v131, v135 offset0:100 offset1:116
	ds_write2_b32 v165, v132, v136 offset0:168 offset1:184
	ds_write2_b32 v165, v133, v137 offset0:236 offset1:252
	v_add_co_u32_e32 v10, vcc, s33, v162
	s_nop 1
	v_addc_co_u32_e32 v11, vcc, 0, v163, vcc
	global_load_dwordx4 v[110:113], v[10:11], off
	v_add_co_u32_e32 v10, vcc, s2, v162
	s_mov_b32 s2, 0x28000
	s_nop 0
	v_addc_co_u32_e32 v11, vcc, 0, v163, vcc
	global_load_dwordx4 v[102:105], v[10:11], off
	v_add_co_u32_e32 v10, vcc, s2, v162
	s_mov_b32 s2, 0x2c000
	s_nop 0
	v_addc_co_u32_e32 v11, vcc, 0, v163, vcc
	global_load_dwordx4 v[94:97], v[10:11], off
	v_add_co_u32_e32 v10, vcc, s2, v162
	s_mov_b32 s2, 0x34000
	s_nop 0
	v_addc_co_u32_e32 v11, vcc, 0, v163, vcc
	global_load_dwordx4 v[86:89], v[10:11], off
	ds_read_b128 v[10:13], v164
	v_add_co_u32_e32 v14, vcc, s85, v152
	s_waitcnt lgkmcnt(0)
	v_pk_mul_f32 v[10:11], v[18:19], v[10:11]
	v_pk_mul_f32 v[12:13], v[20:21], v[12:13]
	s_waitcnt vmcnt(11)
	v_pk_fma_f32 v[10:11], v[146:147], s[34:35], v[10:11] op_sel_hi:[1,0,1]
	v_pk_fma_f32 v[12:13], v[148:149], s[34:35], v[12:13] op_sel_hi:[1,0,1]
	v_addc_co_u32_e32 v15, vcc, 0, v153, vcc
	global_store_dwordx4 v[14:15], v[10:13], off sc1
	ds_read_b128 v[10:13], v158
	v_add_co_u32_e32 v14, vcc, s85, v156
	s_waitcnt lgkmcnt(0)
	v_pk_mul_f32 v[10:11], v[18:19], v[10:11]
	v_pk_mul_f32 v[12:13], v[20:21], v[12:13]
	s_waitcnt vmcnt(11)
	v_pk_fma_f32 v[10:11], v[106:107], s[34:35], v[10:11] op_sel_hi:[1,0,1]
	v_pk_fma_f32 v[12:13], v[108:109], s[34:35], v[12:13] op_sel_hi:[1,0,1]
	v_addc_co_u32_e32 v15, vcc, 0, v157, vcc
	global_store_dwordx4 v[14:15], v[10:13], off sc1
	ds_read_b128 v[10:13], v158 offset:1088
	v_add_co_u32_e32 v14, vcc, s85, v154
	s_waitcnt lgkmcnt(0)
	v_pk_mul_f32 v[10:11], v[18:19], v[10:11]
	v_pk_mul_f32 v[12:13], v[20:21], v[12:13]
	s_waitcnt vmcnt(11)
	v_pk_fma_f32 v[10:11], v[98:99], s[34:35], v[10:11] op_sel_hi:[1,0,1]
	v_pk_fma_f32 v[12:13], v[100:101], s[34:35], v[12:13] op_sel_hi:[1,0,1]
	v_addc_co_u32_e32 v15, vcc, 0, v155, vcc
	global_store_dwordx4 v[14:15], v[10:13], off sc1
	ds_read_b128 v[10:13], v158 offset:2176
	v_add_co_u32_e32 v14, vcc, s85, v150
	s_waitcnt lgkmcnt(0)
	v_pk_mul_f32 v[10:11], v[18:19], v[10:11]
	v_pk_mul_f32 v[12:13], v[20:21], v[12:13]
	s_waitcnt vmcnt(11)
	v_pk_fma_f32 v[10:11], v[90:91], s[34:35], v[10:11] op_sel_hi:[1,0,1]
	v_pk_fma_f32 v[12:13], v[92:93], s[34:35], v[12:13] op_sel_hi:[1,0,1]
	v_addc_co_u32_e32 v15, vcc, 0, v151, vcc
	global_store_dwordx4 v[14:15], v[10:13], off sc1
	ds_write2_b32 v165, v122, v126 offset1:16
	ds_write2_b32 v165, v123, v127 offset0:68 offset1:84
	ds_write2_b32 v165, v124, v128 offset0:136 offset1:152
	ds_write2_b32 v165, v125, v129 offset0:204 offset1:220
	ds_write2_b32 v165, v114, v118 offset0:32 offset1:48
	ds_write2_b32 v165, v115, v119 offset0:100 offset1:116
	ds_write2_b32 v165, v116, v120 offset0:168 offset1:184
	ds_write2_b32 v165, v117, v121 offset0:236 offset1:252
	v_add_co_u32_e32 v10, vcc, s46, v162
	s_nop 1
	v_addc_co_u32_e32 v11, vcc, 0, v163, vcc
	global_load_dwordx4 v[114:117], v[10:11], off
	v_add_co_u32_e32 v10, vcc, s2, v162
	s_mov_b32 s2, 0x38000
	s_nop 0
	v_addc_co_u32_e32 v11, vcc, 0, v163, vcc
	global_load_dwordx4 v[106:109], v[10:11], off
	v_add_co_u32_e32 v10, vcc, s2, v162
	s_mov_b32 s2, 0x3c000
	s_nop 0
	v_addc_co_u32_e32 v11, vcc, 0, v163, vcc
	global_load_dwordx4 v[98:101], v[10:11], off
	v_add_co_u32_e32 v10, vcc, s2, v162
	s_mov_b32 s2, 0x44000
	s_nop 0
	v_addc_co_u32_e32 v11, vcc, 0, v163, vcc
	global_load_dwordx4 v[90:93], v[10:11], off
	ds_read_b128 v[10:13], v164
	v_add_co_u32_e32 v14, vcc, s33, v152
	s_waitcnt lgkmcnt(0)
	v_pk_mul_f32 v[10:11], v[18:19], v[10:11]
	v_pk_mul_f32 v[12:13], v[20:21], v[12:13]
	s_waitcnt vmcnt(11)
	v_pk_fma_f32 v[10:11], v[110:111], s[34:35], v[10:11] op_sel_hi:[1,0,1]
	v_pk_fma_f32 v[12:13], v[112:113], s[34:35], v[12:13] op_sel_hi:[1,0,1]
	v_addc_co_u32_e32 v15, vcc, 0, v153, vcc
	global_store_dwordx4 v[14:15], v[10:13], off sc1
	ds_read_b128 v[10:13], v158
	v_add_co_u32_e32 v14, vcc, s33, v156
	s_waitcnt lgkmcnt(0)
	v_pk_mul_f32 v[10:11], v[18:19], v[10:11]
	v_pk_mul_f32 v[12:13], v[20:21], v[12:13]
	s_waitcnt vmcnt(11)
	v_pk_fma_f32 v[10:11], v[102:103], s[34:35], v[10:11] op_sel_hi:[1,0,1]
	v_pk_fma_f32 v[12:13], v[104:105], s[34:35], v[12:13] op_sel_hi:[1,0,1]
	v_addc_co_u32_e32 v15, vcc, 0, v157, vcc
	global_store_dwordx4 v[14:15], v[10:13], off sc1
	ds_read_b128 v[10:13], v158 offset:1088
	v_add_co_u32_e32 v14, vcc, s33, v154
	s_waitcnt lgkmcnt(0)
	v_pk_mul_f32 v[10:11], v[18:19], v[10:11]
	v_pk_mul_f32 v[12:13], v[20:21], v[12:13]
	s_waitcnt vmcnt(11)
	v_pk_fma_f32 v[10:11], v[94:95], s[34:35], v[10:11] op_sel_hi:[1,0,1]
	v_pk_fma_f32 v[12:13], v[96:97], s[34:35], v[12:13] op_sel_hi:[1,0,1]
	v_addc_co_u32_e32 v15, vcc, 0, v155, vcc
	global_store_dwordx4 v[14:15], v[10:13], off sc1
	ds_read_b128 v[10:13], v158 offset:2176
	v_add_co_u32_e32 v14, vcc, s33, v150
	s_waitcnt lgkmcnt(0)
; template <int EPI>
; DI void gemm_phase(const P& p, int l, const u16* __restrict__ A, const u16* __restrict__ Bt, int mpx, char* lds) {
;     ...
;     for (int mi = 0; mi < 8; ++mi) {
;       float4 xv[4];
; #pragma unroll
;       for (int i = 0; i < 4; ++i) xv[i] = xn[i];
;       if (mi < 7) {
; #pragma unroll
;         for (int i = 0; i < 4; ++i) xn[i] = *(const float4*)(xr + (size_t)((mi + 1) * 16 + rr0 + 4 * i) * 1024 + c4);
;       }
; #pragma unroll
;       for (int ni = 0; ni < 4; ++ni)
; #pragma unroll
;         for (int j = 0; j < 4; ++j) Cw[(g * 4 + j) * 68 + ni * 16 + r] = acc[mi][ni][j];
;       __builtin_amdgcn_fence(__ATOMIC_RELEASE, "wavefront");
; #pragma unroll
;       for (int i = 0; i < 4; ++i) {
;         const int row = rr0 + 4 * i;
;         const float4 a = *(const float4*)&Cw[row * 68 + c4];
;         float4 z;
;         z.x = alpha * xv[i].x + gt.x * a.x;
;         z.y = alpha * xv[i].y + gt.y * a.y;
;         z.z = alpha * xv[i].z + gt.z * a.z;
;         z.w = alpha * xv[i].w + gt.w * a.w;
;         *(float4*)(Z + (size_t)(mi * 16 + row) * 1024 + c4) = z;
;       }
;       __builtin_amdgcn_fence(__ATOMIC_RELEASE, "wavefront");
	v_pk_mul_f32 v[10:11], v[18:19], v[10:11]
	v_pk_mul_f32 v[12:13], v[20:21], v[12:13]
	s_waitcnt vmcnt(11)
	v_pk_fma_f32 v[10:11], v[86:87], s[34:35], v[10:11] op_sel_hi:[1,0,1]
	v_pk_fma_f32 v[12:13], v[88:89], s[34:35], v[12:13] op_sel_hi:[1,0,1]
	v_addc_co_u32_e32 v15, vcc, 0, v151, vcc
	global_store_dwordx4 v[14:15], v[10:13], off sc1
	ds_write2_b32 v165, v78, v82 offset1:16
	ds_write2_b32 v165, v79, v83 offset0:68 offset1:84
	ds_write2_b32 v165, v80, v84 offset0:136 offset1:152
	ds_write2_b32 v165, v81, v85 offset0:204 offset1:220
	ds_write2_b32 v165, v70, v74 offset0:32 offset1:48
	ds_write2_b32 v165, v71, v75 offset0:100 offset1:116
	ds_write2_b32 v165, v72, v76 offset0:168 offset1:184
	ds_write2_b32 v165, v73, v77 offset0:236 offset1:252
	v_add_co_u32_e32 v10, vcc, s35, v162
	s_nop 1
	v_addc_co_u32_e32 v11, vcc, 0, v163, vcc
	global_load_dwordx4 v[82:85], v[10:11], off
	v_add_co_u32_e32 v10, vcc, s2, v162
	s_mov_b32 s2, 0x48000
	s_nop 0
	v_addc_co_u32_e32 v11, vcc, 0, v163, vcc
	global_load_dwordx4 v[78:81], v[10:11], off
	v_add_co_u32_e32 v10, vcc, s2, v162
	s_mov_b32 s2, 0x4c000
	s_nop 0
	v_addc_co_u32_e32 v11, vcc, 0, v163, vcc
	global_load_dwordx4 v[74:77], v[10:11], off
	v_add_co_u32_e32 v10, vcc, s2, v162
	s_mov_b32 s2, 0x54000
	s_nop 0
	v_addc_co_u32_e32 v11, vcc, 0, v163, vcc
	global_load_dwordx4 v[70:73], v[10:11], off
	ds_read_b128 v[10:13], v164
	v_add_co_u32_e32 v14, vcc, s46, v152
	s_waitcnt lgkmcnt(0)
	v_pk_mul_f32 v[10:11], v[18:19], v[10:11]
	v_pk_mul_f32 v[12:13], v[20:21], v[12:13]
	s_waitcnt vmcnt(11)
	v_pk_fma_f32 v[10:11], v[114:115], s[34:35], v[10:11] op_sel_hi:[1,0,1]
	v_pk_fma_f32 v[12:13], v[116:117], s[34:35], v[12:13] op_sel_hi:[1,0,1]
	v_addc_co_u32_e32 v15, vcc, 0, v153, vcc
	global_store_dwordx4 v[14:15], v[10:13], off sc1
	ds_read_b128 v[10:13], v158
	v_add_co_u32_e32 v14, vcc, s46, v156
	s_waitcnt lgkmcnt(0)
	v_pk_mul_f32 v[10:11], v[18:19], v[10:11]
	v_pk_mul_f32 v[12:13], v[20:21], v[12:13]
	s_waitcnt vmcnt(11)
	v_pk_fma_f32 v[10:11], v[106:107], s[34:35], v[10:11] op_sel_hi:[1,0,1]
	v_pk_fma_f32 v[12:13], v[108:109], s[34:35], v[12:13] op_sel_hi:[1,0,1]
	v_addc_co_u32_e32 v15, vcc, 0, v157, vcc
	global_store_dwordx4 v[14:15], v[10:13], off sc1
	ds_read_b128 v[10:13], v158 offset:1088
	v_add_co_u32_e32 v14, vcc, s46, v154
	s_waitcnt lgkmcnt(0)
	v_pk_mul_f32 v[10:11], v[18:19], v[10:11]
	v_pk_mul_f32 v[12:13], v[20:21], v[12:13]
	s_waitcnt vmcnt(11)
	v_pk_fma_f32 v[10:11], v[98:99], s[34:35], v[10:11] op_sel_hi:[1,0,1]
	v_pk_fma_f32 v[12:13], v[100:101], s[34:35], v[12:13] op_sel_hi:[1,0,1]
	v_addc_co_u32_e32 v15, vcc, 0, v155, vcc
	global_store_dwordx4 v[14:15], v[10:13], off sc1
	ds_read_b128 v[10:13], v158 offset:2176
	v_add_co_u32_e32 v14, vcc, s46, v150
	s_mov_b32 s46, 0x50000
	s_nop 0
	v_addc_co_u32_e32 v15, vcc, 0, v151, vcc
	s_waitcnt lgkmcnt(0)
	v_pk_mul_f32 v[10:11], v[18:19], v[10:11]
	v_pk_mul_f32 v[12:13], v[20:21], v[12:13]
	s_waitcnt vmcnt(11)
	v_pk_fma_f32 v[10:11], v[90:91], s[34:35], v[10:11] op_sel_hi:[1,0,1]
	v_pk_fma_f32 v[12:13], v[92:93], s[34:35], v[12:13] op_sel_hi:[1,0,1]
	global_store_dwordx4 v[14:15], v[10:13], off sc1
	ds_write2_b32 v165, v62, v66 offset1:16
	ds_write2_b32 v165, v63, v67 offset0:68 offset1:84
	ds_write2_b32 v165, v64, v68 offset0:136 offset1:152
	ds_write2_b32 v165, v65, v69 offset0:204 offset1:220
	ds_write2_b32 v165, v54, v58 offset0:32 offset1:48
	ds_write2_b32 v165, v55, v59 offset0:100 offset1:116
	ds_write2_b32 v165, v56, v60 offset0:168 offset1:184
	ds_write2_b32 v165, v57, v61 offset0:236 offset1:252
	v_add_co_u32_e32 v10, vcc, s46, v162
	s_nop 1
	v_addc_co_u32_e32 v11, vcc, 0, v163, vcc
	global_load_dwordx4 v[66:69], v[10:11], off
	v_add_co_u32_e32 v10, vcc, s2, v162
	s_mov_b32 s2, 0x58000
	s_nop 0
	v_addc_co_u32_e32 v11, vcc, 0, v163, vcc
	global_load_dwordx4 v[62:65], v[10:11], off
	v_add_co_u32_e32 v10, vcc, s2, v162
	s_mov_b32 s2, 0x5c000
	s_nop 0
	v_addc_co_u32_e32 v11, vcc, 0, v163, vcc
	global_load_dwordx4 v[58:61], v[10:11], off
	v_add_co_u32_e32 v10, vcc, s2, v162
	s_mov_b32 s2, 0x64000
	s_nop 0
	v_addc_co_u32_e32 v11, vcc, 0, v163, vcc
	global_load_dwordx4 v[54:57], v[10:11], off
	ds_read_b128 v[10:13], v164
	v_add_co_u32_e32 v14, vcc, s35, v152
	s_waitcnt lgkmcnt(0)
	v_pk_mul_f32 v[10:11], v[18:19], v[10:11]
	v_pk_mul_f32 v[12:13], v[20:21], v[12:13]
	s_waitcnt vmcnt(11)
	v_pk_fma_f32 v[10:11], v[82:83], s[34:35], v[10:11] op_sel_hi:[1,0,1]
	v_pk_fma_f32 v[12:13], v[84:85], s[34:35], v[12:13] op_sel_hi:[1,0,1]
	v_addc_co_u32_e32 v15, vcc, 0, v153, vcc
	global_store_dwordx4 v[14:15], v[10:13], off sc1
	ds_read_b128 v[10:13], v158
	v_add_co_u32_e32 v14, vcc, s35, v156
	s_waitcnt lgkmcnt(0)
	v_pk_mul_f32 v[10:11], v[18:19], v[10:11]
	v_pk_mul_f32 v[12:13], v[20:21], v[12:13]
	s_waitcnt vmcnt(11)
	v_pk_fma_f32 v[10:11], v[78:79], s[34:35], v[10:11] op_sel_hi:[1,0,1]
	v_pk_fma_f32 v[12:13], v[80:81], s[34:35], v[12:13] op_sel_hi:[1,0,1]
	v_addc_co_u32_e32 v15, vcc, 0, v157, vcc
	global_store_dwordx4 v[14:15], v[10:13], off sc1
	ds_read_b128 v[10:13], v158 offset:1088
	v_add_co_u32_e32 v14, vcc, s35, v154
	s_waitcnt lgkmcnt(0)
	v_pk_mul_f32 v[10:11], v[18:19], v[10:11]
	v_pk_mul_f32 v[12:13], v[20:21], v[12:13]
	s_waitcnt vmcnt(11)
	v_pk_fma_f32 v[10:11], v[74:75], s[34:35], v[10:11] op_sel_hi:[1,0,1]
	v_pk_fma_f32 v[12:13], v[76:77], s[34:35], v[12:13] op_sel_hi:[1,0,1]
	v_addc_co_u32_e32 v15, vcc, 0, v155, vcc
	global_store_dwordx4 v[14:15], v[10:13], off sc1
	ds_read_b128 v[10:13], v158 offset:2176
	v_add_co_u32_e32 v14, vcc, s35, v150
	s_waitcnt lgkmcnt(0)
	v_pk_mul_f32 v[10:11], v[18:19], v[10:11]
	v_pk_mul_f32 v[12:13], v[20:21], v[12:13]
	s_waitcnt vmcnt(11)
; template <int EPI>
; DI void gemm_phase(const P& p, int l, const u16* __restrict__ A, const u16* __restrict__ Bt, int mpx, char* lds) {
;     ...
;     for (int mi = 0; mi < 8; ++mi) {
;       float4 xv[4];
; #pragma unroll
;       for (int i = 0; i < 4; ++i) xv[i] = xn[i];
;       if (mi < 7) {
; #pragma unroll
;         for (int i = 0; i < 4; ++i) xn[i] = *(const float4*)(xr + (size_t)((mi + 1) * 16 + rr0 + 4 * i) * 1024 + c4);
;       }
; #pragma unroll
;       for (int ni = 0; ni < 4; ++ni)
; #pragma unroll
;         for (int j = 0; j < 4; ++j) Cw[(g * 4 + j) * 68 + ni * 16 + r] = acc[mi][ni][j];
;       __builtin_amdgcn_fence(__ATOMIC_RELEASE, "wavefront");
; #pragma unroll
;       for (int i = 0; i < 4; ++i) {
;         const int row = rr0 + 4 * i;
;         const float4 a = *(const float4*)&Cw[row * 68 + c4];
;         float4 z;
;         z.x = alpha * xv[i].x + gt.x * a.x;
;         z.y = alpha * xv[i].y + gt.y * a.y;
;         z.z = alpha * xv[i].z + gt.z * a.z;
;         z.w = alpha * xv[i].w + gt.w * a.w;
;         *(float4*)(Z + (size_t)(mi * 16 + row) * 1024 + c4) = z;
;       }
;       __builtin_amdgcn_fence(__ATOMIC_RELEASE, "wavefront");
	v_pk_fma_f32 v[10:11], v[70:71], s[34:35], v[10:11] op_sel_hi:[1,0,1]
	v_pk_fma_f32 v[12:13], v[72:73], s[34:35], v[12:13] op_sel_hi:[1,0,1]
	v_addc_co_u32_e32 v15, vcc, 0, v151, vcc
	global_store_dwordx4 v[14:15], v[10:13], off sc1
	ds_write2_b32 v165, v46, v50 offset1:16
	ds_write2_b32 v165, v47, v51 offset0:68 offset1:84
	ds_write2_b32 v165, v48, v52 offset0:136 offset1:152
	ds_write2_b32 v165, v49, v53 offset0:204 offset1:220
	ds_write2_b32 v165, v38, v42 offset0:32 offset1:48
	ds_write2_b32 v165, v39, v43 offset0:100 offset1:116
	ds_write2_b32 v165, v40, v44 offset0:168 offset1:184
	ds_write2_b32 v165, v41, v45 offset0:236 offset1:252
	v_add_co_u32_e32 v10, vcc, s39, v162
	s_nop 1
	v_addc_co_u32_e32 v11, vcc, 0, v163, vcc
	global_load_dwordx4 v[50:53], v[10:11], off
	v_add_co_u32_e32 v10, vcc, s2, v162
	s_mov_b32 s2, 0x68000
	s_nop 0
	v_addc_co_u32_e32 v11, vcc, 0, v163, vcc
	global_load_dwordx4 v[46:49], v[10:11], off
	v_add_co_u32_e32 v10, vcc, s2, v162
	s_mov_b32 s2, 0x6c000
	s_nop 0
	v_addc_co_u32_e32 v11, vcc, 0, v163, vcc
	global_load_dwordx4 v[42:45], v[10:11], off
	v_add_co_u32_e32 v10, vcc, s2, v162
	s_mov_b32 s2, 0x74000
	s_nop 0
	v_addc_co_u32_e32 v11, vcc, 0, v163, vcc
	global_load_dwordx4 v[38:41], v[10:11], off
	ds_read_b128 v[10:13], v164
	v_add_co_u32_e32 v14, vcc, s46, v152
	s_waitcnt lgkmcnt(0)
	v_pk_mul_f32 v[10:11], v[18:19], v[10:11]
	v_pk_mul_f32 v[12:13], v[20:21], v[12:13]
	s_waitcnt vmcnt(11)
	v_pk_fma_f32 v[10:11], v[66:67], s[34:35], v[10:11] op_sel_hi:[1,0,1]
	v_pk_fma_f32 v[12:13], v[68:69], s[34:35], v[12:13] op_sel_hi:[1,0,1]
	v_addc_co_u32_e32 v15, vcc, 0, v153, vcc
	global_store_dwordx4 v[14:15], v[10:13], off sc1
	ds_read_b128 v[10:13], v158
	v_add_co_u32_e32 v14, vcc, s46, v156
	s_waitcnt lgkmcnt(0)
	v_pk_mul_f32 v[10:11], v[18:19], v[10:11]
	v_pk_mul_f32 v[12:13], v[20:21], v[12:13]
	s_waitcnt vmcnt(11)
	v_pk_fma_f32 v[10:11], v[62:63], s[34:35], v[10:11] op_sel_hi:[1,0,1]
	v_pk_fma_f32 v[12:13], v[64:65], s[34:35], v[12:13] op_sel_hi:[1,0,1]
	v_addc_co_u32_e32 v15, vcc, 0, v157, vcc
	global_store_dwordx4 v[14:15], v[10:13], off sc1
	ds_read_b128 v[10:13], v158 offset:1088
	v_add_co_u32_e32 v14, vcc, s46, v154
	s_waitcnt lgkmcnt(0)
	v_pk_mul_f32 v[10:11], v[18:19], v[10:11]
	v_pk_mul_f32 v[12:13], v[20:21], v[12:13]
	s_waitcnt vmcnt(11)
	v_pk_fma_f32 v[10:11], v[58:59], s[34:35], v[10:11] op_sel_hi:[1,0,1]
	v_pk_fma_f32 v[12:13], v[60:61], s[34:35], v[12:13] op_sel_hi:[1,0,1]
	v_addc_co_u32_e32 v15, vcc, 0, v155, vcc
	global_store_dwordx4 v[14:15], v[10:13], off sc1
	ds_read_b128 v[10:13], v158 offset:2176
	v_add_co_u32_e32 v14, vcc, s46, v150
	s_mov_b32 s46, 0x70000
	s_nop 0
	v_addc_co_u32_e32 v15, vcc, 0, v151, vcc
	s_waitcnt lgkmcnt(0)
	v_pk_mul_f32 v[10:11], v[18:19], v[10:11]
	v_pk_mul_f32 v[12:13], v[20:21], v[12:13]
	s_waitcnt vmcnt(11)
	v_pk_fma_f32 v[10:11], v[54:55], s[34:35], v[10:11] op_sel_hi:[1,0,1]
	v_pk_fma_f32 v[12:13], v[56:57], s[34:35], v[12:13] op_sel_hi:[1,0,1]
	global_store_dwordx4 v[14:15], v[10:13], off sc1
	ds_write2_b32 v165, v30, v34 offset1:16
	ds_write2_b32 v165, v31, v35 offset0:68 offset1:84
	ds_write2_b32 v165, v32, v36 offset0:136 offset1:152
	ds_write2_b32 v165, v33, v37 offset0:204 offset1:220
	ds_write2_b32 v165, v22, v26 offset0:32 offset1:48
	ds_write2_b32 v165, v23, v27 offset0:100 offset1:116
	ds_write2_b32 v165, v24, v28 offset0:168 offset1:184
	ds_write2_b32 v165, v25, v29 offset0:236 offset1:252
	v_add_co_u32_e32 v10, vcc, s46, v162
	s_nop 1
	v_addc_co_u32_e32 v11, vcc, 0, v163, vcc
	global_load_dwordx4 v[10:13], v[10:11], off
	v_add_co_u32_e32 v14, vcc, s2, v162
	s_mov_b32 s2, 0x78000
	s_nop 0
	v_addc_co_u32_e32 v15, vcc, 0, v163, vcc
	global_load_dwordx4 v[30:33], v[14:15], off
	v_add_co_u32_e32 v14, vcc, s2, v162
	s_mov_b32 s2, 0x7c000
	s_nop 0
	v_addc_co_u32_e32 v15, vcc, 0, v163, vcc
	global_load_dwordx4 v[26:29], v[14:15], off
	v_add_co_u32_e32 v14, vcc, s2, v162
	s_nop 1
	v_addc_co_u32_e32 v15, vcc, 0, v163, vcc
	global_load_dwordx4 v[22:25], v[14:15], off
	ds_read_b128 v[14:17], v164
	v_add_co_u32_e32 v34, vcc, s39, v152
	s_waitcnt lgkmcnt(0)
; template <int EPI>
; DI void gemm_phase(const P& p, int l, const u16* __restrict__ A, const u16* __restrict__ Bt, int mpx, char* lds) {
;     ...
;     for (int mi = 0; mi < 8; ++mi) {
;       float4 xv[4];
; #pragma unroll
;       for (int i = 0; i < 4; ++i) xv[i] = xn[i];
;       if (mi < 7) {
; #pragma unroll
;         for (int i = 0; i < 4; ++i) xn[i] = *(const float4*)(xr + (size_t)((mi + 1) * 16 + rr0 + 4 * i) * 1024 + c4);
;       }
; #pragma unroll
;       for (int ni = 0; ni < 4; ++ni)
; #pragma unroll
;         for (int j = 0; j < 4; ++j) Cw[(g * 4 + j) * 68 + ni * 16 + r] = acc[mi][ni][j];
;       __builtin_amdgcn_fence(__ATOMIC_RELEASE, "wavefront");
; #pragma unroll
;       for (int i = 0; i < 4; ++i) {
;         const int row = rr0 + 4 * i;
;         const float4 a = *(const float4*)&Cw[row * 68 + c4];
;         float4 z;
;         z.x = alpha * xv[i].x + gt.x * a.x;
;         z.y = alpha * xv[i].y + gt.y * a.y;
;         z.z = alpha * xv[i].z + gt.z * a.z;
;         z.w = alpha * xv[i].w + gt.w * a.w;
;         *(float4*)(Z + (size_t)(mi * 16 + row) * 1024 + c4) = z;
;       }
;       __builtin_amdgcn_fence(__ATOMIC_RELEASE, "wavefront");
;     ...
;   if (!has_next) break;
;   t = tn; m0 = m1; n0 = n1; Ag = Agn; Bg = Bgn;
	v_pk_mul_f32 v[14:15], v[18:19], v[14:15]
	v_pk_mul_f32 v[16:17], v[20:21], v[16:17]
	s_waitcnt vmcnt(11)
	v_pk_fma_f32 v[14:15], v[50:51], s[34:35], v[14:15] op_sel_hi:[1,0,1]
	v_pk_fma_f32 v[16:17], v[52:53], s[34:35], v[16:17] op_sel_hi:[1,0,1]
	v_addc_co_u32_e32 v35, vcc, 0, v153, vcc
	global_store_dwordx4 v[34:35], v[14:17], off sc1
	ds_read_b128 v[14:17], v158
	v_add_co_u32_e32 v34, vcc, s39, v156
	s_waitcnt lgkmcnt(0)
	v_pk_mul_f32 v[14:15], v[18:19], v[14:15]
	v_pk_mul_f32 v[16:17], v[20:21], v[16:17]
	s_waitcnt vmcnt(11)
	v_pk_fma_f32 v[14:15], v[46:47], s[34:35], v[14:15] op_sel_hi:[1,0,1]
	v_pk_fma_f32 v[16:17], v[48:49], s[34:35], v[16:17] op_sel_hi:[1,0,1]
	v_addc_co_u32_e32 v35, vcc, 0, v157, vcc
	global_store_dwordx4 v[34:35], v[14:17], off sc1
	ds_read_b128 v[14:17], v158 offset:1088
	v_add_co_u32_e32 v34, vcc, s39, v154
	s_waitcnt lgkmcnt(0)
	v_pk_mul_f32 v[14:15], v[18:19], v[14:15]
	v_pk_mul_f32 v[16:17], v[20:21], v[16:17]
	s_waitcnt vmcnt(11)
	v_pk_fma_f32 v[14:15], v[42:43], s[34:35], v[14:15] op_sel_hi:[1,0,1]
	v_pk_fma_f32 v[16:17], v[44:45], s[34:35], v[16:17] op_sel_hi:[1,0,1]
	v_addc_co_u32_e32 v35, vcc, 0, v155, vcc
	global_store_dwordx4 v[34:35], v[14:17], off sc1
	ds_read_b128 v[14:17], v158 offset:2176
	v_add_co_u32_e32 v34, vcc, s39, v150
	s_waitcnt lgkmcnt(0)
	v_pk_mul_f32 v[14:15], v[18:19], v[14:15]
	v_pk_mul_f32 v[16:17], v[20:21], v[16:17]
	s_waitcnt vmcnt(11)
	v_pk_fma_f32 v[14:15], v[38:39], s[34:35], v[14:15] op_sel_hi:[1,0,1]
	v_pk_fma_f32 v[16:17], v[40:41], s[34:35], v[16:17] op_sel_hi:[1,0,1]
	v_addc_co_u32_e32 v35, vcc, 0, v151, vcc
	global_store_dwordx4 v[34:35], v[14:17], off sc1
	ds_write2_b32 v165, v166, v170 offset1:16
	ds_write2_b32 v165, v167, v171 offset0:68 offset1:84
	ds_write2_b32 v165, v168, v172 offset0:136 offset1:152
	ds_write2_b32 v165, v169, v173 offset0:204 offset1:220
	ds_write2_b32 v165, v2, v6 offset0:32 offset1:48
	ds_write2_b32 v165, v3, v7 offset0:100 offset1:116
	ds_write2_b32 v165, v4, v8 offset0:168 offset1:184
	ds_write2_b32 v165, v5, v9 offset0:236 offset1:252
	ds_read_b128 v[2:5], v164
	v_add_co_u32_e32 v6, vcc, s46, v152
	s_waitcnt lgkmcnt(0)
	v_pk_mul_f32 v[2:3], v[18:19], v[2:3]
	v_pk_mul_f32 v[4:5], v[20:21], v[4:5]
	v_addc_co_u32_e32 v7, vcc, 0, v153, vcc
	s_waitcnt vmcnt(7)
	v_pk_fma_f32 v[2:3], v[10:11], s[34:35], v[2:3] op_sel_hi:[1,0,1]
	v_pk_fma_f32 v[4:5], v[12:13], s[34:35], v[4:5] op_sel_hi:[1,0,1]
	global_store_dwordx4 v[6:7], v[2:5], off sc1
	ds_read_b128 v[2:5], v158
	v_add_co_u32_e32 v6, vcc, s46, v156
	s_waitcnt lgkmcnt(0)
	v_pk_mul_f32 v[2:3], v[18:19], v[2:3]
	v_pk_mul_f32 v[4:5], v[20:21], v[4:5]
	s_waitcnt vmcnt(7)
	v_pk_fma_f32 v[2:3], v[30:31], s[34:35], v[2:3] op_sel_hi:[1,0,1]
	v_pk_fma_f32 v[4:5], v[32:33], s[34:35], v[4:5] op_sel_hi:[1,0,1]
	v_addc_co_u32_e32 v7, vcc, 0, v157, vcc
	global_store_dwordx4 v[6:7], v[2:5], off sc1
	ds_read_b128 v[2:5], v158 offset:1088
	v_add_co_u32_e32 v6, vcc, s46, v154
	s_mov_b64 s[46:47], s[44:45]
	s_nop 0
	v_addc_co_u32_e32 v7, vcc, 0, v155, vcc
	s_waitcnt lgkmcnt(0)
	v_pk_mul_f32 v[2:3], v[18:19], v[2:3]
	v_pk_mul_f32 v[4:5], v[20:21], v[4:5]
	s_waitcnt vmcnt(7)
	v_pk_fma_f32 v[2:3], v[26:27], s[34:35], v[2:3] op_sel_hi:[1,0,1]
	v_pk_fma_f32 v[4:5], v[28:29], s[34:35], v[4:5] op_sel_hi:[1,0,1]
	global_store_dwordx4 v[6:7], v[2:5], off sc1
	ds_read_b128 v[2:5], v158 offset:2176
	v_add_co_u32_e32 v6, vcc, 0x70000, v150
	s_waitcnt lgkmcnt(0)
	v_pk_mul_f32 v[2:3], v[18:19], v[2:3]
	v_pk_mul_f32 v[4:5], v[20:21], v[4:5]
	v_addc_co_u32_e32 v7, vcc, 0, v151, vcc
	s_waitcnt vmcnt(7)
	v_pk_fma_f32 v[2:3], v[22:23], s[34:35], v[2:3] op_sel_hi:[1,0,1]
	v_pk_fma_f32 v[4:5], v[24:25], s[34:35], v[4:5] op_sel_hi:[1,0,1]
	s_and_b64 vcc, exec, s[40:41]
	global_store_dwordx4 v[6:7], v[2:5], off sc1
	s_cbranch_vccz .LBB0_69
	v_mov_b32_e32 v236, 0x358637bd

; DI float silu(float v) { return v * __builtin_amdgcn_rcpf(1.f + __builtin_amdgcn_exp2f(-1.4426950408889634f * v)); }
; template <int EPI>
; DI void gemm_phase(const P& p, int l, const u16* __restrict__ A, const u16* __restrict__ Bt, int mpx, char* lds) {
;     ...
;           float v0 = acc[hf * 4 + mi][0][j], v1 = acc[hf * 4 + mi][1][j], v2 = acc[hf * 4 + mi][2][j], v3 = acc[hf * 4 + mi][3][j];
;           const int rowl = mi * 16 + g * 4 + j;
;           const int s = tokw + hf * 64 + rowl;
;           if (tr == 1) {
;             v0 = silu(v0); v1 = silu(v1); v2 = silu(v2); v3 = silu(v3);
;     ...
;           const unsigned u01 = pack2(v0, v1), u23 = pack2(v2, v3);
;           if (kind == 1) {
;             Tl[(0 * 16 + r) * 72 + rowl] = (u16)u01;
;             Tl[(1 * 16 + r) * 72 + rowl] = (u16)(u01 >> 16);
;             Tl[(2 * 16 + r) * 72 + rowl] = (u16)u23;
;             Tl[(3 * 16 + r) * 72 + rowl] = (u16)(u23 >> 16);
;           } else if (tr == 2) {
;             Tl[rowl * 72 + 0 * 16 + r] = f2h(v0);
;             Tl[rowl * 72 + 1 * 16 + r] = f2h(v1);
;             Tl[rowl * 72 + 2 * 16 + r] = f2h(v2);
;             Tl[rowl * 72 + 3 * 16 + r] = f2h(v3);
;           } else {
;             Tl[rowl * 72 + 0 * 16 + r] = (u16)u01;
;             Tl[rowl * 72 + 1 * 16 + r] = (u16)(u01 >> 16);
;             Tl[rowl * 72 + 2 * 16 + r] = (u16)u23;
;             Tl[rowl * 72 + 3 * 16 + r] = (u16)(u23 >> 16);
;           }
;         }
;       }
;       __builtin_amdgcn_fence(__ATOMIC_RELEASE, "wavefront");
;       u16* dh = (kind == 1) ? dst + hf * 64 : dst + (size_t)(hf * 64) * rstride;
; #pragma unroll
;       for (int i = 0; i < 8; ++i) {
;         const int c = lane + i * 64;
;         const int row = c >> 3, cc = c & 7;
;         uint4 v = *(const uint4*)&Tl[row * 72 + cc * 8];
;         *(uint4*)(dh + (size_t)row * rstride + cc * 8) = v;
;       }
.Lfe_k0_silu:
	s_add_u32 s62, s44, 0x1000
	s_addc_u32 s63, s45, 0
	v_mul_f32_e32 v174, 0xbfb8aa3b, v126
	v_mul_f32_e32 v175, 0xbfb8aa3b, v122
	v_mul_f32_e32 v176, 0xbfb8aa3b, v118
	v_mul_f32_e32 v177, 0xbfb8aa3b, v114
	v_exp_f32_e32 v174, v174
	v_exp_f32_e32 v175, v175
	v_exp_f32_e32 v176, v176
	v_exp_f32_e32 v177, v177
	v_add_f32_e32 v174, 1.0, v174
	v_add_f32_e32 v175, 1.0, v175
	v_add_f32_e32 v176, 1.0, v176
	v_add_f32_e32 v177, 1.0, v177
	v_rcp_f32_e32 v174, v174
	v_rcp_f32_e32 v175, v175
	v_rcp_f32_e32 v176, v176
	v_rcp_f32_e32 v177, v177
	v_mul_f32_e32 v174, v126, v174
	v_mul_f32_e32 v175, v122, v175
	v_mul_f32_e32 v176, v118, v176
	v_mul_f32_e32 v177, v114, v177
	v_cvt_pk_bf16_f32 v178, v174, v175
	v_cvt_pk_bf16_f32 v179, v176, v177
	ds_write_b16 v170, v178 offset:0
	ds_write_b16_d16_hi v170, v178 offset:32
	ds_write_b16 v170, v179 offset:64
	ds_write_b16_d16_hi v170, v179 offset:96
	v_mul_f32_e32 v180, 0xbfb8aa3b, v127
	v_mul_f32_e32 v181, 0xbfb8aa3b, v123
	v_mul_f32_e32 v182, 0xbfb8aa3b, v119
	v_mul_f32_e32 v183, 0xbfb8aa3b, v115
	v_exp_f32_e32 v180, v180
	v_exp_f32_e32 v181, v181
	v_exp_f32_e32 v182, v182
	v_exp_f32_e32 v183, v183
	v_add_f32_e32 v180, 1.0, v180
	v_add_f32_e32 v181, 1.0, v181
	v_add_f32_e32 v182, 1.0, v182
	v_add_f32_e32 v183, 1.0, v183
	v_rcp_f32_e32 v180, v180
	v_rcp_f32_e32 v181, v181
	v_rcp_f32_e32 v182, v182
	v_rcp_f32_e32 v183, v183
	v_mul_f32_e32 v180, v127, v180
	v_mul_f32_e32 v181, v123, v181
	v_mul_f32_e32 v182, v119, v182
	v_mul_f32_e32 v183, v115, v183
	v_cvt_pk_bf16_f32 v184, v180, v181
	v_cvt_pk_bf16_f32 v185, v182, v183
	ds_write_b16 v170, v184 offset:144
	ds_write_b16_d16_hi v170, v184 offset:176
	ds_write_b16 v170, v185 offset:208
	ds_write_b16_d16_hi v170, v185 offset:240
	v_mul_f32_e32 v186, 0xbfb8aa3b, v128
	v_mul_f32_e32 v187, 0xbfb8aa3b, v124
	v_mul_f32_e32 v188, 0xbfb8aa3b, v120
	v_mul_f32_e32 v189, 0xbfb8aa3b, v116
	v_exp_f32_e32 v186, v186
	v_exp_f32_e32 v187, v187
	v_exp_f32_e32 v188, v188
	v_exp_f32_e32 v189, v189
	v_add_f32_e32 v186, 1.0, v186
	v_add_f32_e32 v187, 1.0, v187
	v_add_f32_e32 v188, 1.0, v188
	v_add_f32_e32 v189, 1.0, v189
	v_rcp_f32_e32 v186, v186
	v_rcp_f32_e32 v187, v187
	v_rcp_f32_e32 v188, v188
	v_rcp_f32_e32 v189, v189
	v_mul_f32_e32 v186, v128, v186
	v_mul_f32_e32 v187, v124, v187
	v_mul_f32_e32 v188, v120, v188
	v_mul_f32_e32 v189, v116, v189
	v_cvt_pk_bf16_f32 v190, v186, v187
	v_cvt_pk_bf16_f32 v191, v188, v189
	ds_write_b16 v170, v190 offset:288
	ds_write_b16_d16_hi v170, v190 offset:320
	ds_write_b16 v170, v191 offset:352
	ds_write_b16_d16_hi v170, v191 offset:384
	v_mul_f32_e32 v192, 0xbfb8aa3b, v129
	v_mul_f32_e32 v193, 0xbfb8aa3b, v125
	v_mul_f32_e32 v174, 0xbfb8aa3b, v121
	v_mul_f32_e32 v175, 0xbfb8aa3b, v117
	v_exp_f32_e32 v192, v192
	v_exp_f32_e32 v193, v193
	v_exp_f32_e32 v174, v174
	v_exp_f32_e32 v175, v175
	v_add_f32_e32 v192, 1.0, v192
	v_add_f32_e32 v193, 1.0, v193
	v_add_f32_e32 v174, 1.0, v174
	v_add_f32_e32 v175, 1.0, v175
	v_rcp_f32_e32 v192, v192
	v_rcp_f32_e32 v193, v193
	v_rcp_f32_e32 v174, v174
	v_rcp_f32_e32 v175, v175
	v_mul_f32_e32 v192, v129, v192
	v_mul_f32_e32 v193, v125, v193
	v_mul_f32_e32 v174, v121, v174
	v_mul_f32_e32 v175, v117, v175
	v_cvt_pk_bf16_f32 v176, v192, v193
	v_cvt_pk_bf16_f32 v177, v174, v175
	ds_write_b16 v170, v176 offset:432
	ds_write_b16_d16_hi v170, v176 offset:464
	ds_write_b16 v170, v177 offset:496
	ds_write_b16_d16_hi v170, v177 offset:528
	v_mul_f32_e32 v178, 0xbfb8aa3b, v110
	v_mul_f32_e32 v179, 0xbfb8aa3b, v106
	v_mul_f32_e32 v180, 0xbfb8aa3b, v102
	v_mul_f32_e32 v181, 0xbfb8aa3b, v98
	v_exp_f32_e32 v178, v178
	v_exp_f32_e32 v179, v179
	v_exp_f32_e32 v180, v180
	v_exp_f32_e32 v181, v181
	v_add_f32_e32 v178, 1.0, v178
	v_add_f32_e32 v179, 1.0, v179
	v_add_f32_e32 v180, 1.0, v180
	v_add_f32_e32 v181, 1.0, v181
	v_rcp_f32_e32 v178, v178
	v_rcp_f32_e32 v179, v179
	v_rcp_f32_e32 v180, v180
	v_rcp_f32_e32 v181, v181
	v_mul_f32_e32 v178, v110, v178
	v_mul_f32_e32 v179, v106, v179
	v_mul_f32_e32 v180, v102, v180
	v_mul_f32_e32 v181, v98, v181
	v_cvt_pk_bf16_f32 v182, v178, v179
	v_cvt_pk_bf16_f32 v183, v180, v181
	ds_write_b16 v170, v182 offset:2304
	ds_write_b16_d16_hi v170, v182 offset:2336
	ds_write_b16 v170, v183 offset:2368
	ds_write_b16_d16_hi v170, v183 offset:2400
	v_mul_f32_e32 v184, 0xbfb8aa3b, v111
	v_mul_f32_e32 v185, 0xbfb8aa3b, v107
	v_mul_f32_e32 v186, 0xbfb8aa3b, v103
	v_mul_f32_e32 v187, 0xbfb8aa3b, v99
	v_exp_f32_e32 v184, v184
	v_exp_f32_e32 v185, v185
	v_exp_f32_e32 v186, v186
	v_exp_f32_e32 v187, v187
	v_add_f32_e32 v184, 1.0, v184
	v_add_f32_e32 v185, 1.0, v185
	v_add_f32_e32 v186, 1.0, v186
	v_add_f32_e32 v187, 1.0, v187
	v_rcp_f32_e32 v184, v184
	v_rcp_f32_e32 v185, v185
	v_rcp_f32_e32 v186, v186
	v_rcp_f32_e32 v187, v187
	v_mul_f32_e32 v184, v111, v184
	v_mul_f32_e32 v185, v107, v185
	v_mul_f32_e32 v186, v103, v186
	v_mul_f32_e32 v187, v99, v187
	v_cvt_pk_bf16_f32 v188, v184, v185
	v_cvt_pk_bf16_f32 v189, v186, v187
	ds_write_b16 v170, v188 offset:2448
	ds_write_b16_d16_hi v170, v188 offset:2480
	ds_write_b16 v170, v189 offset:2512
	ds_write_b16_d16_hi v170, v189 offset:2544
	v_mul_f32_e32 v190, 0xbfb8aa3b, v112
	v_mul_f32_e32 v191, 0xbfb8aa3b, v108
	v_mul_f32_e32 v192, 0xbfb8aa3b, v104
	v_mul_f32_e32 v193, 0xbfb8aa3b, v100
	v_exp_f32_e32 v190, v190
	v_exp_f32_e32 v191, v191
	v_exp_f32_e32 v192, v192
	v_exp_f32_e32 v193, v193
	v_add_f32_e32 v190, 1.0, v190
	v_add_f32_e32 v191, 1.0, v191
	v_add_f32_e32 v192, 1.0, v192
	v_add_f32_e32 v193, 1.0, v193
	v_rcp_f32_e32 v190, v190
	v_rcp_f32_e32 v191, v191
	v_rcp_f32_e32 v192, v192
	v_rcp_f32_e32 v193, v193
	v_mul_f32_e32 v190, v112, v190
; DI float silu(float v) { return v * __builtin_amdgcn_rcpf(1.f + __builtin_amdgcn_exp2f(-1.4426950408889634f * v)); }
; template <int EPI>
; DI void gemm_phase(const P& p, int l, const u16* __restrict__ A, const u16* __restrict__ Bt, int mpx, char* lds) {
;     ...
;           float v0 = acc[hf * 4 + mi][0][j], v1 = acc[hf * 4 + mi][1][j], v2 = acc[hf * 4 + mi][2][j], v3 = acc[hf * 4 + mi][3][j];
;           const int rowl = mi * 16 + g * 4 + j;
;           const int s = tokw + hf * 64 + rowl;
;           if (tr == 1) {
;             v0 = silu(v0); v1 = silu(v1); v2 = silu(v2); v3 = silu(v3);
;     ...
;           const unsigned u01 = pack2(v0, v1), u23 = pack2(v2, v3);
;           if (kind == 1) {
;             Tl[(0 * 16 + r) * 72 + rowl] = (u16)u01;
;             Tl[(1 * 16 + r) * 72 + rowl] = (u16)(u01 >> 16);
;             Tl[(2 * 16 + r) * 72 + rowl] = (u16)u23;
;             Tl[(3 * 16 + r) * 72 + rowl] = (u16)(u23 >> 16);
;           } else if (tr == 2) {
;             Tl[rowl * 72 + 0 * 16 + r] = f2h(v0);
;             Tl[rowl * 72 + 1 * 16 + r] = f2h(v1);
;             Tl[rowl * 72 + 2 * 16 + r] = f2h(v2);
;             Tl[rowl * 72 + 3 * 16 + r] = f2h(v3);
;           } else {
;             Tl[rowl * 72 + 0 * 16 + r] = (u16)u01;
;             Tl[rowl * 72 + 1 * 16 + r] = (u16)(u01 >> 16);
;             Tl[rowl * 72 + 2 * 16 + r] = (u16)u23;
;             Tl[rowl * 72 + 3 * 16 + r] = (u16)(u23 >> 16);
;           }
	v_mul_f32_e32 v191, v108, v191
	v_mul_f32_e32 v192, v104, v192
	v_mul_f32_e32 v193, v100, v193
	v_cvt_pk_bf16_f32 v174, v190, v191
	v_cvt_pk_bf16_f32 v175, v192, v193
	ds_write_b16 v170, v174 offset:2592
	ds_write_b16_d16_hi v170, v174 offset:2624
	ds_write_b16 v170, v175 offset:2656
	ds_write_b16_d16_hi v170, v175 offset:2688
	v_mul_f32_e32 v176, 0xbfb8aa3b, v113
	v_mul_f32_e32 v177, 0xbfb8aa3b, v109
	v_mul_f32_e32 v178, 0xbfb8aa3b, v105
	v_mul_f32_e32 v179, 0xbfb8aa3b, v101
	v_exp_f32_e32 v176, v176
	v_exp_f32_e32 v177, v177
	v_exp_f32_e32 v178, v178
	v_exp_f32_e32 v179, v179
	v_add_f32_e32 v176, 1.0, v176
	v_add_f32_e32 v177, 1.0, v177
	v_add_f32_e32 v178, 1.0, v178
	v_add_f32_e32 v179, 1.0, v179
	v_rcp_f32_e32 v176, v176
	v_rcp_f32_e32 v177, v177
	v_rcp_f32_e32 v178, v178
	v_rcp_f32_e32 v179, v179
	v_mul_f32_e32 v176, v113, v176
	v_mul_f32_e32 v177, v109, v177
	v_mul_f32_e32 v178, v105, v178
	v_mul_f32_e32 v179, v101, v179
	v_cvt_pk_bf16_f32 v180, v176, v177
	v_cvt_pk_bf16_f32 v181, v178, v179
	ds_write_b16 v170, v180 offset:2736
	ds_write_b16_d16_hi v170, v180 offset:2768
	ds_write_b16 v170, v181 offset:2800
	ds_write_b16_d16_hi v170, v181 offset:2832
	v_mul_f32_e32 v182, 0xbfb8aa3b, v94
	v_mul_f32_e32 v183, 0xbfb8aa3b, v90
	v_mul_f32_e32 v184, 0xbfb8aa3b, v86
	v_mul_f32_e32 v185, 0xbfb8aa3b, v82
	v_exp_f32_e32 v182, v182
	v_exp_f32_e32 v183, v183
	v_exp_f32_e32 v184, v184
	v_exp_f32_e32 v185, v185
	v_add_f32_e32 v182, 1.0, v182
	v_add_f32_e32 v183, 1.0, v183
	v_add_f32_e32 v184, 1.0, v184
	v_add_f32_e32 v185, 1.0, v185
	v_rcp_f32_e32 v182, v182
	v_rcp_f32_e32 v183, v183
	v_rcp_f32_e32 v184, v184
	v_rcp_f32_e32 v185, v185
	v_mul_f32_e32 v182, v94, v182
	v_mul_f32_e32 v183, v90, v183
	v_mul_f32_e32 v184, v86, v184
	v_mul_f32_e32 v185, v82, v185
	v_cvt_pk_bf16_f32 v186, v182, v183
	v_cvt_pk_bf16_f32 v187, v184, v185
	ds_write_b16 v170, v186 offset:4608
	ds_write_b16_d16_hi v170, v186 offset:4640
	ds_write_b16 v170, v187 offset:4672
	ds_write_b16_d16_hi v170, v187 offset:4704
	v_mul_f32_e32 v188, 0xbfb8aa3b, v95
	v_mul_f32_e32 v189, 0xbfb8aa3b, v91
	v_mul_f32_e32 v190, 0xbfb8aa3b, v87
	v_mul_f32_e32 v191, 0xbfb8aa3b, v83
	v_exp_f32_e32 v188, v188
	v_exp_f32_e32 v189, v189
	v_exp_f32_e32 v190, v190
	v_exp_f32_e32 v191, v191
	v_add_f32_e32 v188, 1.0, v188
	v_add_f32_e32 v189, 1.0, v189
	v_add_f32_e32 v190, 1.0, v190
	v_add_f32_e32 v191, 1.0, v191
	v_rcp_f32_e32 v188, v188
	v_rcp_f32_e32 v189, v189
	v_rcp_f32_e32 v190, v190
	v_rcp_f32_e32 v191, v191
	v_mul_f32_e32 v188, v95, v188
	v_mul_f32_e32 v189, v91, v189
	v_mul_f32_e32 v190, v87, v190
	v_mul_f32_e32 v191, v83, v191
	v_cvt_pk_bf16_f32 v192, v188, v189
	v_cvt_pk_bf16_f32 v193, v190, v191
	ds_write_b16 v170, v192 offset:4752
	ds_write_b16_d16_hi v170, v192 offset:4784
	ds_write_b16 v170, v193 offset:4816
	ds_write_b16_d16_hi v170, v193 offset:4848
	v_mul_f32_e32 v174, 0xbfb8aa3b, v96
	v_mul_f32_e32 v175, 0xbfb8aa3b, v92
	v_mul_f32_e32 v176, 0xbfb8aa3b, v88
	v_mul_f32_e32 v177, 0xbfb8aa3b, v84
	v_exp_f32_e32 v174, v174
	v_exp_f32_e32 v175, v175
	v_exp_f32_e32 v176, v176
	v_exp_f32_e32 v177, v177
	v_add_f32_e32 v174, 1.0, v174
	v_add_f32_e32 v175, 1.0, v175
	v_add_f32_e32 v176, 1.0, v176
	v_add_f32_e32 v177, 1.0, v177
	v_rcp_f32_e32 v174, v174
	v_rcp_f32_e32 v175, v175
	v_rcp_f32_e32 v176, v176
	v_rcp_f32_e32 v177, v177
	v_mul_f32_e32 v174, v96, v174
	v_mul_f32_e32 v175, v92, v175
	v_mul_f32_e32 v176, v88, v176
	v_mul_f32_e32 v177, v84, v177
	v_cvt_pk_bf16_f32 v178, v174, v175
	v_cvt_pk_bf16_f32 v179, v176, v177
	ds_write_b16 v170, v178 offset:4896
	ds_write_b16_d16_hi v170, v178 offset:4928
	ds_write_b16 v170, v179 offset:4960
	ds_write_b16_d16_hi v170, v179 offset:4992
	v_mul_f32_e32 v180, 0xbfb8aa3b, v97
	v_mul_f32_e32 v181, 0xbfb8aa3b, v93
	v_mul_f32_e32 v182, 0xbfb8aa3b, v89
	v_mul_f32_e32 v183, 0xbfb8aa3b, v85
	v_exp_f32_e32 v180, v180
	v_exp_f32_e32 v181, v181
	v_exp_f32_e32 v182, v182
	v_exp_f32_e32 v183, v183
	v_add_f32_e32 v180, 1.0, v180
	v_add_f32_e32 v181, 1.0, v181
	v_add_f32_e32 v182, 1.0, v182
	v_add_f32_e32 v183, 1.0, v183
	v_rcp_f32_e32 v180, v180
	v_rcp_f32_e32 v181, v181
	v_rcp_f32_e32 v182, v182
	v_rcp_f32_e32 v183, v183
	v_mul_f32_e32 v180, v97, v180
	v_mul_f32_e32 v181, v93, v181
	v_mul_f32_e32 v182, v89, v182
	v_mul_f32_e32 v183, v85, v183
	v_cvt_pk_bf16_f32 v184, v180, v181
	v_cvt_pk_bf16_f32 v185, v182, v183
	ds_write_b16 v170, v184 offset:5040
	ds_write_b16_d16_hi v170, v184 offset:5072
	ds_write_b16 v170, v185 offset:5104
	ds_write_b16_d16_hi v170, v185 offset:5136
	v_mul_f32_e32 v186, 0xbfb8aa3b, v78
	v_mul_f32_e32 v187, 0xbfb8aa3b, v74
	v_mul_f32_e32 v188, 0xbfb8aa3b, v70
	v_mul_f32_e32 v189, 0xbfb8aa3b, v66
	v_exp_f32_e32 v186, v186
	v_exp_f32_e32 v187, v187
	v_exp_f32_e32 v188, v188
	v_exp_f32_e32 v189, v189
	v_add_f32_e32 v186, 1.0, v186
	v_add_f32_e32 v187, 1.0, v187
	v_add_f32_e32 v188, 1.0, v188
	v_add_f32_e32 v189, 1.0, v189
	v_rcp_f32_e32 v186, v186
	v_rcp_f32_e32 v187, v187
	v_rcp_f32_e32 v188, v188
	v_rcp_f32_e32 v189, v189
	v_mul_f32_e32 v186, v78, v186
	v_mul_f32_e32 v187, v74, v187
	v_mul_f32_e32 v188, v70, v188
	v_mul_f32_e32 v189, v66, v189
	v_cvt_pk_bf16_f32 v190, v186, v187
	v_cvt_pk_bf16_f32 v191, v188, v189
	ds_write_b16 v170, v190 offset:6912
	ds_write_b16_d16_hi v170, v190 offset:6944
	ds_write_b16 v170, v191 offset:6976
	ds_write_b16_d16_hi v170, v191 offset:7008
	v_mul_f32_e32 v192, 0xbfb8aa3b, v79
	v_mul_f32_e32 v193, 0xbfb8aa3b, v75
	v_mul_f32_e32 v174, 0xbfb8aa3b, v71
	v_mul_f32_e32 v175, 0xbfb8aa3b, v67
	v_exp_f32_e32 v192, v192
	v_exp_f32_e32 v193, v193
	v_exp_f32_e32 v174, v174
	v_exp_f32_e32 v175, v175
	v_add_f32_e32 v192, 1.0, v192
; DI float silu(float v) { return v * __builtin_amdgcn_rcpf(1.f + __builtin_amdgcn_exp2f(-1.4426950408889634f * v)); }
; template <int EPI>
; DI void gemm_phase(const P& p, int l, const u16* __restrict__ A, const u16* __restrict__ Bt, int mpx, char* lds) {
;     ...
;           float v0 = acc[hf * 4 + mi][0][j], v1 = acc[hf * 4 + mi][1][j], v2 = acc[hf * 4 + mi][2][j], v3 = acc[hf * 4 + mi][3][j];
;           const int rowl = mi * 16 + g * 4 + j;
;           const int s = tokw + hf * 64 + rowl;
;           if (tr == 1) {
;             v0 = silu(v0); v1 = silu(v1); v2 = silu(v2); v3 = silu(v3);
;     ...
;           const unsigned u01 = pack2(v0, v1), u23 = pack2(v2, v3);
;           if (kind == 1) {
;             Tl[(0 * 16 + r) * 72 + rowl] = (u16)u01;
;             Tl[(1 * 16 + r) * 72 + rowl] = (u16)(u01 >> 16);
;             Tl[(2 * 16 + r) * 72 + rowl] = (u16)u23;
;             Tl[(3 * 16 + r) * 72 + rowl] = (u16)(u23 >> 16);
;           } else if (tr == 2) {
;             Tl[rowl * 72 + 0 * 16 + r] = f2h(v0);
;             Tl[rowl * 72 + 1 * 16 + r] = f2h(v1);
;             Tl[rowl * 72 + 2 * 16 + r] = f2h(v2);
;             Tl[rowl * 72 + 3 * 16 + r] = f2h(v3);
;           } else {
;             Tl[rowl * 72 + 0 * 16 + r] = (u16)u01;
;             Tl[rowl * 72 + 1 * 16 + r] = (u16)(u01 >> 16);
;             Tl[rowl * 72 + 2 * 16 + r] = (u16)u23;
;             Tl[rowl * 72 + 3 * 16 + r] = (u16)(u23 >> 16);
;           }
;         }
;       }
;       __builtin_amdgcn_fence(__ATOMIC_RELEASE, "wavefront");
;       u16* dh = (kind == 1) ? dst + hf * 64 : dst + (size_t)(hf * 64) * rstride;
; #pragma unroll
;       for (int i = 0; i < 8; ++i) {
;         const int c = lane + i * 64;
;         const int row = c >> 3, cc = c & 7;
;         uint4 v = *(const uint4*)&Tl[row * 72 + cc * 8];
;         *(uint4*)(dh + (size_t)row * rstride + cc * 8) = v;
;       }
	v_add_f32_e32 v193, 1.0, v193
	v_add_f32_e32 v174, 1.0, v174
	v_add_f32_e32 v175, 1.0, v175
	v_rcp_f32_e32 v192, v192
	v_rcp_f32_e32 v193, v193
	v_rcp_f32_e32 v174, v174
	v_rcp_f32_e32 v175, v175
	v_mul_f32_e32 v192, v79, v192
	v_mul_f32_e32 v193, v75, v193
	v_mul_f32_e32 v174, v71, v174
	v_mul_f32_e32 v175, v67, v175
	v_cvt_pk_bf16_f32 v176, v192, v193
	v_cvt_pk_bf16_f32 v177, v174, v175
	ds_write_b16 v170, v176 offset:7056
	ds_write_b16_d16_hi v170, v176 offset:7088
	ds_write_b16 v170, v177 offset:7120
	ds_write_b16_d16_hi v170, v177 offset:7152
	v_mul_f32_e32 v178, 0xbfb8aa3b, v80
	v_mul_f32_e32 v179, 0xbfb8aa3b, v76
	v_mul_f32_e32 v180, 0xbfb8aa3b, v72
	v_mul_f32_e32 v181, 0xbfb8aa3b, v68
	v_exp_f32_e32 v178, v178
	v_exp_f32_e32 v179, v179
	v_exp_f32_e32 v180, v180
	v_exp_f32_e32 v181, v181
	v_add_f32_e32 v178, 1.0, v178
	v_add_f32_e32 v179, 1.0, v179
	v_add_f32_e32 v180, 1.0, v180
	v_add_f32_e32 v181, 1.0, v181
	v_rcp_f32_e32 v178, v178
	v_rcp_f32_e32 v179, v179
	v_rcp_f32_e32 v180, v180
	v_rcp_f32_e32 v181, v181
	v_mul_f32_e32 v178, v80, v178
	v_mul_f32_e32 v179, v76, v179
	v_mul_f32_e32 v180, v72, v180
	v_mul_f32_e32 v181, v68, v181
	v_cvt_pk_bf16_f32 v182, v178, v179
	v_cvt_pk_bf16_f32 v183, v180, v181
	ds_write_b16 v170, v182 offset:7200
	ds_write_b16_d16_hi v170, v182 offset:7232
	ds_write_b16 v170, v183 offset:7264
	ds_write_b16_d16_hi v170, v183 offset:7296
	v_mul_f32_e32 v184, 0xbfb8aa3b, v81
	v_mul_f32_e32 v185, 0xbfb8aa3b, v77
	v_mul_f32_e32 v186, 0xbfb8aa3b, v73
	v_mul_f32_e32 v187, 0xbfb8aa3b, v69
	v_exp_f32_e32 v184, v184
	v_exp_f32_e32 v185, v185
	v_exp_f32_e32 v186, v186
	v_exp_f32_e32 v187, v187
	v_add_f32_e32 v184, 1.0, v184
	v_add_f32_e32 v185, 1.0, v185
	v_add_f32_e32 v186, 1.0, v186
	v_add_f32_e32 v187, 1.0, v187
	v_rcp_f32_e32 v184, v184
	v_rcp_f32_e32 v185, v185
	v_rcp_f32_e32 v186, v186
	v_rcp_f32_e32 v187, v187
	v_mul_f32_e32 v184, v81, v184
	v_mul_f32_e32 v185, v77, v185
	v_mul_f32_e32 v186, v73, v186
	v_mul_f32_e32 v187, v69, v187
	v_cvt_pk_bf16_f32 v188, v184, v185
	v_cvt_pk_bf16_f32 v189, v186, v187
	ds_write_b16 v170, v188 offset:7344
	ds_write_b16_d16_hi v170, v188 offset:7376
	ds_write_b16 v170, v189 offset:7408
	ds_write_b16_d16_hi v170, v189 offset:7440
	ds_read_b128 v[130:133], v171 offset:0
	ds_read_b128 v[134:137], v171 offset:1152
	ds_read_b128 v[138:141], v171 offset:2304
	ds_read_b128 v[142:145], v171 offset:3456
	ds_read_b128 v[146:149], v171 offset:4608
	ds_read_b128 v[150:153], v171 offset:5760
	ds_read_b128 v[154:157], v171 offset:6912
	ds_read_b128 v[158:161], v171 offset:8064
	s_waitcnt lgkmcnt(7)
	global_store_dwordx4 v172, v[130:133], s[44:45] offset:0 sc1
	s_waitcnt lgkmcnt(6)
	global_store_dwordx4 v172, v[134:137], s[44:45] offset:1024 sc1
	s_waitcnt lgkmcnt(5)
	global_store_dwordx4 v172, v[138:141], s[44:45] offset:2048 sc1
	s_waitcnt lgkmcnt(4)
	global_store_dwordx4 v172, v[142:145], s[44:45] offset:3072 sc1
	s_waitcnt lgkmcnt(3)
	global_store_dwordx4 v172, v[146:149], s[62:63] offset:0 sc1
	s_waitcnt lgkmcnt(2)
	global_store_dwordx4 v172, v[150:153], s[62:63] offset:1024 sc1
	s_waitcnt lgkmcnt(1)
	global_store_dwordx4 v172, v[154:157], s[62:63] offset:2048 sc1
	s_waitcnt lgkmcnt(0)
	global_store_dwordx4 v172, v[158:161], s[62:63] offset:3072 sc1
	s_add_u32 s44, s44, 0x2000
	s_addc_u32 s45, s45, 0
	s_add_u32 s62, s62, 0x2000
	s_addc_u32 s63, s63, 0
	v_mul_f32_e32 v174, 0xbfb8aa3b, v62
	v_mul_f32_e32 v175, 0xbfb8aa3b, v58
	v_mul_f32_e32 v176, 0xbfb8aa3b, v54
	v_mul_f32_e32 v177, 0xbfb8aa3b, v50
	v_exp_f32_e32 v174, v174
	v_exp_f32_e32 v175, v175
	v_exp_f32_e32 v176, v176
	v_exp_f32_e32 v177, v177
	v_add_f32_e32 v174, 1.0, v174
	v_add_f32_e32 v175, 1.0, v175
	v_add_f32_e32 v176, 1.0, v176
	v_add_f32_e32 v177, 1.0, v177
	v_rcp_f32_e32 v174, v174
	v_rcp_f32_e32 v175, v175
	v_rcp_f32_e32 v176, v176
	v_rcp_f32_e32 v177, v177
	v_mul_f32_e32 v174, v62, v174
	v_mul_f32_e32 v175, v58, v175
	v_mul_f32_e32 v176, v54, v176
	v_mul_f32_e32 v177, v50, v177
	v_cvt_pk_bf16_f32 v178, v174, v175
	v_cvt_pk_bf16_f32 v179, v176, v177
	ds_write_b16 v170, v178 offset:0
	ds_write_b16_d16_hi v170, v178 offset:32
	ds_write_b16 v170, v179 offset:64
	ds_write_b16_d16_hi v170, v179 offset:96
	v_mul_f32_e32 v180, 0xbfb8aa3b, v63
	v_mul_f32_e32 v181, 0xbfb8aa3b, v59
	v_mul_f32_e32 v182, 0xbfb8aa3b, v55
	v_mul_f32_e32 v183, 0xbfb8aa3b, v51
	v_exp_f32_e32 v180, v180
	v_exp_f32_e32 v181, v181
	v_exp_f32_e32 v182, v182
	v_exp_f32_e32 v183, v183
	v_add_f32_e32 v180, 1.0, v180
	v_add_f32_e32 v181, 1.0, v181
	v_add_f32_e32 v182, 1.0, v182
	v_add_f32_e32 v183, 1.0, v183
	v_rcp_f32_e32 v180, v180
	v_rcp_f32_e32 v181, v181
	v_rcp_f32_e32 v182, v182
	v_rcp_f32_e32 v183, v183
	v_mul_f32_e32 v180, v63, v180
	v_mul_f32_e32 v181, v59, v181
	v_mul_f32_e32 v182, v55, v182
	v_mul_f32_e32 v183, v51, v183
	v_cvt_pk_bf16_f32 v184, v180, v181
	v_cvt_pk_bf16_f32 v185, v182, v183
	ds_write_b16 v170, v184 offset:144
	ds_write_b16_d16_hi v170, v184 offset:176
	ds_write_b16 v170, v185 offset:208
	ds_write_b16_d16_hi v170, v185 offset:240
	v_mul_f32_e32 v186, 0xbfb8aa3b, v64
	v_mul_f32_e32 v187, 0xbfb8aa3b, v60
	v_mul_f32_e32 v188, 0xbfb8aa3b, v56
	v_mul_f32_e32 v189, 0xbfb8aa3b, v52
	v_exp_f32_e32 v186, v186
	v_exp_f32_e32 v187, v187
	v_exp_f32_e32 v188, v188
	v_exp_f32_e32 v189, v189
	v_add_f32_e32 v186, 1.0, v186
	v_add_f32_e32 v187, 1.0, v187
	v_add_f32_e32 v188, 1.0, v188
	v_add_f32_e32 v189, 1.0, v189
	v_rcp_f32_e32 v186, v186
	v_rcp_f32_e32 v187, v187
	v_rcp_f32_e32 v188, v188
	v_rcp_f32_e32 v189, v189
	v_mul_f32_e32 v186, v64, v186
	v_mul_f32_e32 v187, v60, v187
	v_mul_f32_e32 v188, v56, v188
	v_mul_f32_e32 v189, v52, v189
; DI float silu(float v) { return v * __builtin_amdgcn_rcpf(1.f + __builtin_amdgcn_exp2f(-1.4426950408889634f * v)); }
; template <int EPI>
; DI void gemm_phase(const P& p, int l, const u16* __restrict__ A, const u16* __restrict__ Bt, int mpx, char* lds) {
;     ...
;           float v0 = acc[hf * 4 + mi][0][j], v1 = acc[hf * 4 + mi][1][j], v2 = acc[hf * 4 + mi][2][j], v3 = acc[hf * 4 + mi][3][j];
;           const int rowl = mi * 16 + g * 4 + j;
;           const int s = tokw + hf * 64 + rowl;
;           if (tr == 1) {
;             v0 = silu(v0); v1 = silu(v1); v2 = silu(v2); v3 = silu(v3);
;     ...
;           const unsigned u01 = pack2(v0, v1), u23 = pack2(v2, v3);
;           if (kind == 1) {
;             Tl[(0 * 16 + r) * 72 + rowl] = (u16)u01;
;             Tl[(1 * 16 + r) * 72 + rowl] = (u16)(u01 >> 16);
;             Tl[(2 * 16 + r) * 72 + rowl] = (u16)u23;
;             Tl[(3 * 16 + r) * 72 + rowl] = (u16)(u23 >> 16);
;           } else if (tr == 2) {
;             Tl[rowl * 72 + 0 * 16 + r] = f2h(v0);
;             Tl[rowl * 72 + 1 * 16 + r] = f2h(v1);
;             Tl[rowl * 72 + 2 * 16 + r] = f2h(v2);
;             Tl[rowl * 72 + 3 * 16 + r] = f2h(v3);
;           } else {
;             Tl[rowl * 72 + 0 * 16 + r] = (u16)u01;
;             Tl[rowl * 72 + 1 * 16 + r] = (u16)(u01 >> 16);
;             Tl[rowl * 72 + 2 * 16 + r] = (u16)u23;
;             Tl[rowl * 72 + 3 * 16 + r] = (u16)(u23 >> 16);
;           }
	v_cvt_pk_bf16_f32 v190, v186, v187
	v_cvt_pk_bf16_f32 v191, v188, v189
	ds_write_b16 v170, v190 offset:288
	ds_write_b16_d16_hi v170, v190 offset:320
	ds_write_b16 v170, v191 offset:352
	ds_write_b16_d16_hi v170, v191 offset:384
	v_mul_f32_e32 v192, 0xbfb8aa3b, v65
	v_mul_f32_e32 v193, 0xbfb8aa3b, v61
	v_mul_f32_e32 v174, 0xbfb8aa3b, v57
	v_mul_f32_e32 v175, 0xbfb8aa3b, v53
	v_exp_f32_e32 v192, v192
	v_exp_f32_e32 v193, v193
	v_exp_f32_e32 v174, v174
	v_exp_f32_e32 v175, v175
	v_add_f32_e32 v192, 1.0, v192
	v_add_f32_e32 v193, 1.0, v193
	v_add_f32_e32 v174, 1.0, v174
	v_add_f32_e32 v175, 1.0, v175
	v_rcp_f32_e32 v192, v192
	v_rcp_f32_e32 v193, v193
	v_rcp_f32_e32 v174, v174
	v_rcp_f32_e32 v175, v175
	v_mul_f32_e32 v192, v65, v192
	v_mul_f32_e32 v193, v61, v193
	v_mul_f32_e32 v174, v57, v174
	v_mul_f32_e32 v175, v53, v175
	v_cvt_pk_bf16_f32 v176, v192, v193
	v_cvt_pk_bf16_f32 v177, v174, v175
	ds_write_b16 v170, v176 offset:432
	ds_write_b16_d16_hi v170, v176 offset:464
	ds_write_b16 v170, v177 offset:496
	ds_write_b16_d16_hi v170, v177 offset:528
	v_mul_f32_e32 v178, 0xbfb8aa3b, v46
	v_mul_f32_e32 v179, 0xbfb8aa3b, v42
	v_mul_f32_e32 v180, 0xbfb8aa3b, v38
	v_mul_f32_e32 v181, 0xbfb8aa3b, v34
	v_exp_f32_e32 v178, v178
	v_exp_f32_e32 v179, v179
	v_exp_f32_e32 v180, v180
	v_exp_f32_e32 v181, v181
	v_add_f32_e32 v178, 1.0, v178
	v_add_f32_e32 v179, 1.0, v179
	v_add_f32_e32 v180, 1.0, v180
	v_add_f32_e32 v181, 1.0, v181
	v_rcp_f32_e32 v178, v178
	v_rcp_f32_e32 v179, v179
	v_rcp_f32_e32 v180, v180
	v_rcp_f32_e32 v181, v181
	v_mul_f32_e32 v178, v46, v178
	v_mul_f32_e32 v179, v42, v179
	v_mul_f32_e32 v180, v38, v180
	v_mul_f32_e32 v181, v34, v181
	v_cvt_pk_bf16_f32 v182, v178, v179
	v_cvt_pk_bf16_f32 v183, v180, v181
	ds_write_b16 v170, v182 offset:2304
	ds_write_b16_d16_hi v170, v182 offset:2336
	ds_write_b16 v170, v183 offset:2368
	ds_write_b16_d16_hi v170, v183 offset:2400
	v_mul_f32_e32 v184, 0xbfb8aa3b, v47
	v_mul_f32_e32 v185, 0xbfb8aa3b, v43
	v_mul_f32_e32 v186, 0xbfb8aa3b, v39
	v_mul_f32_e32 v187, 0xbfb8aa3b, v35
	v_exp_f32_e32 v184, v184
	v_exp_f32_e32 v185, v185
	v_exp_f32_e32 v186, v186
	v_exp_f32_e32 v187, v187
	v_add_f32_e32 v184, 1.0, v184
	v_add_f32_e32 v185, 1.0, v185
	v_add_f32_e32 v186, 1.0, v186
	v_add_f32_e32 v187, 1.0, v187
	v_rcp_f32_e32 v184, v184
	v_rcp_f32_e32 v185, v185
	v_rcp_f32_e32 v186, v186
	v_rcp_f32_e32 v187, v187
	v_mul_f32_e32 v184, v47, v184
	v_mul_f32_e32 v185, v43, v185
	v_mul_f32_e32 v186, v39, v186
	v_mul_f32_e32 v187, v35, v187
	v_cvt_pk_bf16_f32 v188, v184, v185
	v_cvt_pk_bf16_f32 v189, v186, v187
	ds_write_b16 v170, v188 offset:2448
	ds_write_b16_d16_hi v170, v188 offset:2480
	ds_write_b16 v170, v189 offset:2512
	ds_write_b16_d16_hi v170, v189 offset:2544
	v_mul_f32_e32 v190, 0xbfb8aa3b, v48
	v_mul_f32_e32 v191, 0xbfb8aa3b, v44
	v_mul_f32_e32 v192, 0xbfb8aa3b, v40
	v_mul_f32_e32 v193, 0xbfb8aa3b, v36
	v_exp_f32_e32 v190, v190
	v_exp_f32_e32 v191, v191
	v_exp_f32_e32 v192, v192
	v_exp_f32_e32 v193, v193
	v_add_f32_e32 v190, 1.0, v190
	v_add_f32_e32 v191, 1.0, v191
	v_add_f32_e32 v192, 1.0, v192
	v_add_f32_e32 v193, 1.0, v193
	v_rcp_f32_e32 v190, v190
	v_rcp_f32_e32 v191, v191
	v_rcp_f32_e32 v192, v192
	v_rcp_f32_e32 v193, v193
	v_mul_f32_e32 v190, v48, v190
	v_mul_f32_e32 v191, v44, v191
	v_mul_f32_e32 v192, v40, v192
	v_mul_f32_e32 v193, v36, v193
	v_cvt_pk_bf16_f32 v174, v190, v191
	v_cvt_pk_bf16_f32 v175, v192, v193
	ds_write_b16 v170, v174 offset:2592
	ds_write_b16_d16_hi v170, v174 offset:2624
	ds_write_b16 v170, v175 offset:2656
	ds_write_b16_d16_hi v170, v175 offset:2688
	v_mul_f32_e32 v176, 0xbfb8aa3b, v49
	v_mul_f32_e32 v177, 0xbfb8aa3b, v45
	v_mul_f32_e32 v178, 0xbfb8aa3b, v41
	v_mul_f32_e32 v179, 0xbfb8aa3b, v37
	v_exp_f32_e32 v176, v176
	v_exp_f32_e32 v177, v177
	v_exp_f32_e32 v178, v178
	v_exp_f32_e32 v179, v179
	v_add_f32_e32 v176, 1.0, v176
	v_add_f32_e32 v177, 1.0, v177
	v_add_f32_e32 v178, 1.0, v178
	v_add_f32_e32 v179, 1.0, v179
	v_rcp_f32_e32 v176, v176
	v_rcp_f32_e32 v177, v177
	v_rcp_f32_e32 v178, v178
	v_rcp_f32_e32 v179, v179
	v_mul_f32_e32 v176, v49, v176
	v_mul_f32_e32 v177, v45, v177
	v_mul_f32_e32 v178, v41, v178
	v_mul_f32_e32 v179, v37, v179
	v_cvt_pk_bf16_f32 v180, v176, v177
	v_cvt_pk_bf16_f32 v181, v178, v179
	ds_write_b16 v170, v180 offset:2736
	ds_write_b16_d16_hi v170, v180 offset:2768
	ds_write_b16 v170, v181 offset:2800
	ds_write_b16_d16_hi v170, v181 offset:2832
	v_mul_f32_e32 v182, 0xbfb8aa3b, v30
	v_mul_f32_e32 v183, 0xbfb8aa3b, v26
	v_mul_f32_e32 v184, 0xbfb8aa3b, v22
	v_mul_f32_e32 v185, 0xbfb8aa3b, v18
	v_exp_f32_e32 v182, v182
	v_exp_f32_e32 v183, v183
	v_exp_f32_e32 v184, v184
	v_exp_f32_e32 v185, v185
	v_add_f32_e32 v182, 1.0, v182
	v_add_f32_e32 v183, 1.0, v183
	v_add_f32_e32 v184, 1.0, v184
	v_add_f32_e32 v185, 1.0, v185
	v_rcp_f32_e32 v182, v182
	v_rcp_f32_e32 v183, v183
	v_rcp_f32_e32 v184, v184
	v_rcp_f32_e32 v185, v185
	v_mul_f32_e32 v182, v30, v182
	v_mul_f32_e32 v183, v26, v183
	v_mul_f32_e32 v184, v22, v184
	v_mul_f32_e32 v185, v18, v185
	v_cvt_pk_bf16_f32 v186, v182, v183
	v_cvt_pk_bf16_f32 v187, v184, v185
	ds_write_b16 v170, v186 offset:4608
	ds_write_b16_d16_hi v170, v186 offset:4640
	ds_write_b16 v170, v187 offset:4672
	ds_write_b16_d16_hi v170, v187 offset:4704
	v_mul_f32_e32 v188, 0xbfb8aa3b, v31
	v_mul_f32_e32 v189, 0xbfb8aa3b, v27
	v_mul_f32_e32 v190, 0xbfb8aa3b, v23
	v_mul_f32_e32 v191, 0xbfb8aa3b, v19
	v_exp_f32_e32 v188, v188
	v_exp_f32_e32 v189, v189
	v_exp_f32_e32 v190, v190
	v_exp_f32_e32 v191, v191
	v_add_f32_e32 v188, 1.0, v188
	v_add_f32_e32 v189, 1.0, v189
	v_add_f32_e32 v190, 1.0, v190
	v_add_f32_e32 v191, 1.0, v191
; DI float silu(float v) { return v * __builtin_amdgcn_rcpf(1.f + __builtin_amdgcn_exp2f(-1.4426950408889634f * v)); }
; template <int EPI>
; DI void gemm_phase(const P& p, int l, const u16* __restrict__ A, const u16* __restrict__ Bt, int mpx, char* lds) {
;     ...
;           float v0 = acc[hf * 4 + mi][0][j], v1 = acc[hf * 4 + mi][1][j], v2 = acc[hf * 4 + mi][2][j], v3 = acc[hf * 4 + mi][3][j];
;           const int rowl = mi * 16 + g * 4 + j;
;           const int s = tokw + hf * 64 + rowl;
;           if (tr == 1) {
;             v0 = silu(v0); v1 = silu(v1); v2 = silu(v2); v3 = silu(v3);
;     ...
;           const unsigned u01 = pack2(v0, v1), u23 = pack2(v2, v3);
;           if (kind == 1) {
;             Tl[(0 * 16 + r) * 72 + rowl] = (u16)u01;
;             Tl[(1 * 16 + r) * 72 + rowl] = (u16)(u01 >> 16);
;             Tl[(2 * 16 + r) * 72 + rowl] = (u16)u23;
;             Tl[(3 * 16 + r) * 72 + rowl] = (u16)(u23 >> 16);
;           } else if (tr == 2) {
;             Tl[rowl * 72 + 0 * 16 + r] = f2h(v0);
;             Tl[rowl * 72 + 1 * 16 + r] = f2h(v1);
;             Tl[rowl * 72 + 2 * 16 + r] = f2h(v2);
;             Tl[rowl * 72 + 3 * 16 + r] = f2h(v3);
;           } else {
;             Tl[rowl * 72 + 0 * 16 + r] = (u16)u01;
;             Tl[rowl * 72 + 1 * 16 + r] = (u16)(u01 >> 16);
;             Tl[rowl * 72 + 2 * 16 + r] = (u16)u23;
;             Tl[rowl * 72 + 3 * 16 + r] = (u16)(u23 >> 16);
;           }
;         }
;       }
;       __builtin_amdgcn_fence(__ATOMIC_RELEASE, "wavefront");
;       u16* dh = (kind == 1) ? dst + hf * 64 : dst + (size_t)(hf * 64) * rstride;
; #pragma unroll
;       for (int i = 0; i < 8; ++i) {
;         const int c = lane + i * 64;
;         const int row = c >> 3, cc = c & 7;
;         uint4 v = *(const uint4*)&Tl[row * 72 + cc * 8];
;         *(uint4*)(dh + (size_t)row * rstride + cc * 8) = v;
;       }
	v_rcp_f32_e32 v188, v188
	v_rcp_f32_e32 v189, v189
	v_rcp_f32_e32 v190, v190
	v_rcp_f32_e32 v191, v191
	v_mul_f32_e32 v188, v31, v188
	v_mul_f32_e32 v189, v27, v189
	v_mul_f32_e32 v190, v23, v190
	v_mul_f32_e32 v191, v19, v191
	v_cvt_pk_bf16_f32 v192, v188, v189
	v_cvt_pk_bf16_f32 v193, v190, v191
	ds_write_b16 v170, v192 offset:4752
	ds_write_b16_d16_hi v170, v192 offset:4784
	ds_write_b16 v170, v193 offset:4816
	ds_write_b16_d16_hi v170, v193 offset:4848
	v_mul_f32_e32 v174, 0xbfb8aa3b, v32
	v_mul_f32_e32 v175, 0xbfb8aa3b, v28
	v_mul_f32_e32 v176, 0xbfb8aa3b, v24
	v_mul_f32_e32 v177, 0xbfb8aa3b, v20
	v_exp_f32_e32 v174, v174
	v_exp_f32_e32 v175, v175
	v_exp_f32_e32 v176, v176
	v_exp_f32_e32 v177, v177
	v_add_f32_e32 v174, 1.0, v174
	v_add_f32_e32 v175, 1.0, v175
	v_add_f32_e32 v176, 1.0, v176
	v_add_f32_e32 v177, 1.0, v177
	v_rcp_f32_e32 v174, v174
	v_rcp_f32_e32 v175, v175
	v_rcp_f32_e32 v176, v176
	v_rcp_f32_e32 v177, v177
	v_mul_f32_e32 v174, v32, v174
	v_mul_f32_e32 v175, v28, v175
	v_mul_f32_e32 v176, v24, v176
	v_mul_f32_e32 v177, v20, v177
	v_cvt_pk_bf16_f32 v178, v174, v175
	v_cvt_pk_bf16_f32 v179, v176, v177
	ds_write_b16 v170, v178 offset:4896
	ds_write_b16_d16_hi v170, v178 offset:4928
	ds_write_b16 v170, v179 offset:4960
	ds_write_b16_d16_hi v170, v179 offset:4992
	v_mul_f32_e32 v180, 0xbfb8aa3b, v33
	v_mul_f32_e32 v181, 0xbfb8aa3b, v29
	v_mul_f32_e32 v182, 0xbfb8aa3b, v25
	v_mul_f32_e32 v183, 0xbfb8aa3b, v21
	v_exp_f32_e32 v180, v180
	v_exp_f32_e32 v181, v181
	v_exp_f32_e32 v182, v182
	v_exp_f32_e32 v183, v183
	v_add_f32_e32 v180, 1.0, v180
	v_add_f32_e32 v181, 1.0, v181
	v_add_f32_e32 v182, 1.0, v182
	v_add_f32_e32 v183, 1.0, v183
	v_rcp_f32_e32 v180, v180
	v_rcp_f32_e32 v181, v181
	v_rcp_f32_e32 v182, v182
	v_rcp_f32_e32 v183, v183
	v_mul_f32_e32 v180, v33, v180
	v_mul_f32_e32 v181, v29, v181
	v_mul_f32_e32 v182, v25, v182
	v_mul_f32_e32 v183, v21, v183
	v_cvt_pk_bf16_f32 v184, v180, v181
	v_cvt_pk_bf16_f32 v185, v182, v183
	ds_write_b16 v170, v184 offset:5040
	ds_write_b16_d16_hi v170, v184 offset:5072
	ds_write_b16 v170, v185 offset:5104
	ds_write_b16_d16_hi v170, v185 offset:5136
	v_mul_f32_e32 v186, 0xbfb8aa3b, v166
	v_mul_f32_e32 v187, 0xbfb8aa3b, v162
	v_mul_f32_e32 v188, 0xbfb8aa3b, v2
	v_mul_f32_e32 v189, 0xbfb8aa3b, v6
	v_exp_f32_e32 v186, v186
	v_exp_f32_e32 v187, v187
	v_exp_f32_e32 v188, v188
	v_exp_f32_e32 v189, v189
	v_add_f32_e32 v186, 1.0, v186
	v_add_f32_e32 v187, 1.0, v187
	v_add_f32_e32 v188, 1.0, v188
	v_add_f32_e32 v189, 1.0, v189
	v_rcp_f32_e32 v186, v186
	v_rcp_f32_e32 v187, v187
	v_rcp_f32_e32 v188, v188
	v_rcp_f32_e32 v189, v189
	v_mul_f32_e32 v186, v166, v186
	v_mul_f32_e32 v187, v162, v187
	v_mul_f32_e32 v188, v2, v188
	v_mul_f32_e32 v189, v6, v189
	v_cvt_pk_bf16_f32 v190, v186, v187
	v_cvt_pk_bf16_f32 v191, v188, v189
	ds_write_b16 v170, v190 offset:6912
	ds_write_b16_d16_hi v170, v190 offset:6944
	ds_write_b16 v170, v191 offset:6976
	ds_write_b16_d16_hi v170, v191 offset:7008
	v_mul_f32_e32 v192, 0xbfb8aa3b, v167
	v_mul_f32_e32 v193, 0xbfb8aa3b, v163
	v_mul_f32_e32 v174, 0xbfb8aa3b, v3
	v_mul_f32_e32 v175, 0xbfb8aa3b, v7
	v_exp_f32_e32 v192, v192
	v_exp_f32_e32 v193, v193
	v_exp_f32_e32 v174, v174
	v_exp_f32_e32 v175, v175
	v_add_f32_e32 v192, 1.0, v192
	v_add_f32_e32 v193, 1.0, v193
	v_add_f32_e32 v174, 1.0, v174
	v_add_f32_e32 v175, 1.0, v175
	v_rcp_f32_e32 v192, v192
	v_rcp_f32_e32 v193, v193
	v_rcp_f32_e32 v174, v174
	v_rcp_f32_e32 v175, v175
	v_mul_f32_e32 v192, v167, v192
	v_mul_f32_e32 v193, v163, v193
	v_mul_f32_e32 v174, v3, v174
	v_mul_f32_e32 v175, v7, v175
	v_cvt_pk_bf16_f32 v176, v192, v193
	v_cvt_pk_bf16_f32 v177, v174, v175
	ds_write_b16 v170, v176 offset:7056
	ds_write_b16_d16_hi v170, v176 offset:7088
	ds_write_b16 v170, v177 offset:7120
	ds_write_b16_d16_hi v170, v177 offset:7152
	v_mul_f32_e32 v178, 0xbfb8aa3b, v168
	v_mul_f32_e32 v179, 0xbfb8aa3b, v164
	v_mul_f32_e32 v180, 0xbfb8aa3b, v4
	v_mul_f32_e32 v181, 0xbfb8aa3b, v8
	v_exp_f32_e32 v178, v178
	v_exp_f32_e32 v179, v179
	v_exp_f32_e32 v180, v180
	v_exp_f32_e32 v181, v181
	v_add_f32_e32 v178, 1.0, v178
	v_add_f32_e32 v179, 1.0, v179
	v_add_f32_e32 v180, 1.0, v180
	v_add_f32_e32 v181, 1.0, v181
	v_rcp_f32_e32 v178, v178
	v_rcp_f32_e32 v179, v179
	v_rcp_f32_e32 v180, v180
	v_rcp_f32_e32 v181, v181
	v_mul_f32_e32 v178, v168, v178
	v_mul_f32_e32 v179, v164, v179
	v_mul_f32_e32 v180, v4, v180
	v_mul_f32_e32 v181, v8, v181
	v_cvt_pk_bf16_f32 v182, v178, v179
	v_cvt_pk_bf16_f32 v183, v180, v181
	ds_write_b16 v170, v182 offset:7200
	ds_write_b16_d16_hi v170, v182 offset:7232
	ds_write_b16 v170, v183 offset:7264
	ds_write_b16_d16_hi v170, v183 offset:7296
	v_mul_f32_e32 v184, 0xbfb8aa3b, v169
	v_mul_f32_e32 v185, 0xbfb8aa3b, v165
	v_mul_f32_e32 v186, 0xbfb8aa3b, v5
	v_mul_f32_e32 v187, 0xbfb8aa3b, v9
	v_exp_f32_e32 v184, v184
	v_exp_f32_e32 v185, v185
	v_exp_f32_e32 v186, v186
	v_exp_f32_e32 v187, v187
	v_add_f32_e32 v184, 1.0, v184
	v_add_f32_e32 v185, 1.0, v185
	v_add_f32_e32 v186, 1.0, v186
	v_add_f32_e32 v187, 1.0, v187
	v_rcp_f32_e32 v184, v184
	v_rcp_f32_e32 v185, v185
	v_rcp_f32_e32 v186, v186
	v_rcp_f32_e32 v187, v187
	v_mul_f32_e32 v184, v169, v184
	v_mul_f32_e32 v185, v165, v185
	v_mul_f32_e32 v186, v5, v186
	v_mul_f32_e32 v187, v9, v187
	v_cvt_pk_bf16_f32 v188, v184, v185
	v_cvt_pk_bf16_f32 v189, v186, v187
	ds_write_b16 v170, v188 offset:7344
	ds_write_b16_d16_hi v170, v188 offset:7376
	ds_write_b16 v170, v189 offset:7408
	ds_write_b16_d16_hi v170, v189 offset:7440
	ds_read_b128 v[130:133], v171 offset:0
	ds_read_b128 v[134:137], v171 offset:1152
	ds_read_b128 v[138:141], v171 offset:2304
	ds_read_b128 v[142:145], v171 offset:3456
	ds_read_b128 v[146:149], v171 offset:4608
	ds_read_b128 v[150:153], v171 offset:5760
	ds_read_b128 v[154:157], v171 offset:6912
	ds_read_b128 v[158:161], v171 offset:8064
	s_waitcnt lgkmcnt(7)
	global_store_dwordx4 v172, v[130:133], s[44:45] offset:0 sc1
	s_waitcnt lgkmcnt(6)
	global_store_dwordx4 v172, v[134:137], s[44:45] offset:1024 sc1
	s_waitcnt lgkmcnt(5)
	global_store_dwordx4 v172, v[138:141], s[44:45] offset:2048 sc1
	s_waitcnt lgkmcnt(4)
	global_store_dwordx4 v172, v[142:145], s[44:45] offset:3072 sc1
	s_waitcnt lgkmcnt(3)
	global_store_dwordx4 v172, v[146:149], s[62:63] offset:0 sc1
	s_waitcnt lgkmcnt(2)
	global_store_dwordx4 v172, v[150:153], s[62:63] offset:1024 sc1
	s_waitcnt lgkmcnt(1)
	global_store_dwordx4 v172, v[154:157], s[62:63] offset:2048 sc1
	s_waitcnt lgkmcnt(0)
	global_store_dwordx4 v172, v[158:161], s[62:63] offset:3072 sc1
	s_branch .Lfe_done
; template <int EPI>
; DI void gemm_phase(const P& p, int l, const u16* __restrict__ A, const u16* __restrict__ Bt, int mpx, char* lds) {
;     ...
;           const unsigned u01 = pack2(v0, v1), u23 = pack2(v2, v3);
;           if (kind == 1) {
;             Tl[(0 * 16 + r) * 72 + rowl] = (u16)u01;
;             Tl[(1 * 16 + r) * 72 + rowl] = (u16)(u01 >> 16);
;             Tl[(2 * 16 + r) * 72 + rowl] = (u16)u23;
;             Tl[(3 * 16 + r) * 72 + rowl] = (u16)(u23 >> 16);
;           } else if (tr == 2) {
;             Tl[rowl * 72 + 0 * 16 + r] = f2h(v0);
;             Tl[rowl * 72 + 1 * 16 + r] = f2h(v1);
;             Tl[rowl * 72 + 2 * 16 + r] = f2h(v2);
;             Tl[rowl * 72 + 3 * 16 + r] = f2h(v3);
;           } else {
;             Tl[rowl * 72 + 0 * 16 + r] = (u16)u01;
;             Tl[rowl * 72 + 1 * 16 + r] = (u16)(u01 >> 16);
;             Tl[rowl * 72 + 2 * 16 + r] = (u16)u23;
;             Tl[rowl * 72 + 3 * 16 + r] = (u16)(u23 >> 16);
;           }
;         }
;       }
;       __builtin_amdgcn_fence(__ATOMIC_RELEASE, "wavefront");
;       u16* dh = (kind == 1) ? dst + hf * 64 : dst + (size_t)(hf * 64) * rstride;
; #pragma unroll
;       for (int i = 0; i < 8; ++i) {
;         const int c = lane + i * 64;
;         const int row = c >> 3, cc = c & 7;
;         uint4 v = *(const uint4*)&Tl[row * 72 + cc * 8];
;         *(uint4*)(dh + (size_t)row * rstride + cc * 8) = v;
;       }
.Lfe_k0_plain:
	s_add_u32 s62, s44, 0x1000
	s_addc_u32 s63, s45, 0
	v_cvt_pk_bf16_f32 v178, v126, v122
	v_cvt_pk_bf16_f32 v179, v118, v114
	ds_write_b16 v170, v178 offset:0
	ds_write_b16_d16_hi v170, v178 offset:32
	ds_write_b16 v170, v179 offset:64
	ds_write_b16_d16_hi v170, v179 offset:96
	v_cvt_pk_bf16_f32 v184, v127, v123
	v_cvt_pk_bf16_f32 v185, v119, v115
	ds_write_b16 v170, v184 offset:144
	ds_write_b16_d16_hi v170, v184 offset:176
	ds_write_b16 v170, v185 offset:208
	ds_write_b16_d16_hi v170, v185 offset:240
	v_cvt_pk_bf16_f32 v190, v128, v124
	v_cvt_pk_bf16_f32 v191, v120, v116
	ds_write_b16 v170, v190 offset:288
	ds_write_b16_d16_hi v170, v190 offset:320
	ds_write_b16 v170, v191 offset:352
	ds_write_b16_d16_hi v170, v191 offset:384
	v_cvt_pk_bf16_f32 v176, v129, v125
	v_cvt_pk_bf16_f32 v177, v121, v117
	ds_write_b16 v170, v176 offset:432
	ds_write_b16_d16_hi v170, v176 offset:464
	ds_write_b16 v170, v177 offset:496
	ds_write_b16_d16_hi v170, v177 offset:528
	v_cvt_pk_bf16_f32 v182, v110, v106
	v_cvt_pk_bf16_f32 v183, v102, v98
	ds_write_b16 v170, v182 offset:2304
	ds_write_b16_d16_hi v170, v182 offset:2336
	ds_write_b16 v170, v183 offset:2368
	ds_write_b16_d16_hi v170, v183 offset:2400
	v_cvt_pk_bf16_f32 v188, v111, v107
	v_cvt_pk_bf16_f32 v189, v103, v99
	ds_write_b16 v170, v188 offset:2448
	ds_write_b16_d16_hi v170, v188 offset:2480
	ds_write_b16 v170, v189 offset:2512
	ds_write_b16_d16_hi v170, v189 offset:2544
	v_cvt_pk_bf16_f32 v174, v112, v108
	v_cvt_pk_bf16_f32 v175, v104, v100
	ds_write_b16 v170, v174 offset:2592
	ds_write_b16_d16_hi v170, v174 offset:2624
	ds_write_b16 v170, v175 offset:2656
	ds_write_b16_d16_hi v170, v175 offset:2688
	v_cvt_pk_bf16_f32 v180, v113, v109
	v_cvt_pk_bf16_f32 v181, v105, v101
	ds_write_b16 v170, v180 offset:2736
	ds_write_b16_d16_hi v170, v180 offset:2768
	ds_write_b16 v170, v181 offset:2800
	ds_write_b16_d16_hi v170, v181 offset:2832
	v_cvt_pk_bf16_f32 v186, v94, v90
	v_cvt_pk_bf16_f32 v187, v86, v82
	ds_write_b16 v170, v186 offset:4608
	ds_write_b16_d16_hi v170, v186 offset:4640
	ds_write_b16 v170, v187 offset:4672
	ds_write_b16_d16_hi v170, v187 offset:4704
	v_cvt_pk_bf16_f32 v192, v95, v91
	v_cvt_pk_bf16_f32 v193, v87, v83
	ds_write_b16 v170, v192 offset:4752
	ds_write_b16_d16_hi v170, v192 offset:4784
	ds_write_b16 v170, v193 offset:4816
	ds_write_b16_d16_hi v170, v193 offset:4848
	v_cvt_pk_bf16_f32 v178, v96, v92
	v_cvt_pk_bf16_f32 v179, v88, v84
	ds_write_b16 v170, v178 offset:4896
	ds_write_b16_d16_hi v170, v178 offset:4928
	ds_write_b16 v170, v179 offset:4960
	ds_write_b16_d16_hi v170, v179 offset:4992
	v_cvt_pk_bf16_f32 v184, v97, v93
	v_cvt_pk_bf16_f32 v185, v89, v85
	ds_write_b16 v170, v184 offset:5040
	ds_write_b16_d16_hi v170, v184 offset:5072
	ds_write_b16 v170, v185 offset:5104
	ds_write_b16_d16_hi v170, v185 offset:5136
	v_cvt_pk_bf16_f32 v190, v78, v74
	v_cvt_pk_bf16_f32 v191, v70, v66
	ds_write_b16 v170, v190 offset:6912
	ds_write_b16_d16_hi v170, v190 offset:6944
	ds_write_b16 v170, v191 offset:6976
	ds_write_b16_d16_hi v170, v191 offset:7008
	v_cvt_pk_bf16_f32 v176, v79, v75
	v_cvt_pk_bf16_f32 v177, v71, v67
	ds_write_b16 v170, v176 offset:7056
	ds_write_b16_d16_hi v170, v176 offset:7088
	ds_write_b16 v170, v177 offset:7120
	ds_write_b16_d16_hi v170, v177 offset:7152
	v_cvt_pk_bf16_f32 v182, v80, v76
	v_cvt_pk_bf16_f32 v183, v72, v68
	ds_write_b16 v170, v182 offset:7200
	ds_write_b16_d16_hi v170, v182 offset:7232
	ds_write_b16 v170, v183 offset:7264
	ds_write_b16_d16_hi v170, v183 offset:7296
	v_cvt_pk_bf16_f32 v188, v81, v77
	v_cvt_pk_bf16_f32 v189, v73, v69
	ds_write_b16 v170, v188 offset:7344
	ds_write_b16_d16_hi v170, v188 offset:7376
	ds_write_b16 v170, v189 offset:7408
	ds_write_b16_d16_hi v170, v189 offset:7440
	ds_read_b128 v[130:133], v171 offset:0
	ds_read_b128 v[134:137], v171 offset:1152
	ds_read_b128 v[138:141], v171 offset:2304
	ds_read_b128 v[142:145], v171 offset:3456
	ds_read_b128 v[146:149], v171 offset:4608
	ds_read_b128 v[150:153], v171 offset:5760
	ds_read_b128 v[154:157], v171 offset:6912
	ds_read_b128 v[158:161], v171 offset:8064
	s_waitcnt lgkmcnt(7)
	global_store_dwordx4 v172, v[130:133], s[44:45] offset:0 sc1
	s_waitcnt lgkmcnt(6)
	global_store_dwordx4 v172, v[134:137], s[44:45] offset:1024 sc1
	s_waitcnt lgkmcnt(5)
	global_store_dwordx4 v172, v[138:141], s[44:45] offset:2048 sc1
	s_waitcnt lgkmcnt(4)
	global_store_dwordx4 v172, v[142:145], s[44:45] offset:3072 sc1
	s_waitcnt lgkmcnt(3)
	global_store_dwordx4 v172, v[146:149], s[62:63] offset:0 sc1
	s_waitcnt lgkmcnt(2)
	global_store_dwordx4 v172, v[150:153], s[62:63] offset:1024 sc1
	s_waitcnt lgkmcnt(1)
	global_store_dwordx4 v172, v[154:157], s[62:63] offset:2048 sc1
	s_waitcnt lgkmcnt(0)
; template <int EPI>
; DI void gemm_phase(const P& p, int l, const u16* __restrict__ A, const u16* __restrict__ Bt, int mpx, char* lds) {
;     ...
;           const unsigned u01 = pack2(v0, v1), u23 = pack2(v2, v3);
;           if (kind == 1) {
;             Tl[(0 * 16 + r) * 72 + rowl] = (u16)u01;
;             Tl[(1 * 16 + r) * 72 + rowl] = (u16)(u01 >> 16);
;             Tl[(2 * 16 + r) * 72 + rowl] = (u16)u23;
;             Tl[(3 * 16 + r) * 72 + rowl] = (u16)(u23 >> 16);
;           } else if (tr == 2) {
;             Tl[rowl * 72 + 0 * 16 + r] = f2h(v0);
;             Tl[rowl * 72 + 1 * 16 + r] = f2h(v1);
;             Tl[rowl * 72 + 2 * 16 + r] = f2h(v2);
;             Tl[rowl * 72 + 3 * 16 + r] = f2h(v3);
;           } else {
;             Tl[rowl * 72 + 0 * 16 + r] = (u16)u01;
;             Tl[rowl * 72 + 1 * 16 + r] = (u16)(u01 >> 16);
;             Tl[rowl * 72 + 2 * 16 + r] = (u16)u23;
;             Tl[rowl * 72 + 3 * 16 + r] = (u16)(u23 >> 16);
;           }
;         }
;       }
;       __builtin_amdgcn_fence(__ATOMIC_RELEASE, "wavefront");
;       u16* dh = (kind == 1) ? dst + hf * 64 : dst + (size_t)(hf * 64) * rstride;
; #pragma unroll
;       for (int i = 0; i < 8; ++i) {
;         const int c = lane + i * 64;
;         const int row = c >> 3, cc = c & 7;
;         uint4 v = *(const uint4*)&Tl[row * 72 + cc * 8];
;         *(uint4*)(dh + (size_t)row * rstride + cc * 8) = v;
;       }
	global_store_dwordx4 v172, v[158:161], s[62:63] offset:3072 sc1
	s_add_u32 s44, s44, 0x2000
	s_addc_u32 s45, s45, 0
	s_add_u32 s62, s62, 0x2000
	s_addc_u32 s63, s63, 0
	v_cvt_pk_bf16_f32 v178, v62, v58
	v_cvt_pk_bf16_f32 v179, v54, v50
	ds_write_b16 v170, v178 offset:0
	ds_write_b16_d16_hi v170, v178 offset:32
	ds_write_b16 v170, v179 offset:64
	ds_write_b16_d16_hi v170, v179 offset:96
	v_cvt_pk_bf16_f32 v184, v63, v59
	v_cvt_pk_bf16_f32 v185, v55, v51
	ds_write_b16 v170, v184 offset:144
	ds_write_b16_d16_hi v170, v184 offset:176
	ds_write_b16 v170, v185 offset:208
	ds_write_b16_d16_hi v170, v185 offset:240
	v_cvt_pk_bf16_f32 v190, v64, v60
	v_cvt_pk_bf16_f32 v191, v56, v52
	ds_write_b16 v170, v190 offset:288
	ds_write_b16_d16_hi v170, v190 offset:320
	ds_write_b16 v170, v191 offset:352
	ds_write_b16_d16_hi v170, v191 offset:384
	v_cvt_pk_bf16_f32 v176, v65, v61
	v_cvt_pk_bf16_f32 v177, v57, v53
	ds_write_b16 v170, v176 offset:432
	ds_write_b16_d16_hi v170, v176 offset:464
	ds_write_b16 v170, v177 offset:496
	ds_write_b16_d16_hi v170, v177 offset:528
	v_cvt_pk_bf16_f32 v182, v46, v42
	v_cvt_pk_bf16_f32 v183, v38, v34
	ds_write_b16 v170, v182 offset:2304
	ds_write_b16_d16_hi v170, v182 offset:2336
	ds_write_b16 v170, v183 offset:2368
	ds_write_b16_d16_hi v170, v183 offset:2400
	v_cvt_pk_bf16_f32 v188, v47, v43
	v_cvt_pk_bf16_f32 v189, v39, v35
	ds_write_b16 v170, v188 offset:2448
	ds_write_b16_d16_hi v170, v188 offset:2480
	ds_write_b16 v170, v189 offset:2512
	ds_write_b16_d16_hi v170, v189 offset:2544
	v_cvt_pk_bf16_f32 v174, v48, v44
	v_cvt_pk_bf16_f32 v175, v40, v36
	ds_write_b16 v170, v174 offset:2592
	ds_write_b16_d16_hi v170, v174 offset:2624
	ds_write_b16 v170, v175 offset:2656
	ds_write_b16_d16_hi v170, v175 offset:2688
	v_cvt_pk_bf16_f32 v180, v49, v45
	v_cvt_pk_bf16_f32 v181, v41, v37
	ds_write_b16 v170, v180 offset:2736
	ds_write_b16_d16_hi v170, v180 offset:2768
	ds_write_b16 v170, v181 offset:2800
	ds_write_b16_d16_hi v170, v181 offset:2832
	v_cvt_pk_bf16_f32 v186, v30, v26
	v_cvt_pk_bf16_f32 v187, v22, v18
	ds_write_b16 v170, v186 offset:4608
	ds_write_b16_d16_hi v170, v186 offset:4640
	ds_write_b16 v170, v187 offset:4672
	ds_write_b16_d16_hi v170, v187 offset:4704
	v_cvt_pk_bf16_f32 v192, v31, v27
	v_cvt_pk_bf16_f32 v193, v23, v19
	ds_write_b16 v170, v192 offset:4752
	ds_write_b16_d16_hi v170, v192 offset:4784
	ds_write_b16 v170, v193 offset:4816
	ds_write_b16_d16_hi v170, v193 offset:4848
	v_cvt_pk_bf16_f32 v178, v32, v28
	v_cvt_pk_bf16_f32 v179, v24, v20
	ds_write_b16 v170, v178 offset:4896
	ds_write_b16_d16_hi v170, v178 offset:4928
	ds_write_b16 v170, v179 offset:4960
	ds_write_b16_d16_hi v170, v179 offset:4992
	v_cvt_pk_bf16_f32 v184, v33, v29
	v_cvt_pk_bf16_f32 v185, v25, v21
	ds_write_b16 v170, v184 offset:5040
	ds_write_b16_d16_hi v170, v184 offset:5072
	ds_write_b16 v170, v185 offset:5104
	ds_write_b16_d16_hi v170, v185 offset:5136
	v_cvt_pk_bf16_f32 v190, v166, v162
	v_cvt_pk_bf16_f32 v191, v2, v6
	ds_write_b16 v170, v190 offset:6912
	ds_write_b16_d16_hi v170, v190 offset:6944
	ds_write_b16 v170, v191 offset:6976
	ds_write_b16_d16_hi v170, v191 offset:7008
	v_cvt_pk_bf16_f32 v176, v167, v163
	v_cvt_pk_bf16_f32 v177, v3, v7
	ds_write_b16 v170, v176 offset:7056
	ds_write_b16_d16_hi v170, v176 offset:7088
	ds_write_b16 v170, v177 offset:7120
	ds_write_b16_d16_hi v170, v177 offset:7152
	v_cvt_pk_bf16_f32 v182, v168, v164
	v_cvt_pk_bf16_f32 v183, v4, v8
	ds_write_b16 v170, v182 offset:7200
	ds_write_b16_d16_hi v170, v182 offset:7232
	ds_write_b16 v170, v183 offset:7264
	ds_write_b16_d16_hi v170, v183 offset:7296
	v_cvt_pk_bf16_f32 v188, v169, v165
	v_cvt_pk_bf16_f32 v189, v5, v9
	ds_write_b16 v170, v188 offset:7344
	ds_write_b16_d16_hi v170, v188 offset:7376
	ds_write_b16 v170, v189 offset:7408
	ds_write_b16_d16_hi v170, v189 offset:7440
	ds_read_b128 v[130:133], v171 offset:0
	ds_read_b128 v[134:137], v171 offset:1152
	ds_read_b128 v[138:141], v171 offset:2304
	ds_read_b128 v[142:145], v171 offset:3456
	ds_read_b128 v[146:149], v171 offset:4608
	ds_read_b128 v[150:153], v171 offset:5760
	ds_read_b128 v[154:157], v171 offset:6912
	ds_read_b128 v[158:161], v171 offset:8064
	s_waitcnt lgkmcnt(7)
	global_store_dwordx4 v172, v[130:133], s[44:45] offset:0 sc1
	s_waitcnt lgkmcnt(6)
	global_store_dwordx4 v172, v[134:137], s[44:45] offset:1024 sc1
	s_waitcnt lgkmcnt(5)
	global_store_dwordx4 v172, v[138:141], s[44:45] offset:2048 sc1
	s_waitcnt lgkmcnt(4)
	global_store_dwordx4 v172, v[142:145], s[44:45] offset:3072 sc1
	s_waitcnt lgkmcnt(3)
	global_store_dwordx4 v172, v[146:149], s[62:63] offset:0 sc1
	s_waitcnt lgkmcnt(2)
	global_store_dwordx4 v172, v[150:153], s[62:63] offset:1024 sc1
	s_waitcnt lgkmcnt(1)
	global_store_dwordx4 v172, v[154:157], s[62:63] offset:2048 sc1
	s_waitcnt lgkmcnt(0)
	global_store_dwordx4 v172, v[158:161], s[62:63] offset:3072 sc1
	s_branch .Lfe_done
; template <int EPI>
; DI void gemm_phase(const P& p, int l, const u16* __restrict__ A, const u16* __restrict__ Bt, int mpx, char* lds) {
;     ...
;             Tl[rowl * 72 + 0 * 16 + r] = f2h(v0);
;             Tl[rowl * 72 + 1 * 16 + r] = f2h(v1);
;             Tl[rowl * 72 + 2 * 16 + r] = f2h(v2);
;             Tl[rowl * 72 + 3 * 16 + r] = f2h(v3);
;     ...
;       __builtin_amdgcn_fence(__ATOMIC_RELEASE, "wavefront");
;       u16* dh = (kind == 1) ? dst + hf * 64 : dst + (size_t)(hf * 64) * rstride;
; #pragma unroll
;       for (int i = 0; i < 8; ++i) {
;         const int c = lane + i * 64;
;         const int row = c >> 3, cc = c & 7;
;         uint4 v = *(const uint4*)&Tl[row * 72 + cc * 8];
;         *(uint4*)(dh + (size_t)row * rstride + cc * 8) = v;
;       }
.Lfe_k0_fp16:
	s_add_u32 s62, s44, 0x1000
	s_addc_u32 s63, s45, 0
	v_cvt_f16_f32_e32 v174, v126
	v_cvt_f16_f32_e32 v175, v122
	v_cvt_f16_f32_e32 v176, v118
	v_cvt_f16_f32_e32 v177, v114
	ds_write_b16 v170, v174 offset:0
	ds_write_b16 v170, v175 offset:32
	ds_write_b16 v170, v176 offset:64
	ds_write_b16 v170, v177 offset:96
	v_cvt_f16_f32_e32 v180, v127
	v_cvt_f16_f32_e32 v181, v123
	v_cvt_f16_f32_e32 v182, v119
	v_cvt_f16_f32_e32 v183, v115
	ds_write_b16 v170, v180 offset:144
	ds_write_b16 v170, v181 offset:176
	ds_write_b16 v170, v182 offset:208
	ds_write_b16 v170, v183 offset:240
	v_cvt_f16_f32_e32 v186, v128
	v_cvt_f16_f32_e32 v187, v124
	v_cvt_f16_f32_e32 v188, v120
	v_cvt_f16_f32_e32 v189, v116
	ds_write_b16 v170, v186 offset:288
	ds_write_b16 v170, v187 offset:320
	ds_write_b16 v170, v188 offset:352
	ds_write_b16 v170, v189 offset:384
	v_cvt_f16_f32_e32 v192, v129
	v_cvt_f16_f32_e32 v193, v125
	v_cvt_f16_f32_e32 v174, v121
	v_cvt_f16_f32_e32 v175, v117
	ds_write_b16 v170, v192 offset:432
	ds_write_b16 v170, v193 offset:464
	ds_write_b16 v170, v174 offset:496
	ds_write_b16 v170, v175 offset:528
	v_cvt_f16_f32_e32 v178, v110
	v_cvt_f16_f32_e32 v179, v106
	v_cvt_f16_f32_e32 v180, v102
	v_cvt_f16_f32_e32 v181, v98
	ds_write_b16 v170, v178 offset:2304
	ds_write_b16 v170, v179 offset:2336
	ds_write_b16 v170, v180 offset:2368
	ds_write_b16 v170, v181 offset:2400
	v_cvt_f16_f32_e32 v184, v111
	v_cvt_f16_f32_e32 v185, v107
	v_cvt_f16_f32_e32 v186, v103
	v_cvt_f16_f32_e32 v187, v99
	ds_write_b16 v170, v184 offset:2448
	ds_write_b16 v170, v185 offset:2480
	ds_write_b16 v170, v186 offset:2512
	ds_write_b16 v170, v187 offset:2544
	v_cvt_f16_f32_e32 v190, v112
	v_cvt_f16_f32_e32 v191, v108
	v_cvt_f16_f32_e32 v192, v104
	v_cvt_f16_f32_e32 v193, v100
	ds_write_b16 v170, v190 offset:2592
	ds_write_b16 v170, v191 offset:2624
	ds_write_b16 v170, v192 offset:2656
	ds_write_b16 v170, v193 offset:2688
	v_cvt_f16_f32_e32 v176, v113
	v_cvt_f16_f32_e32 v177, v109
	v_cvt_f16_f32_e32 v178, v105
	v_cvt_f16_f32_e32 v179, v101
	ds_write_b16 v170, v176 offset:2736
	ds_write_b16 v170, v177 offset:2768
	ds_write_b16 v170, v178 offset:2800
	ds_write_b16 v170, v179 offset:2832
	v_cvt_f16_f32_e32 v182, v94
	v_cvt_f16_f32_e32 v183, v90
	v_cvt_f16_f32_e32 v184, v86
	v_cvt_f16_f32_e32 v185, v82
	ds_write_b16 v170, v182 offset:4608
	ds_write_b16 v170, v183 offset:4640
	ds_write_b16 v170, v184 offset:4672
	ds_write_b16 v170, v185 offset:4704
	v_cvt_f16_f32_e32 v188, v95
	v_cvt_f16_f32_e32 v189, v91
	v_cvt_f16_f32_e32 v190, v87
	v_cvt_f16_f32_e32 v191, v83
	ds_write_b16 v170, v188 offset:4752
	ds_write_b16 v170, v189 offset:4784
	ds_write_b16 v170, v190 offset:4816
	ds_write_b16 v170, v191 offset:4848
	v_cvt_f16_f32_e32 v174, v96
	v_cvt_f16_f32_e32 v175, v92
	v_cvt_f16_f32_e32 v176, v88
	v_cvt_f16_f32_e32 v177, v84
	ds_write_b16 v170, v174 offset:4896
	ds_write_b16 v170, v175 offset:4928
	ds_write_b16 v170, v176 offset:4960
	ds_write_b16 v170, v177 offset:4992
	v_cvt_f16_f32_e32 v180, v97
	v_cvt_f16_f32_e32 v181, v93
	v_cvt_f16_f32_e32 v182, v89
	v_cvt_f16_f32_e32 v183, v85
	ds_write_b16 v170, v180 offset:5040
	ds_write_b16 v170, v181 offset:5072
	ds_write_b16 v170, v182 offset:5104
	ds_write_b16 v170, v183 offset:5136
	v_cvt_f16_f32_e32 v186, v78
	v_cvt_f16_f32_e32 v187, v74
	v_cvt_f16_f32_e32 v188, v70
	v_cvt_f16_f32_e32 v189, v66
	ds_write_b16 v170, v186 offset:6912
	ds_write_b16 v170, v187 offset:6944
	ds_write_b16 v170, v188 offset:6976
	ds_write_b16 v170, v189 offset:7008
	v_cvt_f16_f32_e32 v192, v79
	v_cvt_f16_f32_e32 v193, v75
	v_cvt_f16_f32_e32 v174, v71
	v_cvt_f16_f32_e32 v175, v67
	ds_write_b16 v170, v192 offset:7056
	ds_write_b16 v170, v193 offset:7088
	ds_write_b16 v170, v174 offset:7120
	ds_write_b16 v170, v175 offset:7152
	v_cvt_f16_f32_e32 v178, v80
	v_cvt_f16_f32_e32 v179, v76
	v_cvt_f16_f32_e32 v180, v72
	v_cvt_f16_f32_e32 v181, v68
	ds_write_b16 v170, v178 offset:7200
	ds_write_b16 v170, v179 offset:7232
	ds_write_b16 v170, v180 offset:7264
	ds_write_b16 v170, v181 offset:7296
	v_cvt_f16_f32_e32 v184, v81
	v_cvt_f16_f32_e32 v185, v77
	v_cvt_f16_f32_e32 v186, v73
	v_cvt_f16_f32_e32 v187, v69
	ds_write_b16 v170, v184 offset:7344
	ds_write_b16 v170, v185 offset:7376
	ds_write_b16 v170, v186 offset:7408
	ds_write_b16 v170, v187 offset:7440
	ds_read_b128 v[130:133], v171 offset:0
	ds_read_b128 v[134:137], v171 offset:1152
	ds_read_b128 v[138:141], v171 offset:2304
	ds_read_b128 v[142:145], v171 offset:3456
	ds_read_b128 v[146:149], v171 offset:4608
	ds_read_b128 v[150:153], v171 offset:5760
	ds_read_b128 v[154:157], v171 offset:6912
	ds_read_b128 v[158:161], v171 offset:8064
	s_waitcnt lgkmcnt(7)
	global_store_dwordx4 v172, v[130:133], s[44:45] offset:0 sc1
	s_waitcnt lgkmcnt(6)
	global_store_dwordx4 v172, v[134:137], s[44:45] offset:1024 sc1
	s_waitcnt lgkmcnt(5)
	global_store_dwordx4 v172, v[138:141], s[44:45] offset:2048 sc1
	s_waitcnt lgkmcnt(4)
	global_store_dwordx4 v172, v[142:145], s[44:45] offset:3072 sc1
	s_waitcnt lgkmcnt(3)
	global_store_dwordx4 v172, v[146:149], s[62:63] offset:0 sc1
	s_waitcnt lgkmcnt(2)
	global_store_dwordx4 v172, v[150:153], s[62:63] offset:1024 sc1
	s_waitcnt lgkmcnt(1)
	global_store_dwordx4 v172, v[154:157], s[62:63] offset:2048 sc1
	s_waitcnt lgkmcnt(0)
; template <int EPI>
; DI void gemm_phase(const P& p, int l, const u16* __restrict__ A, const u16* __restrict__ Bt, int mpx, char* lds) {
;     ...
;             Tl[rowl * 72 + 0 * 16 + r] = f2h(v0);
;             Tl[rowl * 72 + 1 * 16 + r] = f2h(v1);
;             Tl[rowl * 72 + 2 * 16 + r] = f2h(v2);
;             Tl[rowl * 72 + 3 * 16 + r] = f2h(v3);
;     ...
;       __builtin_amdgcn_fence(__ATOMIC_RELEASE, "wavefront");
;       u16* dh = (kind == 1) ? dst + hf * 64 : dst + (size_t)(hf * 64) * rstride;
; #pragma unroll
;       for (int i = 0; i < 8; ++i) {
;         const int c = lane + i * 64;
;         const int row = c >> 3, cc = c & 7;
;         uint4 v = *(const uint4*)&Tl[row * 72 + cc * 8];
;         *(uint4*)(dh + (size_t)row * rstride + cc * 8) = v;
;       }
	global_store_dwordx4 v172, v[158:161], s[62:63] offset:3072 sc1
	s_add_u32 s44, s44, 0x2000
	s_addc_u32 s45, s45, 0
	s_add_u32 s62, s62, 0x2000
	s_addc_u32 s63, s63, 0
	v_cvt_f16_f32_e32 v174, v62
	v_cvt_f16_f32_e32 v175, v58
	v_cvt_f16_f32_e32 v176, v54
	v_cvt_f16_f32_e32 v177, v50
	ds_write_b16 v170, v174 offset:0
	ds_write_b16 v170, v175 offset:32
	ds_write_b16 v170, v176 offset:64
	ds_write_b16 v170, v177 offset:96
	v_cvt_f16_f32_e32 v180, v63
	v_cvt_f16_f32_e32 v181, v59
	v_cvt_f16_f32_e32 v182, v55
	v_cvt_f16_f32_e32 v183, v51
	ds_write_b16 v170, v180 offset:144
	ds_write_b16 v170, v181 offset:176
	ds_write_b16 v170, v182 offset:208
	ds_write_b16 v170, v183 offset:240
	v_cvt_f16_f32_e32 v186, v64
	v_cvt_f16_f32_e32 v187, v60
	v_cvt_f16_f32_e32 v188, v56
	v_cvt_f16_f32_e32 v189, v52
	ds_write_b16 v170, v186 offset:288
	ds_write_b16 v170, v187 offset:320
	ds_write_b16 v170, v188 offset:352
	ds_write_b16 v170, v189 offset:384
	v_cvt_f16_f32_e32 v192, v65
	v_cvt_f16_f32_e32 v193, v61
	v_cvt_f16_f32_e32 v174, v57
	v_cvt_f16_f32_e32 v175, v53
	ds_write_b16 v170, v192 offset:432
	ds_write_b16 v170, v193 offset:464
	ds_write_b16 v170, v174 offset:496
	ds_write_b16 v170, v175 offset:528
	v_cvt_f16_f32_e32 v178, v46
	v_cvt_f16_f32_e32 v179, v42
	v_cvt_f16_f32_e32 v180, v38
	v_cvt_f16_f32_e32 v181, v34
	ds_write_b16 v170, v178 offset:2304
	ds_write_b16 v170, v179 offset:2336
	ds_write_b16 v170, v180 offset:2368
	ds_write_b16 v170, v181 offset:2400
	v_cvt_f16_f32_e32 v184, v47
	v_cvt_f16_f32_e32 v185, v43
	v_cvt_f16_f32_e32 v186, v39
	v_cvt_f16_f32_e32 v187, v35
	ds_write_b16 v170, v184 offset:2448
	ds_write_b16 v170, v185 offset:2480
	ds_write_b16 v170, v186 offset:2512
	ds_write_b16 v170, v187 offset:2544
	v_cvt_f16_f32_e32 v190, v48
	v_cvt_f16_f32_e32 v191, v44
	v_cvt_f16_f32_e32 v192, v40
	v_cvt_f16_f32_e32 v193, v36
	ds_write_b16 v170, v190 offset:2592
	ds_write_b16 v170, v191 offset:2624
	ds_write_b16 v170, v192 offset:2656
	ds_write_b16 v170, v193 offset:2688
	v_cvt_f16_f32_e32 v176, v49
	v_cvt_f16_f32_e32 v177, v45
	v_cvt_f16_f32_e32 v178, v41
	v_cvt_f16_f32_e32 v179, v37
	ds_write_b16 v170, v176 offset:2736
	ds_write_b16 v170, v177 offset:2768
	ds_write_b16 v170, v178 offset:2800
	ds_write_b16 v170, v179 offset:2832
	v_cvt_f16_f32_e32 v182, v30
	v_cvt_f16_f32_e32 v183, v26
	v_cvt_f16_f32_e32 v184, v22
	v_cvt_f16_f32_e32 v185, v18
	ds_write_b16 v170, v182 offset:4608
	ds_write_b16 v170, v183 offset:4640
	ds_write_b16 v170, v184 offset:4672
	ds_write_b16 v170, v185 offset:4704
	v_cvt_f16_f32_e32 v188, v31
	v_cvt_f16_f32_e32 v189, v27
	v_cvt_f16_f32_e32 v190, v23
	v_cvt_f16_f32_e32 v191, v19
	ds_write_b16 v170, v188 offset:4752
	ds_write_b16 v170, v189 offset:4784
	ds_write_b16 v170, v190 offset:4816
	ds_write_b16 v170, v191 offset:4848
	v_cvt_f16_f32_e32 v174, v32
	v_cvt_f16_f32_e32 v175, v28
	v_cvt_f16_f32_e32 v176, v24
	v_cvt_f16_f32_e32 v177, v20
	ds_write_b16 v170, v174 offset:4896
	ds_write_b16 v170, v175 offset:4928
	ds_write_b16 v170, v176 offset:4960
	ds_write_b16 v170, v177 offset:4992
	v_cvt_f16_f32_e32 v180, v33
	v_cvt_f16_f32_e32 v181, v29
	v_cvt_f16_f32_e32 v182, v25
	v_cvt_f16_f32_e32 v183, v21
	ds_write_b16 v170, v180 offset:5040
	ds_write_b16 v170, v181 offset:5072
	ds_write_b16 v170, v182 offset:5104
	ds_write_b16 v170, v183 offset:5136
	v_cvt_f16_f32_e32 v186, v166
	v_cvt_f16_f32_e32 v187, v162
	v_cvt_f16_f32_e32 v188, v2
	v_cvt_f16_f32_e32 v189, v6
	ds_write_b16 v170, v186 offset:6912
	ds_write_b16 v170, v187 offset:6944
	ds_write_b16 v170, v188 offset:6976
	ds_write_b16 v170, v189 offset:7008
	v_cvt_f16_f32_e32 v192, v167
	v_cvt_f16_f32_e32 v193, v163
	v_cvt_f16_f32_e32 v174, v3
	v_cvt_f16_f32_e32 v175, v7
	ds_write_b16 v170, v192 offset:7056
	ds_write_b16 v170, v193 offset:7088
	ds_write_b16 v170, v174 offset:7120
	ds_write_b16 v170, v175 offset:7152
	v_cvt_f16_f32_e32 v178, v168
	v_cvt_f16_f32_e32 v179, v164
	v_cvt_f16_f32_e32 v180, v4
	v_cvt_f16_f32_e32 v181, v8
	ds_write_b16 v170, v178 offset:7200
	ds_write_b16 v170, v179 offset:7232
	ds_write_b16 v170, v180 offset:7264
	ds_write_b16 v170, v181 offset:7296
	v_cvt_f16_f32_e32 v184, v169
	v_cvt_f16_f32_e32 v185, v165
	v_cvt_f16_f32_e32 v186, v5
	v_cvt_f16_f32_e32 v187, v9
	ds_write_b16 v170, v184 offset:7344
	ds_write_b16 v170, v185 offset:7376
	ds_write_b16 v170, v186 offset:7408
	ds_write_b16 v170, v187 offset:7440
	ds_read_b128 v[130:133], v171 offset:0
	ds_read_b128 v[134:137], v171 offset:1152
	ds_read_b128 v[138:141], v171 offset:2304
	ds_read_b128 v[142:145], v171 offset:3456
	ds_read_b128 v[146:149], v171 offset:4608
	ds_read_b128 v[150:153], v171 offset:5760
	ds_read_b128 v[154:157], v171 offset:6912
	ds_read_b128 v[158:161], v171 offset:8064
	s_waitcnt lgkmcnt(7)
	global_store_dwordx4 v172, v[130:133], s[44:45] offset:0 sc1
	s_waitcnt lgkmcnt(6)
	global_store_dwordx4 v172, v[134:137], s[44:45] offset:1024 sc1
	s_waitcnt lgkmcnt(5)
	global_store_dwordx4 v172, v[138:141], s[44:45] offset:2048 sc1
	s_waitcnt lgkmcnt(4)
	global_store_dwordx4 v172, v[142:145], s[44:45] offset:3072 sc1
	s_waitcnt lgkmcnt(3)
	global_store_dwordx4 v172, v[146:149], s[62:63] offset:0 sc1
	s_waitcnt lgkmcnt(2)
	global_store_dwordx4 v172, v[150:153], s[62:63] offset:1024 sc1
	s_waitcnt lgkmcnt(1)
	global_store_dwordx4 v172, v[154:157], s[62:63] offset:2048 sc1
	s_waitcnt lgkmcnt(0)
	global_store_dwordx4 v172, v[158:161], s[62:63] offset:3072 sc1
	s_branch .Lfe_done
; DI void sincos_rev(float ang, float& s, float& c) {
;   float rev = ang * 0.15915494309189535f;
;   rev -= rintf(rev);
;   s = __builtin_amdgcn_sinf(rev);
;   c = __builtin_amdgcn_cosf(rev);
; }
; template <int EPI>
; DI void gemm_phase(const P& p, int l, const u16* __restrict__ A, const u16* __restrict__ Bt, int mpx, char* lds) {
;     ...
;     const float invf64 = exp2f(-13.287712379549449f * (float)r * (1.f / 16.f));
;     ...
;             if (dorope) {
;               float sr, cr, sc, cc;
;               sincos_rev((float)(s >> 6) * invf64, sr, cr);
;               sincos_rev((float)(s & 63) * invf64, sc, cc);
;               const float a1 = v0, a2 = v1, b1 = v2, b2 = v3;
;               v0 = a1 * cr - a2 * sr;
;               v1 = a2 * cr + a1 * sr;
;               v2 = b1 * cc - b2 * sc;
;               v3 = b2 * cc + b1 * sc;
;             }
.Lfe_k0_rope64:
	v_and_b32_e32 v0, 15, v226
	v_cvt_f32_ubyte0_e32 v0, v0
	v_mul_f32_e32 v0, 0xc1549a78, v0
	v_mul_f32_e32 v0, 0x3d800000, v0
	v_exp_f32_e32 v174, v0
	v_lshrrev_b32_e32 v0, 4, v226
	v_lshlrev_b32_e32 v0, 2, v0
	v_add_u32_e32 v182, 0, v0
	v_cvt_f32_i32_e32 v182, v182
	v_mul_f32_e32 v182, v174, v182
	v_mul_f32_e32 v183, 0.15915494, v182
	v_rndne_f32_e32 v183, v183
	v_fma_f32 v183, v182, 0.15915494, -v183
	v_sin_f32_e32 v212, v183
	v_cos_f32_e32 v238, v183
	v_add_u32_e32 v182, 1, v0
	v_cvt_f32_i32_e32 v182, v182
	v_mul_f32_e32 v182, v174, v182
	v_mul_f32_e32 v183, 0.15915494, v182
	v_rndne_f32_e32 v183, v183
	v_fma_f32 v183, v182, 0.15915494, -v183
	v_sin_f32_e32 v213, v183
	v_cos_f32_e32 v239, v183
	v_add_u32_e32 v182, 2, v0
	v_cvt_f32_i32_e32 v182, v182
	v_mul_f32_e32 v182, v174, v182
	v_mul_f32_e32 v183, 0.15915494, v182
	v_rndne_f32_e32 v183, v183
	v_fma_f32 v183, v182, 0.15915494, -v183
	v_sin_f32_e32 v214, v183
	v_cos_f32_e32 v240, v183
	v_add_u32_e32 v182, 3, v0
	v_cvt_f32_i32_e32 v182, v182
	v_mul_f32_e32 v182, v174, v182
	v_mul_f32_e32 v183, 0.15915494, v182
	v_rndne_f32_e32 v183, v183
	v_fma_f32 v183, v182, 0.15915494, -v183
	v_sin_f32_e32 v215, v183
	v_cos_f32_e32 v241, v183
	v_add_u32_e32 v182, 16, v0
	v_cvt_f32_i32_e32 v182, v182
	v_mul_f32_e32 v182, v174, v182
	v_mul_f32_e32 v183, 0.15915494, v182
	v_rndne_f32_e32 v183, v183
	v_fma_f32 v183, v182, 0.15915494, -v183
	v_sin_f32_e32 v216, v183
	v_cos_f32_e32 v242, v183
	v_add_u32_e32 v182, 17, v0
	v_cvt_f32_i32_e32 v182, v182
	v_mul_f32_e32 v182, v174, v182
	v_mul_f32_e32 v183, 0.15915494, v182
	v_rndne_f32_e32 v183, v183
	v_fma_f32 v183, v182, 0.15915494, -v183
	v_sin_f32_e32 v217, v183
	v_cos_f32_e32 v243, v183
	v_add_u32_e32 v182, 18, v0
	v_cvt_f32_i32_e32 v182, v182
	v_mul_f32_e32 v182, v174, v182
	v_mul_f32_e32 v183, 0.15915494, v182
	v_rndne_f32_e32 v183, v183
	v_fma_f32 v183, v182, 0.15915494, -v183
	v_sin_f32_e32 v218, v183
	v_cos_f32_e32 v244, v183
	v_add_u32_e32 v182, 19, v0
	v_cvt_f32_i32_e32 v182, v182
	v_mul_f32_e32 v182, v174, v182
	v_mul_f32_e32 v183, 0.15915494, v182
	v_rndne_f32_e32 v183, v183
	v_fma_f32 v183, v182, 0.15915494, -v183
	v_sin_f32_e32 v219, v183
	v_cos_f32_e32 v245, v183
	v_add_u32_e32 v182, 32, v0
	v_cvt_f32_i32_e32 v182, v182
	v_mul_f32_e32 v182, v174, v182
	v_mul_f32_e32 v183, 0.15915494, v182
	v_rndne_f32_e32 v183, v183
	v_fma_f32 v183, v182, 0.15915494, -v183
	v_sin_f32_e32 v220, v183
	v_cos_f32_e32 v246, v183
	v_add_u32_e32 v182, 33, v0
	v_cvt_f32_i32_e32 v182, v182
	v_mul_f32_e32 v182, v174, v182
	v_mul_f32_e32 v183, 0.15915494, v182
	v_rndne_f32_e32 v183, v183
	v_fma_f32 v183, v182, 0.15915494, -v183
	v_sin_f32_e32 v221, v183
	v_cos_f32_e32 v247, v183
	v_add_u32_e32 v182, 34, v0
	v_cvt_f32_i32_e32 v182, v182
	v_mul_f32_e32 v182, v174, v182
	v_mul_f32_e32 v183, 0.15915494, v182
	v_rndne_f32_e32 v183, v183
	v_fma_f32 v183, v182, 0.15915494, -v183
	v_sin_f32_e32 v222, v183
	v_cos_f32_e32 v248, v183
	v_add_u32_e32 v182, 35, v0
	v_cvt_f32_i32_e32 v182, v182
	v_mul_f32_e32 v182, v174, v182
	v_mul_f32_e32 v183, 0.15915494, v182
	v_rndne_f32_e32 v183, v183
	v_fma_f32 v183, v182, 0.15915494, -v183
	v_sin_f32_e32 v223, v183
	v_cos_f32_e32 v249, v183
	v_add_u32_e32 v182, 48, v0
	v_cvt_f32_i32_e32 v182, v182
	v_mul_f32_e32 v182, v174, v182
	v_mul_f32_e32 v183, 0.15915494, v182
	v_rndne_f32_e32 v183, v183
	v_fma_f32 v183, v182, 0.15915494, -v183
	v_sin_f32_e32 v234, v183
	v_cos_f32_e32 v250, v183
	v_add_u32_e32 v182, 49, v0
	v_cvt_f32_i32_e32 v182, v182
	v_mul_f32_e32 v182, v174, v182
	v_mul_f32_e32 v183, 0.15915494, v182
	v_rndne_f32_e32 v183, v183
	v_fma_f32 v183, v182, 0.15915494, -v183
	v_sin_f32_e32 v235, v183
	v_cos_f32_e32 v251, v183
	v_add_u32_e32 v182, 50, v0
	v_cvt_f32_i32_e32 v182, v182
	v_mul_f32_e32 v182, v174, v182
	v_mul_f32_e32 v183, 0.15915494, v182
	v_rndne_f32_e32 v183, v183
	v_fma_f32 v183, v182, 0.15915494, -v183
	v_sin_f32_e32 v236, v183
	v_cos_f32_e32 v252, v183
	v_add_u32_e32 v182, 51, v0
	v_cvt_f32_i32_e32 v182, v182
	v_mul_f32_e32 v182, v174, v182
	v_mul_f32_e32 v183, 0.15915494, v182
	v_rndne_f32_e32 v183, v183
	v_fma_f32 v183, v182, 0.15915494, -v183
	v_sin_f32_e32 v237, v183
	v_cos_f32_e32 v253, v183
	s_add_u32 s62, s44, 0x1000
	s_addc_u32 s63, s45, 0
	s_lshr_b32 s70, s69, 6
	v_cvt_f32_i32_e32 v182, s70
	v_mul_f32_e32 v182, v174, v182
	v_mul_f32_e32 v183, 0.15915494, v182
	v_rndne_f32_e32 v183, v183
	v_fma_f32 v183, v182, 0.15915494, -v183
	v_sin_f32_e32 v175, v183
	v_cos_f32_e32 v176, v183
	v_mul_f32_e32 v186, v175, v122
	v_mul_f32_e32 v187, v176, v122
	v_fma_f32 v188, v176, v126, -v186
	v_fma_f32 v189, v175, v126, v187
	v_mul_f32_e32 v186, v212, v114
	v_mul_f32_e32 v187, v238, v114
	v_fma_f32 v190, v238, v118, -v186
	v_fma_f32 v191, v212, v118, v187
	v_cvt_pk_bf16_f32 v192, v188, v189
	v_cvt_pk_bf16_f32 v193, v190, v191
	ds_write_b16 v170, v192 offset:0
	ds_write_b16_d16_hi v170, v192 offset:32
	ds_write_b16 v170, v193 offset:64
	ds_write_b16_d16_hi v170, v193 offset:96
	v_mul_f32_e32 v186, v175, v123
	v_mul_f32_e32 v187, v176, v123
	v_fma_f32 v188, v176, v127, -v186
	v_fma_f32 v189, v175, v127, v187
	v_mul_f32_e32 v186, v213, v115
	v_mul_f32_e32 v187, v239, v115
	v_fma_f32 v190, v239, v119, -v186
	v_fma_f32 v191, v213, v119, v187
	v_cvt_pk_bf16_f32 v192, v188, v189
	v_cvt_pk_bf16_f32 v193, v190, v191
	ds_write_b16 v170, v192 offset:144
	ds_write_b16_d16_hi v170, v192 offset:176
	ds_write_b16 v170, v193 offset:208
	ds_write_b16_d16_hi v170, v193 offset:240
	v_mul_f32_e32 v186, v175, v124
	v_mul_f32_e32 v187, v176, v124
	v_fma_f32 v188, v176, v128, -v186
	v_fma_f32 v189, v175, v128, v187
	v_mul_f32_e32 v186, v214, v116
; template <int EPI>
; DI void gemm_phase(const P& p, int l, const u16* __restrict__ A, const u16* __restrict__ Bt, int mpx, char* lds) {
;     ...
;             if (dorope) {
;               float sr, cr, sc, cc;
;               sincos_rev((float)(s >> 6) * invf64, sr, cr);
;               sincos_rev((float)(s & 63) * invf64, sc, cc);
;               const float a1 = v0, a2 = v1, b1 = v2, b2 = v3;
;               v0 = a1 * cr - a2 * sr;
;               v1 = a2 * cr + a1 * sr;
;               v2 = b1 * cc - b2 * sc;
;               v3 = b2 * cc + b1 * sc;
;             }
;     ...
;             Tl[rowl * 72 + 0 * 16 + r] = (u16)u01;
;             Tl[rowl * 72 + 1 * 16 + r] = (u16)(u01 >> 16);
;             Tl[rowl * 72 + 2 * 16 + r] = (u16)u23;
;             Tl[rowl * 72 + 3 * 16 + r] = (u16)(u23 >> 16);
	v_mul_f32_e32 v187, v240, v116
	v_fma_f32 v190, v240, v120, -v186
	v_fma_f32 v191, v214, v120, v187
	v_cvt_pk_bf16_f32 v192, v188, v189
	v_cvt_pk_bf16_f32 v193, v190, v191
	ds_write_b16 v170, v192 offset:288
	ds_write_b16_d16_hi v170, v192 offset:320
	ds_write_b16 v170, v193 offset:352
	ds_write_b16_d16_hi v170, v193 offset:384
	v_mul_f32_e32 v186, v175, v125
	v_mul_f32_e32 v187, v176, v125
	v_fma_f32 v188, v176, v129, -v186
	v_fma_f32 v189, v175, v129, v187
	v_mul_f32_e32 v186, v215, v117
	v_mul_f32_e32 v187, v241, v117
	v_fma_f32 v190, v241, v121, -v186
	v_fma_f32 v191, v215, v121, v187
	v_cvt_pk_bf16_f32 v192, v188, v189
	v_cvt_pk_bf16_f32 v193, v190, v191
	ds_write_b16 v170, v192 offset:432
	ds_write_b16_d16_hi v170, v192 offset:464
	ds_write_b16 v170, v193 offset:496
	ds_write_b16_d16_hi v170, v193 offset:528
	v_mul_f32_e32 v186, v175, v106
	v_mul_f32_e32 v187, v176, v106
	v_fma_f32 v188, v176, v110, -v186
	v_fma_f32 v189, v175, v110, v187
	v_mul_f32_e32 v186, v216, v98
	v_mul_f32_e32 v187, v242, v98
	v_fma_f32 v190, v242, v102, -v186
	v_fma_f32 v191, v216, v102, v187
	v_cvt_pk_bf16_f32 v192, v188, v189
	v_cvt_pk_bf16_f32 v193, v190, v191
	ds_write_b16 v170, v192 offset:2304
	ds_write_b16_d16_hi v170, v192 offset:2336
	ds_write_b16 v170, v193 offset:2368
	ds_write_b16_d16_hi v170, v193 offset:2400
	v_mul_f32_e32 v186, v175, v107
	v_mul_f32_e32 v187, v176, v107
	v_fma_f32 v188, v176, v111, -v186
	v_fma_f32 v189, v175, v111, v187
	v_mul_f32_e32 v186, v217, v99
	v_mul_f32_e32 v187, v243, v99
	v_fma_f32 v190, v243, v103, -v186
	v_fma_f32 v191, v217, v103, v187
	v_cvt_pk_bf16_f32 v192, v188, v189
	v_cvt_pk_bf16_f32 v193, v190, v191
	ds_write_b16 v170, v192 offset:2448
	ds_write_b16_d16_hi v170, v192 offset:2480
	ds_write_b16 v170, v193 offset:2512
	ds_write_b16_d16_hi v170, v193 offset:2544
	v_mul_f32_e32 v186, v175, v108
	v_mul_f32_e32 v187, v176, v108
	v_fma_f32 v188, v176, v112, -v186
	v_fma_f32 v189, v175, v112, v187
	v_mul_f32_e32 v186, v218, v100
	v_mul_f32_e32 v187, v244, v100
	v_fma_f32 v190, v244, v104, -v186
	v_fma_f32 v191, v218, v104, v187
	v_cvt_pk_bf16_f32 v192, v188, v189
	v_cvt_pk_bf16_f32 v193, v190, v191
	ds_write_b16 v170, v192 offset:2592
	ds_write_b16_d16_hi v170, v192 offset:2624
	ds_write_b16 v170, v193 offset:2656
	ds_write_b16_d16_hi v170, v193 offset:2688
	v_mul_f32_e32 v186, v175, v109
	v_mul_f32_e32 v187, v176, v109
	v_fma_f32 v188, v176, v113, -v186
	v_fma_f32 v189, v175, v113, v187
	v_mul_f32_e32 v186, v219, v101
	v_mul_f32_e32 v187, v245, v101
	v_fma_f32 v190, v245, v105, -v186
	v_fma_f32 v191, v219, v105, v187
	v_cvt_pk_bf16_f32 v192, v188, v189
	v_cvt_pk_bf16_f32 v193, v190, v191
	ds_write_b16 v170, v192 offset:2736
	ds_write_b16_d16_hi v170, v192 offset:2768
	ds_write_b16 v170, v193 offset:2800
	ds_write_b16_d16_hi v170, v193 offset:2832
	v_mul_f32_e32 v186, v175, v90
	v_mul_f32_e32 v187, v176, v90
	v_fma_f32 v188, v176, v94, -v186
	v_fma_f32 v189, v175, v94, v187
	v_mul_f32_e32 v186, v220, v82
	v_mul_f32_e32 v187, v246, v82
	v_fma_f32 v190, v246, v86, -v186
	v_fma_f32 v191, v220, v86, v187
	v_cvt_pk_bf16_f32 v192, v188, v189
	v_cvt_pk_bf16_f32 v193, v190, v191
	ds_write_b16 v170, v192 offset:4608
	ds_write_b16_d16_hi v170, v192 offset:4640
	ds_write_b16 v170, v193 offset:4672
	ds_write_b16_d16_hi v170, v193 offset:4704
	v_mul_f32_e32 v186, v175, v91
	v_mul_f32_e32 v187, v176, v91
	v_fma_f32 v188, v176, v95, -v186
	v_fma_f32 v189, v175, v95, v187
	v_mul_f32_e32 v186, v221, v83
	v_mul_f32_e32 v187, v247, v83
	v_fma_f32 v190, v247, v87, -v186
	v_fma_f32 v191, v221, v87, v187
	v_cvt_pk_bf16_f32 v192, v188, v189
	v_cvt_pk_bf16_f32 v193, v190, v191
	ds_write_b16 v170, v192 offset:4752
	ds_write_b16_d16_hi v170, v192 offset:4784
	ds_write_b16 v170, v193 offset:4816
	ds_write_b16_d16_hi v170, v193 offset:4848
	v_mul_f32_e32 v186, v175, v92
	v_mul_f32_e32 v187, v176, v92
	v_fma_f32 v188, v176, v96, -v186
	v_fma_f32 v189, v175, v96, v187
	v_mul_f32_e32 v186, v222, v84
	v_mul_f32_e32 v187, v248, v84
	v_fma_f32 v190, v248, v88, -v186
	v_fma_f32 v191, v222, v88, v187
	v_cvt_pk_bf16_f32 v192, v188, v189
	v_cvt_pk_bf16_f32 v193, v190, v191
	ds_write_b16 v170, v192 offset:4896
	ds_write_b16_d16_hi v170, v192 offset:4928
	ds_write_b16 v170, v193 offset:4960
	ds_write_b16_d16_hi v170, v193 offset:4992
	v_mul_f32_e32 v186, v175, v93
	v_mul_f32_e32 v187, v176, v93
	v_fma_f32 v188, v176, v97, -v186
	v_fma_f32 v189, v175, v97, v187
	v_mul_f32_e32 v186, v223, v85
	v_mul_f32_e32 v187, v249, v85
	v_fma_f32 v190, v249, v89, -v186
	v_fma_f32 v191, v223, v89, v187
	v_cvt_pk_bf16_f32 v192, v188, v189
	v_cvt_pk_bf16_f32 v193, v190, v191
	ds_write_b16 v170, v192 offset:5040
	ds_write_b16_d16_hi v170, v192 offset:5072
	ds_write_b16 v170, v193 offset:5104
	ds_write_b16_d16_hi v170, v193 offset:5136
	v_mul_f32_e32 v186, v175, v74
	v_mul_f32_e32 v187, v176, v74
	v_fma_f32 v188, v176, v78, -v186
	v_fma_f32 v189, v175, v78, v187
	v_mul_f32_e32 v186, v234, v66
	v_mul_f32_e32 v187, v250, v66
	v_fma_f32 v190, v250, v70, -v186
	v_fma_f32 v191, v234, v70, v187
	v_cvt_pk_bf16_f32 v192, v188, v189
	v_cvt_pk_bf16_f32 v193, v190, v191
	ds_write_b16 v170, v192 offset:6912
	ds_write_b16_d16_hi v170, v192 offset:6944
	ds_write_b16 v170, v193 offset:6976
	ds_write_b16_d16_hi v170, v193 offset:7008
	v_mul_f32_e32 v186, v175, v75
	v_mul_f32_e32 v187, v176, v75
	v_fma_f32 v188, v176, v79, -v186
	v_fma_f32 v189, v175, v79, v187
	v_mul_f32_e32 v186, v235, v67
	v_mul_f32_e32 v187, v251, v67
	v_fma_f32 v190, v251, v71, -v186
	v_fma_f32 v191, v235, v71, v187
	v_cvt_pk_bf16_f32 v192, v188, v189
	v_cvt_pk_bf16_f32 v193, v190, v191
	ds_write_b16 v170, v192 offset:7056
; template <int EPI>
; DI void gemm_phase(const P& p, int l, const u16* __restrict__ A, const u16* __restrict__ Bt, int mpx, char* lds) {
;     ...
;             if (dorope) {
;               float sr, cr, sc, cc;
;               sincos_rev((float)(s >> 6) * invf64, sr, cr);
;               sincos_rev((float)(s & 63) * invf64, sc, cc);
;               const float a1 = v0, a2 = v1, b1 = v2, b2 = v3;
;               v0 = a1 * cr - a2 * sr;
;               v1 = a2 * cr + a1 * sr;
;               v2 = b1 * cc - b2 * sc;
;               v3 = b2 * cc + b1 * sc;
;             }
;     ...
;             Tl[rowl * 72 + 0 * 16 + r] = (u16)u01;
;             Tl[rowl * 72 + 1 * 16 + r] = (u16)(u01 >> 16);
;             Tl[rowl * 72 + 2 * 16 + r] = (u16)u23;
;             Tl[rowl * 72 + 3 * 16 + r] = (u16)(u23 >> 16);
;           }
;         }
;       }
;       __builtin_amdgcn_fence(__ATOMIC_RELEASE, "wavefront");
;       u16* dh = (kind == 1) ? dst + hf * 64 : dst + (size_t)(hf * 64) * rstride;
; #pragma unroll
;       for (int i = 0; i < 8; ++i) {
;         const int c = lane + i * 64;
;         const int row = c >> 3, cc = c & 7;
;         uint4 v = *(const uint4*)&Tl[row * 72 + cc * 8];
;         *(uint4*)(dh + (size_t)row * rstride + cc * 8) = v;
;       }
	ds_write_b16_d16_hi v170, v192 offset:7088
	ds_write_b16 v170, v193 offset:7120
	ds_write_b16_d16_hi v170, v193 offset:7152
	v_mul_f32_e32 v186, v175, v76
	v_mul_f32_e32 v187, v176, v76
	v_fma_f32 v188, v176, v80, -v186
	v_fma_f32 v189, v175, v80, v187
	v_mul_f32_e32 v186, v236, v68
	v_mul_f32_e32 v187, v252, v68
	v_fma_f32 v190, v252, v72, -v186
	v_fma_f32 v191, v236, v72, v187
	v_cvt_pk_bf16_f32 v192, v188, v189
	v_cvt_pk_bf16_f32 v193, v190, v191
	ds_write_b16 v170, v192 offset:7200
	ds_write_b16_d16_hi v170, v192 offset:7232
	ds_write_b16 v170, v193 offset:7264
	ds_write_b16_d16_hi v170, v193 offset:7296
	v_mul_f32_e32 v186, v175, v77
	v_mul_f32_e32 v187, v176, v77
	v_fma_f32 v188, v176, v81, -v186
	v_fma_f32 v189, v175, v81, v187
	v_mul_f32_e32 v186, v237, v69
	v_mul_f32_e32 v187, v253, v69
	v_fma_f32 v190, v253, v73, -v186
	v_fma_f32 v191, v237, v73, v187
	v_cvt_pk_bf16_f32 v192, v188, v189
	v_cvt_pk_bf16_f32 v193, v190, v191
	ds_write_b16 v170, v192 offset:7344
	ds_write_b16_d16_hi v170, v192 offset:7376
	ds_write_b16 v170, v193 offset:7408
	ds_write_b16_d16_hi v170, v193 offset:7440
	ds_read_b128 v[130:133], v171 offset:0
	ds_read_b128 v[134:137], v171 offset:1152
	ds_read_b128 v[138:141], v171 offset:2304
	ds_read_b128 v[142:145], v171 offset:3456
	ds_read_b128 v[146:149], v171 offset:4608
	ds_read_b128 v[150:153], v171 offset:5760
	ds_read_b128 v[154:157], v171 offset:6912
	ds_read_b128 v[158:161], v171 offset:8064
	s_waitcnt lgkmcnt(7)
	global_store_dwordx4 v172, v[130:133], s[44:45] offset:0 sc1
	s_waitcnt lgkmcnt(6)
	global_store_dwordx4 v172, v[134:137], s[44:45] offset:1024 sc1
	s_waitcnt lgkmcnt(5)
	global_store_dwordx4 v172, v[138:141], s[44:45] offset:2048 sc1
	s_waitcnt lgkmcnt(4)
	global_store_dwordx4 v172, v[142:145], s[44:45] offset:3072 sc1
	s_waitcnt lgkmcnt(3)
	global_store_dwordx4 v172, v[146:149], s[62:63] offset:0 sc1
	s_waitcnt lgkmcnt(2)
	global_store_dwordx4 v172, v[150:153], s[62:63] offset:1024 sc1
	s_waitcnt lgkmcnt(1)
	global_store_dwordx4 v172, v[154:157], s[62:63] offset:2048 sc1
	s_waitcnt lgkmcnt(0)
	global_store_dwordx4 v172, v[158:161], s[62:63] offset:3072 sc1
	s_add_u32 s44, s44, 0x2000
	s_addc_u32 s45, s45, 0
	s_add_u32 s62, s62, 0x2000
	s_addc_u32 s63, s63, 0
	s_lshr_b32 s70, s69, 6
	s_add_i32 s70, s70, 1
	v_cvt_f32_i32_e32 v182, s70
	v_mul_f32_e32 v182, v174, v182
	v_mul_f32_e32 v183, 0.15915494, v182
	v_rndne_f32_e32 v183, v183
	v_fma_f32 v183, v182, 0.15915494, -v183
	v_sin_f32_e32 v175, v183
	v_cos_f32_e32 v176, v183
	v_mul_f32_e32 v186, v175, v58
	v_mul_f32_e32 v187, v176, v58
	v_fma_f32 v188, v176, v62, -v186
	v_fma_f32 v189, v175, v62, v187
	v_mul_f32_e32 v186, v212, v50
	v_mul_f32_e32 v187, v238, v50
	v_fma_f32 v190, v238, v54, -v186
	v_fma_f32 v191, v212, v54, v187
	v_cvt_pk_bf16_f32 v192, v188, v189
	v_cvt_pk_bf16_f32 v193, v190, v191
	ds_write_b16 v170, v192 offset:0
	ds_write_b16_d16_hi v170, v192 offset:32
	ds_write_b16 v170, v193 offset:64
	ds_write_b16_d16_hi v170, v193 offset:96
	v_mul_f32_e32 v186, v175, v59
	v_mul_f32_e32 v187, v176, v59
	v_fma_f32 v188, v176, v63, -v186
	v_fma_f32 v189, v175, v63, v187
	v_mul_f32_e32 v186, v213, v51
	v_mul_f32_e32 v187, v239, v51
	v_fma_f32 v190, v239, v55, -v186
	v_fma_f32 v191, v213, v55, v187
	v_cvt_pk_bf16_f32 v192, v188, v189
	v_cvt_pk_bf16_f32 v193, v190, v191
	ds_write_b16 v170, v192 offset:144
	ds_write_b16_d16_hi v170, v192 offset:176
	ds_write_b16 v170, v193 offset:208
	ds_write_b16_d16_hi v170, v193 offset:240
	v_mul_f32_e32 v186, v175, v60
	v_mul_f32_e32 v187, v176, v60
	v_fma_f32 v188, v176, v64, -v186
	v_fma_f32 v189, v175, v64, v187
	v_mul_f32_e32 v186, v214, v52
	v_mul_f32_e32 v187, v240, v52
	v_fma_f32 v190, v240, v56, -v186
	v_fma_f32 v191, v214, v56, v187
	v_cvt_pk_bf16_f32 v192, v188, v189
	v_cvt_pk_bf16_f32 v193, v190, v191
	ds_write_b16 v170, v192 offset:288
	ds_write_b16_d16_hi v170, v192 offset:320
	ds_write_b16 v170, v193 offset:352
	ds_write_b16_d16_hi v170, v193 offset:384
	v_mul_f32_e32 v186, v175, v61
	v_mul_f32_e32 v187, v176, v61
	v_fma_f32 v188, v176, v65, -v186
	v_fma_f32 v189, v175, v65, v187
	v_mul_f32_e32 v186, v215, v53
	v_mul_f32_e32 v187, v241, v53
	v_fma_f32 v190, v241, v57, -v186
	v_fma_f32 v191, v215, v57, v187
	v_cvt_pk_bf16_f32 v192, v188, v189
	v_cvt_pk_bf16_f32 v193, v190, v191
	ds_write_b16 v170, v192 offset:432
	ds_write_b16_d16_hi v170, v192 offset:464
	ds_write_b16 v170, v193 offset:496
	ds_write_b16_d16_hi v170, v193 offset:528
	v_mul_f32_e32 v186, v175, v42
	v_mul_f32_e32 v187, v176, v42
	v_fma_f32 v188, v176, v46, -v186
	v_fma_f32 v189, v175, v46, v187
	v_mul_f32_e32 v186, v216, v34
	v_mul_f32_e32 v187, v242, v34
	v_fma_f32 v190, v242, v38, -v186
	v_fma_f32 v191, v216, v38, v187
	v_cvt_pk_bf16_f32 v192, v188, v189
	v_cvt_pk_bf16_f32 v193, v190, v191
	ds_write_b16 v170, v192 offset:2304
	ds_write_b16_d16_hi v170, v192 offset:2336
	ds_write_b16 v170, v193 offset:2368
	ds_write_b16_d16_hi v170, v193 offset:2400
	v_mul_f32_e32 v186, v175, v43
	v_mul_f32_e32 v187, v176, v43
	v_fma_f32 v188, v176, v47, -v186
	v_fma_f32 v189, v175, v47, v187
	v_mul_f32_e32 v186, v217, v35
	v_mul_f32_e32 v187, v243, v35
	v_fma_f32 v190, v243, v39, -v186
	v_fma_f32 v191, v217, v39, v187
	v_cvt_pk_bf16_f32 v192, v188, v189
	v_cvt_pk_bf16_f32 v193, v190, v191
	ds_write_b16 v170, v192 offset:2448
	ds_write_b16_d16_hi v170, v192 offset:2480
	ds_write_b16 v170, v193 offset:2512
	ds_write_b16_d16_hi v170, v193 offset:2544
	v_mul_f32_e32 v186, v175, v44
	v_mul_f32_e32 v187, v176, v44
	v_fma_f32 v188, v176, v48, -v186
	v_fma_f32 v189, v175, v48, v187
	v_mul_f32_e32 v186, v218, v36
	v_mul_f32_e32 v187, v244, v36
; template <int EPI>
; DI void gemm_phase(const P& p, int l, const u16* __restrict__ A, const u16* __restrict__ Bt, int mpx, char* lds) {
;     ...
;             if (dorope) {
;               float sr, cr, sc, cc;
;               sincos_rev((float)(s >> 6) * invf64, sr, cr);
;               sincos_rev((float)(s & 63) * invf64, sc, cc);
;               const float a1 = v0, a2 = v1, b1 = v2, b2 = v3;
;               v0 = a1 * cr - a2 * sr;
;               v1 = a2 * cr + a1 * sr;
;               v2 = b1 * cc - b2 * sc;
;               v3 = b2 * cc + b1 * sc;
;             }
;     ...
;             Tl[rowl * 72 + 0 * 16 + r] = (u16)u01;
;             Tl[rowl * 72 + 1 * 16 + r] = (u16)(u01 >> 16);
;             Tl[rowl * 72 + 2 * 16 + r] = (u16)u23;
;             Tl[rowl * 72 + 3 * 16 + r] = (u16)(u23 >> 16);
;           }
;         }
;       }
;       __builtin_amdgcn_fence(__ATOMIC_RELEASE, "wavefront");
;       u16* dh = (kind == 1) ? dst + hf * 64 : dst + (size_t)(hf * 64) * rstride;
; #pragma unroll
;       for (int i = 0; i < 8; ++i) {
;         const int c = lane + i * 64;
;         const int row = c >> 3, cc = c & 7;
;         uint4 v = *(const uint4*)&Tl[row * 72 + cc * 8];
;         *(uint4*)(dh + (size_t)row * rstride + cc * 8) = v;
;       }
	v_fma_f32 v190, v244, v40, -v186
	v_fma_f32 v191, v218, v40, v187
	v_cvt_pk_bf16_f32 v192, v188, v189
	v_cvt_pk_bf16_f32 v193, v190, v191
	ds_write_b16 v170, v192 offset:2592
	ds_write_b16_d16_hi v170, v192 offset:2624
	ds_write_b16 v170, v193 offset:2656
	ds_write_b16_d16_hi v170, v193 offset:2688
	v_mul_f32_e32 v186, v175, v45
	v_mul_f32_e32 v187, v176, v45
	v_fma_f32 v188, v176, v49, -v186
	v_fma_f32 v189, v175, v49, v187
	v_mul_f32_e32 v186, v219, v37
	v_mul_f32_e32 v187, v245, v37
	v_fma_f32 v190, v245, v41, -v186
	v_fma_f32 v191, v219, v41, v187
	v_cvt_pk_bf16_f32 v192, v188, v189
	v_cvt_pk_bf16_f32 v193, v190, v191
	ds_write_b16 v170, v192 offset:2736
	ds_write_b16_d16_hi v170, v192 offset:2768
	ds_write_b16 v170, v193 offset:2800
	ds_write_b16_d16_hi v170, v193 offset:2832
	v_mul_f32_e32 v186, v175, v26
	v_mul_f32_e32 v187, v176, v26
	v_fma_f32 v188, v176, v30, -v186
	v_fma_f32 v189, v175, v30, v187
	v_mul_f32_e32 v186, v220, v18
	v_mul_f32_e32 v187, v246, v18
	v_fma_f32 v190, v246, v22, -v186
	v_fma_f32 v191, v220, v22, v187
	v_cvt_pk_bf16_f32 v192, v188, v189
	v_cvt_pk_bf16_f32 v193, v190, v191
	ds_write_b16 v170, v192 offset:4608
	ds_write_b16_d16_hi v170, v192 offset:4640
	ds_write_b16 v170, v193 offset:4672
	ds_write_b16_d16_hi v170, v193 offset:4704
	v_mul_f32_e32 v186, v175, v27
	v_mul_f32_e32 v187, v176, v27
	v_fma_f32 v188, v176, v31, -v186
	v_fma_f32 v189, v175, v31, v187
	v_mul_f32_e32 v186, v221, v19
	v_mul_f32_e32 v187, v247, v19
	v_fma_f32 v190, v247, v23, -v186
	v_fma_f32 v191, v221, v23, v187
	v_cvt_pk_bf16_f32 v192, v188, v189
	v_cvt_pk_bf16_f32 v193, v190, v191
	ds_write_b16 v170, v192 offset:4752
	ds_write_b16_d16_hi v170, v192 offset:4784
	ds_write_b16 v170, v193 offset:4816
	ds_write_b16_d16_hi v170, v193 offset:4848
	v_mul_f32_e32 v186, v175, v28
	v_mul_f32_e32 v187, v176, v28
	v_fma_f32 v188, v176, v32, -v186
	v_fma_f32 v189, v175, v32, v187
	v_mul_f32_e32 v186, v222, v20
	v_mul_f32_e32 v187, v248, v20
	v_fma_f32 v190, v248, v24, -v186
	v_fma_f32 v191, v222, v24, v187
	v_cvt_pk_bf16_f32 v192, v188, v189
	v_cvt_pk_bf16_f32 v193, v190, v191
	ds_write_b16 v170, v192 offset:4896
	ds_write_b16_d16_hi v170, v192 offset:4928
	ds_write_b16 v170, v193 offset:4960
	ds_write_b16_d16_hi v170, v193 offset:4992
	v_mul_f32_e32 v186, v175, v29
	v_mul_f32_e32 v187, v176, v29
	v_fma_f32 v188, v176, v33, -v186
	v_fma_f32 v189, v175, v33, v187
	v_mul_f32_e32 v186, v223, v21
	v_mul_f32_e32 v187, v249, v21
	v_fma_f32 v190, v249, v25, -v186
	v_fma_f32 v191, v223, v25, v187
	v_cvt_pk_bf16_f32 v192, v188, v189
	v_cvt_pk_bf16_f32 v193, v190, v191
	ds_write_b16 v170, v192 offset:5040
	ds_write_b16_d16_hi v170, v192 offset:5072
	ds_write_b16 v170, v193 offset:5104
	ds_write_b16_d16_hi v170, v193 offset:5136
	v_mul_f32_e32 v186, v175, v162
	v_mul_f32_e32 v187, v176, v162
	v_fma_f32 v188, v176, v166, -v186
	v_fma_f32 v189, v175, v166, v187
	v_mul_f32_e32 v186, v234, v6
	v_mul_f32_e32 v187, v250, v6
	v_fma_f32 v190, v250, v2, -v186
	v_fma_f32 v191, v234, v2, v187
	v_cvt_pk_bf16_f32 v192, v188, v189
	v_cvt_pk_bf16_f32 v193, v190, v191
	ds_write_b16 v170, v192 offset:6912
	ds_write_b16_d16_hi v170, v192 offset:6944
	ds_write_b16 v170, v193 offset:6976
	ds_write_b16_d16_hi v170, v193 offset:7008
	v_mul_f32_e32 v186, v175, v163
	v_mul_f32_e32 v187, v176, v163
	v_fma_f32 v188, v176, v167, -v186
	v_fma_f32 v189, v175, v167, v187
	v_mul_f32_e32 v186, v235, v7
	v_mul_f32_e32 v187, v251, v7
	v_fma_f32 v190, v251, v3, -v186
	v_fma_f32 v191, v235, v3, v187
	v_cvt_pk_bf16_f32 v192, v188, v189
	v_cvt_pk_bf16_f32 v193, v190, v191
	ds_write_b16 v170, v192 offset:7056
	ds_write_b16_d16_hi v170, v192 offset:7088
	ds_write_b16 v170, v193 offset:7120
	ds_write_b16_d16_hi v170, v193 offset:7152
	v_mul_f32_e32 v186, v175, v164
	v_mul_f32_e32 v187, v176, v164
	v_fma_f32 v188, v176, v168, -v186
	v_fma_f32 v189, v175, v168, v187
	v_mul_f32_e32 v186, v236, v8
	v_mul_f32_e32 v187, v252, v8
	v_fma_f32 v190, v252, v4, -v186
	v_fma_f32 v191, v236, v4, v187
	v_cvt_pk_bf16_f32 v192, v188, v189
	v_cvt_pk_bf16_f32 v193, v190, v191
	ds_write_b16 v170, v192 offset:7200
	ds_write_b16_d16_hi v170, v192 offset:7232
	ds_write_b16 v170, v193 offset:7264
	ds_write_b16_d16_hi v170, v193 offset:7296
	v_mul_f32_e32 v186, v175, v165
	v_mul_f32_e32 v187, v176, v165
	v_fma_f32 v188, v176, v169, -v186
	v_fma_f32 v189, v175, v169, v187
	v_mul_f32_e32 v186, v237, v9
	v_mul_f32_e32 v187, v253, v9
	v_fma_f32 v190, v253, v5, -v186
	v_fma_f32 v191, v237, v5, v187
	v_cvt_pk_bf16_f32 v192, v188, v189
	v_cvt_pk_bf16_f32 v193, v190, v191
	ds_write_b16 v170, v192 offset:7344
	ds_write_b16_d16_hi v170, v192 offset:7376
	ds_write_b16 v170, v193 offset:7408
	ds_write_b16_d16_hi v170, v193 offset:7440
	ds_read_b128 v[130:133], v171 offset:0
	ds_read_b128 v[134:137], v171 offset:1152
	ds_read_b128 v[138:141], v171 offset:2304
	ds_read_b128 v[142:145], v171 offset:3456
	ds_read_b128 v[146:149], v171 offset:4608
	ds_read_b128 v[150:153], v171 offset:5760
	ds_read_b128 v[154:157], v171 offset:6912
	ds_read_b128 v[158:161], v171 offset:8064
	s_waitcnt lgkmcnt(7)
	global_store_dwordx4 v172, v[130:133], s[44:45] offset:0 sc1
	s_waitcnt lgkmcnt(6)
	global_store_dwordx4 v172, v[134:137], s[44:45] offset:1024 sc1
	s_waitcnt lgkmcnt(5)
	global_store_dwordx4 v172, v[138:141], s[44:45] offset:2048 sc1
	s_waitcnt lgkmcnt(4)
	global_store_dwordx4 v172, v[142:145], s[44:45] offset:3072 sc1
	s_waitcnt lgkmcnt(3)
	global_store_dwordx4 v172, v[146:149], s[62:63] offset:0 sc1
	s_waitcnt lgkmcnt(2)
	global_store_dwordx4 v172, v[150:153], s[62:63] offset:1024 sc1
	s_waitcnt lgkmcnt(1)
	global_store_dwordx4 v172, v[154:157], s[62:63] offset:2048 sc1
	s_waitcnt lgkmcnt(0)
	global_store_dwordx4 v172, v[158:161], s[62:63] offset:3072 sc1
	s_branch .Lfe_done
; DI void sincos_rev(float ang, float& s, float& c) {
;   float rev = ang * 0.15915494309189535f;
;   rev -= rintf(rev);
;   s = __builtin_amdgcn_sinf(rev);
;   c = __builtin_amdgcn_cosf(rev);
; }
; template <int EPI>
; DI void gemm_phase(const P& p, int l, const u16* __restrict__ A, const u16* __restrict__ Bt, int mpx, char* lds) {
;     ...
;     const float invf32 = exp2f(-13.287712379549449f * (float)(r & 7) * (1.f / 8.f));
;     const bool lo8 = r < 8;
;     ...
;           } else if (tr == 4) {
;             float sr, cr, sc, cc;
;             sincos_rev((float)(s >> 6) * invf32, sr, cr);
;             sincos_rev((float)(s & 63) * invf32, sc, cc);
;             const float p0 = __shfl_xor(v0, 8), p1 = __shfl_xor(v1, 8), p2 = __shfl_xor(v2, 8), p3 = __shfl_xor(v3, 8);
;             v0 = lo8 ? (v0 * cr - p0 * sr) : (v0 * cr + p0 * sr);
.Lfe_k0_rope32:
	v_and_b32_e32 v0, 7, v226
	v_cvt_f32_ubyte0_e32 v0, v0
	v_mul_f32_e32 v0, 0xc1549a78, v0
	v_mul_f32_e32 v0, 0x3e000000, v0
	v_exp_f32_e32 v174, v0
	v_lshrrev_b32_e32 v0, 4, v226
	v_lshlrev_b32_e32 v0, 2, v0
	v_add_u32_e32 v182, 0, v0
	v_cvt_f32_i32_e32 v182, v182
	v_mul_f32_e32 v182, v174, v182
	v_mul_f32_e32 v183, 0.15915494, v182
	v_rndne_f32_e32 v183, v183
	v_fma_f32 v183, v182, 0.15915494, -v183
	v_sin_f32_e32 v212, v183
	v_cos_f32_e32 v238, v183
	v_add_u32_e32 v182, 1, v0
	v_cvt_f32_i32_e32 v182, v182
	v_mul_f32_e32 v182, v174, v182
	v_mul_f32_e32 v183, 0.15915494, v182
	v_rndne_f32_e32 v183, v183
	v_fma_f32 v183, v182, 0.15915494, -v183
	v_sin_f32_e32 v213, v183
	v_cos_f32_e32 v239, v183
	v_add_u32_e32 v182, 2, v0
	v_cvt_f32_i32_e32 v182, v182
	v_mul_f32_e32 v182, v174, v182
	v_mul_f32_e32 v183, 0.15915494, v182
	v_rndne_f32_e32 v183, v183
	v_fma_f32 v183, v182, 0.15915494, -v183
	v_sin_f32_e32 v214, v183
	v_cos_f32_e32 v240, v183
	v_add_u32_e32 v182, 3, v0
	v_cvt_f32_i32_e32 v182, v182
	v_mul_f32_e32 v182, v174, v182
	v_mul_f32_e32 v183, 0.15915494, v182
	v_rndne_f32_e32 v183, v183
	v_fma_f32 v183, v182, 0.15915494, -v183
	v_sin_f32_e32 v215, v183
	v_cos_f32_e32 v241, v183
	v_add_u32_e32 v182, 16, v0
	v_cvt_f32_i32_e32 v182, v182
	v_mul_f32_e32 v182, v174, v182
	v_mul_f32_e32 v183, 0.15915494, v182
	v_rndne_f32_e32 v183, v183
	v_fma_f32 v183, v182, 0.15915494, -v183
	v_sin_f32_e32 v216, v183
	v_cos_f32_e32 v242, v183
	v_add_u32_e32 v182, 17, v0
	v_cvt_f32_i32_e32 v182, v182
	v_mul_f32_e32 v182, v174, v182
	v_mul_f32_e32 v183, 0.15915494, v182
	v_rndne_f32_e32 v183, v183
	v_fma_f32 v183, v182, 0.15915494, -v183
	v_sin_f32_e32 v217, v183
	v_cos_f32_e32 v243, v183
	v_add_u32_e32 v182, 18, v0
	v_cvt_f32_i32_e32 v182, v182
	v_mul_f32_e32 v182, v174, v182
	v_mul_f32_e32 v183, 0.15915494, v182
	v_rndne_f32_e32 v183, v183
	v_fma_f32 v183, v182, 0.15915494, -v183
	v_sin_f32_e32 v218, v183
	v_cos_f32_e32 v244, v183
	v_add_u32_e32 v182, 19, v0
	v_cvt_f32_i32_e32 v182, v182
	v_mul_f32_e32 v182, v174, v182
	v_mul_f32_e32 v183, 0.15915494, v182
	v_rndne_f32_e32 v183, v183
	v_fma_f32 v183, v182, 0.15915494, -v183
	v_sin_f32_e32 v219, v183
	v_cos_f32_e32 v245, v183
	v_add_u32_e32 v182, 32, v0
	v_cvt_f32_i32_e32 v182, v182
	v_mul_f32_e32 v182, v174, v182
	v_mul_f32_e32 v183, 0.15915494, v182
	v_rndne_f32_e32 v183, v183
	v_fma_f32 v183, v182, 0.15915494, -v183
	v_sin_f32_e32 v220, v183
	v_cos_f32_e32 v246, v183
	v_add_u32_e32 v182, 33, v0
	v_cvt_f32_i32_e32 v182, v182
	v_mul_f32_e32 v182, v174, v182
	v_mul_f32_e32 v183, 0.15915494, v182
	v_rndne_f32_e32 v183, v183
	v_fma_f32 v183, v182, 0.15915494, -v183
	v_sin_f32_e32 v221, v183
	v_cos_f32_e32 v247, v183
	v_add_u32_e32 v182, 34, v0
	v_cvt_f32_i32_e32 v182, v182
	v_mul_f32_e32 v182, v174, v182
	v_mul_f32_e32 v183, 0.15915494, v182
	v_rndne_f32_e32 v183, v183
	v_fma_f32 v183, v182, 0.15915494, -v183
	v_sin_f32_e32 v222, v183
	v_cos_f32_e32 v248, v183
	v_add_u32_e32 v182, 35, v0
	v_cvt_f32_i32_e32 v182, v182
	v_mul_f32_e32 v182, v174, v182
	v_mul_f32_e32 v183, 0.15915494, v182
	v_rndne_f32_e32 v183, v183
	v_fma_f32 v183, v182, 0.15915494, -v183
	v_sin_f32_e32 v223, v183
	v_cos_f32_e32 v249, v183
	v_add_u32_e32 v182, 48, v0
	v_cvt_f32_i32_e32 v182, v182
	v_mul_f32_e32 v182, v174, v182
	v_mul_f32_e32 v183, 0.15915494, v182
	v_rndne_f32_e32 v183, v183
	v_fma_f32 v183, v182, 0.15915494, -v183
	v_sin_f32_e32 v234, v183
	v_cos_f32_e32 v250, v183
	v_add_u32_e32 v182, 49, v0
	v_cvt_f32_i32_e32 v182, v182
	v_mul_f32_e32 v182, v174, v182
	v_mul_f32_e32 v183, 0.15915494, v182
	v_rndne_f32_e32 v183, v183
	v_fma_f32 v183, v182, 0.15915494, -v183
	v_sin_f32_e32 v235, v183
	v_cos_f32_e32 v251, v183
	v_add_u32_e32 v182, 50, v0
	v_cvt_f32_i32_e32 v182, v182
	v_mul_f32_e32 v182, v174, v182
	v_mul_f32_e32 v183, 0.15915494, v182
	v_rndne_f32_e32 v183, v183
	v_fma_f32 v183, v182, 0.15915494, -v183
	v_sin_f32_e32 v236, v183
	v_cos_f32_e32 v252, v183
	v_add_u32_e32 v182, 51, v0
	v_cvt_f32_i32_e32 v182, v182
	v_mul_f32_e32 v182, v174, v182
	v_mul_f32_e32 v183, 0.15915494, v182
	v_rndne_f32_e32 v183, v183
	v_fma_f32 v183, v182, 0.15915494, -v183
	v_sin_f32_e32 v237, v183
	v_cos_f32_e32 v253, v183
	v_and_b32_e32 v0, 8, v226
	v_cmp_eq_u32_e32 vcc, 0, v0
	s_nop 1
	v_cndmask_b32_e64 v212, v212, -v212, vcc
	v_cndmask_b32_e64 v213, v213, -v213, vcc
	v_cndmask_b32_e64 v214, v214, -v214, vcc
	v_cndmask_b32_e64 v215, v215, -v215, vcc
	v_cndmask_b32_e64 v216, v216, -v216, vcc
	v_cndmask_b32_e64 v217, v217, -v217, vcc
	v_cndmask_b32_e64 v218, v218, -v218, vcc
	v_cndmask_b32_e64 v219, v219, -v219, vcc
	v_cndmask_b32_e64 v220, v220, -v220, vcc
	v_cndmask_b32_e64 v221, v221, -v221, vcc
	v_cndmask_b32_e64 v222, v222, -v222, vcc
	v_cndmask_b32_e64 v223, v223, -v223, vcc
	v_cndmask_b32_e64 v234, v234, -v234, vcc
	v_cndmask_b32_e64 v235, v235, -v235, vcc
	v_cndmask_b32_e64 v236, v236, -v236, vcc
	v_cndmask_b32_e64 v237, v237, -v237, vcc
	s_add_u32 s62, s44, 0x1000
	s_addc_u32 s63, s45, 0
	s_lshr_b32 s70, s69, 6
	v_cvt_f32_i32_e32 v182, s70
	v_mul_f32_e32 v182, v174, v182
	v_mul_f32_e32 v183, 0.15915494, v182
	v_rndne_f32_e32 v183, v183
	v_fma_f32 v183, v182, 0.15915494, -v183
	v_sin_f32_e32 v175, v183
	v_cos_f32_e32 v176, v183
	s_nop 0
	v_cndmask_b32_e64 v177, v175, -v175, vcc
	v_mul_f32_dpp v182, v126, v177 row_ror:8 row_mask:0xf bank_mask:0xf
	v_mul_f32_dpp v183, v122, v212 row_ror:8 row_mask:0xf bank_mask:0xf
	v_mul_f32_dpp v184, v118, v177 row_ror:8 row_mask:0xf bank_mask:0xf
	v_mul_f32_dpp v185, v114, v212 row_ror:8 row_mask:0xf bank_mask:0xf
	v_fma_f32 v186, v126, v176, v182
	v_fma_f32 v187, v122, v238, v183
; template <int EPI>
; DI void gemm_phase(const P& p, int l, const u16* __restrict__ A, const u16* __restrict__ Bt, int mpx, char* lds) {
;     ...
;           } else if (tr == 4) {
;             float sr, cr, sc, cc;
;             sincos_rev((float)(s >> 6) * invf32, sr, cr);
;             sincos_rev((float)(s & 63) * invf32, sc, cc);
;             const float p0 = __shfl_xor(v0, 8), p1 = __shfl_xor(v1, 8), p2 = __shfl_xor(v2, 8), p3 = __shfl_xor(v3, 8);
;             v0 = lo8 ? (v0 * cr - p0 * sr) : (v0 * cr + p0 * sr);
;             v1 = lo8 ? (v1 * cc - p1 * sc) : (v1 * cc + p1 * sc);
;             v2 = lo8 ? (v2 * cr - p2 * sr) : (v2 * cr + p2 * sr);
;             v3 = lo8 ? (v3 * cc - p3 * sc) : (v3 * cc + p3 * sc);
;           }
;           const unsigned u01 = pack2(v0, v1), u23 = pack2(v2, v3);
;     ...
;             Tl[rowl * 72 + 0 * 16 + r] = (u16)u01;
;             Tl[rowl * 72 + 1 * 16 + r] = (u16)(u01 >> 16);
;             Tl[rowl * 72 + 2 * 16 + r] = (u16)u23;
;             Tl[rowl * 72 + 3 * 16 + r] = (u16)(u23 >> 16);
	v_fma_f32 v188, v118, v176, v184
	v_fma_f32 v189, v114, v238, v185
	v_cvt_pk_bf16_f32 v192, v186, v187
	v_cvt_pk_bf16_f32 v193, v188, v189
	ds_write_b16 v170, v192 offset:0
	ds_write_b16_d16_hi v170, v192 offset:32
	ds_write_b16 v170, v193 offset:64
	ds_write_b16_d16_hi v170, v193 offset:96
	v_mul_f32_dpp v182, v127, v177 row_ror:8 row_mask:0xf bank_mask:0xf
	v_mul_f32_dpp v183, v123, v213 row_ror:8 row_mask:0xf bank_mask:0xf
	v_mul_f32_dpp v184, v119, v177 row_ror:8 row_mask:0xf bank_mask:0xf
	v_mul_f32_dpp v185, v115, v213 row_ror:8 row_mask:0xf bank_mask:0xf
	v_fma_f32 v186, v127, v176, v182
	v_fma_f32 v187, v123, v239, v183
	v_fma_f32 v188, v119, v176, v184
	v_fma_f32 v189, v115, v239, v185
	v_cvt_pk_bf16_f32 v192, v186, v187
	v_cvt_pk_bf16_f32 v193, v188, v189
	ds_write_b16 v170, v192 offset:144
	ds_write_b16_d16_hi v170, v192 offset:176
	ds_write_b16 v170, v193 offset:208
	ds_write_b16_d16_hi v170, v193 offset:240
	v_mul_f32_dpp v182, v128, v177 row_ror:8 row_mask:0xf bank_mask:0xf
	v_mul_f32_dpp v183, v124, v214 row_ror:8 row_mask:0xf bank_mask:0xf
	v_mul_f32_dpp v184, v120, v177 row_ror:8 row_mask:0xf bank_mask:0xf
	v_mul_f32_dpp v185, v116, v214 row_ror:8 row_mask:0xf bank_mask:0xf
	v_fma_f32 v186, v128, v176, v182
	v_fma_f32 v187, v124, v240, v183
	v_fma_f32 v188, v120, v176, v184
	v_fma_f32 v189, v116, v240, v185
	v_cvt_pk_bf16_f32 v192, v186, v187
	v_cvt_pk_bf16_f32 v193, v188, v189
	ds_write_b16 v170, v192 offset:288
	ds_write_b16_d16_hi v170, v192 offset:320
	ds_write_b16 v170, v193 offset:352
	ds_write_b16_d16_hi v170, v193 offset:384
	v_mul_f32_dpp v182, v129, v177 row_ror:8 row_mask:0xf bank_mask:0xf
	v_mul_f32_dpp v183, v125, v215 row_ror:8 row_mask:0xf bank_mask:0xf
	v_mul_f32_dpp v184, v121, v177 row_ror:8 row_mask:0xf bank_mask:0xf
	v_mul_f32_dpp v185, v117, v215 row_ror:8 row_mask:0xf bank_mask:0xf
	v_fma_f32 v186, v129, v176, v182
	v_fma_f32 v187, v125, v241, v183
	v_fma_f32 v188, v121, v176, v184
	v_fma_f32 v189, v117, v241, v185
	v_cvt_pk_bf16_f32 v192, v186, v187
	v_cvt_pk_bf16_f32 v193, v188, v189
	ds_write_b16 v170, v192 offset:432
	ds_write_b16_d16_hi v170, v192 offset:464
	ds_write_b16 v170, v193 offset:496
	ds_write_b16_d16_hi v170, v193 offset:528
	v_mul_f32_dpp v182, v110, v177 row_ror:8 row_mask:0xf bank_mask:0xf
	v_mul_f32_dpp v183, v106, v216 row_ror:8 row_mask:0xf bank_mask:0xf
	v_mul_f32_dpp v184, v102, v177 row_ror:8 row_mask:0xf bank_mask:0xf
	v_mul_f32_dpp v185, v98, v216 row_ror:8 row_mask:0xf bank_mask:0xf
	v_fma_f32 v186, v110, v176, v182
	v_fma_f32 v187, v106, v242, v183
	v_fma_f32 v188, v102, v176, v184
	v_fma_f32 v189, v98, v242, v185
	v_cvt_pk_bf16_f32 v192, v186, v187
	v_cvt_pk_bf16_f32 v193, v188, v189
	ds_write_b16 v170, v192 offset:2304
	ds_write_b16_d16_hi v170, v192 offset:2336
	ds_write_b16 v170, v193 offset:2368
	ds_write_b16_d16_hi v170, v193 offset:2400
	v_mul_f32_dpp v182, v111, v177 row_ror:8 row_mask:0xf bank_mask:0xf
	v_mul_f32_dpp v183, v107, v217 row_ror:8 row_mask:0xf bank_mask:0xf
	v_mul_f32_dpp v184, v103, v177 row_ror:8 row_mask:0xf bank_mask:0xf
	v_mul_f32_dpp v185, v99, v217 row_ror:8 row_mask:0xf bank_mask:0xf
	v_fma_f32 v186, v111, v176, v182
	v_fma_f32 v187, v107, v243, v183
	v_fma_f32 v188, v103, v176, v184
	v_fma_f32 v189, v99, v243, v185
	v_cvt_pk_bf16_f32 v192, v186, v187
	v_cvt_pk_bf16_f32 v193, v188, v189
	ds_write_b16 v170, v192 offset:2448
	ds_write_b16_d16_hi v170, v192 offset:2480
	ds_write_b16 v170, v193 offset:2512
	ds_write_b16_d16_hi v170, v193 offset:2544
	v_mul_f32_dpp v182, v112, v177 row_ror:8 row_mask:0xf bank_mask:0xf
	v_mul_f32_dpp v183, v108, v218 row_ror:8 row_mask:0xf bank_mask:0xf
	v_mul_f32_dpp v184, v104, v177 row_ror:8 row_mask:0xf bank_mask:0xf
	v_mul_f32_dpp v185, v100, v218 row_ror:8 row_mask:0xf bank_mask:0xf
	v_fma_f32 v186, v112, v176, v182
	v_fma_f32 v187, v108, v244, v183
	v_fma_f32 v188, v104, v176, v184
	v_fma_f32 v189, v100, v244, v185
	v_cvt_pk_bf16_f32 v192, v186, v187
	v_cvt_pk_bf16_f32 v193, v188, v189
	ds_write_b16 v170, v192 offset:2592
	ds_write_b16_d16_hi v170, v192 offset:2624
	ds_write_b16 v170, v193 offset:2656
	ds_write_b16_d16_hi v170, v193 offset:2688
	v_mul_f32_dpp v182, v113, v177 row_ror:8 row_mask:0xf bank_mask:0xf
	v_mul_f32_dpp v183, v109, v219 row_ror:8 row_mask:0xf bank_mask:0xf
	v_mul_f32_dpp v184, v105, v177 row_ror:8 row_mask:0xf bank_mask:0xf
	v_mul_f32_dpp v185, v101, v219 row_ror:8 row_mask:0xf bank_mask:0xf
	v_fma_f32 v186, v113, v176, v182
	v_fma_f32 v187, v109, v245, v183
	v_fma_f32 v188, v105, v176, v184
	v_fma_f32 v189, v101, v245, v185
	v_cvt_pk_bf16_f32 v192, v186, v187
	v_cvt_pk_bf16_f32 v193, v188, v189
	ds_write_b16 v170, v192 offset:2736
	ds_write_b16_d16_hi v170, v192 offset:2768
	ds_write_b16 v170, v193 offset:2800
	ds_write_b16_d16_hi v170, v193 offset:2832
	v_mul_f32_dpp v182, v94, v177 row_ror:8 row_mask:0xf bank_mask:0xf
	v_mul_f32_dpp v183, v90, v220 row_ror:8 row_mask:0xf bank_mask:0xf
	v_mul_f32_dpp v184, v86, v177 row_ror:8 row_mask:0xf bank_mask:0xf
	v_mul_f32_dpp v185, v82, v220 row_ror:8 row_mask:0xf bank_mask:0xf
	v_fma_f32 v186, v94, v176, v182
	v_fma_f32 v187, v90, v246, v183
	v_fma_f32 v188, v86, v176, v184
	v_fma_f32 v189, v82, v246, v185
	v_cvt_pk_bf16_f32 v192, v186, v187
	v_cvt_pk_bf16_f32 v193, v188, v189
	ds_write_b16 v170, v192 offset:4608
	ds_write_b16_d16_hi v170, v192 offset:4640
	ds_write_b16 v170, v193 offset:4672
	ds_write_b16_d16_hi v170, v193 offset:4704
	v_mul_f32_dpp v182, v95, v177 row_ror:8 row_mask:0xf bank_mask:0xf
	v_mul_f32_dpp v183, v91, v221 row_ror:8 row_mask:0xf bank_mask:0xf
	v_mul_f32_dpp v184, v87, v177 row_ror:8 row_mask:0xf bank_mask:0xf
; template <int EPI>
; DI void gemm_phase(const P& p, int l, const u16* __restrict__ A, const u16* __restrict__ Bt, int mpx, char* lds) {
;     ...
;           } else if (tr == 4) {
;             float sr, cr, sc, cc;
;             sincos_rev((float)(s >> 6) * invf32, sr, cr);
;             sincos_rev((float)(s & 63) * invf32, sc, cc);
;             const float p0 = __shfl_xor(v0, 8), p1 = __shfl_xor(v1, 8), p2 = __shfl_xor(v2, 8), p3 = __shfl_xor(v3, 8);
;             v0 = lo8 ? (v0 * cr - p0 * sr) : (v0 * cr + p0 * sr);
;             v1 = lo8 ? (v1 * cc - p1 * sc) : (v1 * cc + p1 * sc);
;             v2 = lo8 ? (v2 * cr - p2 * sr) : (v2 * cr + p2 * sr);
;             v3 = lo8 ? (v3 * cc - p3 * sc) : (v3 * cc + p3 * sc);
;           }
;           const unsigned u01 = pack2(v0, v1), u23 = pack2(v2, v3);
;     ...
;             Tl[rowl * 72 + 0 * 16 + r] = (u16)u01;
;             Tl[rowl * 72 + 1 * 16 + r] = (u16)(u01 >> 16);
;             Tl[rowl * 72 + 2 * 16 + r] = (u16)u23;
;             Tl[rowl * 72 + 3 * 16 + r] = (u16)(u23 >> 16);
;           }
;         }
;       }
;       __builtin_amdgcn_fence(__ATOMIC_RELEASE, "wavefront");
;       u16* dh = (kind == 1) ? dst + hf * 64 : dst + (size_t)(hf * 64) * rstride;
; #pragma unroll
;       for (int i = 0; i < 8; ++i) {
;         const int c = lane + i * 64;
;         const int row = c >> 3, cc = c & 7;
;         uint4 v = *(const uint4*)&Tl[row * 72 + cc * 8];
;         *(uint4*)(dh + (size_t)row * rstride + cc * 8) = v;
;       }
	v_mul_f32_dpp v185, v83, v221 row_ror:8 row_mask:0xf bank_mask:0xf
	v_fma_f32 v186, v95, v176, v182
	v_fma_f32 v187, v91, v247, v183
	v_fma_f32 v188, v87, v176, v184
	v_fma_f32 v189, v83, v247, v185
	v_cvt_pk_bf16_f32 v192, v186, v187
	v_cvt_pk_bf16_f32 v193, v188, v189
	ds_write_b16 v170, v192 offset:4752
	ds_write_b16_d16_hi v170, v192 offset:4784
	ds_write_b16 v170, v193 offset:4816
	ds_write_b16_d16_hi v170, v193 offset:4848
	v_mul_f32_dpp v182, v96, v177 row_ror:8 row_mask:0xf bank_mask:0xf
	v_mul_f32_dpp v183, v92, v222 row_ror:8 row_mask:0xf bank_mask:0xf
	v_mul_f32_dpp v184, v88, v177 row_ror:8 row_mask:0xf bank_mask:0xf
	v_mul_f32_dpp v185, v84, v222 row_ror:8 row_mask:0xf bank_mask:0xf
	v_fma_f32 v186, v96, v176, v182
	v_fma_f32 v187, v92, v248, v183
	v_fma_f32 v188, v88, v176, v184
	v_fma_f32 v189, v84, v248, v185
	v_cvt_pk_bf16_f32 v192, v186, v187
	v_cvt_pk_bf16_f32 v193, v188, v189
	ds_write_b16 v170, v192 offset:4896
	ds_write_b16_d16_hi v170, v192 offset:4928
	ds_write_b16 v170, v193 offset:4960
	ds_write_b16_d16_hi v170, v193 offset:4992
	v_mul_f32_dpp v182, v97, v177 row_ror:8 row_mask:0xf bank_mask:0xf
	v_mul_f32_dpp v183, v93, v223 row_ror:8 row_mask:0xf bank_mask:0xf
	v_mul_f32_dpp v184, v89, v177 row_ror:8 row_mask:0xf bank_mask:0xf
	v_mul_f32_dpp v185, v85, v223 row_ror:8 row_mask:0xf bank_mask:0xf
	v_fma_f32 v186, v97, v176, v182
	v_fma_f32 v187, v93, v249, v183
	v_fma_f32 v188, v89, v176, v184
	v_fma_f32 v189, v85, v249, v185
	v_cvt_pk_bf16_f32 v192, v186, v187
	v_cvt_pk_bf16_f32 v193, v188, v189
	ds_write_b16 v170, v192 offset:5040
	ds_write_b16_d16_hi v170, v192 offset:5072
	ds_write_b16 v170, v193 offset:5104
	ds_write_b16_d16_hi v170, v193 offset:5136
	v_mul_f32_dpp v182, v78, v177 row_ror:8 row_mask:0xf bank_mask:0xf
	v_mul_f32_dpp v183, v74, v234 row_ror:8 row_mask:0xf bank_mask:0xf
	v_mul_f32_dpp v184, v70, v177 row_ror:8 row_mask:0xf bank_mask:0xf
	v_mul_f32_dpp v185, v66, v234 row_ror:8 row_mask:0xf bank_mask:0xf
	v_fma_f32 v186, v78, v176, v182
	v_fma_f32 v187, v74, v250, v183
	v_fma_f32 v188, v70, v176, v184
	v_fma_f32 v189, v66, v250, v185
	v_cvt_pk_bf16_f32 v192, v186, v187
	v_cvt_pk_bf16_f32 v193, v188, v189
	ds_write_b16 v170, v192 offset:6912
	ds_write_b16_d16_hi v170, v192 offset:6944
	ds_write_b16 v170, v193 offset:6976
	ds_write_b16_d16_hi v170, v193 offset:7008
	v_mul_f32_dpp v182, v79, v177 row_ror:8 row_mask:0xf bank_mask:0xf
	v_mul_f32_dpp v183, v75, v235 row_ror:8 row_mask:0xf bank_mask:0xf
	v_mul_f32_dpp v184, v71, v177 row_ror:8 row_mask:0xf bank_mask:0xf
	v_mul_f32_dpp v185, v67, v235 row_ror:8 row_mask:0xf bank_mask:0xf
	v_fma_f32 v186, v79, v176, v182
	v_fma_f32 v187, v75, v251, v183
	v_fma_f32 v188, v71, v176, v184
	v_fma_f32 v189, v67, v251, v185
	v_cvt_pk_bf16_f32 v192, v186, v187
	v_cvt_pk_bf16_f32 v193, v188, v189
	ds_write_b16 v170, v192 offset:7056
	ds_write_b16_d16_hi v170, v192 offset:7088
	ds_write_b16 v170, v193 offset:7120
	ds_write_b16_d16_hi v170, v193 offset:7152
	v_mul_f32_dpp v182, v80, v177 row_ror:8 row_mask:0xf bank_mask:0xf
	v_mul_f32_dpp v183, v76, v236 row_ror:8 row_mask:0xf bank_mask:0xf
	v_mul_f32_dpp v184, v72, v177 row_ror:8 row_mask:0xf bank_mask:0xf
	v_mul_f32_dpp v185, v68, v236 row_ror:8 row_mask:0xf bank_mask:0xf
	v_fma_f32 v186, v80, v176, v182
	v_fma_f32 v187, v76, v252, v183
	v_fma_f32 v188, v72, v176, v184
	v_fma_f32 v189, v68, v252, v185
	v_cvt_pk_bf16_f32 v192, v186, v187
	v_cvt_pk_bf16_f32 v193, v188, v189
	ds_write_b16 v170, v192 offset:7200
	ds_write_b16_d16_hi v170, v192 offset:7232
	ds_write_b16 v170, v193 offset:7264
	ds_write_b16_d16_hi v170, v193 offset:7296
	v_mul_f32_dpp v182, v81, v177 row_ror:8 row_mask:0xf bank_mask:0xf
	v_mul_f32_dpp v183, v77, v237 row_ror:8 row_mask:0xf bank_mask:0xf
	v_mul_f32_dpp v184, v73, v177 row_ror:8 row_mask:0xf bank_mask:0xf
	v_mul_f32_dpp v185, v69, v237 row_ror:8 row_mask:0xf bank_mask:0xf
	v_fma_f32 v186, v81, v176, v182
	v_fma_f32 v187, v77, v253, v183
	v_fma_f32 v188, v73, v176, v184
	v_fma_f32 v189, v69, v253, v185
	v_cvt_pk_bf16_f32 v192, v186, v187
	v_cvt_pk_bf16_f32 v193, v188, v189
	ds_write_b16 v170, v192 offset:7344
	ds_write_b16_d16_hi v170, v192 offset:7376
	ds_write_b16 v170, v193 offset:7408
	ds_write_b16_d16_hi v170, v193 offset:7440
	ds_read_b128 v[130:133], v171 offset:0
	ds_read_b128 v[134:137], v171 offset:1152
	ds_read_b128 v[138:141], v171 offset:2304
	ds_read_b128 v[142:145], v171 offset:3456
	ds_read_b128 v[146:149], v171 offset:4608
	ds_read_b128 v[150:153], v171 offset:5760
	ds_read_b128 v[154:157], v171 offset:6912
	ds_read_b128 v[158:161], v171 offset:8064
	s_waitcnt lgkmcnt(7)
	global_store_dwordx4 v172, v[130:133], s[44:45] offset:0 sc1
	s_waitcnt lgkmcnt(6)
	global_store_dwordx4 v172, v[134:137], s[44:45] offset:1024 sc1
	s_waitcnt lgkmcnt(5)
	global_store_dwordx4 v172, v[138:141], s[44:45] offset:2048 sc1
	s_waitcnt lgkmcnt(4)
	global_store_dwordx4 v172, v[142:145], s[44:45] offset:3072 sc1
	s_waitcnt lgkmcnt(3)
	global_store_dwordx4 v172, v[146:149], s[62:63] offset:0 sc1
	s_waitcnt lgkmcnt(2)
	global_store_dwordx4 v172, v[150:153], s[62:63] offset:1024 sc1
	s_waitcnt lgkmcnt(1)
	global_store_dwordx4 v172, v[154:157], s[62:63] offset:2048 sc1
	s_waitcnt lgkmcnt(0)
; template <int EPI>
; DI void gemm_phase(const P& p, int l, const u16* __restrict__ A, const u16* __restrict__ Bt, int mpx, char* lds) {
;     ...
;           } else if (tr == 4) {
;             float sr, cr, sc, cc;
;             sincos_rev((float)(s >> 6) * invf32, sr, cr);
;             sincos_rev((float)(s & 63) * invf32, sc, cc);
;             const float p0 = __shfl_xor(v0, 8), p1 = __shfl_xor(v1, 8), p2 = __shfl_xor(v2, 8), p3 = __shfl_xor(v3, 8);
;             v0 = lo8 ? (v0 * cr - p0 * sr) : (v0 * cr + p0 * sr);
;             v1 = lo8 ? (v1 * cc - p1 * sc) : (v1 * cc + p1 * sc);
;             v2 = lo8 ? (v2 * cr - p2 * sr) : (v2 * cr + p2 * sr);
;             v3 = lo8 ? (v3 * cc - p3 * sc) : (v3 * cc + p3 * sc);
;           }
;           const unsigned u01 = pack2(v0, v1), u23 = pack2(v2, v3);
;     ...
;             Tl[rowl * 72 + 0 * 16 + r] = (u16)u01;
;             Tl[rowl * 72 + 1 * 16 + r] = (u16)(u01 >> 16);
;             Tl[rowl * 72 + 2 * 16 + r] = (u16)u23;
;             Tl[rowl * 72 + 3 * 16 + r] = (u16)(u23 >> 16);
;           }
;         }
;       }
;       __builtin_amdgcn_fence(__ATOMIC_RELEASE, "wavefront");
;       u16* dh = (kind == 1) ? dst + hf * 64 : dst + (size_t)(hf * 64) * rstride;
; #pragma unroll
;       for (int i = 0; i < 8; ++i) {
;         const int c = lane + i * 64;
;         const int row = c >> 3, cc = c & 7;
;         uint4 v = *(const uint4*)&Tl[row * 72 + cc * 8];
;         *(uint4*)(dh + (size_t)row * rstride + cc * 8) = v;
;       }
	global_store_dwordx4 v172, v[158:161], s[62:63] offset:3072 sc1
	s_add_u32 s44, s44, 0x2000
	s_addc_u32 s45, s45, 0
	s_add_u32 s62, s62, 0x2000
	s_addc_u32 s63, s63, 0
	s_lshr_b32 s70, s69, 6
	s_add_i32 s70, s70, 1
	v_cvt_f32_i32_e32 v182, s70
	v_mul_f32_e32 v182, v174, v182
	v_mul_f32_e32 v183, 0.15915494, v182
	v_rndne_f32_e32 v183, v183
	v_fma_f32 v183, v182, 0.15915494, -v183
	v_sin_f32_e32 v175, v183
	v_cos_f32_e32 v176, v183
	s_nop 0
	v_cndmask_b32_e64 v177, v175, -v175, vcc
	v_mul_f32_dpp v182, v62, v177 row_ror:8 row_mask:0xf bank_mask:0xf
	v_mul_f32_dpp v183, v58, v212 row_ror:8 row_mask:0xf bank_mask:0xf
	v_mul_f32_dpp v184, v54, v177 row_ror:8 row_mask:0xf bank_mask:0xf
	v_mul_f32_dpp v185, v50, v212 row_ror:8 row_mask:0xf bank_mask:0xf
	v_fma_f32 v186, v62, v176, v182
	v_fma_f32 v187, v58, v238, v183
	v_fma_f32 v188, v54, v176, v184
	v_fma_f32 v189, v50, v238, v185
	v_cvt_pk_bf16_f32 v192, v186, v187
	v_cvt_pk_bf16_f32 v193, v188, v189
	ds_write_b16 v170, v192 offset:0
	ds_write_b16_d16_hi v170, v192 offset:32
	ds_write_b16 v170, v193 offset:64
	ds_write_b16_d16_hi v170, v193 offset:96
	v_mul_f32_dpp v182, v63, v177 row_ror:8 row_mask:0xf bank_mask:0xf
	v_mul_f32_dpp v183, v59, v213 row_ror:8 row_mask:0xf bank_mask:0xf
	v_mul_f32_dpp v184, v55, v177 row_ror:8 row_mask:0xf bank_mask:0xf
	v_mul_f32_dpp v185, v51, v213 row_ror:8 row_mask:0xf bank_mask:0xf
	v_fma_f32 v186, v63, v176, v182
	v_fma_f32 v187, v59, v239, v183
	v_fma_f32 v188, v55, v176, v184
	v_fma_f32 v189, v51, v239, v185
	v_cvt_pk_bf16_f32 v192, v186, v187
	v_cvt_pk_bf16_f32 v193, v188, v189
	ds_write_b16 v170, v192 offset:144
	ds_write_b16_d16_hi v170, v192 offset:176
	ds_write_b16 v170, v193 offset:208
	ds_write_b16_d16_hi v170, v193 offset:240
	v_mul_f32_dpp v182, v64, v177 row_ror:8 row_mask:0xf bank_mask:0xf
	v_mul_f32_dpp v183, v60, v214 row_ror:8 row_mask:0xf bank_mask:0xf
	v_mul_f32_dpp v184, v56, v177 row_ror:8 row_mask:0xf bank_mask:0xf
	v_mul_f32_dpp v185, v52, v214 row_ror:8 row_mask:0xf bank_mask:0xf
	v_fma_f32 v186, v64, v176, v182
	v_fma_f32 v187, v60, v240, v183
	v_fma_f32 v188, v56, v176, v184
	v_fma_f32 v189, v52, v240, v185
	v_cvt_pk_bf16_f32 v192, v186, v187
	v_cvt_pk_bf16_f32 v193, v188, v189
	ds_write_b16 v170, v192 offset:288
	ds_write_b16_d16_hi v170, v192 offset:320
	ds_write_b16 v170, v193 offset:352
	ds_write_b16_d16_hi v170, v193 offset:384
	v_mul_f32_dpp v182, v65, v177 row_ror:8 row_mask:0xf bank_mask:0xf
	v_mul_f32_dpp v183, v61, v215 row_ror:8 row_mask:0xf bank_mask:0xf
	v_mul_f32_dpp v184, v57, v177 row_ror:8 row_mask:0xf bank_mask:0xf
	v_mul_f32_dpp v185, v53, v215 row_ror:8 row_mask:0xf bank_mask:0xf
	v_fma_f32 v186, v65, v176, v182
	v_fma_f32 v187, v61, v241, v183
	v_fma_f32 v188, v57, v176, v184
	v_fma_f32 v189, v53, v241, v185
	v_cvt_pk_bf16_f32 v192, v186, v187
	v_cvt_pk_bf16_f32 v193, v188, v189
	ds_write_b16 v170, v192 offset:432
	ds_write_b16_d16_hi v170, v192 offset:464
	ds_write_b16 v170, v193 offset:496
	ds_write_b16_d16_hi v170, v193 offset:528
	v_mul_f32_dpp v182, v46, v177 row_ror:8 row_mask:0xf bank_mask:0xf
	v_mul_f32_dpp v183, v42, v216 row_ror:8 row_mask:0xf bank_mask:0xf
	v_mul_f32_dpp v184, v38, v177 row_ror:8 row_mask:0xf bank_mask:0xf
	v_mul_f32_dpp v185, v34, v216 row_ror:8 row_mask:0xf bank_mask:0xf
	v_fma_f32 v186, v46, v176, v182
	v_fma_f32 v187, v42, v242, v183
	v_fma_f32 v188, v38, v176, v184
	v_fma_f32 v189, v34, v242, v185
	v_cvt_pk_bf16_f32 v192, v186, v187
	v_cvt_pk_bf16_f32 v193, v188, v189
	ds_write_b16 v170, v192 offset:2304
	ds_write_b16_d16_hi v170, v192 offset:2336
	ds_write_b16 v170, v193 offset:2368
	ds_write_b16_d16_hi v170, v193 offset:2400
	v_mul_f32_dpp v182, v47, v177 row_ror:8 row_mask:0xf bank_mask:0xf
	v_mul_f32_dpp v183, v43, v217 row_ror:8 row_mask:0xf bank_mask:0xf
	v_mul_f32_dpp v184, v39, v177 row_ror:8 row_mask:0xf bank_mask:0xf
	v_mul_f32_dpp v185, v35, v217 row_ror:8 row_mask:0xf bank_mask:0xf
	v_fma_f32 v186, v47, v176, v182
	v_fma_f32 v187, v43, v243, v183
	v_fma_f32 v188, v39, v176, v184
	v_fma_f32 v189, v35, v243, v185
	v_cvt_pk_bf16_f32 v192, v186, v187
	v_cvt_pk_bf16_f32 v193, v188, v189
	ds_write_b16 v170, v192 offset:2448
	ds_write_b16_d16_hi v170, v192 offset:2480
	ds_write_b16 v170, v193 offset:2512
	ds_write_b16_d16_hi v170, v193 offset:2544
	v_mul_f32_dpp v182, v48, v177 row_ror:8 row_mask:0xf bank_mask:0xf
	v_mul_f32_dpp v183, v44, v218 row_ror:8 row_mask:0xf bank_mask:0xf
	v_mul_f32_dpp v184, v40, v177 row_ror:8 row_mask:0xf bank_mask:0xf
	v_mul_f32_dpp v185, v36, v218 row_ror:8 row_mask:0xf bank_mask:0xf
	v_fma_f32 v186, v48, v176, v182
	v_fma_f32 v187, v44, v244, v183
	v_fma_f32 v188, v40, v176, v184
	v_fma_f32 v189, v36, v244, v185
	v_cvt_pk_bf16_f32 v192, v186, v187
	v_cvt_pk_bf16_f32 v193, v188, v189
	ds_write_b16 v170, v192 offset:2592
	ds_write_b16_d16_hi v170, v192 offset:2624
	ds_write_b16 v170, v193 offset:2656
	ds_write_b16_d16_hi v170, v193 offset:2688
	v_mul_f32_dpp v182, v49, v177 row_ror:8 row_mask:0xf bank_mask:0xf
	v_mul_f32_dpp v183, v45, v219 row_ror:8 row_mask:0xf bank_mask:0xf
	v_mul_f32_dpp v184, v41, v177 row_ror:8 row_mask:0xf bank_mask:0xf
	v_mul_f32_dpp v185, v37, v219 row_ror:8 row_mask:0xf bank_mask:0xf
	v_fma_f32 v186, v49, v176, v182
	v_fma_f32 v187, v45, v245, v183
	v_fma_f32 v188, v41, v176, v184
	v_fma_f32 v189, v37, v245, v185
	v_cvt_pk_bf16_f32 v192, v186, v187
	v_cvt_pk_bf16_f32 v193, v188, v189
	ds_write_b16 v170, v192 offset:2736
	ds_write_b16_d16_hi v170, v192 offset:2768
	ds_write_b16 v170, v193 offset:2800
	ds_write_b16_d16_hi v170, v193 offset:2832
	v_mul_f32_dpp v182, v30, v177 row_ror:8 row_mask:0xf bank_mask:0xf
; template <int EPI>
; DI void gemm_phase(const P& p, int l, const u16* __restrict__ A, const u16* __restrict__ Bt, int mpx, char* lds) {
;     ...
;           } else if (tr == 4) {
;             float sr, cr, sc, cc;
;             sincos_rev((float)(s >> 6) * invf32, sr, cr);
;             sincos_rev((float)(s & 63) * invf32, sc, cc);
;             const float p0 = __shfl_xor(v0, 8), p1 = __shfl_xor(v1, 8), p2 = __shfl_xor(v2, 8), p3 = __shfl_xor(v3, 8);
;             v0 = lo8 ? (v0 * cr - p0 * sr) : (v0 * cr + p0 * sr);
;             v1 = lo8 ? (v1 * cc - p1 * sc) : (v1 * cc + p1 * sc);
;             v2 = lo8 ? (v2 * cr - p2 * sr) : (v2 * cr + p2 * sr);
;             v3 = lo8 ? (v3 * cc - p3 * sc) : (v3 * cc + p3 * sc);
;           }
;           const unsigned u01 = pack2(v0, v1), u23 = pack2(v2, v3);
;           if (kind == 1) {
;             Tl[(0 * 16 + r) * 72 + rowl] = (u16)u01;
;             Tl[(1 * 16 + r) * 72 + rowl] = (u16)(u01 >> 16);
;             Tl[(2 * 16 + r) * 72 + rowl] = (u16)u23;
;             Tl[(3 * 16 + r) * 72 + rowl] = (u16)(u23 >> 16);
;           } else if (tr == 2) {
;             Tl[rowl * 72 + 0 * 16 + r] = f2h(v0);
;             Tl[rowl * 72 + 1 * 16 + r] = f2h(v1);
;             Tl[rowl * 72 + 2 * 16 + r] = f2h(v2);
;             Tl[rowl * 72 + 3 * 16 + r] = f2h(v3);
;           } else {
;             Tl[rowl * 72 + 0 * 16 + r] = (u16)u01;
;             Tl[rowl * 72 + 1 * 16 + r] = (u16)(u01 >> 16);
;             Tl[rowl * 72 + 2 * 16 + r] = (u16)u23;
;             Tl[rowl * 72 + 3 * 16 + r] = (u16)(u23 >> 16);
;           }
;         }
;       }
;       __builtin_amdgcn_fence(__ATOMIC_RELEASE, "wavefront");
;       u16* dh = (kind == 1) ? dst + hf * 64 : dst + (size_t)(hf * 64) * rstride;
; #pragma unroll
;       for (int i = 0; i < 8; ++i) {
;         const int c = lane + i * 64;
;         const int row = c >> 3, cc = c & 7;
;         uint4 v = *(const uint4*)&Tl[row * 72 + cc * 8];
;         *(uint4*)(dh + (size_t)row * rstride + cc * 8) = v;
;       }
	v_mul_f32_dpp v183, v26, v220 row_ror:8 row_mask:0xf bank_mask:0xf
	v_mul_f32_dpp v184, v22, v177 row_ror:8 row_mask:0xf bank_mask:0xf
	v_mul_f32_dpp v185, v18, v220 row_ror:8 row_mask:0xf bank_mask:0xf
	v_fma_f32 v186, v30, v176, v182
	v_fma_f32 v187, v26, v246, v183
	v_fma_f32 v188, v22, v176, v184
	v_fma_f32 v189, v18, v246, v185
	v_cvt_pk_bf16_f32 v192, v186, v187
	v_cvt_pk_bf16_f32 v193, v188, v189
	ds_write_b16 v170, v192 offset:4608
	ds_write_b16_d16_hi v170, v192 offset:4640
	ds_write_b16 v170, v193 offset:4672
	ds_write_b16_d16_hi v170, v193 offset:4704
	v_mul_f32_dpp v182, v31, v177 row_ror:8 row_mask:0xf bank_mask:0xf
	v_mul_f32_dpp v183, v27, v221 row_ror:8 row_mask:0xf bank_mask:0xf
	v_mul_f32_dpp v184, v23, v177 row_ror:8 row_mask:0xf bank_mask:0xf
	v_mul_f32_dpp v185, v19, v221 row_ror:8 row_mask:0xf bank_mask:0xf
	v_fma_f32 v186, v31, v176, v182
	v_fma_f32 v187, v27, v247, v183
	v_fma_f32 v188, v23, v176, v184
	v_fma_f32 v189, v19, v247, v185
	v_cvt_pk_bf16_f32 v192, v186, v187
	v_cvt_pk_bf16_f32 v193, v188, v189
	ds_write_b16 v170, v192 offset:4752
	ds_write_b16_d16_hi v170, v192 offset:4784
	ds_write_b16 v170, v193 offset:4816
	ds_write_b16_d16_hi v170, v193 offset:4848
	v_mul_f32_dpp v182, v32, v177 row_ror:8 row_mask:0xf bank_mask:0xf
	v_mul_f32_dpp v183, v28, v222 row_ror:8 row_mask:0xf bank_mask:0xf
	v_mul_f32_dpp v184, v24, v177 row_ror:8 row_mask:0xf bank_mask:0xf
	v_mul_f32_dpp v185, v20, v222 row_ror:8 row_mask:0xf bank_mask:0xf
	v_fma_f32 v186, v32, v176, v182
	v_fma_f32 v187, v28, v248, v183
	v_fma_f32 v188, v24, v176, v184
	v_fma_f32 v189, v20, v248, v185
	v_cvt_pk_bf16_f32 v192, v186, v187
	v_cvt_pk_bf16_f32 v193, v188, v189
	ds_write_b16 v170, v192 offset:4896
	ds_write_b16_d16_hi v170, v192 offset:4928
	ds_write_b16 v170, v193 offset:4960
	ds_write_b16_d16_hi v170, v193 offset:4992
	v_mul_f32_dpp v182, v33, v177 row_ror:8 row_mask:0xf bank_mask:0xf
	v_mul_f32_dpp v183, v29, v223 row_ror:8 row_mask:0xf bank_mask:0xf
	v_mul_f32_dpp v184, v25, v177 row_ror:8 row_mask:0xf bank_mask:0xf
	v_mul_f32_dpp v185, v21, v223 row_ror:8 row_mask:0xf bank_mask:0xf
	v_fma_f32 v186, v33, v176, v182
	v_fma_f32 v187, v29, v249, v183
	v_fma_f32 v188, v25, v176, v184
	v_fma_f32 v189, v21, v249, v185
	v_cvt_pk_bf16_f32 v192, v186, v187
	v_cvt_pk_bf16_f32 v193, v188, v189
	ds_write_b16 v170, v192 offset:5040
	ds_write_b16_d16_hi v170, v192 offset:5072
	ds_write_b16 v170, v193 offset:5104
	ds_write_b16_d16_hi v170, v193 offset:5136
	v_mul_f32_dpp v182, v166, v177 row_ror:8 row_mask:0xf bank_mask:0xf
	v_mul_f32_dpp v183, v162, v234 row_ror:8 row_mask:0xf bank_mask:0xf
	v_mul_f32_dpp v184, v2, v177 row_ror:8 row_mask:0xf bank_mask:0xf
	v_mul_f32_dpp v185, v6, v234 row_ror:8 row_mask:0xf bank_mask:0xf
	v_fma_f32 v186, v166, v176, v182
	v_fma_f32 v187, v162, v250, v183
	v_fma_f32 v188, v2, v176, v184
	v_fma_f32 v189, v6, v250, v185
	v_cvt_pk_bf16_f32 v192, v186, v187
	v_cvt_pk_bf16_f32 v193, v188, v189
	ds_write_b16 v170, v192 offset:6912
	ds_write_b16_d16_hi v170, v192 offset:6944
	ds_write_b16 v170, v193 offset:6976
	ds_write_b16_d16_hi v170, v193 offset:7008
	v_mul_f32_dpp v182, v167, v177 row_ror:8 row_mask:0xf bank_mask:0xf
	v_mul_f32_dpp v183, v163, v235 row_ror:8 row_mask:0xf bank_mask:0xf
	v_mul_f32_dpp v184, v3, v177 row_ror:8 row_mask:0xf bank_mask:0xf
	v_mul_f32_dpp v185, v7, v235 row_ror:8 row_mask:0xf bank_mask:0xf
	v_fma_f32 v186, v167, v176, v182
	v_fma_f32 v187, v163, v251, v183
	v_fma_f32 v188, v3, v176, v184
	v_fma_f32 v189, v7, v251, v185
	v_cvt_pk_bf16_f32 v192, v186, v187
	v_cvt_pk_bf16_f32 v193, v188, v189
	ds_write_b16 v170, v192 offset:7056
	ds_write_b16_d16_hi v170, v192 offset:7088
	ds_write_b16 v170, v193 offset:7120
	ds_write_b16_d16_hi v170, v193 offset:7152
	v_mul_f32_dpp v182, v168, v177 row_ror:8 row_mask:0xf bank_mask:0xf
	v_mul_f32_dpp v183, v164, v236 row_ror:8 row_mask:0xf bank_mask:0xf
	v_mul_f32_dpp v184, v4, v177 row_ror:8 row_mask:0xf bank_mask:0xf
	v_mul_f32_dpp v185, v8, v236 row_ror:8 row_mask:0xf bank_mask:0xf
	v_fma_f32 v186, v168, v176, v182
	v_fma_f32 v187, v164, v252, v183
	v_fma_f32 v188, v4, v176, v184
	v_fma_f32 v189, v8, v252, v185
	v_cvt_pk_bf16_f32 v192, v186, v187
	v_cvt_pk_bf16_f32 v193, v188, v189
	ds_write_b16 v170, v192 offset:7200
	ds_write_b16_d16_hi v170, v192 offset:7232
	ds_write_b16 v170, v193 offset:7264
	ds_write_b16_d16_hi v170, v193 offset:7296
	v_mul_f32_dpp v182, v169, v177 row_ror:8 row_mask:0xf bank_mask:0xf
	v_mul_f32_dpp v183, v165, v237 row_ror:8 row_mask:0xf bank_mask:0xf
	v_mul_f32_dpp v184, v5, v177 row_ror:8 row_mask:0xf bank_mask:0xf
	v_mul_f32_dpp v185, v9, v237 row_ror:8 row_mask:0xf bank_mask:0xf
	v_fma_f32 v186, v169, v176, v182
	v_fma_f32 v187, v165, v253, v183
	v_fma_f32 v188, v5, v176, v184
	v_fma_f32 v189, v9, v253, v185
	v_cvt_pk_bf16_f32 v192, v186, v187
	v_cvt_pk_bf16_f32 v193, v188, v189
	ds_write_b16 v170, v192 offset:7344
	ds_write_b16_d16_hi v170, v192 offset:7376
	ds_write_b16 v170, v193 offset:7408
	ds_write_b16_d16_hi v170, v193 offset:7440
	ds_read_b128 v[130:133], v171 offset:0
	ds_read_b128 v[134:137], v171 offset:1152
	ds_read_b128 v[138:141], v171 offset:2304
	ds_read_b128 v[142:145], v171 offset:3456
	ds_read_b128 v[146:149], v171 offset:4608
	ds_read_b128 v[150:153], v171 offset:5760
	ds_read_b128 v[154:157], v171 offset:6912
	ds_read_b128 v[158:161], v171 offset:8064
	s_waitcnt lgkmcnt(7)
	global_store_dwordx4 v172, v[130:133], s[44:45] offset:0 sc1
	s_waitcnt lgkmcnt(6)
	global_store_dwordx4 v172, v[134:137], s[44:45] offset:1024 sc1
	s_waitcnt lgkmcnt(5)
	global_store_dwordx4 v172, v[138:141], s[44:45] offset:2048 sc1
	s_waitcnt lgkmcnt(4)
	global_store_dwordx4 v172, v[142:145], s[44:45] offset:3072 sc1
	s_waitcnt lgkmcnt(3)
	global_store_dwordx4 v172, v[146:149], s[62:63] offset:0 sc1
	s_waitcnt lgkmcnt(2)
	global_store_dwordx4 v172, v[150:153], s[62:63] offset:1024 sc1
	s_waitcnt lgkmcnt(1)
	global_store_dwordx4 v172, v[154:157], s[62:63] offset:2048 sc1
	s_waitcnt lgkmcnt(0)
	global_store_dwordx4 v172, v[158:161], s[62:63] offset:3072 sc1
	s_branch .Lfe_done
; template <int EPI>
; DI void gemm_phase(const P& p, int l, const u16* __restrict__ A, const u16* __restrict__ Bt, int mpx, char* lds) {
;     ...
;     const float* gw = (cb < 1280 ? p.ga_qn : p.ga_kn) + l * 64;
;     float gv0 = 1.f, gv1 = 1.f, gv2 = 1.f, gv3 = 1.f;
;     if (donorm) { gv0 = gw[r]; gv1 = gw[16 + r]; gv2 = gw[32 + r]; gv3 = gw[48 + r]; }
;     const bool dorope = (tr == 3) && !isctx;
;     const float invf64 = exp2f(-13.287712379549449f * (float)r * (1.f / 16.f));
;     const float invf32 = exp2f(-13.287712379549449f * (float)(r & 7) * (1.f / 8.f));
;     ...
;             if (dorope) {
;               float sr, cr, sc, cc;
;               sincos_rev((float)(s >> 6) * invf64, sr, cr);
;               sincos_rev((float)(s & 63) * invf64, sc, cc);
.Lfe_k0_normrope:
	s_cmp_lt_u32 s43, 20
	s_movk_i32 s70, 0x68
	s_cselect_b32 s70, 0x60, s70
	s_add_u32 s70, s96, s70
	s_addc_u32 s71, s97, 0
	s_load_dwordx2 s[70:71], s[70:71], 0x0
	v_and_b32_e32 v0, 15, v226
	v_lshlrev_b32_e32 v0, 2, v0
	v_mov_b32_e32 v173, 0x358637bd
	s_waitcnt lgkmcnt(0)
	s_lshl_b32 s63, s52, 2
	s_add_u32 s70, s70, s63
	s_addc_u32 s71, s71, 0
	global_load_dword v178, v0, s[70:71] offset:0
	global_load_dword v179, v0, s[70:71] offset:64
	global_load_dword v180, v0, s[70:71] offset:128
	global_load_dword v181, v0, s[70:71] offset:192
	v_and_b32_e32 v0, 15, v226
	v_cvt_f32_ubyte0_e32 v0, v0
	v_mul_f32_e32 v0, 0xc1549a78, v0
	v_mul_f32_e32 v0, 0x3d800000, v0
	v_exp_f32_e32 v174, v0
	v_lshrrev_b32_e32 v0, 4, v226
	v_lshlrev_b32_e32 v0, 2, v0
	v_add_u32_e32 v182, 0, v0
	v_cvt_f32_i32_e32 v182, v182
	v_mul_f32_e32 v182, v174, v182
	v_mul_f32_e32 v183, 0.15915494, v182
	v_rndne_f32_e32 v183, v183
	v_fma_f32 v183, v182, 0.15915494, -v183
	v_sin_f32_e32 v212, v183
	v_cos_f32_e32 v238, v183
	v_add_u32_e32 v182, 1, v0
	v_cvt_f32_i32_e32 v182, v182
	v_mul_f32_e32 v182, v174, v182
	v_mul_f32_e32 v183, 0.15915494, v182
	v_rndne_f32_e32 v183, v183
	v_fma_f32 v183, v182, 0.15915494, -v183
	v_sin_f32_e32 v213, v183
	v_cos_f32_e32 v239, v183
	v_add_u32_e32 v182, 2, v0
	v_cvt_f32_i32_e32 v182, v182
	v_mul_f32_e32 v182, v174, v182
	v_mul_f32_e32 v183, 0.15915494, v182
	v_rndne_f32_e32 v183, v183
	v_fma_f32 v183, v182, 0.15915494, -v183
	v_sin_f32_e32 v214, v183
	v_cos_f32_e32 v240, v183
	v_add_u32_e32 v182, 3, v0
	v_cvt_f32_i32_e32 v182, v182
	v_mul_f32_e32 v182, v174, v182
	v_mul_f32_e32 v183, 0.15915494, v182
	v_rndne_f32_e32 v183, v183
	v_fma_f32 v183, v182, 0.15915494, -v183
	v_sin_f32_e32 v215, v183
	v_cos_f32_e32 v241, v183
	v_add_u32_e32 v182, 16, v0
	v_cvt_f32_i32_e32 v182, v182
	v_mul_f32_e32 v182, v174, v182
	v_mul_f32_e32 v183, 0.15915494, v182
	v_rndne_f32_e32 v183, v183
	v_fma_f32 v183, v182, 0.15915494, -v183
	v_sin_f32_e32 v216, v183
	v_cos_f32_e32 v242, v183
	v_add_u32_e32 v182, 17, v0
	v_cvt_f32_i32_e32 v182, v182
	v_mul_f32_e32 v182, v174, v182
	v_mul_f32_e32 v183, 0.15915494, v182
	v_rndne_f32_e32 v183, v183
	v_fma_f32 v183, v182, 0.15915494, -v183
	v_sin_f32_e32 v217, v183
	v_cos_f32_e32 v243, v183
	v_add_u32_e32 v182, 18, v0
	v_cvt_f32_i32_e32 v182, v182
	v_mul_f32_e32 v182, v174, v182
	v_mul_f32_e32 v183, 0.15915494, v182
	v_rndne_f32_e32 v183, v183
	v_fma_f32 v183, v182, 0.15915494, -v183
	v_sin_f32_e32 v218, v183
	v_cos_f32_e32 v244, v183
	v_add_u32_e32 v182, 19, v0
	v_cvt_f32_i32_e32 v182, v182
	v_mul_f32_e32 v182, v174, v182
	v_mul_f32_e32 v183, 0.15915494, v182
	v_rndne_f32_e32 v183, v183
	v_fma_f32 v183, v182, 0.15915494, -v183
	v_sin_f32_e32 v219, v183
	v_cos_f32_e32 v245, v183
	v_add_u32_e32 v182, 32, v0
	v_cvt_f32_i32_e32 v182, v182
	v_mul_f32_e32 v182, v174, v182
	v_mul_f32_e32 v183, 0.15915494, v182
	v_rndne_f32_e32 v183, v183
	v_fma_f32 v183, v182, 0.15915494, -v183
	v_sin_f32_e32 v220, v183
	v_cos_f32_e32 v246, v183
	v_add_u32_e32 v182, 33, v0
	v_cvt_f32_i32_e32 v182, v182
	v_mul_f32_e32 v182, v174, v182
	v_mul_f32_e32 v183, 0.15915494, v182
	v_rndne_f32_e32 v183, v183
	v_fma_f32 v183, v182, 0.15915494, -v183
	v_sin_f32_e32 v221, v183
	v_cos_f32_e32 v247, v183
	v_add_u32_e32 v182, 34, v0
	v_cvt_f32_i32_e32 v182, v182
	v_mul_f32_e32 v182, v174, v182
	v_mul_f32_e32 v183, 0.15915494, v182
	v_rndne_f32_e32 v183, v183
	v_fma_f32 v183, v182, 0.15915494, -v183
	v_sin_f32_e32 v222, v183
	v_cos_f32_e32 v248, v183
	v_add_u32_e32 v182, 35, v0
	v_cvt_f32_i32_e32 v182, v182
	v_mul_f32_e32 v182, v174, v182
	v_mul_f32_e32 v183, 0.15915494, v182
	v_rndne_f32_e32 v183, v183
	v_fma_f32 v183, v182, 0.15915494, -v183
	v_sin_f32_e32 v223, v183
	v_cos_f32_e32 v249, v183
	v_add_u32_e32 v182, 48, v0
	v_cvt_f32_i32_e32 v182, v182
	v_mul_f32_e32 v182, v174, v182
	v_mul_f32_e32 v183, 0.15915494, v182
	v_rndne_f32_e32 v183, v183
	v_fma_f32 v183, v182, 0.15915494, -v183
	v_sin_f32_e32 v234, v183
	v_cos_f32_e32 v250, v183
	v_add_u32_e32 v182, 49, v0
	v_cvt_f32_i32_e32 v182, v182
	v_mul_f32_e32 v182, v174, v182
	v_mul_f32_e32 v183, 0.15915494, v182
	v_rndne_f32_e32 v183, v183
	v_fma_f32 v183, v182, 0.15915494, -v183
	v_sin_f32_e32 v235, v183
	v_cos_f32_e32 v251, v183
	v_add_u32_e32 v182, 50, v0
	v_cvt_f32_i32_e32 v182, v182
	v_mul_f32_e32 v182, v174, v182
	v_mul_f32_e32 v183, 0.15915494, v182
	v_rndne_f32_e32 v183, v183
	v_fma_f32 v183, v182, 0.15915494, -v183
	v_sin_f32_e32 v236, v183
	v_cos_f32_e32 v252, v183
	v_add_u32_e32 v182, 51, v0
	v_cvt_f32_i32_e32 v182, v182
	v_mul_f32_e32 v182, v174, v182
	v_mul_f32_e32 v183, 0.15915494, v182
	v_rndne_f32_e32 v183, v183
	v_fma_f32 v183, v182, 0.15915494, -v183
	v_sin_f32_e32 v237, v183
	v_cos_f32_e32 v253, v183
	s_waitcnt vmcnt(0)
; template <int EPI>
; DI void gemm_phase(const P& p, int l, const u16* __restrict__ A, const u16* __restrict__ Bt, int mpx, char* lds) {
;     ...
;           } else if (tr == 3) {
;             if (donorm) {
;               float ss = v0 * v0 + v1 * v1 + v2 * v2 + v3 * v3;
;               ss += __shfl_xor(ss, 1);
;               ss += __shfl_xor(ss, 2);
;               ss += __shfl_xor(ss, 4);
;               ss += __shfl_xor(ss, 8);
;               const float inv = rsqrtf(ss * (1.f / 64.f) + 1e-6f);
;               v0 *= inv * gv0; v1 *= inv * gv1; v2 *= inv * gv2; v3 *= inv * gv3;
;             }
;             if (dorope) {
;               float sr, cr, sc, cc;
;               sincos_rev((float)(s >> 6) * invf64, sr, cr);
;               sincos_rev((float)(s & 63) * invf64, sc, cc);
;               const float a1 = v0, a2 = v1, b1 = v2, b2 = v3;
;               v0 = a1 * cr - a2 * sr;
;               v1 = a2 * cr + a1 * sr;
;               v2 = b1 * cc - b2 * sc;
;               v3 = b2 * cc + b1 * sc;
;             }
;           } else if (tr == 4) {
;             float sr, cr, sc, cc;
;             sincos_rev((float)(s >> 6) * invf32, sr, cr);
;             sincos_rev((float)(s & 63) * invf32, sc, cc);
;             const float p0 = __shfl_xor(v0, 8), p1 = __shfl_xor(v1, 8), p2 = __shfl_xor(v2, 8), p3 = __shfl_xor(v3, 8);
;             v0 = lo8 ? (v0 * cr - p0 * sr) : (v0 * cr + p0 * sr);
;             v1 = lo8 ? (v1 * cc - p1 * sc) : (v1 * cc + p1 * sc);
;             v2 = lo8 ? (v2 * cr - p2 * sr) : (v2 * cr + p2 * sr);
;             v3 = lo8 ? (v3 * cc - p3 * sc) : (v3 * cc + p3 * sc);
;           }
;           const unsigned u01 = pack2(v0, v1), u23 = pack2(v2, v3);
;           if (kind == 1) {
;             Tl[(0 * 16 + r) * 72 + rowl] = (u16)u01;
;             Tl[(1 * 16 + r) * 72 + rowl] = (u16)(u01 >> 16);
;             Tl[(2 * 16 + r) * 72 + rowl] = (u16)u23;
;             Tl[(3 * 16 + r) * 72 + rowl] = (u16)(u23 >> 16);
;           } else if (tr == 2) {
;             Tl[rowl * 72 + 0 * 16 + r] = f2h(v0);
;             Tl[rowl * 72 + 1 * 16 + r] = f2h(v1);
;             Tl[rowl * 72 + 2 * 16 + r] = f2h(v2);
;             Tl[rowl * 72 + 3 * 16 + r] = f2h(v3);
;           } else {
;             Tl[rowl * 72 + 0 * 16 + r] = (u16)u01;
;             Tl[rowl * 72 + 1 * 16 + r] = (u16)(u01 >> 16);
;             Tl[rowl * 72 + 2 * 16 + r] = (u16)u23;
	s_add_u32 s62, s44, 0x1000
	s_addc_u32 s63, s45, 0
	s_lshr_b32 s70, s69, 6
	v_cvt_f32_i32_e32 v182, s70
	v_mul_f32_e32 v182, v174, v182
	v_mul_f32_e32 v183, 0.15915494, v182
	v_rndne_f32_e32 v183, v183
	v_fma_f32 v183, v182, 0.15915494, -v183
	v_sin_f32_e32 v175, v183
	v_cos_f32_e32 v176, v183
	v_mul_f32_e32 v182, v126, v126
	v_mul_f32_e32 v183, v122, v122
	v_mul_f32_e32 v184, v118, v118
	v_mul_f32_e32 v185, v114, v114
	v_add_f32_e32 v186, v182, v183
	v_add_f32_e32 v186, v186, v184
	v_add_f32_e32 v186, v186, v185
	s_nop 1
	v_add_f32_dpp v186, v186, v186 quad_perm:[1,0,3,2] row_mask:0xf bank_mask:0xf
	s_nop 1
	v_add_f32_dpp v186, v186, v186 quad_perm:[2,3,0,1] row_mask:0xf bank_mask:0xf
	s_nop 1
	v_add_f32_dpp v186, v186, v186 row_half_mirror row_mask:0xf bank_mask:0xf
	s_nop 1
	v_add_f32_dpp v186, v186, v186 row_mirror row_mask:0xf bank_mask:0xf
	v_fmamk_f32 v186, v186, 0x3c800000, v173
	v_rsq_f32_e32 v186, v186
	s_nop 0
	v_mul_f32_e32 v187, v178, v186
	v_mul_f32_e32 v188, v179, v186
	v_mul_f32_e32 v189, v180, v186
	v_mul_f32_e32 v190, v181, v186
	v_mul_f32_e32 v182, v126, v187
	v_mul_f32_e32 v183, v122, v188
	v_mul_f32_e32 v184, v118, v189
	v_mul_f32_e32 v185, v114, v190
	v_mul_f32_e32 v186, v175, v183
	v_mul_f32_e32 v187, v176, v183
	v_fma_f32 v188, v176, v182, -v186
	v_fma_f32 v189, v175, v182, v187
	v_mul_f32_e32 v186, v212, v185
	v_mul_f32_e32 v187, v238, v185
	v_fma_f32 v190, v238, v184, -v186
	v_fma_f32 v191, v212, v184, v187
	v_cvt_pk_bf16_f32 v192, v188, v189
	v_cvt_pk_bf16_f32 v193, v190, v191
	ds_write_b16 v170, v192 offset:0
	ds_write_b16_d16_hi v170, v192 offset:32
	ds_write_b16 v170, v193 offset:64
	ds_write_b16_d16_hi v170, v193 offset:96
	v_mul_f32_e32 v182, v127, v127
	v_mul_f32_e32 v183, v123, v123
	v_mul_f32_e32 v184, v119, v119
	v_mul_f32_e32 v185, v115, v115
	v_add_f32_e32 v186, v182, v183
	v_add_f32_e32 v186, v186, v184
	v_add_f32_e32 v186, v186, v185
	s_nop 1
	v_add_f32_dpp v186, v186, v186 quad_perm:[1,0,3,2] row_mask:0xf bank_mask:0xf
	s_nop 1
	v_add_f32_dpp v186, v186, v186 quad_perm:[2,3,0,1] row_mask:0xf bank_mask:0xf
	s_nop 1
	v_add_f32_dpp v186, v186, v186 row_half_mirror row_mask:0xf bank_mask:0xf
	s_nop 1
	v_add_f32_dpp v186, v186, v186 row_mirror row_mask:0xf bank_mask:0xf
	v_fmamk_f32 v186, v186, 0x3c800000, v173
	v_rsq_f32_e32 v186, v186
	s_nop 0
	v_mul_f32_e32 v187, v178, v186
	v_mul_f32_e32 v188, v179, v186
	v_mul_f32_e32 v189, v180, v186
	v_mul_f32_e32 v190, v181, v186
	v_mul_f32_e32 v182, v127, v187
	v_mul_f32_e32 v183, v123, v188
	v_mul_f32_e32 v184, v119, v189
	v_mul_f32_e32 v185, v115, v190
	v_mul_f32_e32 v186, v175, v183
	v_mul_f32_e32 v187, v176, v183
	v_fma_f32 v188, v176, v182, -v186
	v_fma_f32 v189, v175, v182, v187
	v_mul_f32_e32 v186, v213, v185
	v_mul_f32_e32 v187, v239, v185
	v_fma_f32 v190, v239, v184, -v186
	v_fma_f32 v191, v213, v184, v187
	v_cvt_pk_bf16_f32 v192, v188, v189
	v_cvt_pk_bf16_f32 v193, v190, v191
	ds_write_b16 v170, v192 offset:144
	ds_write_b16_d16_hi v170, v192 offset:176
	ds_write_b16 v170, v193 offset:208
	ds_write_b16_d16_hi v170, v193 offset:240
	v_mul_f32_e32 v182, v128, v128
	v_mul_f32_e32 v183, v124, v124
	v_mul_f32_e32 v184, v120, v120
	v_mul_f32_e32 v185, v116, v116
	v_add_f32_e32 v186, v182, v183
	v_add_f32_e32 v186, v186, v184
	v_add_f32_e32 v186, v186, v185
	s_nop 1
	v_add_f32_dpp v186, v186, v186 quad_perm:[1,0,3,2] row_mask:0xf bank_mask:0xf
	s_nop 1
	v_add_f32_dpp v186, v186, v186 quad_perm:[2,3,0,1] row_mask:0xf bank_mask:0xf
	s_nop 1
	v_add_f32_dpp v186, v186, v186 row_half_mirror row_mask:0xf bank_mask:0xf
	s_nop 1
	v_add_f32_dpp v186, v186, v186 row_mirror row_mask:0xf bank_mask:0xf
	v_fmamk_f32 v186, v186, 0x3c800000, v173
	v_rsq_f32_e32 v186, v186
	s_nop 0
	v_mul_f32_e32 v187, v178, v186
	v_mul_f32_e32 v188, v179, v186
	v_mul_f32_e32 v189, v180, v186
	v_mul_f32_e32 v190, v181, v186
	v_mul_f32_e32 v182, v128, v187
	v_mul_f32_e32 v183, v124, v188
	v_mul_f32_e32 v184, v120, v189
	v_mul_f32_e32 v185, v116, v190
	v_mul_f32_e32 v186, v175, v183
	v_mul_f32_e32 v187, v176, v183
	v_fma_f32 v188, v176, v182, -v186
	v_fma_f32 v189, v175, v182, v187
	v_mul_f32_e32 v186, v214, v185
	v_mul_f32_e32 v187, v240, v185
	v_fma_f32 v190, v240, v184, -v186
	v_fma_f32 v191, v214, v184, v187
	v_cvt_pk_bf16_f32 v192, v188, v189
	v_cvt_pk_bf16_f32 v193, v190, v191
	ds_write_b16 v170, v192 offset:288
	ds_write_b16_d16_hi v170, v192 offset:320
	ds_write_b16 v170, v193 offset:352
	ds_write_b16_d16_hi v170, v193 offset:384
	v_mul_f32_e32 v182, v129, v129
	v_mul_f32_e32 v183, v125, v125
	v_mul_f32_e32 v184, v121, v121
	v_mul_f32_e32 v185, v117, v117
	v_add_f32_e32 v186, v182, v183
	v_add_f32_e32 v186, v186, v184
	v_add_f32_e32 v186, v186, v185
	s_nop 1
	v_add_f32_dpp v186, v186, v186 quad_perm:[1,0,3,2] row_mask:0xf bank_mask:0xf
	s_nop 1
	v_add_f32_dpp v186, v186, v186 quad_perm:[2,3,0,1] row_mask:0xf bank_mask:0xf
	s_nop 1
	v_add_f32_dpp v186, v186, v186 row_half_mirror row_mask:0xf bank_mask:0xf
	s_nop 1
	v_add_f32_dpp v186, v186, v186 row_mirror row_mask:0xf bank_mask:0xf
	v_fmamk_f32 v186, v186, 0x3c800000, v173
	v_rsq_f32_e32 v186, v186
	s_nop 0
	v_mul_f32_e32 v187, v178, v186
	v_mul_f32_e32 v188, v179, v186
	v_mul_f32_e32 v189, v180, v186
	v_mul_f32_e32 v190, v181, v186
	v_mul_f32_e32 v182, v129, v187
	v_mul_f32_e32 v183, v125, v188
	v_mul_f32_e32 v184, v121, v189
	v_mul_f32_e32 v185, v117, v190
	v_mul_f32_e32 v186, v175, v183
	v_mul_f32_e32 v187, v176, v183
	v_fma_f32 v188, v176, v182, -v186
	v_fma_f32 v189, v175, v182, v187
	v_mul_f32_e32 v186, v215, v185
	v_mul_f32_e32 v187, v241, v185
	v_fma_f32 v190, v241, v184, -v186
	v_fma_f32 v191, v215, v184, v187
; template <int EPI>
; DI void gemm_phase(const P& p, int l, const u16* __restrict__ A, const u16* __restrict__ Bt, int mpx, char* lds) {
;     ...
;           } else if (tr == 3) {
;             if (donorm) {
;               float ss = v0 * v0 + v1 * v1 + v2 * v2 + v3 * v3;
;               ss += __shfl_xor(ss, 1);
;               ss += __shfl_xor(ss, 2);
;               ss += __shfl_xor(ss, 4);
;               ss += __shfl_xor(ss, 8);
;               const float inv = rsqrtf(ss * (1.f / 64.f) + 1e-6f);
;               v0 *= inv * gv0; v1 *= inv * gv1; v2 *= inv * gv2; v3 *= inv * gv3;
;             }
;             if (dorope) {
;               float sr, cr, sc, cc;
;               sincos_rev((float)(s >> 6) * invf64, sr, cr);
;               sincos_rev((float)(s & 63) * invf64, sc, cc);
;               const float a1 = v0, a2 = v1, b1 = v2, b2 = v3;
;               v0 = a1 * cr - a2 * sr;
;               v1 = a2 * cr + a1 * sr;
;               v2 = b1 * cc - b2 * sc;
;               v3 = b2 * cc + b1 * sc;
;             }
;           } else if (tr == 4) {
;             float sr, cr, sc, cc;
;             sincos_rev((float)(s >> 6) * invf32, sr, cr);
;             sincos_rev((float)(s & 63) * invf32, sc, cc);
;             const float p0 = __shfl_xor(v0, 8), p1 = __shfl_xor(v1, 8), p2 = __shfl_xor(v2, 8), p3 = __shfl_xor(v3, 8);
;             v0 = lo8 ? (v0 * cr - p0 * sr) : (v0 * cr + p0 * sr);
;             v1 = lo8 ? (v1 * cc - p1 * sc) : (v1 * cc + p1 * sc);
;             v2 = lo8 ? (v2 * cr - p2 * sr) : (v2 * cr + p2 * sr);
;             v3 = lo8 ? (v3 * cc - p3 * sc) : (v3 * cc + p3 * sc);
;           }
;           const unsigned u01 = pack2(v0, v1), u23 = pack2(v2, v3);
;           if (kind == 1) {
;             Tl[(0 * 16 + r) * 72 + rowl] = (u16)u01;
;             Tl[(1 * 16 + r) * 72 + rowl] = (u16)(u01 >> 16);
;             Tl[(2 * 16 + r) * 72 + rowl] = (u16)u23;
;             Tl[(3 * 16 + r) * 72 + rowl] = (u16)(u23 >> 16);
;           } else if (tr == 2) {
;             Tl[rowl * 72 + 0 * 16 + r] = f2h(v0);
;             Tl[rowl * 72 + 1 * 16 + r] = f2h(v1);
;             Tl[rowl * 72 + 2 * 16 + r] = f2h(v2);
;             Tl[rowl * 72 + 3 * 16 + r] = f2h(v3);
;           } else {
;             Tl[rowl * 72 + 0 * 16 + r] = (u16)u01;
;             Tl[rowl * 72 + 1 * 16 + r] = (u16)(u01 >> 16);
;             Tl[rowl * 72 + 2 * 16 + r] = (u16)u23;
	v_cvt_pk_bf16_f32 v192, v188, v189
	v_cvt_pk_bf16_f32 v193, v190, v191
	ds_write_b16 v170, v192 offset:432
	ds_write_b16_d16_hi v170, v192 offset:464
	ds_write_b16 v170, v193 offset:496
	ds_write_b16_d16_hi v170, v193 offset:528
	v_mul_f32_e32 v182, v110, v110
	v_mul_f32_e32 v183, v106, v106
	v_mul_f32_e32 v184, v102, v102
	v_mul_f32_e32 v185, v98, v98
	v_add_f32_e32 v186, v182, v183
	v_add_f32_e32 v186, v186, v184
	v_add_f32_e32 v186, v186, v185
	s_nop 1
	v_add_f32_dpp v186, v186, v186 quad_perm:[1,0,3,2] row_mask:0xf bank_mask:0xf
	s_nop 1
	v_add_f32_dpp v186, v186, v186 quad_perm:[2,3,0,1] row_mask:0xf bank_mask:0xf
	s_nop 1
	v_add_f32_dpp v186, v186, v186 row_half_mirror row_mask:0xf bank_mask:0xf
	s_nop 1
	v_add_f32_dpp v186, v186, v186 row_mirror row_mask:0xf bank_mask:0xf
	v_fmamk_f32 v186, v186, 0x3c800000, v173
	v_rsq_f32_e32 v186, v186
	s_nop 0
	v_mul_f32_e32 v187, v178, v186
	v_mul_f32_e32 v188, v179, v186
	v_mul_f32_e32 v189, v180, v186
	v_mul_f32_e32 v190, v181, v186
	v_mul_f32_e32 v182, v110, v187
	v_mul_f32_e32 v183, v106, v188
	v_mul_f32_e32 v184, v102, v189
	v_mul_f32_e32 v185, v98, v190
	v_mul_f32_e32 v186, v175, v183
	v_mul_f32_e32 v187, v176, v183
	v_fma_f32 v188, v176, v182, -v186
	v_fma_f32 v189, v175, v182, v187
	v_mul_f32_e32 v186, v216, v185
	v_mul_f32_e32 v187, v242, v185
	v_fma_f32 v190, v242, v184, -v186
	v_fma_f32 v191, v216, v184, v187
	v_cvt_pk_bf16_f32 v192, v188, v189
	v_cvt_pk_bf16_f32 v193, v190, v191
	ds_write_b16 v170, v192 offset:2304
	ds_write_b16_d16_hi v170, v192 offset:2336
	ds_write_b16 v170, v193 offset:2368
	ds_write_b16_d16_hi v170, v193 offset:2400
	v_mul_f32_e32 v182, v111, v111
	v_mul_f32_e32 v183, v107, v107
	v_mul_f32_e32 v184, v103, v103
	v_mul_f32_e32 v185, v99, v99
	v_add_f32_e32 v186, v182, v183
	v_add_f32_e32 v186, v186, v184
	v_add_f32_e32 v186, v186, v185
	s_nop 1
	v_add_f32_dpp v186, v186, v186 quad_perm:[1,0,3,2] row_mask:0xf bank_mask:0xf
	s_nop 1
	v_add_f32_dpp v186, v186, v186 quad_perm:[2,3,0,1] row_mask:0xf bank_mask:0xf
	s_nop 1
	v_add_f32_dpp v186, v186, v186 row_half_mirror row_mask:0xf bank_mask:0xf
	s_nop 1
	v_add_f32_dpp v186, v186, v186 row_mirror row_mask:0xf bank_mask:0xf
	v_fmamk_f32 v186, v186, 0x3c800000, v173
	v_rsq_f32_e32 v186, v186
	s_nop 0
	v_mul_f32_e32 v187, v178, v186
	v_mul_f32_e32 v188, v179, v186
	v_mul_f32_e32 v189, v180, v186
	v_mul_f32_e32 v190, v181, v186
	v_mul_f32_e32 v182, v111, v187
	v_mul_f32_e32 v183, v107, v188
	v_mul_f32_e32 v184, v103, v189
	v_mul_f32_e32 v185, v99, v190
	v_mul_f32_e32 v186, v175, v183
	v_mul_f32_e32 v187, v176, v183
	v_fma_f32 v188, v176, v182, -v186
	v_fma_f32 v189, v175, v182, v187
	v_mul_f32_e32 v186, v217, v185
	v_mul_f32_e32 v187, v243, v185
	v_fma_f32 v190, v243, v184, -v186
	v_fma_f32 v191, v217, v184, v187
	v_cvt_pk_bf16_f32 v192, v188, v189
	v_cvt_pk_bf16_f32 v193, v190, v191
	ds_write_b16 v170, v192 offset:2448
	ds_write_b16_d16_hi v170, v192 offset:2480
	ds_write_b16 v170, v193 offset:2512
	ds_write_b16_d16_hi v170, v193 offset:2544
	v_mul_f32_e32 v182, v112, v112
	v_mul_f32_e32 v183, v108, v108
	v_mul_f32_e32 v184, v104, v104
	v_mul_f32_e32 v185, v100, v100
	v_add_f32_e32 v186, v182, v183
	v_add_f32_e32 v186, v186, v184
	v_add_f32_e32 v186, v186, v185
	s_nop 1
	v_add_f32_dpp v186, v186, v186 quad_perm:[1,0,3,2] row_mask:0xf bank_mask:0xf
	s_nop 1
	v_add_f32_dpp v186, v186, v186 quad_perm:[2,3,0,1] row_mask:0xf bank_mask:0xf
	s_nop 1
	v_add_f32_dpp v186, v186, v186 row_half_mirror row_mask:0xf bank_mask:0xf
	s_nop 1
	v_add_f32_dpp v186, v186, v186 row_mirror row_mask:0xf bank_mask:0xf
	v_fmamk_f32 v186, v186, 0x3c800000, v173
	v_rsq_f32_e32 v186, v186
	s_nop 0
	v_mul_f32_e32 v187, v178, v186
	v_mul_f32_e32 v188, v179, v186
	v_mul_f32_e32 v189, v180, v186
	v_mul_f32_e32 v190, v181, v186
	v_mul_f32_e32 v182, v112, v187
	v_mul_f32_e32 v183, v108, v188
	v_mul_f32_e32 v184, v104, v189
	v_mul_f32_e32 v185, v100, v190
	v_mul_f32_e32 v186, v175, v183
	v_mul_f32_e32 v187, v176, v183
	v_fma_f32 v188, v176, v182, -v186
	v_fma_f32 v189, v175, v182, v187
	v_mul_f32_e32 v186, v218, v185
	v_mul_f32_e32 v187, v244, v185
	v_fma_f32 v190, v244, v184, -v186
	v_fma_f32 v191, v218, v184, v187
	v_cvt_pk_bf16_f32 v192, v188, v189
	v_cvt_pk_bf16_f32 v193, v190, v191
	ds_write_b16 v170, v192 offset:2592
	ds_write_b16_d16_hi v170, v192 offset:2624
	ds_write_b16 v170, v193 offset:2656
	ds_write_b16_d16_hi v170, v193 offset:2688
	v_mul_f32_e32 v182, v113, v113
	v_mul_f32_e32 v183, v109, v109
	v_mul_f32_e32 v184, v105, v105
	v_mul_f32_e32 v185, v101, v101
	v_add_f32_e32 v186, v182, v183
	v_add_f32_e32 v186, v186, v184
	v_add_f32_e32 v186, v186, v185
	s_nop 1
	v_add_f32_dpp v186, v186, v186 quad_perm:[1,0,3,2] row_mask:0xf bank_mask:0xf
	s_nop 1
	v_add_f32_dpp v186, v186, v186 quad_perm:[2,3,0,1] row_mask:0xf bank_mask:0xf
	s_nop 1
	v_add_f32_dpp v186, v186, v186 row_half_mirror row_mask:0xf bank_mask:0xf
	s_nop 1
	v_add_f32_dpp v186, v186, v186 row_mirror row_mask:0xf bank_mask:0xf
	v_fmamk_f32 v186, v186, 0x3c800000, v173
	v_rsq_f32_e32 v186, v186
	s_nop 0
	v_mul_f32_e32 v187, v178, v186
	v_mul_f32_e32 v188, v179, v186
	v_mul_f32_e32 v189, v180, v186
	v_mul_f32_e32 v190, v181, v186
	v_mul_f32_e32 v182, v113, v187
	v_mul_f32_e32 v183, v109, v188
	v_mul_f32_e32 v184, v105, v189
	v_mul_f32_e32 v185, v101, v190
	v_mul_f32_e32 v186, v175, v183
	v_mul_f32_e32 v187, v176, v183
	v_fma_f32 v188, v176, v182, -v186
	v_fma_f32 v189, v175, v182, v187
	v_mul_f32_e32 v186, v219, v185
	v_mul_f32_e32 v187, v245, v185
	v_fma_f32 v190, v245, v184, -v186
	v_fma_f32 v191, v219, v184, v187
	v_cvt_pk_bf16_f32 v192, v188, v189
	v_cvt_pk_bf16_f32 v193, v190, v191
; template <int EPI>
; DI void gemm_phase(const P& p, int l, const u16* __restrict__ A, const u16* __restrict__ Bt, int mpx, char* lds) {
;     ...
;           } else if (tr == 3) {
;             if (donorm) {
;               float ss = v0 * v0 + v1 * v1 + v2 * v2 + v3 * v3;
;               ss += __shfl_xor(ss, 1);
;               ss += __shfl_xor(ss, 2);
;               ss += __shfl_xor(ss, 4);
;               ss += __shfl_xor(ss, 8);
;               const float inv = rsqrtf(ss * (1.f / 64.f) + 1e-6f);
;               v0 *= inv * gv0; v1 *= inv * gv1; v2 *= inv * gv2; v3 *= inv * gv3;
;             }
;             if (dorope) {
;               float sr, cr, sc, cc;
;               sincos_rev((float)(s >> 6) * invf64, sr, cr);
;               sincos_rev((float)(s & 63) * invf64, sc, cc);
;               const float a1 = v0, a2 = v1, b1 = v2, b2 = v3;
;               v0 = a1 * cr - a2 * sr;
;               v1 = a2 * cr + a1 * sr;
;               v2 = b1 * cc - b2 * sc;
;               v3 = b2 * cc + b1 * sc;
;             }
;           } else if (tr == 4) {
;             float sr, cr, sc, cc;
;             sincos_rev((float)(s >> 6) * invf32, sr, cr);
;             sincos_rev((float)(s & 63) * invf32, sc, cc);
;             const float p0 = __shfl_xor(v0, 8), p1 = __shfl_xor(v1, 8), p2 = __shfl_xor(v2, 8), p3 = __shfl_xor(v3, 8);
;             v0 = lo8 ? (v0 * cr - p0 * sr) : (v0 * cr + p0 * sr);
;             v1 = lo8 ? (v1 * cc - p1 * sc) : (v1 * cc + p1 * sc);
;             v2 = lo8 ? (v2 * cr - p2 * sr) : (v2 * cr + p2 * sr);
;             v3 = lo8 ? (v3 * cc - p3 * sc) : (v3 * cc + p3 * sc);
;           }
;           const unsigned u01 = pack2(v0, v1), u23 = pack2(v2, v3);
;           if (kind == 1) {
;             Tl[(0 * 16 + r) * 72 + rowl] = (u16)u01;
;             Tl[(1 * 16 + r) * 72 + rowl] = (u16)(u01 >> 16);
;             Tl[(2 * 16 + r) * 72 + rowl] = (u16)u23;
;             Tl[(3 * 16 + r) * 72 + rowl] = (u16)(u23 >> 16);
;           } else if (tr == 2) {
;             Tl[rowl * 72 + 0 * 16 + r] = f2h(v0);
;             Tl[rowl * 72 + 1 * 16 + r] = f2h(v1);
;             Tl[rowl * 72 + 2 * 16 + r] = f2h(v2);
;             Tl[rowl * 72 + 3 * 16 + r] = f2h(v3);
;           } else {
;             Tl[rowl * 72 + 0 * 16 + r] = (u16)u01;
;             Tl[rowl * 72 + 1 * 16 + r] = (u16)(u01 >> 16);
;             Tl[rowl * 72 + 2 * 16 + r] = (u16)u23;
	ds_write_b16 v170, v192 offset:2736
	ds_write_b16_d16_hi v170, v192 offset:2768
	ds_write_b16 v170, v193 offset:2800
	ds_write_b16_d16_hi v170, v193 offset:2832
	v_mul_f32_e32 v182, v94, v94
	v_mul_f32_e32 v183, v90, v90
	v_mul_f32_e32 v184, v86, v86
	v_mul_f32_e32 v185, v82, v82
	v_add_f32_e32 v186, v182, v183
	v_add_f32_e32 v186, v186, v184
	v_add_f32_e32 v186, v186, v185
	s_nop 1
	v_add_f32_dpp v186, v186, v186 quad_perm:[1,0,3,2] row_mask:0xf bank_mask:0xf
	s_nop 1
	v_add_f32_dpp v186, v186, v186 quad_perm:[2,3,0,1] row_mask:0xf bank_mask:0xf
	s_nop 1
	v_add_f32_dpp v186, v186, v186 row_half_mirror row_mask:0xf bank_mask:0xf
	s_nop 1
	v_add_f32_dpp v186, v186, v186 row_mirror row_mask:0xf bank_mask:0xf
	v_fmamk_f32 v186, v186, 0x3c800000, v173
	v_rsq_f32_e32 v186, v186
	s_nop 0
	v_mul_f32_e32 v187, v178, v186
	v_mul_f32_e32 v188, v179, v186
	v_mul_f32_e32 v189, v180, v186
	v_mul_f32_e32 v190, v181, v186
	v_mul_f32_e32 v182, v94, v187
	v_mul_f32_e32 v183, v90, v188
	v_mul_f32_e32 v184, v86, v189
	v_mul_f32_e32 v185, v82, v190
	v_mul_f32_e32 v186, v175, v183
	v_mul_f32_e32 v187, v176, v183
	v_fma_f32 v188, v176, v182, -v186
	v_fma_f32 v189, v175, v182, v187
	v_mul_f32_e32 v186, v220, v185
	v_mul_f32_e32 v187, v246, v185
	v_fma_f32 v190, v246, v184, -v186
	v_fma_f32 v191, v220, v184, v187
	v_cvt_pk_bf16_f32 v192, v188, v189
	v_cvt_pk_bf16_f32 v193, v190, v191
	ds_write_b16 v170, v192 offset:4608
	ds_write_b16_d16_hi v170, v192 offset:4640
	ds_write_b16 v170, v193 offset:4672
	ds_write_b16_d16_hi v170, v193 offset:4704
	v_mul_f32_e32 v182, v95, v95
	v_mul_f32_e32 v183, v91, v91
	v_mul_f32_e32 v184, v87, v87
	v_mul_f32_e32 v185, v83, v83
	v_add_f32_e32 v186, v182, v183
	v_add_f32_e32 v186, v186, v184
	v_add_f32_e32 v186, v186, v185
	s_nop 1
	v_add_f32_dpp v186, v186, v186 quad_perm:[1,0,3,2] row_mask:0xf bank_mask:0xf
	s_nop 1
	v_add_f32_dpp v186, v186, v186 quad_perm:[2,3,0,1] row_mask:0xf bank_mask:0xf
	s_nop 1
	v_add_f32_dpp v186, v186, v186 row_half_mirror row_mask:0xf bank_mask:0xf
	s_nop 1
	v_add_f32_dpp v186, v186, v186 row_mirror row_mask:0xf bank_mask:0xf
	v_fmamk_f32 v186, v186, 0x3c800000, v173
	v_rsq_f32_e32 v186, v186
	s_nop 0
	v_mul_f32_e32 v187, v178, v186
	v_mul_f32_e32 v188, v179, v186
	v_mul_f32_e32 v189, v180, v186
	v_mul_f32_e32 v190, v181, v186
	v_mul_f32_e32 v182, v95, v187
	v_mul_f32_e32 v183, v91, v188
	v_mul_f32_e32 v184, v87, v189
	v_mul_f32_e32 v185, v83, v190
	v_mul_f32_e32 v186, v175, v183
	v_mul_f32_e32 v187, v176, v183
	v_fma_f32 v188, v176, v182, -v186
	v_fma_f32 v189, v175, v182, v187
	v_mul_f32_e32 v186, v221, v185
	v_mul_f32_e32 v187, v247, v185
	v_fma_f32 v190, v247, v184, -v186
	v_fma_f32 v191, v221, v184, v187
	v_cvt_pk_bf16_f32 v192, v188, v189
	v_cvt_pk_bf16_f32 v193, v190, v191
	ds_write_b16 v170, v192 offset:4752
	ds_write_b16_d16_hi v170, v192 offset:4784
	ds_write_b16 v170, v193 offset:4816
	ds_write_b16_d16_hi v170, v193 offset:4848
	v_mul_f32_e32 v182, v96, v96
	v_mul_f32_e32 v183, v92, v92
	v_mul_f32_e32 v184, v88, v88
	v_mul_f32_e32 v185, v84, v84
	v_add_f32_e32 v186, v182, v183
	v_add_f32_e32 v186, v186, v184
	v_add_f32_e32 v186, v186, v185
	s_nop 1
	v_add_f32_dpp v186, v186, v186 quad_perm:[1,0,3,2] row_mask:0xf bank_mask:0xf
	s_nop 1
	v_add_f32_dpp v186, v186, v186 quad_perm:[2,3,0,1] row_mask:0xf bank_mask:0xf
	s_nop 1
	v_add_f32_dpp v186, v186, v186 row_half_mirror row_mask:0xf bank_mask:0xf
	s_nop 1
	v_add_f32_dpp v186, v186, v186 row_mirror row_mask:0xf bank_mask:0xf
	v_fmamk_f32 v186, v186, 0x3c800000, v173
	v_rsq_f32_e32 v186, v186
	s_nop 0
	v_mul_f32_e32 v187, v178, v186
	v_mul_f32_e32 v188, v179, v186
	v_mul_f32_e32 v189, v180, v186
	v_mul_f32_e32 v190, v181, v186
	v_mul_f32_e32 v182, v96, v187
	v_mul_f32_e32 v183, v92, v188
	v_mul_f32_e32 v184, v88, v189
	v_mul_f32_e32 v185, v84, v190
	v_mul_f32_e32 v186, v175, v183
	v_mul_f32_e32 v187, v176, v183
	v_fma_f32 v188, v176, v182, -v186
	v_fma_f32 v189, v175, v182, v187
	v_mul_f32_e32 v186, v222, v185
	v_mul_f32_e32 v187, v248, v185
	v_fma_f32 v190, v248, v184, -v186
	v_fma_f32 v191, v222, v184, v187
	v_cvt_pk_bf16_f32 v192, v188, v189
	v_cvt_pk_bf16_f32 v193, v190, v191
	ds_write_b16 v170, v192 offset:4896
	ds_write_b16_d16_hi v170, v192 offset:4928
	ds_write_b16 v170, v193 offset:4960
	ds_write_b16_d16_hi v170, v193 offset:4992
	v_mul_f32_e32 v182, v97, v97
	v_mul_f32_e32 v183, v93, v93
	v_mul_f32_e32 v184, v89, v89
	v_mul_f32_e32 v185, v85, v85
	v_add_f32_e32 v186, v182, v183
	v_add_f32_e32 v186, v186, v184
	v_add_f32_e32 v186, v186, v185
	s_nop 1
	v_add_f32_dpp v186, v186, v186 quad_perm:[1,0,3,2] row_mask:0xf bank_mask:0xf
	s_nop 1
	v_add_f32_dpp v186, v186, v186 quad_perm:[2,3,0,1] row_mask:0xf bank_mask:0xf
	s_nop 1
	v_add_f32_dpp v186, v186, v186 row_half_mirror row_mask:0xf bank_mask:0xf
	s_nop 1
	v_add_f32_dpp v186, v186, v186 row_mirror row_mask:0xf bank_mask:0xf
	v_fmamk_f32 v186, v186, 0x3c800000, v173
	v_rsq_f32_e32 v186, v186
	s_nop 0
	v_mul_f32_e32 v187, v178, v186
	v_mul_f32_e32 v188, v179, v186
	v_mul_f32_e32 v189, v180, v186
	v_mul_f32_e32 v190, v181, v186
	v_mul_f32_e32 v182, v97, v187
	v_mul_f32_e32 v183, v93, v188
	v_mul_f32_e32 v184, v89, v189
	v_mul_f32_e32 v185, v85, v190
	v_mul_f32_e32 v186, v175, v183
	v_mul_f32_e32 v187, v176, v183
	v_fma_f32 v188, v176, v182, -v186
	v_fma_f32 v189, v175, v182, v187
	v_mul_f32_e32 v186, v223, v185
	v_mul_f32_e32 v187, v249, v185
	v_fma_f32 v190, v249, v184, -v186
	v_fma_f32 v191, v223, v184, v187
	v_cvt_pk_bf16_f32 v192, v188, v189
	v_cvt_pk_bf16_f32 v193, v190, v191
	ds_write_b16 v170, v192 offset:5040
	ds_write_b16_d16_hi v170, v192 offset:5072
	ds_write_b16 v170, v193 offset:5104
; template <int EPI>
; DI void gemm_phase(const P& p, int l, const u16* __restrict__ A, const u16* __restrict__ Bt, int mpx, char* lds) {
;     ...
;           } else if (tr == 3) {
;             if (donorm) {
;               float ss = v0 * v0 + v1 * v1 + v2 * v2 + v3 * v3;
;               ss += __shfl_xor(ss, 1);
;               ss += __shfl_xor(ss, 2);
;               ss += __shfl_xor(ss, 4);
;               ss += __shfl_xor(ss, 8);
;               const float inv = rsqrtf(ss * (1.f / 64.f) + 1e-6f);
;               v0 *= inv * gv0; v1 *= inv * gv1; v2 *= inv * gv2; v3 *= inv * gv3;
;             }
;             if (dorope) {
;               float sr, cr, sc, cc;
;               sincos_rev((float)(s >> 6) * invf64, sr, cr);
;               sincos_rev((float)(s & 63) * invf64, sc, cc);
;               const float a1 = v0, a2 = v1, b1 = v2, b2 = v3;
;               v0 = a1 * cr - a2 * sr;
;               v1 = a2 * cr + a1 * sr;
;               v2 = b1 * cc - b2 * sc;
;               v3 = b2 * cc + b1 * sc;
;             }
;           } else if (tr == 4) {
;             float sr, cr, sc, cc;
;             sincos_rev((float)(s >> 6) * invf32, sr, cr);
;             sincos_rev((float)(s & 63) * invf32, sc, cc);
;             const float p0 = __shfl_xor(v0, 8), p1 = __shfl_xor(v1, 8), p2 = __shfl_xor(v2, 8), p3 = __shfl_xor(v3, 8);
;             v0 = lo8 ? (v0 * cr - p0 * sr) : (v0 * cr + p0 * sr);
;             v1 = lo8 ? (v1 * cc - p1 * sc) : (v1 * cc + p1 * sc);
;             v2 = lo8 ? (v2 * cr - p2 * sr) : (v2 * cr + p2 * sr);
;             v3 = lo8 ? (v3 * cc - p3 * sc) : (v3 * cc + p3 * sc);
;           }
;           const unsigned u01 = pack2(v0, v1), u23 = pack2(v2, v3);
;           if (kind == 1) {
;             Tl[(0 * 16 + r) * 72 + rowl] = (u16)u01;
;             Tl[(1 * 16 + r) * 72 + rowl] = (u16)(u01 >> 16);
;             Tl[(2 * 16 + r) * 72 + rowl] = (u16)u23;
;             Tl[(3 * 16 + r) * 72 + rowl] = (u16)(u23 >> 16);
;           } else if (tr == 2) {
;             Tl[rowl * 72 + 0 * 16 + r] = f2h(v0);
;             Tl[rowl * 72 + 1 * 16 + r] = f2h(v1);
;             Tl[rowl * 72 + 2 * 16 + r] = f2h(v2);
;             Tl[rowl * 72 + 3 * 16 + r] = f2h(v3);
;           } else {
;             Tl[rowl * 72 + 0 * 16 + r] = (u16)u01;
;             Tl[rowl * 72 + 1 * 16 + r] = (u16)(u01 >> 16);
;             Tl[rowl * 72 + 2 * 16 + r] = (u16)u23;
	ds_write_b16_d16_hi v170, v193 offset:5136
	v_mul_f32_e32 v182, v78, v78
	v_mul_f32_e32 v183, v74, v74
	v_mul_f32_e32 v184, v70, v70
	v_mul_f32_e32 v185, v66, v66
	v_add_f32_e32 v186, v182, v183
	v_add_f32_e32 v186, v186, v184
	v_add_f32_e32 v186, v186, v185
	s_nop 1
	v_add_f32_dpp v186, v186, v186 quad_perm:[1,0,3,2] row_mask:0xf bank_mask:0xf
	s_nop 1
	v_add_f32_dpp v186, v186, v186 quad_perm:[2,3,0,1] row_mask:0xf bank_mask:0xf
	s_nop 1
	v_add_f32_dpp v186, v186, v186 row_half_mirror row_mask:0xf bank_mask:0xf
	s_nop 1
	v_add_f32_dpp v186, v186, v186 row_mirror row_mask:0xf bank_mask:0xf
	v_fmamk_f32 v186, v186, 0x3c800000, v173
	v_rsq_f32_e32 v186, v186
	s_nop 0
	v_mul_f32_e32 v187, v178, v186
	v_mul_f32_e32 v188, v179, v186
	v_mul_f32_e32 v189, v180, v186
	v_mul_f32_e32 v190, v181, v186
	v_mul_f32_e32 v182, v78, v187
	v_mul_f32_e32 v183, v74, v188
	v_mul_f32_e32 v184, v70, v189
	v_mul_f32_e32 v185, v66, v190
	v_mul_f32_e32 v186, v175, v183
	v_mul_f32_e32 v187, v176, v183
	v_fma_f32 v188, v176, v182, -v186
	v_fma_f32 v189, v175, v182, v187
	v_mul_f32_e32 v186, v234, v185
	v_mul_f32_e32 v187, v250, v185
	v_fma_f32 v190, v250, v184, -v186
	v_fma_f32 v191, v234, v184, v187
	v_cvt_pk_bf16_f32 v192, v188, v189
	v_cvt_pk_bf16_f32 v193, v190, v191
	ds_write_b16 v170, v192 offset:6912
	ds_write_b16_d16_hi v170, v192 offset:6944
	ds_write_b16 v170, v193 offset:6976
	ds_write_b16_d16_hi v170, v193 offset:7008
	v_mul_f32_e32 v182, v79, v79
	v_mul_f32_e32 v183, v75, v75
	v_mul_f32_e32 v184, v71, v71
	v_mul_f32_e32 v185, v67, v67
	v_add_f32_e32 v186, v182, v183
	v_add_f32_e32 v186, v186, v184
	v_add_f32_e32 v186, v186, v185
	s_nop 1
	v_add_f32_dpp v186, v186, v186 quad_perm:[1,0,3,2] row_mask:0xf bank_mask:0xf
	s_nop 1
	v_add_f32_dpp v186, v186, v186 quad_perm:[2,3,0,1] row_mask:0xf bank_mask:0xf
	s_nop 1
	v_add_f32_dpp v186, v186, v186 row_half_mirror row_mask:0xf bank_mask:0xf
	s_nop 1
	v_add_f32_dpp v186, v186, v186 row_mirror row_mask:0xf bank_mask:0xf
	v_fmamk_f32 v186, v186, 0x3c800000, v173
	v_rsq_f32_e32 v186, v186
	s_nop 0
	v_mul_f32_e32 v187, v178, v186
	v_mul_f32_e32 v188, v179, v186
	v_mul_f32_e32 v189, v180, v186
	v_mul_f32_e32 v190, v181, v186
	v_mul_f32_e32 v182, v79, v187
	v_mul_f32_e32 v183, v75, v188
	v_mul_f32_e32 v184, v71, v189
	v_mul_f32_e32 v185, v67, v190
	v_mul_f32_e32 v186, v175, v183
	v_mul_f32_e32 v187, v176, v183
	v_fma_f32 v188, v176, v182, -v186
	v_fma_f32 v189, v175, v182, v187
	v_mul_f32_e32 v186, v235, v185
	v_mul_f32_e32 v187, v251, v185
	v_fma_f32 v190, v251, v184, -v186
	v_fma_f32 v191, v235, v184, v187
	v_cvt_pk_bf16_f32 v192, v188, v189
	v_cvt_pk_bf16_f32 v193, v190, v191
	ds_write_b16 v170, v192 offset:7056
	ds_write_b16_d16_hi v170, v192 offset:7088
	ds_write_b16 v170, v193 offset:7120
	ds_write_b16_d16_hi v170, v193 offset:7152
	v_mul_f32_e32 v182, v80, v80
	v_mul_f32_e32 v183, v76, v76
	v_mul_f32_e32 v184, v72, v72
	v_mul_f32_e32 v185, v68, v68
	v_add_f32_e32 v186, v182, v183
	v_add_f32_e32 v186, v186, v184
	v_add_f32_e32 v186, v186, v185
	s_nop 1
	v_add_f32_dpp v186, v186, v186 quad_perm:[1,0,3,2] row_mask:0xf bank_mask:0xf
	s_nop 1
	v_add_f32_dpp v186, v186, v186 quad_perm:[2,3,0,1] row_mask:0xf bank_mask:0xf
	s_nop 1
	v_add_f32_dpp v186, v186, v186 row_half_mirror row_mask:0xf bank_mask:0xf
	s_nop 1
	v_add_f32_dpp v186, v186, v186 row_mirror row_mask:0xf bank_mask:0xf
	v_fmamk_f32 v186, v186, 0x3c800000, v173
	v_rsq_f32_e32 v186, v186
	s_nop 0
	v_mul_f32_e32 v187, v178, v186
	v_mul_f32_e32 v188, v179, v186
	v_mul_f32_e32 v189, v180, v186
	v_mul_f32_e32 v190, v181, v186
	v_mul_f32_e32 v182, v80, v187
	v_mul_f32_e32 v183, v76, v188
	v_mul_f32_e32 v184, v72, v189
	v_mul_f32_e32 v185, v68, v190
	v_mul_f32_e32 v186, v175, v183
	v_mul_f32_e32 v187, v176, v183
	v_fma_f32 v188, v176, v182, -v186
	v_fma_f32 v189, v175, v182, v187
	v_mul_f32_e32 v186, v236, v185
	v_mul_f32_e32 v187, v252, v185
	v_fma_f32 v190, v252, v184, -v186
	v_fma_f32 v191, v236, v184, v187
	v_cvt_pk_bf16_f32 v192, v188, v189
	v_cvt_pk_bf16_f32 v193, v190, v191
	ds_write_b16 v170, v192 offset:7200
	ds_write_b16_d16_hi v170, v192 offset:7232
	ds_write_b16 v170, v193 offset:7264
	ds_write_b16_d16_hi v170, v193 offset:7296
	v_mul_f32_e32 v182, v81, v81
	v_mul_f32_e32 v183, v77, v77
	v_mul_f32_e32 v184, v73, v73
	v_mul_f32_e32 v185, v69, v69
	v_add_f32_e32 v186, v182, v183
	v_add_f32_e32 v186, v186, v184
	v_add_f32_e32 v186, v186, v185
	s_nop 1
	v_add_f32_dpp v186, v186, v186 quad_perm:[1,0,3,2] row_mask:0xf bank_mask:0xf
	s_nop 1
	v_add_f32_dpp v186, v186, v186 quad_perm:[2,3,0,1] row_mask:0xf bank_mask:0xf
	s_nop 1
	v_add_f32_dpp v186, v186, v186 row_half_mirror row_mask:0xf bank_mask:0xf
	s_nop 1
	v_add_f32_dpp v186, v186, v186 row_mirror row_mask:0xf bank_mask:0xf
	v_fmamk_f32 v186, v186, 0x3c800000, v173
	v_rsq_f32_e32 v186, v186
	s_nop 0
	v_mul_f32_e32 v187, v178, v186
	v_mul_f32_e32 v188, v179, v186
	v_mul_f32_e32 v189, v180, v186
	v_mul_f32_e32 v190, v181, v186
	v_mul_f32_e32 v182, v81, v187
	v_mul_f32_e32 v183, v77, v188
	v_mul_f32_e32 v184, v73, v189
	v_mul_f32_e32 v185, v69, v190
	v_mul_f32_e32 v186, v175, v183
	v_mul_f32_e32 v187, v176, v183
	v_fma_f32 v188, v176, v182, -v186
	v_fma_f32 v189, v175, v182, v187
	v_mul_f32_e32 v186, v237, v185
	v_mul_f32_e32 v187, v253, v185
	v_fma_f32 v190, v253, v184, -v186
	v_fma_f32 v191, v237, v184, v187
	v_cvt_pk_bf16_f32 v192, v188, v189
	v_cvt_pk_bf16_f32 v193, v190, v191
	ds_write_b16 v170, v192 offset:7344
	ds_write_b16_d16_hi v170, v192 offset:7376
	ds_write_b16 v170, v193 offset:7408
	ds_write_b16_d16_hi v170, v193 offset:7440
	ds_read_b128 v[130:133], v171 offset:0
	ds_read_b128 v[134:137], v171 offset:1152
	ds_read_b128 v[138:141], v171 offset:2304
	ds_read_b128 v[142:145], v171 offset:3456
	ds_read_b128 v[146:149], v171 offset:4608
	ds_read_b128 v[150:153], v171 offset:5760
	ds_read_b128 v[154:157], v171 offset:6912
	ds_read_b128 v[158:161], v171 offset:8064
	s_waitcnt lgkmcnt(7)
; template <int EPI>
; DI void gemm_phase(const P& p, int l, const u16* __restrict__ A, const u16* __restrict__ Bt, int mpx, char* lds) {
;     ...
;           } else if (tr == 3) {
;             if (donorm) {
;               float ss = v0 * v0 + v1 * v1 + v2 * v2 + v3 * v3;
;               ss += __shfl_xor(ss, 1);
;               ss += __shfl_xor(ss, 2);
;               ss += __shfl_xor(ss, 4);
;               ss += __shfl_xor(ss, 8);
;               const float inv = rsqrtf(ss * (1.f / 64.f) + 1e-6f);
;               v0 *= inv * gv0; v1 *= inv * gv1; v2 *= inv * gv2; v3 *= inv * gv3;
;             }
;             if (dorope) {
;               float sr, cr, sc, cc;
;               sincos_rev((float)(s >> 6) * invf64, sr, cr);
;               sincos_rev((float)(s & 63) * invf64, sc, cc);
;               const float a1 = v0, a2 = v1, b1 = v2, b2 = v3;
;               v0 = a1 * cr - a2 * sr;
;               v1 = a2 * cr + a1 * sr;
;               v2 = b1 * cc - b2 * sc;
;               v3 = b2 * cc + b1 * sc;
;             }
;           } else if (tr == 4) {
;             float sr, cr, sc, cc;
;             sincos_rev((float)(s >> 6) * invf32, sr, cr);
;             sincos_rev((float)(s & 63) * invf32, sc, cc);
;             const float p0 = __shfl_xor(v0, 8), p1 = __shfl_xor(v1, 8), p2 = __shfl_xor(v2, 8), p3 = __shfl_xor(v3, 8);
;             v0 = lo8 ? (v0 * cr - p0 * sr) : (v0 * cr + p0 * sr);
;             v1 = lo8 ? (v1 * cc - p1 * sc) : (v1 * cc + p1 * sc);
;             v2 = lo8 ? (v2 * cr - p2 * sr) : (v2 * cr + p2 * sr);
;             v3 = lo8 ? (v3 * cc - p3 * sc) : (v3 * cc + p3 * sc);
;           }
;           const unsigned u01 = pack2(v0, v1), u23 = pack2(v2, v3);
;           if (kind == 1) {
;             Tl[(0 * 16 + r) * 72 + rowl] = (u16)u01;
;             Tl[(1 * 16 + r) * 72 + rowl] = (u16)(u01 >> 16);
;             Tl[(2 * 16 + r) * 72 + rowl] = (u16)u23;
;             Tl[(3 * 16 + r) * 72 + rowl] = (u16)(u23 >> 16);
;     ...
;       __builtin_amdgcn_fence(__ATOMIC_RELEASE, "wavefront");
;       u16* dh = (kind == 1) ? dst + hf * 64 : dst + (size_t)(hf * 64) * rstride;
; #pragma unroll
;       for (int i = 0; i < 8; ++i) {
;         const int c = lane + i * 64;
;         const int row = c >> 3, cc = c & 7;
;         uint4 v = *(const uint4*)&Tl[row * 72 + cc * 8];
;         *(uint4*)(dh + (size_t)row * rstride + cc * 8) = v;
;       }
	global_store_dwordx4 v172, v[130:133], s[44:45] offset:0 sc1
	s_waitcnt lgkmcnt(6)
	global_store_dwordx4 v172, v[134:137], s[44:45] offset:1024 sc1
	s_waitcnt lgkmcnt(5)
	global_store_dwordx4 v172, v[138:141], s[44:45] offset:2048 sc1
	s_waitcnt lgkmcnt(4)
	global_store_dwordx4 v172, v[142:145], s[44:45] offset:3072 sc1
	s_waitcnt lgkmcnt(3)
	global_store_dwordx4 v172, v[146:149], s[62:63] offset:0 sc1
	s_waitcnt lgkmcnt(2)
	global_store_dwordx4 v172, v[150:153], s[62:63] offset:1024 sc1
	s_waitcnt lgkmcnt(1)
	global_store_dwordx4 v172, v[154:157], s[62:63] offset:2048 sc1
	s_waitcnt lgkmcnt(0)
	global_store_dwordx4 v172, v[158:161], s[62:63] offset:3072 sc1
	s_add_u32 s44, s44, 0x2000
	s_addc_u32 s45, s45, 0
	s_add_u32 s62, s62, 0x2000
	s_addc_u32 s63, s63, 0
	s_lshr_b32 s70, s69, 6
	s_add_i32 s70, s70, 1
	v_cvt_f32_i32_e32 v182, s70
	v_mul_f32_e32 v182, v174, v182
	v_mul_f32_e32 v183, 0.15915494, v182
	v_rndne_f32_e32 v183, v183
	v_fma_f32 v183, v182, 0.15915494, -v183
	v_sin_f32_e32 v175, v183
	v_cos_f32_e32 v176, v183
	v_mul_f32_e32 v182, v62, v62
	v_mul_f32_e32 v183, v58, v58
	v_mul_f32_e32 v184, v54, v54
	v_mul_f32_e32 v185, v50, v50
	v_add_f32_e32 v186, v182, v183
	v_add_f32_e32 v186, v186, v184
	v_add_f32_e32 v186, v186, v185
	s_nop 1
	v_add_f32_dpp v186, v186, v186 quad_perm:[1,0,3,2] row_mask:0xf bank_mask:0xf
	s_nop 1
	v_add_f32_dpp v186, v186, v186 quad_perm:[2,3,0,1] row_mask:0xf bank_mask:0xf
	s_nop 1
	v_add_f32_dpp v186, v186, v186 row_half_mirror row_mask:0xf bank_mask:0xf
	s_nop 1
	v_add_f32_dpp v186, v186, v186 row_mirror row_mask:0xf bank_mask:0xf
	v_fmamk_f32 v186, v186, 0x3c800000, v173
	v_rsq_f32_e32 v186, v186
	s_nop 0
	v_mul_f32_e32 v187, v178, v186
	v_mul_f32_e32 v188, v179, v186
	v_mul_f32_e32 v189, v180, v186
	v_mul_f32_e32 v190, v181, v186
	v_mul_f32_e32 v182, v62, v187
	v_mul_f32_e32 v183, v58, v188
	v_mul_f32_e32 v184, v54, v189
	v_mul_f32_e32 v185, v50, v190
	v_mul_f32_e32 v186, v175, v183
	v_mul_f32_e32 v187, v176, v183
	v_fma_f32 v188, v176, v182, -v186
	v_fma_f32 v189, v175, v182, v187
	v_mul_f32_e32 v186, v212, v185
	v_mul_f32_e32 v187, v238, v185
	v_fma_f32 v190, v238, v184, -v186
	v_fma_f32 v191, v212, v184, v187
	v_cvt_pk_bf16_f32 v192, v188, v189
	v_cvt_pk_bf16_f32 v193, v190, v191
	ds_write_b16 v170, v192 offset:0
	ds_write_b16_d16_hi v170, v192 offset:32
	ds_write_b16 v170, v193 offset:64
	ds_write_b16_d16_hi v170, v193 offset:96
	v_mul_f32_e32 v182, v63, v63
	v_mul_f32_e32 v183, v59, v59
	v_mul_f32_e32 v184, v55, v55
	v_mul_f32_e32 v185, v51, v51
	v_add_f32_e32 v186, v182, v183
	v_add_f32_e32 v186, v186, v184
	v_add_f32_e32 v186, v186, v185
	s_nop 1
	v_add_f32_dpp v186, v186, v186 quad_perm:[1,0,3,2] row_mask:0xf bank_mask:0xf
	s_nop 1
	v_add_f32_dpp v186, v186, v186 quad_perm:[2,3,0,1] row_mask:0xf bank_mask:0xf
	s_nop 1
	v_add_f32_dpp v186, v186, v186 row_half_mirror row_mask:0xf bank_mask:0xf
	s_nop 1
	v_add_f32_dpp v186, v186, v186 row_mirror row_mask:0xf bank_mask:0xf
	v_fmamk_f32 v186, v186, 0x3c800000, v173
	v_rsq_f32_e32 v186, v186
	s_nop 0
	v_mul_f32_e32 v187, v178, v186
	v_mul_f32_e32 v188, v179, v186
	v_mul_f32_e32 v189, v180, v186
	v_mul_f32_e32 v190, v181, v186
	v_mul_f32_e32 v182, v63, v187
	v_mul_f32_e32 v183, v59, v188
	v_mul_f32_e32 v184, v55, v189
	v_mul_f32_e32 v185, v51, v190
	v_mul_f32_e32 v186, v175, v183
	v_mul_f32_e32 v187, v176, v183
	v_fma_f32 v188, v176, v182, -v186
	v_fma_f32 v189, v175, v182, v187
	v_mul_f32_e32 v186, v213, v185
	v_mul_f32_e32 v187, v239, v185
	v_fma_f32 v190, v239, v184, -v186
	v_fma_f32 v191, v213, v184, v187
	v_cvt_pk_bf16_f32 v192, v188, v189
	v_cvt_pk_bf16_f32 v193, v190, v191
	ds_write_b16 v170, v192 offset:144
	ds_write_b16_d16_hi v170, v192 offset:176
	ds_write_b16 v170, v193 offset:208
	ds_write_b16_d16_hi v170, v193 offset:240
	v_mul_f32_e32 v182, v64, v64
	v_mul_f32_e32 v183, v60, v60
	v_mul_f32_e32 v184, v56, v56
	v_mul_f32_e32 v185, v52, v52
	v_add_f32_e32 v186, v182, v183
	v_add_f32_e32 v186, v186, v184
	v_add_f32_e32 v186, v186, v185
	s_nop 1
	v_add_f32_dpp v186, v186, v186 quad_perm:[1,0,3,2] row_mask:0xf bank_mask:0xf
	s_nop 1
	v_add_f32_dpp v186, v186, v186 quad_perm:[2,3,0,1] row_mask:0xf bank_mask:0xf
	s_nop 1
	v_add_f32_dpp v186, v186, v186 row_half_mirror row_mask:0xf bank_mask:0xf
	s_nop 1
	v_add_f32_dpp v186, v186, v186 row_mirror row_mask:0xf bank_mask:0xf
	v_fmamk_f32 v186, v186, 0x3c800000, v173
	v_rsq_f32_e32 v186, v186
	s_nop 0
	v_mul_f32_e32 v187, v178, v186
	v_mul_f32_e32 v188, v179, v186
	v_mul_f32_e32 v189, v180, v186
	v_mul_f32_e32 v190, v181, v186
	v_mul_f32_e32 v182, v64, v187
	v_mul_f32_e32 v183, v60, v188
	v_mul_f32_e32 v184, v56, v189
	v_mul_f32_e32 v185, v52, v190
	v_mul_f32_e32 v186, v175, v183
	v_mul_f32_e32 v187, v176, v183
	v_fma_f32 v188, v176, v182, -v186
	v_fma_f32 v189, v175, v182, v187
	v_mul_f32_e32 v186, v214, v185
	v_mul_f32_e32 v187, v240, v185
	v_fma_f32 v190, v240, v184, -v186
	v_fma_f32 v191, v214, v184, v187
	v_cvt_pk_bf16_f32 v192, v188, v189
	v_cvt_pk_bf16_f32 v193, v190, v191
	ds_write_b16 v170, v192 offset:288
	ds_write_b16_d16_hi v170, v192 offset:320
	ds_write_b16 v170, v193 offset:352
	ds_write_b16_d16_hi v170, v193 offset:384
	v_mul_f32_e32 v182, v65, v65
	v_mul_f32_e32 v183, v61, v61
	v_mul_f32_e32 v184, v57, v57
	v_mul_f32_e32 v185, v53, v53
	v_add_f32_e32 v186, v182, v183
	v_add_f32_e32 v186, v186, v184
	v_add_f32_e32 v186, v186, v185
	s_nop 1
	v_add_f32_dpp v186, v186, v186 quad_perm:[1,0,3,2] row_mask:0xf bank_mask:0xf
	s_nop 1
	v_add_f32_dpp v186, v186, v186 quad_perm:[2,3,0,1] row_mask:0xf bank_mask:0xf
	s_nop 1
	v_add_f32_dpp v186, v186, v186 row_half_mirror row_mask:0xf bank_mask:0xf
; template <int EPI>
; DI void gemm_phase(const P& p, int l, const u16* __restrict__ A, const u16* __restrict__ Bt, int mpx, char* lds) {
;     ...
;           } else if (tr == 3) {
;             if (donorm) {
;               float ss = v0 * v0 + v1 * v1 + v2 * v2 + v3 * v3;
;               ss += __shfl_xor(ss, 1);
;               ss += __shfl_xor(ss, 2);
;               ss += __shfl_xor(ss, 4);
;               ss += __shfl_xor(ss, 8);
;               const float inv = rsqrtf(ss * (1.f / 64.f) + 1e-6f);
;               v0 *= inv * gv0; v1 *= inv * gv1; v2 *= inv * gv2; v3 *= inv * gv3;
;             }
;             if (dorope) {
;               float sr, cr, sc, cc;
;               sincos_rev((float)(s >> 6) * invf64, sr, cr);
;               sincos_rev((float)(s & 63) * invf64, sc, cc);
;               const float a1 = v0, a2 = v1, b1 = v2, b2 = v3;
;               v0 = a1 * cr - a2 * sr;
;               v1 = a2 * cr + a1 * sr;
;               v2 = b1 * cc - b2 * sc;
;               v3 = b2 * cc + b1 * sc;
;             }
;           } else if (tr == 4) {
;             float sr, cr, sc, cc;
;             sincos_rev((float)(s >> 6) * invf32, sr, cr);
;             sincos_rev((float)(s & 63) * invf32, sc, cc);
;             const float p0 = __shfl_xor(v0, 8), p1 = __shfl_xor(v1, 8), p2 = __shfl_xor(v2, 8), p3 = __shfl_xor(v3, 8);
;             v0 = lo8 ? (v0 * cr - p0 * sr) : (v0 * cr + p0 * sr);
;             v1 = lo8 ? (v1 * cc - p1 * sc) : (v1 * cc + p1 * sc);
;             v2 = lo8 ? (v2 * cr - p2 * sr) : (v2 * cr + p2 * sr);
;             v3 = lo8 ? (v3 * cc - p3 * sc) : (v3 * cc + p3 * sc);
;           }
;           const unsigned u01 = pack2(v0, v1), u23 = pack2(v2, v3);
;           if (kind == 1) {
;             Tl[(0 * 16 + r) * 72 + rowl] = (u16)u01;
;             Tl[(1 * 16 + r) * 72 + rowl] = (u16)(u01 >> 16);
;             Tl[(2 * 16 + r) * 72 + rowl] = (u16)u23;
;             Tl[(3 * 16 + r) * 72 + rowl] = (u16)(u23 >> 16);
;           } else if (tr == 2) {
;             Tl[rowl * 72 + 0 * 16 + r] = f2h(v0);
;             Tl[rowl * 72 + 1 * 16 + r] = f2h(v1);
;             Tl[rowl * 72 + 2 * 16 + r] = f2h(v2);
;             Tl[rowl * 72 + 3 * 16 + r] = f2h(v3);
;           } else {
;             Tl[rowl * 72 + 0 * 16 + r] = (u16)u01;
;             Tl[rowl * 72 + 1 * 16 + r] = (u16)(u01 >> 16);
;             Tl[rowl * 72 + 2 * 16 + r] = (u16)u23;
	s_nop 1
	v_add_f32_dpp v186, v186, v186 row_mirror row_mask:0xf bank_mask:0xf
	v_fmamk_f32 v186, v186, 0x3c800000, v173
	v_rsq_f32_e32 v186, v186
	s_nop 0
	v_mul_f32_e32 v187, v178, v186
	v_mul_f32_e32 v188, v179, v186
	v_mul_f32_e32 v189, v180, v186
	v_mul_f32_e32 v190, v181, v186
	v_mul_f32_e32 v182, v65, v187
	v_mul_f32_e32 v183, v61, v188
	v_mul_f32_e32 v184, v57, v189
	v_mul_f32_e32 v185, v53, v190
	v_mul_f32_e32 v186, v175, v183
	v_mul_f32_e32 v187, v176, v183
	v_fma_f32 v188, v176, v182, -v186
	v_fma_f32 v189, v175, v182, v187
	v_mul_f32_e32 v186, v215, v185
	v_mul_f32_e32 v187, v241, v185
	v_fma_f32 v190, v241, v184, -v186
	v_fma_f32 v191, v215, v184, v187
	v_cvt_pk_bf16_f32 v192, v188, v189
	v_cvt_pk_bf16_f32 v193, v190, v191
	ds_write_b16 v170, v192 offset:432
	ds_write_b16_d16_hi v170, v192 offset:464
	ds_write_b16 v170, v193 offset:496
	ds_write_b16_d16_hi v170, v193 offset:528
	v_mul_f32_e32 v182, v46, v46
	v_mul_f32_e32 v183, v42, v42
	v_mul_f32_e32 v184, v38, v38
	v_mul_f32_e32 v185, v34, v34
	v_add_f32_e32 v186, v182, v183
	v_add_f32_e32 v186, v186, v184
	v_add_f32_e32 v186, v186, v185
	s_nop 1
	v_add_f32_dpp v186, v186, v186 quad_perm:[1,0,3,2] row_mask:0xf bank_mask:0xf
	s_nop 1
	v_add_f32_dpp v186, v186, v186 quad_perm:[2,3,0,1] row_mask:0xf bank_mask:0xf
	s_nop 1
	v_add_f32_dpp v186, v186, v186 row_half_mirror row_mask:0xf bank_mask:0xf
	s_nop 1
	v_add_f32_dpp v186, v186, v186 row_mirror row_mask:0xf bank_mask:0xf
	v_fmamk_f32 v186, v186, 0x3c800000, v173
	v_rsq_f32_e32 v186, v186
	s_nop 0
	v_mul_f32_e32 v187, v178, v186
	v_mul_f32_e32 v188, v179, v186
	v_mul_f32_e32 v189, v180, v186
	v_mul_f32_e32 v190, v181, v186
	v_mul_f32_e32 v182, v46, v187
	v_mul_f32_e32 v183, v42, v188
	v_mul_f32_e32 v184, v38, v189
	v_mul_f32_e32 v185, v34, v190
	v_mul_f32_e32 v186, v175, v183
	v_mul_f32_e32 v187, v176, v183
	v_fma_f32 v188, v176, v182, -v186
	v_fma_f32 v189, v175, v182, v187
	v_mul_f32_e32 v186, v216, v185
	v_mul_f32_e32 v187, v242, v185
	v_fma_f32 v190, v242, v184, -v186
	v_fma_f32 v191, v216, v184, v187
	v_cvt_pk_bf16_f32 v192, v188, v189
	v_cvt_pk_bf16_f32 v193, v190, v191
	ds_write_b16 v170, v192 offset:2304
	ds_write_b16_d16_hi v170, v192 offset:2336
	ds_write_b16 v170, v193 offset:2368
	ds_write_b16_d16_hi v170, v193 offset:2400
	v_mul_f32_e32 v182, v47, v47
	v_mul_f32_e32 v183, v43, v43
	v_mul_f32_e32 v184, v39, v39
	v_mul_f32_e32 v185, v35, v35
	v_add_f32_e32 v186, v182, v183
	v_add_f32_e32 v186, v186, v184
	v_add_f32_e32 v186, v186, v185
	s_nop 1
	v_add_f32_dpp v186, v186, v186 quad_perm:[1,0,3,2] row_mask:0xf bank_mask:0xf
	s_nop 1
	v_add_f32_dpp v186, v186, v186 quad_perm:[2,3,0,1] row_mask:0xf bank_mask:0xf
	s_nop 1
	v_add_f32_dpp v186, v186, v186 row_half_mirror row_mask:0xf bank_mask:0xf
	s_nop 1
	v_add_f32_dpp v186, v186, v186 row_mirror row_mask:0xf bank_mask:0xf
	v_fmamk_f32 v186, v186, 0x3c800000, v173
	v_rsq_f32_e32 v186, v186
	s_nop 0
	v_mul_f32_e32 v187, v178, v186
	v_mul_f32_e32 v188, v179, v186
	v_mul_f32_e32 v189, v180, v186
	v_mul_f32_e32 v190, v181, v186
	v_mul_f32_e32 v182, v47, v187
	v_mul_f32_e32 v183, v43, v188
	v_mul_f32_e32 v184, v39, v189
	v_mul_f32_e32 v185, v35, v190
	v_mul_f32_e32 v186, v175, v183
	v_mul_f32_e32 v187, v176, v183
	v_fma_f32 v188, v176, v182, -v186
	v_fma_f32 v189, v175, v182, v187
	v_mul_f32_e32 v186, v217, v185
	v_mul_f32_e32 v187, v243, v185
	v_fma_f32 v190, v243, v184, -v186
	v_fma_f32 v191, v217, v184, v187
	v_cvt_pk_bf16_f32 v192, v188, v189
	v_cvt_pk_bf16_f32 v193, v190, v191
	ds_write_b16 v170, v192 offset:2448
	ds_write_b16_d16_hi v170, v192 offset:2480
	ds_write_b16 v170, v193 offset:2512
	ds_write_b16_d16_hi v170, v193 offset:2544
	v_mul_f32_e32 v182, v48, v48
	v_mul_f32_e32 v183, v44, v44
	v_mul_f32_e32 v184, v40, v40
	v_mul_f32_e32 v185, v36, v36
	v_add_f32_e32 v186, v182, v183
	v_add_f32_e32 v186, v186, v184
	v_add_f32_e32 v186, v186, v185
	s_nop 1
	v_add_f32_dpp v186, v186, v186 quad_perm:[1,0,3,2] row_mask:0xf bank_mask:0xf
	s_nop 1
	v_add_f32_dpp v186, v186, v186 quad_perm:[2,3,0,1] row_mask:0xf bank_mask:0xf
	s_nop 1
	v_add_f32_dpp v186, v186, v186 row_half_mirror row_mask:0xf bank_mask:0xf
	s_nop 1
	v_add_f32_dpp v186, v186, v186 row_mirror row_mask:0xf bank_mask:0xf
	v_fmamk_f32 v186, v186, 0x3c800000, v173
	v_rsq_f32_e32 v186, v186
	s_nop 0
	v_mul_f32_e32 v187, v178, v186
	v_mul_f32_e32 v188, v179, v186
	v_mul_f32_e32 v189, v180, v186
	v_mul_f32_e32 v190, v181, v186
	v_mul_f32_e32 v182, v48, v187
	v_mul_f32_e32 v183, v44, v188
	v_mul_f32_e32 v184, v40, v189
	v_mul_f32_e32 v185, v36, v190
	v_mul_f32_e32 v186, v175, v183
	v_mul_f32_e32 v187, v176, v183
	v_fma_f32 v188, v176, v182, -v186
	v_fma_f32 v189, v175, v182, v187
	v_mul_f32_e32 v186, v218, v185
	v_mul_f32_e32 v187, v244, v185
	v_fma_f32 v190, v244, v184, -v186
	v_fma_f32 v191, v218, v184, v187
	v_cvt_pk_bf16_f32 v192, v188, v189
	v_cvt_pk_bf16_f32 v193, v190, v191
	ds_write_b16 v170, v192 offset:2592
	ds_write_b16_d16_hi v170, v192 offset:2624
	ds_write_b16 v170, v193 offset:2656
	ds_write_b16_d16_hi v170, v193 offset:2688
	v_mul_f32_e32 v182, v49, v49
	v_mul_f32_e32 v183, v45, v45
	v_mul_f32_e32 v184, v41, v41
	v_mul_f32_e32 v185, v37, v37
	v_add_f32_e32 v186, v182, v183
	v_add_f32_e32 v186, v186, v184
	v_add_f32_e32 v186, v186, v185
	s_nop 1
	v_add_f32_dpp v186, v186, v186 quad_perm:[1,0,3,2] row_mask:0xf bank_mask:0xf
	s_nop 1
	v_add_f32_dpp v186, v186, v186 quad_perm:[2,3,0,1] row_mask:0xf bank_mask:0xf
	s_nop 1
	v_add_f32_dpp v186, v186, v186 row_half_mirror row_mask:0xf bank_mask:0xf
	s_nop 1
	v_add_f32_dpp v186, v186, v186 row_mirror row_mask:0xf bank_mask:0xf
	v_fmamk_f32 v186, v186, 0x3c800000, v173
; template <int EPI>
; DI void gemm_phase(const P& p, int l, const u16* __restrict__ A, const u16* __restrict__ Bt, int mpx, char* lds) {
;     ...
;           } else if (tr == 3) {
;             if (donorm) {
;               float ss = v0 * v0 + v1 * v1 + v2 * v2 + v3 * v3;
;               ss += __shfl_xor(ss, 1);
;               ss += __shfl_xor(ss, 2);
;               ss += __shfl_xor(ss, 4);
;               ss += __shfl_xor(ss, 8);
;               const float inv = rsqrtf(ss * (1.f / 64.f) + 1e-6f);
;               v0 *= inv * gv0; v1 *= inv * gv1; v2 *= inv * gv2; v3 *= inv * gv3;
;             }
;             if (dorope) {
;               float sr, cr, sc, cc;
;               sincos_rev((float)(s >> 6) * invf64, sr, cr);
;               sincos_rev((float)(s & 63) * invf64, sc, cc);
;               const float a1 = v0, a2 = v1, b1 = v2, b2 = v3;
;               v0 = a1 * cr - a2 * sr;
;               v1 = a2 * cr + a1 * sr;
;               v2 = b1 * cc - b2 * sc;
;               v3 = b2 * cc + b1 * sc;
;             }
;           } else if (tr == 4) {
;             float sr, cr, sc, cc;
;             sincos_rev((float)(s >> 6) * invf32, sr, cr);
;             sincos_rev((float)(s & 63) * invf32, sc, cc);
;             const float p0 = __shfl_xor(v0, 8), p1 = __shfl_xor(v1, 8), p2 = __shfl_xor(v2, 8), p3 = __shfl_xor(v3, 8);
;             v0 = lo8 ? (v0 * cr - p0 * sr) : (v0 * cr + p0 * sr);
;             v1 = lo8 ? (v1 * cc - p1 * sc) : (v1 * cc + p1 * sc);
;             v2 = lo8 ? (v2 * cr - p2 * sr) : (v2 * cr + p2 * sr);
;             v3 = lo8 ? (v3 * cc - p3 * sc) : (v3 * cc + p3 * sc);
;           }
;           const unsigned u01 = pack2(v0, v1), u23 = pack2(v2, v3);
;           if (kind == 1) {
;             Tl[(0 * 16 + r) * 72 + rowl] = (u16)u01;
;             Tl[(1 * 16 + r) * 72 + rowl] = (u16)(u01 >> 16);
;             Tl[(2 * 16 + r) * 72 + rowl] = (u16)u23;
;             Tl[(3 * 16 + r) * 72 + rowl] = (u16)(u23 >> 16);
;           } else if (tr == 2) {
;             Tl[rowl * 72 + 0 * 16 + r] = f2h(v0);
;             Tl[rowl * 72 + 1 * 16 + r] = f2h(v1);
;             Tl[rowl * 72 + 2 * 16 + r] = f2h(v2);
;             Tl[rowl * 72 + 3 * 16 + r] = f2h(v3);
;           } else {
;             Tl[rowl * 72 + 0 * 16 + r] = (u16)u01;
;             Tl[rowl * 72 + 1 * 16 + r] = (u16)(u01 >> 16);
;             Tl[rowl * 72 + 2 * 16 + r] = (u16)u23;
	v_rsq_f32_e32 v186, v186
	s_nop 0
	v_mul_f32_e32 v187, v178, v186
	v_mul_f32_e32 v188, v179, v186
	v_mul_f32_e32 v189, v180, v186
	v_mul_f32_e32 v190, v181, v186
	v_mul_f32_e32 v182, v49, v187
	v_mul_f32_e32 v183, v45, v188
	v_mul_f32_e32 v184, v41, v189
	v_mul_f32_e32 v185, v37, v190
	v_mul_f32_e32 v186, v175, v183
	v_mul_f32_e32 v187, v176, v183
	v_fma_f32 v188, v176, v182, -v186
	v_fma_f32 v189, v175, v182, v187
	v_mul_f32_e32 v186, v219, v185
	v_mul_f32_e32 v187, v245, v185
	v_fma_f32 v190, v245, v184, -v186
	v_fma_f32 v191, v219, v184, v187
	v_cvt_pk_bf16_f32 v192, v188, v189
	v_cvt_pk_bf16_f32 v193, v190, v191
	ds_write_b16 v170, v192 offset:2736
	ds_write_b16_d16_hi v170, v192 offset:2768
	ds_write_b16 v170, v193 offset:2800
	ds_write_b16_d16_hi v170, v193 offset:2832
	v_mul_f32_e32 v182, v30, v30
	v_mul_f32_e32 v183, v26, v26
	v_mul_f32_e32 v184, v22, v22
	v_mul_f32_e32 v185, v18, v18
	v_add_f32_e32 v186, v182, v183
	v_add_f32_e32 v186, v186, v184
	v_add_f32_e32 v186, v186, v185
	s_nop 1
	v_add_f32_dpp v186, v186, v186 quad_perm:[1,0,3,2] row_mask:0xf bank_mask:0xf
	s_nop 1
	v_add_f32_dpp v186, v186, v186 quad_perm:[2,3,0,1] row_mask:0xf bank_mask:0xf
	s_nop 1
	v_add_f32_dpp v186, v186, v186 row_half_mirror row_mask:0xf bank_mask:0xf
	s_nop 1
	v_add_f32_dpp v186, v186, v186 row_mirror row_mask:0xf bank_mask:0xf
	v_fmamk_f32 v186, v186, 0x3c800000, v173
	v_rsq_f32_e32 v186, v186
	s_nop 0
	v_mul_f32_e32 v187, v178, v186
	v_mul_f32_e32 v188, v179, v186
	v_mul_f32_e32 v189, v180, v186
	v_mul_f32_e32 v190, v181, v186
	v_mul_f32_e32 v182, v30, v187
	v_mul_f32_e32 v183, v26, v188
	v_mul_f32_e32 v184, v22, v189
	v_mul_f32_e32 v185, v18, v190
	v_mul_f32_e32 v186, v175, v183
	v_mul_f32_e32 v187, v176, v183
	v_fma_f32 v188, v176, v182, -v186
	v_fma_f32 v189, v175, v182, v187
	v_mul_f32_e32 v186, v220, v185
	v_mul_f32_e32 v187, v246, v185
	v_fma_f32 v190, v246, v184, -v186
	v_fma_f32 v191, v220, v184, v187
	v_cvt_pk_bf16_f32 v192, v188, v189
	v_cvt_pk_bf16_f32 v193, v190, v191
	ds_write_b16 v170, v192 offset:4608
	ds_write_b16_d16_hi v170, v192 offset:4640
	ds_write_b16 v170, v193 offset:4672
	ds_write_b16_d16_hi v170, v193 offset:4704
	v_mul_f32_e32 v182, v31, v31
	v_mul_f32_e32 v183, v27, v27
	v_mul_f32_e32 v184, v23, v23
	v_mul_f32_e32 v185, v19, v19
	v_add_f32_e32 v186, v182, v183
	v_add_f32_e32 v186, v186, v184
	v_add_f32_e32 v186, v186, v185
	s_nop 1
	v_add_f32_dpp v186, v186, v186 quad_perm:[1,0,3,2] row_mask:0xf bank_mask:0xf
	s_nop 1
	v_add_f32_dpp v186, v186, v186 quad_perm:[2,3,0,1] row_mask:0xf bank_mask:0xf
	s_nop 1
	v_add_f32_dpp v186, v186, v186 row_half_mirror row_mask:0xf bank_mask:0xf
	s_nop 1
	v_add_f32_dpp v186, v186, v186 row_mirror row_mask:0xf bank_mask:0xf
	v_fmamk_f32 v186, v186, 0x3c800000, v173
	v_rsq_f32_e32 v186, v186
	s_nop 0
	v_mul_f32_e32 v187, v178, v186
	v_mul_f32_e32 v188, v179, v186
	v_mul_f32_e32 v189, v180, v186
	v_mul_f32_e32 v190, v181, v186
	v_mul_f32_e32 v182, v31, v187
	v_mul_f32_e32 v183, v27, v188
	v_mul_f32_e32 v184, v23, v189
	v_mul_f32_e32 v185, v19, v190
	v_mul_f32_e32 v186, v175, v183
	v_mul_f32_e32 v187, v176, v183
	v_fma_f32 v188, v176, v182, -v186
	v_fma_f32 v189, v175, v182, v187
	v_mul_f32_e32 v186, v221, v185
	v_mul_f32_e32 v187, v247, v185
	v_fma_f32 v190, v247, v184, -v186
	v_fma_f32 v191, v221, v184, v187
	v_cvt_pk_bf16_f32 v192, v188, v189
	v_cvt_pk_bf16_f32 v193, v190, v191
	ds_write_b16 v170, v192 offset:4752
	ds_write_b16_d16_hi v170, v192 offset:4784
	ds_write_b16 v170, v193 offset:4816
	ds_write_b16_d16_hi v170, v193 offset:4848
	v_mul_f32_e32 v182, v32, v32
	v_mul_f32_e32 v183, v28, v28
	v_mul_f32_e32 v184, v24, v24
	v_mul_f32_e32 v185, v20, v20
	v_add_f32_e32 v186, v182, v183
	v_add_f32_e32 v186, v186, v184
	v_add_f32_e32 v186, v186, v185
	s_nop 1
	v_add_f32_dpp v186, v186, v186 quad_perm:[1,0,3,2] row_mask:0xf bank_mask:0xf
	s_nop 1
	v_add_f32_dpp v186, v186, v186 quad_perm:[2,3,0,1] row_mask:0xf bank_mask:0xf
	s_nop 1
	v_add_f32_dpp v186, v186, v186 row_half_mirror row_mask:0xf bank_mask:0xf
	s_nop 1
	v_add_f32_dpp v186, v186, v186 row_mirror row_mask:0xf bank_mask:0xf
	v_fmamk_f32 v186, v186, 0x3c800000, v173
	v_rsq_f32_e32 v186, v186
	s_nop 0
	v_mul_f32_e32 v187, v178, v186
	v_mul_f32_e32 v188, v179, v186
	v_mul_f32_e32 v189, v180, v186
	v_mul_f32_e32 v190, v181, v186
	v_mul_f32_e32 v182, v32, v187
	v_mul_f32_e32 v183, v28, v188
	v_mul_f32_e32 v184, v24, v189
	v_mul_f32_e32 v185, v20, v190
	v_mul_f32_e32 v186, v175, v183
	v_mul_f32_e32 v187, v176, v183
	v_fma_f32 v188, v176, v182, -v186
	v_fma_f32 v189, v175, v182, v187
	v_mul_f32_e32 v186, v222, v185
	v_mul_f32_e32 v187, v248, v185
	v_fma_f32 v190, v248, v184, -v186
	v_fma_f32 v191, v222, v184, v187
	v_cvt_pk_bf16_f32 v192, v188, v189
	v_cvt_pk_bf16_f32 v193, v190, v191
	ds_write_b16 v170, v192 offset:4896
	ds_write_b16_d16_hi v170, v192 offset:4928
	ds_write_b16 v170, v193 offset:4960
	ds_write_b16_d16_hi v170, v193 offset:4992
	v_mul_f32_e32 v182, v33, v33
	v_mul_f32_e32 v183, v29, v29
	v_mul_f32_e32 v184, v25, v25
	v_mul_f32_e32 v185, v21, v21
	v_add_f32_e32 v186, v182, v183
	v_add_f32_e32 v186, v186, v184
	v_add_f32_e32 v186, v186, v185
	s_nop 1
	v_add_f32_dpp v186, v186, v186 quad_perm:[1,0,3,2] row_mask:0xf bank_mask:0xf
	s_nop 1
	v_add_f32_dpp v186, v186, v186 quad_perm:[2,3,0,1] row_mask:0xf bank_mask:0xf
	s_nop 1
	v_add_f32_dpp v186, v186, v186 row_half_mirror row_mask:0xf bank_mask:0xf
	s_nop 1
	v_add_f32_dpp v186, v186, v186 row_mirror row_mask:0xf bank_mask:0xf
	v_fmamk_f32 v186, v186, 0x3c800000, v173
	v_rsq_f32_e32 v186, v186
	s_nop 0
	v_mul_f32_e32 v187, v178, v186
	v_mul_f32_e32 v188, v179, v186
; template <int EPI>
; DI void gemm_phase(const P& p, int l, const u16* __restrict__ A, const u16* __restrict__ Bt, int mpx, char* lds) {
;     ...
;           } else if (tr == 3) {
;             if (donorm) {
;               float ss = v0 * v0 + v1 * v1 + v2 * v2 + v3 * v3;
;               ss += __shfl_xor(ss, 1);
;               ss += __shfl_xor(ss, 2);
;               ss += __shfl_xor(ss, 4);
;               ss += __shfl_xor(ss, 8);
;               const float inv = rsqrtf(ss * (1.f / 64.f) + 1e-6f);
;               v0 *= inv * gv0; v1 *= inv * gv1; v2 *= inv * gv2; v3 *= inv * gv3;
;             }
;             if (dorope) {
;               float sr, cr, sc, cc;
;               sincos_rev((float)(s >> 6) * invf64, sr, cr);
;               sincos_rev((float)(s & 63) * invf64, sc, cc);
;               const float a1 = v0, a2 = v1, b1 = v2, b2 = v3;
;               v0 = a1 * cr - a2 * sr;
;               v1 = a2 * cr + a1 * sr;
;               v2 = b1 * cc - b2 * sc;
;               v3 = b2 * cc + b1 * sc;
;             }
;           } else if (tr == 4) {
;             float sr, cr, sc, cc;
;             sincos_rev((float)(s >> 6) * invf32, sr, cr);
;             sincos_rev((float)(s & 63) * invf32, sc, cc);
;             const float p0 = __shfl_xor(v0, 8), p1 = __shfl_xor(v1, 8), p2 = __shfl_xor(v2, 8), p3 = __shfl_xor(v3, 8);
;             v0 = lo8 ? (v0 * cr - p0 * sr) : (v0 * cr + p0 * sr);
;             v1 = lo8 ? (v1 * cc - p1 * sc) : (v1 * cc + p1 * sc);
;             v2 = lo8 ? (v2 * cr - p2 * sr) : (v2 * cr + p2 * sr);
;             v3 = lo8 ? (v3 * cc - p3 * sc) : (v3 * cc + p3 * sc);
;           }
;           const unsigned u01 = pack2(v0, v1), u23 = pack2(v2, v3);
;           if (kind == 1) {
;             Tl[(0 * 16 + r) * 72 + rowl] = (u16)u01;
;             Tl[(1 * 16 + r) * 72 + rowl] = (u16)(u01 >> 16);
;             Tl[(2 * 16 + r) * 72 + rowl] = (u16)u23;
;             Tl[(3 * 16 + r) * 72 + rowl] = (u16)(u23 >> 16);
;           } else if (tr == 2) {
;             Tl[rowl * 72 + 0 * 16 + r] = f2h(v0);
;             Tl[rowl * 72 + 1 * 16 + r] = f2h(v1);
;             Tl[rowl * 72 + 2 * 16 + r] = f2h(v2);
;             Tl[rowl * 72 + 3 * 16 + r] = f2h(v3);
;           } else {
;             Tl[rowl * 72 + 0 * 16 + r] = (u16)u01;
;             Tl[rowl * 72 + 1 * 16 + r] = (u16)(u01 >> 16);
;             Tl[rowl * 72 + 2 * 16 + r] = (u16)u23;
	v_mul_f32_e32 v189, v180, v186
	v_mul_f32_e32 v190, v181, v186
	v_mul_f32_e32 v182, v33, v187
	v_mul_f32_e32 v183, v29, v188
	v_mul_f32_e32 v184, v25, v189
	v_mul_f32_e32 v185, v21, v190
	v_mul_f32_e32 v186, v175, v183
	v_mul_f32_e32 v187, v176, v183
	v_fma_f32 v188, v176, v182, -v186
	v_fma_f32 v189, v175, v182, v187
	v_mul_f32_e32 v186, v223, v185
	v_mul_f32_e32 v187, v249, v185
	v_fma_f32 v190, v249, v184, -v186
	v_fma_f32 v191, v223, v184, v187
	v_cvt_pk_bf16_f32 v192, v188, v189
	v_cvt_pk_bf16_f32 v193, v190, v191
	ds_write_b16 v170, v192 offset:5040
	ds_write_b16_d16_hi v170, v192 offset:5072
	ds_write_b16 v170, v193 offset:5104
	ds_write_b16_d16_hi v170, v193 offset:5136
	v_mul_f32_e32 v182, v166, v166
	v_mul_f32_e32 v183, v162, v162
	v_mul_f32_e32 v184, v2, v2
	v_mul_f32_e32 v185, v6, v6
	v_add_f32_e32 v186, v182, v183
	v_add_f32_e32 v186, v186, v184
	v_add_f32_e32 v186, v186, v185
	s_nop 1
	v_add_f32_dpp v186, v186, v186 quad_perm:[1,0,3,2] row_mask:0xf bank_mask:0xf
	s_nop 1
	v_add_f32_dpp v186, v186, v186 quad_perm:[2,3,0,1] row_mask:0xf bank_mask:0xf
	s_nop 1
	v_add_f32_dpp v186, v186, v186 row_half_mirror row_mask:0xf bank_mask:0xf
	s_nop 1
	v_add_f32_dpp v186, v186, v186 row_mirror row_mask:0xf bank_mask:0xf
	v_fmamk_f32 v186, v186, 0x3c800000, v173
	v_rsq_f32_e32 v186, v186
	s_nop 0
	v_mul_f32_e32 v187, v178, v186
	v_mul_f32_e32 v188, v179, v186
	v_mul_f32_e32 v189, v180, v186
	v_mul_f32_e32 v190, v181, v186
	v_mul_f32_e32 v182, v166, v187
	v_mul_f32_e32 v183, v162, v188
	v_mul_f32_e32 v184, v2, v189
	v_mul_f32_e32 v185, v6, v190
	v_mul_f32_e32 v186, v175, v183
	v_mul_f32_e32 v187, v176, v183
	v_fma_f32 v188, v176, v182, -v186
	v_fma_f32 v189, v175, v182, v187
	v_mul_f32_e32 v186, v234, v185
	v_mul_f32_e32 v187, v250, v185
	v_fma_f32 v190, v250, v184, -v186
	v_fma_f32 v191, v234, v184, v187
	v_cvt_pk_bf16_f32 v192, v188, v189
	v_cvt_pk_bf16_f32 v193, v190, v191
	ds_write_b16 v170, v192 offset:6912
	ds_write_b16_d16_hi v170, v192 offset:6944
	ds_write_b16 v170, v193 offset:6976
	ds_write_b16_d16_hi v170, v193 offset:7008
	v_mul_f32_e32 v182, v167, v167
	v_mul_f32_e32 v183, v163, v163
	v_mul_f32_e32 v184, v3, v3
	v_mul_f32_e32 v185, v7, v7
	v_add_f32_e32 v186, v182, v183
	v_add_f32_e32 v186, v186, v184
	v_add_f32_e32 v186, v186, v185
	s_nop 1
	v_add_f32_dpp v186, v186, v186 quad_perm:[1,0,3,2] row_mask:0xf bank_mask:0xf
	s_nop 1
	v_add_f32_dpp v186, v186, v186 quad_perm:[2,3,0,1] row_mask:0xf bank_mask:0xf
	s_nop 1
	v_add_f32_dpp v186, v186, v186 row_half_mirror row_mask:0xf bank_mask:0xf
	s_nop 1
	v_add_f32_dpp v186, v186, v186 row_mirror row_mask:0xf bank_mask:0xf
	v_fmamk_f32 v186, v186, 0x3c800000, v173
	v_rsq_f32_e32 v186, v186
	s_nop 0
	v_mul_f32_e32 v187, v178, v186
	v_mul_f32_e32 v188, v179, v186
	v_mul_f32_e32 v189, v180, v186
	v_mul_f32_e32 v190, v181, v186
	v_mul_f32_e32 v182, v167, v187
	v_mul_f32_e32 v183, v163, v188
	v_mul_f32_e32 v184, v3, v189
	v_mul_f32_e32 v185, v7, v190
	v_mul_f32_e32 v186, v175, v183
	v_mul_f32_e32 v187, v176, v183
	v_fma_f32 v188, v176, v182, -v186
	v_fma_f32 v189, v175, v182, v187
	v_mul_f32_e32 v186, v235, v185
	v_mul_f32_e32 v187, v251, v185
	v_fma_f32 v190, v251, v184, -v186
	v_fma_f32 v191, v235, v184, v187
	v_cvt_pk_bf16_f32 v192, v188, v189
	v_cvt_pk_bf16_f32 v193, v190, v191
	ds_write_b16 v170, v192 offset:7056
	ds_write_b16_d16_hi v170, v192 offset:7088
	ds_write_b16 v170, v193 offset:7120
	ds_write_b16_d16_hi v170, v193 offset:7152
	v_mul_f32_e32 v182, v168, v168
	v_mul_f32_e32 v183, v164, v164
	v_mul_f32_e32 v184, v4, v4
	v_mul_f32_e32 v185, v8, v8
	v_add_f32_e32 v186, v182, v183
	v_add_f32_e32 v186, v186, v184
	v_add_f32_e32 v186, v186, v185
	s_nop 1
	v_add_f32_dpp v186, v186, v186 quad_perm:[1,0,3,2] row_mask:0xf bank_mask:0xf
	s_nop 1
	v_add_f32_dpp v186, v186, v186 quad_perm:[2,3,0,1] row_mask:0xf bank_mask:0xf
	s_nop 1
	v_add_f32_dpp v186, v186, v186 row_half_mirror row_mask:0xf bank_mask:0xf
	s_nop 1
	v_add_f32_dpp v186, v186, v186 row_mirror row_mask:0xf bank_mask:0xf
	v_fmamk_f32 v186, v186, 0x3c800000, v173
	v_rsq_f32_e32 v186, v186
	s_nop 0
	v_mul_f32_e32 v187, v178, v186
	v_mul_f32_e32 v188, v179, v186
	v_mul_f32_e32 v189, v180, v186
	v_mul_f32_e32 v190, v181, v186
	v_mul_f32_e32 v182, v168, v187
	v_mul_f32_e32 v183, v164, v188
	v_mul_f32_e32 v184, v4, v189
	v_mul_f32_e32 v185, v8, v190
	v_mul_f32_e32 v186, v175, v183
	v_mul_f32_e32 v187, v176, v183
	v_fma_f32 v188, v176, v182, -v186
	v_fma_f32 v189, v175, v182, v187
	v_mul_f32_e32 v186, v236, v185
	v_mul_f32_e32 v187, v252, v185
	v_fma_f32 v190, v252, v184, -v186
	v_fma_f32 v191, v236, v184, v187
	v_cvt_pk_bf16_f32 v192, v188, v189
	v_cvt_pk_bf16_f32 v193, v190, v191
	ds_write_b16 v170, v192 offset:7200
	ds_write_b16_d16_hi v170, v192 offset:7232
	ds_write_b16 v170, v193 offset:7264
	ds_write_b16_d16_hi v170, v193 offset:7296
	v_mul_f32_e32 v182, v169, v169
	v_mul_f32_e32 v183, v165, v165
	v_mul_f32_e32 v184, v5, v5
	v_mul_f32_e32 v185, v9, v9
	v_add_f32_e32 v186, v182, v183
	v_add_f32_e32 v186, v186, v184
	v_add_f32_e32 v186, v186, v185
	s_nop 1
	v_add_f32_dpp v186, v186, v186 quad_perm:[1,0,3,2] row_mask:0xf bank_mask:0xf
	s_nop 1
	v_add_f32_dpp v186, v186, v186 quad_perm:[2,3,0,1] row_mask:0xf bank_mask:0xf
	s_nop 1
	v_add_f32_dpp v186, v186, v186 row_half_mirror row_mask:0xf bank_mask:0xf
	s_nop 1
	v_add_f32_dpp v186, v186, v186 row_mirror row_mask:0xf bank_mask:0xf
	v_fmamk_f32 v186, v186, 0x3c800000, v173
	v_rsq_f32_e32 v186, v186
	s_nop 0
	v_mul_f32_e32 v187, v178, v186
	v_mul_f32_e32 v188, v179, v186
	v_mul_f32_e32 v189, v180, v186
	v_mul_f32_e32 v190, v181, v186
	v_mul_f32_e32 v182, v169, v187
	v_mul_f32_e32 v183, v165, v188
	v_mul_f32_e32 v184, v5, v189
	v_mul_f32_e32 v185, v9, v190
	v_mul_f32_e32 v186, v175, v183
	v_mul_f32_e32 v187, v176, v183
	v_fma_f32 v188, v176, v182, -v186
	v_fma_f32 v189, v175, v182, v187
	v_mul_f32_e32 v186, v237, v185
	v_mul_f32_e32 v187, v253, v185
	v_fma_f32 v190, v253, v184, -v186
	v_fma_f32 v191, v237, v184, v187
	v_cvt_pk_bf16_f32 v192, v188, v189
	v_cvt_pk_bf16_f32 v193, v190, v191
	ds_write_b16 v170, v192 offset:7344
	ds_write_b16_d16_hi v170, v192 offset:7376
	ds_write_b16 v170, v193 offset:7408
	ds_write_b16_d16_hi v170, v193 offset:7440
	ds_read_b128 v[130:133], v171 offset:0
	ds_read_b128 v[134:137], v171 offset:1152
	ds_read_b128 v[138:141], v171 offset:2304
	ds_read_b128 v[142:145], v171 offset:3456
	ds_read_b128 v[146:149], v171 offset:4608
	ds_read_b128 v[150:153], v171 offset:5760
	ds_read_b128 v[154:157], v171 offset:6912
	ds_read_b128 v[158:161], v171 offset:8064
	s_waitcnt lgkmcnt(7)
; template <int EPI>
; DI void gemm_phase(const P& p, int l, const u16* __restrict__ A, const u16* __restrict__ Bt, int mpx, char* lds) {
;     ...
;           } else if (tr == 3) {
;             if (donorm) {
;               float ss = v0 * v0 + v1 * v1 + v2 * v2 + v3 * v3;
;               ss += __shfl_xor(ss, 1);
;               ss += __shfl_xor(ss, 2);
;               ss += __shfl_xor(ss, 4);
;               ss += __shfl_xor(ss, 8);
;               const float inv = rsqrtf(ss * (1.f / 64.f) + 1e-6f);
;               v0 *= inv * gv0; v1 *= inv * gv1; v2 *= inv * gv2; v3 *= inv * gv3;
;             }
;             if (dorope) {
;               float sr, cr, sc, cc;
;               sincos_rev((float)(s >> 6) * invf64, sr, cr);
;               sincos_rev((float)(s & 63) * invf64, sc, cc);
;               const float a1 = v0, a2 = v1, b1 = v2, b2 = v3;
;               v0 = a1 * cr - a2 * sr;
;               v1 = a2 * cr + a1 * sr;
;               v2 = b1 * cc - b2 * sc;
;               v3 = b2 * cc + b1 * sc;
;             }
;           } else if (tr == 4) {
;             float sr, cr, sc, cc;
;             sincos_rev((float)(s >> 6) * invf32, sr, cr);
;             sincos_rev((float)(s & 63) * invf32, sc, cc);
;             const float p0 = __shfl_xor(v0, 8), p1 = __shfl_xor(v1, 8), p2 = __shfl_xor(v2, 8), p3 = __shfl_xor(v3, 8);
;             v0 = lo8 ? (v0 * cr - p0 * sr) : (v0 * cr + p0 * sr);
;             v1 = lo8 ? (v1 * cc - p1 * sc) : (v1 * cc + p1 * sc);
;             v2 = lo8 ? (v2 * cr - p2 * sr) : (v2 * cr + p2 * sr);
;             v3 = lo8 ? (v3 * cc - p3 * sc) : (v3 * cc + p3 * sc);
;           }
;           const unsigned u01 = pack2(v0, v1), u23 = pack2(v2, v3);
;           if (kind == 1) {
;             Tl[(0 * 16 + r) * 72 + rowl] = (u16)u01;
;             Tl[(1 * 16 + r) * 72 + rowl] = (u16)(u01 >> 16);
;             Tl[(2 * 16 + r) * 72 + rowl] = (u16)u23;
;             Tl[(3 * 16 + r) * 72 + rowl] = (u16)(u23 >> 16);
;           } else if (tr == 2) {
;             Tl[rowl * 72 + 0 * 16 + r] = f2h(v0);
;             Tl[rowl * 72 + 1 * 16 + r] = f2h(v1);
;             Tl[rowl * 72 + 2 * 16 + r] = f2h(v2);
;             Tl[rowl * 72 + 3 * 16 + r] = f2h(v3);
;           } else {
;             Tl[rowl * 72 + 0 * 16 + r] = (u16)u01;
;             Tl[rowl * 72 + 1 * 16 + r] = (u16)(u01 >> 16);
;             Tl[rowl * 72 + 2 * 16 + r] = (u16)u23;
	global_store_dwordx4 v172, v[130:133], s[44:45] offset:0 sc1
	s_waitcnt lgkmcnt(6)
	global_store_dwordx4 v172, v[134:137], s[44:45] offset:1024 sc1
	s_waitcnt lgkmcnt(5)
	global_store_dwordx4 v172, v[138:141], s[44:45] offset:2048 sc1
	s_waitcnt lgkmcnt(4)
	global_store_dwordx4 v172, v[142:145], s[44:45] offset:3072 sc1
	s_waitcnt lgkmcnt(3)
	global_store_dwordx4 v172, v[146:149], s[62:63] offset:0 sc1
	s_waitcnt lgkmcnt(2)
	global_store_dwordx4 v172, v[150:153], s[62:63] offset:1024 sc1
	s_waitcnt lgkmcnt(1)
	global_store_dwordx4 v172, v[154:157], s[62:63] offset:2048 sc1
	s_waitcnt lgkmcnt(0)
	global_store_dwordx4 v172, v[158:161], s[62:63] offset:3072 sc1
	s_branch .Lfe_done
.Lfe_k0_norm:
	s_cmp_lt_u32 s43, 20
	s_movk_i32 s70, 0x68
	s_cselect_b32 s70, 0x60, s70
	s_add_u32 s70, s96, s70
	s_addc_u32 s71, s97, 0
	s_load_dwordx2 s[70:71], s[70:71], 0x0
	v_and_b32_e32 v0, 15, v226
	v_lshlrev_b32_e32 v0, 2, v0
	v_mov_b32_e32 v173, 0x358637bd
	s_waitcnt lgkmcnt(0)
	s_lshl_b32 s63, s52, 2
	s_add_u32 s70, s70, s63
	s_addc_u32 s71, s71, 0
	global_load_dword v178, v0, s[70:71] offset:0
	global_load_dword v179, v0, s[70:71] offset:64
	global_load_dword v180, v0, s[70:71] offset:128
	global_load_dword v181, v0, s[70:71] offset:192
	s_waitcnt vmcnt(0)
	s_add_u32 s62, s44, 0x1000
	s_addc_u32 s63, s45, 0
	v_mul_f32_e32 v182, v126, v126
	v_mul_f32_e32 v183, v122, v122
	v_mul_f32_e32 v184, v118, v118
	v_mul_f32_e32 v185, v114, v114
	v_add_f32_e32 v186, v182, v183
	v_add_f32_e32 v186, v186, v184
	v_add_f32_e32 v186, v186, v185
	s_nop 1
	v_add_f32_dpp v186, v186, v186 quad_perm:[1,0,3,2] row_mask:0xf bank_mask:0xf
	s_nop 1
	v_add_f32_dpp v186, v186, v186 quad_perm:[2,3,0,1] row_mask:0xf bank_mask:0xf
	s_nop 1
	v_add_f32_dpp v186, v186, v186 row_half_mirror row_mask:0xf bank_mask:0xf
	s_nop 1
	v_add_f32_dpp v186, v186, v186 row_mirror row_mask:0xf bank_mask:0xf
	v_fmamk_f32 v186, v186, 0x3c800000, v173
	v_rsq_f32_e32 v186, v186
	s_nop 0
	v_mul_f32_e32 v187, v178, v186
	v_mul_f32_e32 v188, v179, v186
	v_mul_f32_e32 v189, v180, v186
	v_mul_f32_e32 v190, v181, v186
	v_mul_f32_e32 v182, v126, v187
	v_mul_f32_e32 v183, v122, v188
	v_mul_f32_e32 v184, v118, v189
	v_mul_f32_e32 v185, v114, v190
	v_cvt_pk_bf16_f32 v192, v182, v183
	v_cvt_pk_bf16_f32 v193, v184, v185
	ds_write_b16 v170, v192 offset:0
	ds_write_b16_d16_hi v170, v192 offset:32
	ds_write_b16 v170, v193 offset:64
	ds_write_b16_d16_hi v170, v193 offset:96
	v_mul_f32_e32 v182, v127, v127
	v_mul_f32_e32 v183, v123, v123
	v_mul_f32_e32 v184, v119, v119
	v_mul_f32_e32 v185, v115, v115
	v_add_f32_e32 v186, v182, v183
	v_add_f32_e32 v186, v186, v184
	v_add_f32_e32 v186, v186, v185
	s_nop 1
	v_add_f32_dpp v186, v186, v186 quad_perm:[1,0,3,2] row_mask:0xf bank_mask:0xf
	s_nop 1
	v_add_f32_dpp v186, v186, v186 quad_perm:[2,3,0,1] row_mask:0xf bank_mask:0xf
	s_nop 1
	v_add_f32_dpp v186, v186, v186 row_half_mirror row_mask:0xf bank_mask:0xf
	s_nop 1
	v_add_f32_dpp v186, v186, v186 row_mirror row_mask:0xf bank_mask:0xf
	v_fmamk_f32 v186, v186, 0x3c800000, v173
	v_rsq_f32_e32 v186, v186
	s_nop 0
	v_mul_f32_e32 v187, v178, v186
	v_mul_f32_e32 v188, v179, v186
	v_mul_f32_e32 v189, v180, v186
	v_mul_f32_e32 v190, v181, v186
	v_mul_f32_e32 v182, v127, v187
	v_mul_f32_e32 v183, v123, v188
	v_mul_f32_e32 v184, v119, v189
	v_mul_f32_e32 v185, v115, v190
	v_cvt_pk_bf16_f32 v192, v182, v183
	v_cvt_pk_bf16_f32 v193, v184, v185
	ds_write_b16 v170, v192 offset:144
	ds_write_b16_d16_hi v170, v192 offset:176
	ds_write_b16 v170, v193 offset:208
	ds_write_b16_d16_hi v170, v193 offset:240
	v_mul_f32_e32 v182, v128, v128
	v_mul_f32_e32 v183, v124, v124
	v_mul_f32_e32 v184, v120, v120
	v_mul_f32_e32 v185, v116, v116
	v_add_f32_e32 v186, v182, v183
	v_add_f32_e32 v186, v186, v184
	v_add_f32_e32 v186, v186, v185
	s_nop 1
	v_add_f32_dpp v186, v186, v186 quad_perm:[1,0,3,2] row_mask:0xf bank_mask:0xf
	s_nop 1
	v_add_f32_dpp v186, v186, v186 quad_perm:[2,3,0,1] row_mask:0xf bank_mask:0xf
	s_nop 1
	v_add_f32_dpp v186, v186, v186 row_half_mirror row_mask:0xf bank_mask:0xf
	s_nop 1
	v_add_f32_dpp v186, v186, v186 row_mirror row_mask:0xf bank_mask:0xf
	v_fmamk_f32 v186, v186, 0x3c800000, v173
	v_rsq_f32_e32 v186, v186
	s_nop 0
	v_mul_f32_e32 v187, v178, v186
	v_mul_f32_e32 v188, v179, v186
	v_mul_f32_e32 v189, v180, v186
	v_mul_f32_e32 v190, v181, v186
	v_mul_f32_e32 v182, v128, v187
	v_mul_f32_e32 v183, v124, v188
	v_mul_f32_e32 v184, v120, v189
	v_mul_f32_e32 v185, v116, v190
	v_cvt_pk_bf16_f32 v192, v182, v183
	v_cvt_pk_bf16_f32 v193, v184, v185
	ds_write_b16 v170, v192 offset:288
	ds_write_b16_d16_hi v170, v192 offset:320
	ds_write_b16 v170, v193 offset:352
	ds_write_b16_d16_hi v170, v193 offset:384
	v_mul_f32_e32 v182, v129, v129
	v_mul_f32_e32 v183, v125, v125
	v_mul_f32_e32 v184, v121, v121
	v_mul_f32_e32 v185, v117, v117
	v_add_f32_e32 v186, v182, v183
	v_add_f32_e32 v186, v186, v184
	v_add_f32_e32 v186, v186, v185
	s_nop 1
	v_add_f32_dpp v186, v186, v186 quad_perm:[1,0,3,2] row_mask:0xf bank_mask:0xf
	s_nop 1
	v_add_f32_dpp v186, v186, v186 quad_perm:[2,3,0,1] row_mask:0xf bank_mask:0xf
	s_nop 1
	v_add_f32_dpp v186, v186, v186 row_half_mirror row_mask:0xf bank_mask:0xf
	s_nop 1
	v_add_f32_dpp v186, v186, v186 row_mirror row_mask:0xf bank_mask:0xf
	v_fmamk_f32 v186, v186, 0x3c800000, v173
	v_rsq_f32_e32 v186, v186
	s_nop 0
	v_mul_f32_e32 v187, v178, v186
	v_mul_f32_e32 v188, v179, v186
	v_mul_f32_e32 v189, v180, v186
	v_mul_f32_e32 v190, v181, v186
	v_mul_f32_e32 v182, v129, v187
	v_mul_f32_e32 v183, v125, v188
	v_mul_f32_e32 v184, v121, v189
	v_mul_f32_e32 v185, v117, v190
	v_cvt_pk_bf16_f32 v192, v182, v183
	v_cvt_pk_bf16_f32 v193, v184, v185
; template <int EPI>
; DI void gemm_phase(const P& p, int l, const u16* __restrict__ A, const u16* __restrict__ Bt, int mpx, char* lds) {
;     ...
;             if (donorm) {
;               float ss = v0 * v0 + v1 * v1 + v2 * v2 + v3 * v3;
;               ss += __shfl_xor(ss, 1);
;               ss += __shfl_xor(ss, 2);
;               ss += __shfl_xor(ss, 4);
;               ss += __shfl_xor(ss, 8);
;               const float inv = rsqrtf(ss * (1.f / 64.f) + 1e-6f);
;               v0 *= inv * gv0; v1 *= inv * gv1; v2 *= inv * gv2; v3 *= inv * gv3;
;             }
;             if (dorope) {
;               float sr, cr, sc, cc;
;               sincos_rev((float)(s >> 6) * invf64, sr, cr);
;               sincos_rev((float)(s & 63) * invf64, sc, cc);
;               const float a1 = v0, a2 = v1, b1 = v2, b2 = v3;
;               v0 = a1 * cr - a2 * sr;
;               v1 = a2 * cr + a1 * sr;
;               v2 = b1 * cc - b2 * sc;
;               v3 = b2 * cc + b1 * sc;
;             }
;           } else if (tr == 4) {
;             float sr, cr, sc, cc;
;             sincos_rev((float)(s >> 6) * invf32, sr, cr);
;             sincos_rev((float)(s & 63) * invf32, sc, cc);
;             const float p0 = __shfl_xor(v0, 8), p1 = __shfl_xor(v1, 8), p2 = __shfl_xor(v2, 8), p3 = __shfl_xor(v3, 8);
;             v0 = lo8 ? (v0 * cr - p0 * sr) : (v0 * cr + p0 * sr);
;             v1 = lo8 ? (v1 * cc - p1 * sc) : (v1 * cc + p1 * sc);
;             v2 = lo8 ? (v2 * cr - p2 * sr) : (v2 * cr + p2 * sr);
;             v3 = lo8 ? (v3 * cc - p3 * sc) : (v3 * cc + p3 * sc);
;           }
;           const unsigned u01 = pack2(v0, v1), u23 = pack2(v2, v3);
;           if (kind == 1) {
;             Tl[(0 * 16 + r) * 72 + rowl] = (u16)u01;
;             Tl[(1 * 16 + r) * 72 + rowl] = (u16)(u01 >> 16);
;             Tl[(2 * 16 + r) * 72 + rowl] = (u16)u23;
;             Tl[(3 * 16 + r) * 72 + rowl] = (u16)(u23 >> 16);
;           } else if (tr == 2) {
;             Tl[rowl * 72 + 0 * 16 + r] = f2h(v0);
;             Tl[rowl * 72 + 1 * 16 + r] = f2h(v1);
;             Tl[rowl * 72 + 2 * 16 + r] = f2h(v2);
;             Tl[rowl * 72 + 3 * 16 + r] = f2h(v3);
;           } else {
;             Tl[rowl * 72 + 0 * 16 + r] = (u16)u01;
;             Tl[rowl * 72 + 1 * 16 + r] = (u16)(u01 >> 16);
;             Tl[rowl * 72 + 2 * 16 + r] = (u16)u23;
	ds_write_b16 v170, v192 offset:432
	ds_write_b16_d16_hi v170, v192 offset:464
	ds_write_b16 v170, v193 offset:496
	ds_write_b16_d16_hi v170, v193 offset:528
	v_mul_f32_e32 v182, v110, v110
	v_mul_f32_e32 v183, v106, v106
	v_mul_f32_e32 v184, v102, v102
	v_mul_f32_e32 v185, v98, v98
	v_add_f32_e32 v186, v182, v183
	v_add_f32_e32 v186, v186, v184
	v_add_f32_e32 v186, v186, v185
	s_nop 1
	v_add_f32_dpp v186, v186, v186 quad_perm:[1,0,3,2] row_mask:0xf bank_mask:0xf
	s_nop 1
	v_add_f32_dpp v186, v186, v186 quad_perm:[2,3,0,1] row_mask:0xf bank_mask:0xf
	s_nop 1
	v_add_f32_dpp v186, v186, v186 row_half_mirror row_mask:0xf bank_mask:0xf
	s_nop 1
	v_add_f32_dpp v186, v186, v186 row_mirror row_mask:0xf bank_mask:0xf
	v_fmamk_f32 v186, v186, 0x3c800000, v173
	v_rsq_f32_e32 v186, v186
	s_nop 0
	v_mul_f32_e32 v187, v178, v186
	v_mul_f32_e32 v188, v179, v186
	v_mul_f32_e32 v189, v180, v186
	v_mul_f32_e32 v190, v181, v186
	v_mul_f32_e32 v182, v110, v187
	v_mul_f32_e32 v183, v106, v188
	v_mul_f32_e32 v184, v102, v189
	v_mul_f32_e32 v185, v98, v190
	v_cvt_pk_bf16_f32 v192, v182, v183
	v_cvt_pk_bf16_f32 v193, v184, v185
	ds_write_b16 v170, v192 offset:2304
	ds_write_b16_d16_hi v170, v192 offset:2336
	ds_write_b16 v170, v193 offset:2368
	ds_write_b16_d16_hi v170, v193 offset:2400
	v_mul_f32_e32 v182, v111, v111
	v_mul_f32_e32 v183, v107, v107
	v_mul_f32_e32 v184, v103, v103
	v_mul_f32_e32 v185, v99, v99
	v_add_f32_e32 v186, v182, v183
	v_add_f32_e32 v186, v186, v184
	v_add_f32_e32 v186, v186, v185
	s_nop 1
	v_add_f32_dpp v186, v186, v186 quad_perm:[1,0,3,2] row_mask:0xf bank_mask:0xf
	s_nop 1
	v_add_f32_dpp v186, v186, v186 quad_perm:[2,3,0,1] row_mask:0xf bank_mask:0xf
	s_nop 1
	v_add_f32_dpp v186, v186, v186 row_half_mirror row_mask:0xf bank_mask:0xf
	s_nop 1
	v_add_f32_dpp v186, v186, v186 row_mirror row_mask:0xf bank_mask:0xf
	v_fmamk_f32 v186, v186, 0x3c800000, v173
	v_rsq_f32_e32 v186, v186
	s_nop 0
	v_mul_f32_e32 v187, v178, v186
	v_mul_f32_e32 v188, v179, v186
	v_mul_f32_e32 v189, v180, v186
	v_mul_f32_e32 v190, v181, v186
	v_mul_f32_e32 v182, v111, v187
	v_mul_f32_e32 v183, v107, v188
	v_mul_f32_e32 v184, v103, v189
	v_mul_f32_e32 v185, v99, v190
	v_cvt_pk_bf16_f32 v192, v182, v183
	v_cvt_pk_bf16_f32 v193, v184, v185
	ds_write_b16 v170, v192 offset:2448
	ds_write_b16_d16_hi v170, v192 offset:2480
	ds_write_b16 v170, v193 offset:2512
	ds_write_b16_d16_hi v170, v193 offset:2544
	v_mul_f32_e32 v182, v112, v112
	v_mul_f32_e32 v183, v108, v108
	v_mul_f32_e32 v184, v104, v104
	v_mul_f32_e32 v185, v100, v100
	v_add_f32_e32 v186, v182, v183
	v_add_f32_e32 v186, v186, v184
	v_add_f32_e32 v186, v186, v185
	s_nop 1
	v_add_f32_dpp v186, v186, v186 quad_perm:[1,0,3,2] row_mask:0xf bank_mask:0xf
	s_nop 1
	v_add_f32_dpp v186, v186, v186 quad_perm:[2,3,0,1] row_mask:0xf bank_mask:0xf
	s_nop 1
	v_add_f32_dpp v186, v186, v186 row_half_mirror row_mask:0xf bank_mask:0xf
	s_nop 1
	v_add_f32_dpp v186, v186, v186 row_mirror row_mask:0xf bank_mask:0xf
	v_fmamk_f32 v186, v186, 0x3c800000, v173
	v_rsq_f32_e32 v186, v186
	s_nop 0
	v_mul_f32_e32 v187, v178, v186
	v_mul_f32_e32 v188, v179, v186
	v_mul_f32_e32 v189, v180, v186
	v_mul_f32_e32 v190, v181, v186
	v_mul_f32_e32 v182, v112, v187
	v_mul_f32_e32 v183, v108, v188
	v_mul_f32_e32 v184, v104, v189
	v_mul_f32_e32 v185, v100, v190
	v_cvt_pk_bf16_f32 v192, v182, v183
	v_cvt_pk_bf16_f32 v193, v184, v185
	ds_write_b16 v170, v192 offset:2592
	ds_write_b16_d16_hi v170, v192 offset:2624
	ds_write_b16 v170, v193 offset:2656
	ds_write_b16_d16_hi v170, v193 offset:2688
	v_mul_f32_e32 v182, v113, v113
	v_mul_f32_e32 v183, v109, v109
	v_mul_f32_e32 v184, v105, v105
	v_mul_f32_e32 v185, v101, v101
	v_add_f32_e32 v186, v182, v183
	v_add_f32_e32 v186, v186, v184
	v_add_f32_e32 v186, v186, v185
	s_nop 1
	v_add_f32_dpp v186, v186, v186 quad_perm:[1,0,3,2] row_mask:0xf bank_mask:0xf
	s_nop 1
	v_add_f32_dpp v186, v186, v186 quad_perm:[2,3,0,1] row_mask:0xf bank_mask:0xf
	s_nop 1
	v_add_f32_dpp v186, v186, v186 row_half_mirror row_mask:0xf bank_mask:0xf
	s_nop 1
	v_add_f32_dpp v186, v186, v186 row_mirror row_mask:0xf bank_mask:0xf
	v_fmamk_f32 v186, v186, 0x3c800000, v173
	v_rsq_f32_e32 v186, v186
	s_nop 0
	v_mul_f32_e32 v187, v178, v186
	v_mul_f32_e32 v188, v179, v186
	v_mul_f32_e32 v189, v180, v186
	v_mul_f32_e32 v190, v181, v186
	v_mul_f32_e32 v182, v113, v187
	v_mul_f32_e32 v183, v109, v188
	v_mul_f32_e32 v184, v105, v189
	v_mul_f32_e32 v185, v101, v190
	v_cvt_pk_bf16_f32 v192, v182, v183
	v_cvt_pk_bf16_f32 v193, v184, v185
	ds_write_b16 v170, v192 offset:2736
	ds_write_b16_d16_hi v170, v192 offset:2768
	ds_write_b16 v170, v193 offset:2800
	ds_write_b16_d16_hi v170, v193 offset:2832
	v_mul_f32_e32 v182, v94, v94
	v_mul_f32_e32 v183, v90, v90
	v_mul_f32_e32 v184, v86, v86
	v_mul_f32_e32 v185, v82, v82
	v_add_f32_e32 v186, v182, v183
	v_add_f32_e32 v186, v186, v184
	v_add_f32_e32 v186, v186, v185
	s_nop 1
	v_add_f32_dpp v186, v186, v186 quad_perm:[1,0,3,2] row_mask:0xf bank_mask:0xf
	s_nop 1
	v_add_f32_dpp v186, v186, v186 quad_perm:[2,3,0,1] row_mask:0xf bank_mask:0xf
	s_nop 1
	v_add_f32_dpp v186, v186, v186 row_half_mirror row_mask:0xf bank_mask:0xf
	s_nop 1
	v_add_f32_dpp v186, v186, v186 row_mirror row_mask:0xf bank_mask:0xf
	v_fmamk_f32 v186, v186, 0x3c800000, v173
	v_rsq_f32_e32 v186, v186
	s_nop 0
	v_mul_f32_e32 v187, v178, v186
	v_mul_f32_e32 v188, v179, v186
	v_mul_f32_e32 v189, v180, v186
	v_mul_f32_e32 v190, v181, v186
	v_mul_f32_e32 v182, v94, v187
	v_mul_f32_e32 v183, v90, v188
	v_mul_f32_e32 v184, v86, v189
	v_mul_f32_e32 v185, v82, v190
	v_cvt_pk_bf16_f32 v192, v182, v183
	v_cvt_pk_bf16_f32 v193, v184, v185
; template <int EPI>
; DI void gemm_phase(const P& p, int l, const u16* __restrict__ A, const u16* __restrict__ Bt, int mpx, char* lds) {
;     ...
;             if (donorm) {
;               float ss = v0 * v0 + v1 * v1 + v2 * v2 + v3 * v3;
;               ss += __shfl_xor(ss, 1);
;               ss += __shfl_xor(ss, 2);
;               ss += __shfl_xor(ss, 4);
;               ss += __shfl_xor(ss, 8);
;               const float inv = rsqrtf(ss * (1.f / 64.f) + 1e-6f);
;               v0 *= inv * gv0; v1 *= inv * gv1; v2 *= inv * gv2; v3 *= inv * gv3;
;             }
;             if (dorope) {
;               float sr, cr, sc, cc;
;               sincos_rev((float)(s >> 6) * invf64, sr, cr);
;               sincos_rev((float)(s & 63) * invf64, sc, cc);
;               const float a1 = v0, a2 = v1, b1 = v2, b2 = v3;
;               v0 = a1 * cr - a2 * sr;
;               v1 = a2 * cr + a1 * sr;
;               v2 = b1 * cc - b2 * sc;
;               v3 = b2 * cc + b1 * sc;
;             }
;           } else if (tr == 4) {
;             float sr, cr, sc, cc;
;             sincos_rev((float)(s >> 6) * invf32, sr, cr);
;             sincos_rev((float)(s & 63) * invf32, sc, cc);
;             const float p0 = __shfl_xor(v0, 8), p1 = __shfl_xor(v1, 8), p2 = __shfl_xor(v2, 8), p3 = __shfl_xor(v3, 8);
;             v0 = lo8 ? (v0 * cr - p0 * sr) : (v0 * cr + p0 * sr);
;             v1 = lo8 ? (v1 * cc - p1 * sc) : (v1 * cc + p1 * sc);
;             v2 = lo8 ? (v2 * cr - p2 * sr) : (v2 * cr + p2 * sr);
;             v3 = lo8 ? (v3 * cc - p3 * sc) : (v3 * cc + p3 * sc);
;           }
;           const unsigned u01 = pack2(v0, v1), u23 = pack2(v2, v3);
;           if (kind == 1) {
;             Tl[(0 * 16 + r) * 72 + rowl] = (u16)u01;
;             Tl[(1 * 16 + r) * 72 + rowl] = (u16)(u01 >> 16);
;             Tl[(2 * 16 + r) * 72 + rowl] = (u16)u23;
;             Tl[(3 * 16 + r) * 72 + rowl] = (u16)(u23 >> 16);
;           } else if (tr == 2) {
;             Tl[rowl * 72 + 0 * 16 + r] = f2h(v0);
;             Tl[rowl * 72 + 1 * 16 + r] = f2h(v1);
;             Tl[rowl * 72 + 2 * 16 + r] = f2h(v2);
;             Tl[rowl * 72 + 3 * 16 + r] = f2h(v3);
;           } else {
;             Tl[rowl * 72 + 0 * 16 + r] = (u16)u01;
;             Tl[rowl * 72 + 1 * 16 + r] = (u16)(u01 >> 16);
;             Tl[rowl * 72 + 2 * 16 + r] = (u16)u23;
	ds_write_b16 v170, v192 offset:4608
	ds_write_b16_d16_hi v170, v192 offset:4640
	ds_write_b16 v170, v193 offset:4672
	ds_write_b16_d16_hi v170, v193 offset:4704
	v_mul_f32_e32 v182, v95, v95
	v_mul_f32_e32 v183, v91, v91
	v_mul_f32_e32 v184, v87, v87
	v_mul_f32_e32 v185, v83, v83
	v_add_f32_e32 v186, v182, v183
	v_add_f32_e32 v186, v186, v184
	v_add_f32_e32 v186, v186, v185
	s_nop 1
	v_add_f32_dpp v186, v186, v186 quad_perm:[1,0,3,2] row_mask:0xf bank_mask:0xf
	s_nop 1
	v_add_f32_dpp v186, v186, v186 quad_perm:[2,3,0,1] row_mask:0xf bank_mask:0xf
	s_nop 1
	v_add_f32_dpp v186, v186, v186 row_half_mirror row_mask:0xf bank_mask:0xf
	s_nop 1
	v_add_f32_dpp v186, v186, v186 row_mirror row_mask:0xf bank_mask:0xf
	v_fmamk_f32 v186, v186, 0x3c800000, v173
	v_rsq_f32_e32 v186, v186
	s_nop 0
	v_mul_f32_e32 v187, v178, v186
	v_mul_f32_e32 v188, v179, v186
	v_mul_f32_e32 v189, v180, v186
	v_mul_f32_e32 v190, v181, v186
	v_mul_f32_e32 v182, v95, v187
	v_mul_f32_e32 v183, v91, v188
	v_mul_f32_e32 v184, v87, v189
	v_mul_f32_e32 v185, v83, v190
	v_cvt_pk_bf16_f32 v192, v182, v183
	v_cvt_pk_bf16_f32 v193, v184, v185
	ds_write_b16 v170, v192 offset:4752
	ds_write_b16_d16_hi v170, v192 offset:4784
	ds_write_b16 v170, v193 offset:4816
	ds_write_b16_d16_hi v170, v193 offset:4848
	v_mul_f32_e32 v182, v96, v96
	v_mul_f32_e32 v183, v92, v92
	v_mul_f32_e32 v184, v88, v88
	v_mul_f32_e32 v185, v84, v84
	v_add_f32_e32 v186, v182, v183
	v_add_f32_e32 v186, v186, v184
	v_add_f32_e32 v186, v186, v185
	s_nop 1
	v_add_f32_dpp v186, v186, v186 quad_perm:[1,0,3,2] row_mask:0xf bank_mask:0xf
	s_nop 1
	v_add_f32_dpp v186, v186, v186 quad_perm:[2,3,0,1] row_mask:0xf bank_mask:0xf
	s_nop 1
	v_add_f32_dpp v186, v186, v186 row_half_mirror row_mask:0xf bank_mask:0xf
	s_nop 1
	v_add_f32_dpp v186, v186, v186 row_mirror row_mask:0xf bank_mask:0xf
	v_fmamk_f32 v186, v186, 0x3c800000, v173
	v_rsq_f32_e32 v186, v186
	s_nop 0
	v_mul_f32_e32 v187, v178, v186
	v_mul_f32_e32 v188, v179, v186
	v_mul_f32_e32 v189, v180, v186
	v_mul_f32_e32 v190, v181, v186
	v_mul_f32_e32 v182, v96, v187
	v_mul_f32_e32 v183, v92, v188
	v_mul_f32_e32 v184, v88, v189
	v_mul_f32_e32 v185, v84, v190
	v_cvt_pk_bf16_f32 v192, v182, v183
	v_cvt_pk_bf16_f32 v193, v184, v185
	ds_write_b16 v170, v192 offset:4896
	ds_write_b16_d16_hi v170, v192 offset:4928
	ds_write_b16 v170, v193 offset:4960
	ds_write_b16_d16_hi v170, v193 offset:4992
	v_mul_f32_e32 v182, v97, v97
	v_mul_f32_e32 v183, v93, v93
	v_mul_f32_e32 v184, v89, v89
	v_mul_f32_e32 v185, v85, v85
	v_add_f32_e32 v186, v182, v183
	v_add_f32_e32 v186, v186, v184
	v_add_f32_e32 v186, v186, v185
	s_nop 1
	v_add_f32_dpp v186, v186, v186 quad_perm:[1,0,3,2] row_mask:0xf bank_mask:0xf
	s_nop 1
	v_add_f32_dpp v186, v186, v186 quad_perm:[2,3,0,1] row_mask:0xf bank_mask:0xf
	s_nop 1
	v_add_f32_dpp v186, v186, v186 row_half_mirror row_mask:0xf bank_mask:0xf
	s_nop 1
	v_add_f32_dpp v186, v186, v186 row_mirror row_mask:0xf bank_mask:0xf
	v_fmamk_f32 v186, v186, 0x3c800000, v173
	v_rsq_f32_e32 v186, v186
	s_nop 0
	v_mul_f32_e32 v187, v178, v186
	v_mul_f32_e32 v188, v179, v186
	v_mul_f32_e32 v189, v180, v186
	v_mul_f32_e32 v190, v181, v186
	v_mul_f32_e32 v182, v97, v187
	v_mul_f32_e32 v183, v93, v188
	v_mul_f32_e32 v184, v89, v189
	v_mul_f32_e32 v185, v85, v190
	v_cvt_pk_bf16_f32 v192, v182, v183
	v_cvt_pk_bf16_f32 v193, v184, v185
	ds_write_b16 v170, v192 offset:5040
	ds_write_b16_d16_hi v170, v192 offset:5072
	ds_write_b16 v170, v193 offset:5104
	ds_write_b16_d16_hi v170, v193 offset:5136
	v_mul_f32_e32 v182, v78, v78
	v_mul_f32_e32 v183, v74, v74
	v_mul_f32_e32 v184, v70, v70
	v_mul_f32_e32 v185, v66, v66
	v_add_f32_e32 v186, v182, v183
	v_add_f32_e32 v186, v186, v184
	v_add_f32_e32 v186, v186, v185
	s_nop 1
	v_add_f32_dpp v186, v186, v186 quad_perm:[1,0,3,2] row_mask:0xf bank_mask:0xf
	s_nop 1
	v_add_f32_dpp v186, v186, v186 quad_perm:[2,3,0,1] row_mask:0xf bank_mask:0xf
	s_nop 1
	v_add_f32_dpp v186, v186, v186 row_half_mirror row_mask:0xf bank_mask:0xf
	s_nop 1
	v_add_f32_dpp v186, v186, v186 row_mirror row_mask:0xf bank_mask:0xf
	v_fmamk_f32 v186, v186, 0x3c800000, v173
	v_rsq_f32_e32 v186, v186
	s_nop 0
	v_mul_f32_e32 v187, v178, v186
	v_mul_f32_e32 v188, v179, v186
	v_mul_f32_e32 v189, v180, v186
	v_mul_f32_e32 v190, v181, v186
	v_mul_f32_e32 v182, v78, v187
	v_mul_f32_e32 v183, v74, v188
	v_mul_f32_e32 v184, v70, v189
	v_mul_f32_e32 v185, v66, v190
	v_cvt_pk_bf16_f32 v192, v182, v183
	v_cvt_pk_bf16_f32 v193, v184, v185
	ds_write_b16 v170, v192 offset:6912
	ds_write_b16_d16_hi v170, v192 offset:6944
	ds_write_b16 v170, v193 offset:6976
	ds_write_b16_d16_hi v170, v193 offset:7008
	v_mul_f32_e32 v182, v79, v79
	v_mul_f32_e32 v183, v75, v75
	v_mul_f32_e32 v184, v71, v71
	v_mul_f32_e32 v185, v67, v67
	v_add_f32_e32 v186, v182, v183
	v_add_f32_e32 v186, v186, v184
	v_add_f32_e32 v186, v186, v185
	s_nop 1
	v_add_f32_dpp v186, v186, v186 quad_perm:[1,0,3,2] row_mask:0xf bank_mask:0xf
	s_nop 1
	v_add_f32_dpp v186, v186, v186 quad_perm:[2,3,0,1] row_mask:0xf bank_mask:0xf
	s_nop 1
	v_add_f32_dpp v186, v186, v186 row_half_mirror row_mask:0xf bank_mask:0xf
	s_nop 1
	v_add_f32_dpp v186, v186, v186 row_mirror row_mask:0xf bank_mask:0xf
	v_fmamk_f32 v186, v186, 0x3c800000, v173
	v_rsq_f32_e32 v186, v186
	s_nop 0
	v_mul_f32_e32 v187, v178, v186
	v_mul_f32_e32 v188, v179, v186
	v_mul_f32_e32 v189, v180, v186
	v_mul_f32_e32 v190, v181, v186
	v_mul_f32_e32 v182, v79, v187
	v_mul_f32_e32 v183, v75, v188
	v_mul_f32_e32 v184, v71, v189
	v_mul_f32_e32 v185, v67, v190
	v_cvt_pk_bf16_f32 v192, v182, v183
	v_cvt_pk_bf16_f32 v193, v184, v185
	ds_write_b16 v170, v192 offset:7056
; template <int EPI>
; DI void gemm_phase(const P& p, int l, const u16* __restrict__ A, const u16* __restrict__ Bt, int mpx, char* lds) {
;     ...
;             if (donorm) {
;               float ss = v0 * v0 + v1 * v1 + v2 * v2 + v3 * v3;
;               ss += __shfl_xor(ss, 1);
;               ss += __shfl_xor(ss, 2);
;               ss += __shfl_xor(ss, 4);
;               ss += __shfl_xor(ss, 8);
;               const float inv = rsqrtf(ss * (1.f / 64.f) + 1e-6f);
;               v0 *= inv * gv0; v1 *= inv * gv1; v2 *= inv * gv2; v3 *= inv * gv3;
;             }
;             if (dorope) {
;               float sr, cr, sc, cc;
;               sincos_rev((float)(s >> 6) * invf64, sr, cr);
;               sincos_rev((float)(s & 63) * invf64, sc, cc);
;               const float a1 = v0, a2 = v1, b1 = v2, b2 = v3;
;               v0 = a1 * cr - a2 * sr;
;               v1 = a2 * cr + a1 * sr;
;               v2 = b1 * cc - b2 * sc;
;               v3 = b2 * cc + b1 * sc;
;             }
;           } else if (tr == 4) {
;             float sr, cr, sc, cc;
;             sincos_rev((float)(s >> 6) * invf32, sr, cr);
;             sincos_rev((float)(s & 63) * invf32, sc, cc);
;             const float p0 = __shfl_xor(v0, 8), p1 = __shfl_xor(v1, 8), p2 = __shfl_xor(v2, 8), p3 = __shfl_xor(v3, 8);
;             v0 = lo8 ? (v0 * cr - p0 * sr) : (v0 * cr + p0 * sr);
;             v1 = lo8 ? (v1 * cc - p1 * sc) : (v1 * cc + p1 * sc);
;             v2 = lo8 ? (v2 * cr - p2 * sr) : (v2 * cr + p2 * sr);
;             v3 = lo8 ? (v3 * cc - p3 * sc) : (v3 * cc + p3 * sc);
;           }
;           const unsigned u01 = pack2(v0, v1), u23 = pack2(v2, v3);
;           if (kind == 1) {
;             Tl[(0 * 16 + r) * 72 + rowl] = (u16)u01;
;             Tl[(1 * 16 + r) * 72 + rowl] = (u16)(u01 >> 16);
;             Tl[(2 * 16 + r) * 72 + rowl] = (u16)u23;
;             Tl[(3 * 16 + r) * 72 + rowl] = (u16)(u23 >> 16);
;           } else if (tr == 2) {
;             Tl[rowl * 72 + 0 * 16 + r] = f2h(v0);
;             Tl[rowl * 72 + 1 * 16 + r] = f2h(v1);
;             Tl[rowl * 72 + 2 * 16 + r] = f2h(v2);
;             Tl[rowl * 72 + 3 * 16 + r] = f2h(v3);
;           } else {
;             Tl[rowl * 72 + 0 * 16 + r] = (u16)u01;
;             Tl[rowl * 72 + 1 * 16 + r] = (u16)(u01 >> 16);
;             Tl[rowl * 72 + 2 * 16 + r] = (u16)u23;
	ds_write_b16_d16_hi v170, v192 offset:7088
	ds_write_b16 v170, v193 offset:7120
	ds_write_b16_d16_hi v170, v193 offset:7152
	v_mul_f32_e32 v182, v80, v80
	v_mul_f32_e32 v183, v76, v76
	v_mul_f32_e32 v184, v72, v72
	v_mul_f32_e32 v185, v68, v68
	v_add_f32_e32 v186, v182, v183
	v_add_f32_e32 v186, v186, v184
	v_add_f32_e32 v186, v186, v185
	s_nop 1
	v_add_f32_dpp v186, v186, v186 quad_perm:[1,0,3,2] row_mask:0xf bank_mask:0xf
	s_nop 1
	v_add_f32_dpp v186, v186, v186 quad_perm:[2,3,0,1] row_mask:0xf bank_mask:0xf
	s_nop 1
	v_add_f32_dpp v186, v186, v186 row_half_mirror row_mask:0xf bank_mask:0xf
	s_nop 1
	v_add_f32_dpp v186, v186, v186 row_mirror row_mask:0xf bank_mask:0xf
	v_fmamk_f32 v186, v186, 0x3c800000, v173
	v_rsq_f32_e32 v186, v186
	s_nop 0
	v_mul_f32_e32 v187, v178, v186
	v_mul_f32_e32 v188, v179, v186
	v_mul_f32_e32 v189, v180, v186
	v_mul_f32_e32 v190, v181, v186
	v_mul_f32_e32 v182, v80, v187
	v_mul_f32_e32 v183, v76, v188
	v_mul_f32_e32 v184, v72, v189
	v_mul_f32_e32 v185, v68, v190
	v_cvt_pk_bf16_f32 v192, v182, v183
	v_cvt_pk_bf16_f32 v193, v184, v185
	ds_write_b16 v170, v192 offset:7200
	ds_write_b16_d16_hi v170, v192 offset:7232
	ds_write_b16 v170, v193 offset:7264
	ds_write_b16_d16_hi v170, v193 offset:7296
	v_mul_f32_e32 v182, v81, v81
	v_mul_f32_e32 v183, v77, v77
	v_mul_f32_e32 v184, v73, v73
	v_mul_f32_e32 v185, v69, v69
	v_add_f32_e32 v186, v182, v183
	v_add_f32_e32 v186, v186, v184
	v_add_f32_e32 v186, v186, v185
	s_nop 1
	v_add_f32_dpp v186, v186, v186 quad_perm:[1,0,3,2] row_mask:0xf bank_mask:0xf
	s_nop 1
	v_add_f32_dpp v186, v186, v186 quad_perm:[2,3,0,1] row_mask:0xf bank_mask:0xf
	s_nop 1
	v_add_f32_dpp v186, v186, v186 row_half_mirror row_mask:0xf bank_mask:0xf
	s_nop 1
	v_add_f32_dpp v186, v186, v186 row_mirror row_mask:0xf bank_mask:0xf
	v_fmamk_f32 v186, v186, 0x3c800000, v173
	v_rsq_f32_e32 v186, v186
	s_nop 0
	v_mul_f32_e32 v187, v178, v186
	v_mul_f32_e32 v188, v179, v186
	v_mul_f32_e32 v189, v180, v186
	v_mul_f32_e32 v190, v181, v186
	v_mul_f32_e32 v182, v81, v187
	v_mul_f32_e32 v183, v77, v188
	v_mul_f32_e32 v184, v73, v189
	v_mul_f32_e32 v185, v69, v190
	v_cvt_pk_bf16_f32 v192, v182, v183
	v_cvt_pk_bf16_f32 v193, v184, v185
	ds_write_b16 v170, v192 offset:7344
	ds_write_b16_d16_hi v170, v192 offset:7376
	ds_write_b16 v170, v193 offset:7408
	ds_write_b16_d16_hi v170, v193 offset:7440
	ds_read_b128 v[130:133], v171 offset:0
	ds_read_b128 v[134:137], v171 offset:1152
	ds_read_b128 v[138:141], v171 offset:2304
	ds_read_b128 v[142:145], v171 offset:3456
	ds_read_b128 v[146:149], v171 offset:4608
	ds_read_b128 v[150:153], v171 offset:5760
	ds_read_b128 v[154:157], v171 offset:6912
	ds_read_b128 v[158:161], v171 offset:8064
	s_waitcnt lgkmcnt(7)
	global_store_dwordx4 v172, v[130:133], s[44:45] offset:0 sc1
	s_waitcnt lgkmcnt(6)
	global_store_dwordx4 v172, v[134:137], s[44:45] offset:1024 sc1
	s_waitcnt lgkmcnt(5)
	global_store_dwordx4 v172, v[138:141], s[44:45] offset:2048 sc1
	s_waitcnt lgkmcnt(4)
	global_store_dwordx4 v172, v[142:145], s[44:45] offset:3072 sc1
	s_waitcnt lgkmcnt(3)
	global_store_dwordx4 v172, v[146:149], s[62:63] offset:0 sc1
	s_waitcnt lgkmcnt(2)
	global_store_dwordx4 v172, v[150:153], s[62:63] offset:1024 sc1
	s_waitcnt lgkmcnt(1)
	global_store_dwordx4 v172, v[154:157], s[62:63] offset:2048 sc1
	s_waitcnt lgkmcnt(0)
	global_store_dwordx4 v172, v[158:161], s[62:63] offset:3072 sc1
	s_add_u32 s44, s44, 0x2000
	s_addc_u32 s45, s45, 0
	s_add_u32 s62, s62, 0x2000
	s_addc_u32 s63, s63, 0
	v_mul_f32_e32 v182, v62, v62
	v_mul_f32_e32 v183, v58, v58
	v_mul_f32_e32 v184, v54, v54
	v_mul_f32_e32 v185, v50, v50
	v_add_f32_e32 v186, v182, v183
	v_add_f32_e32 v186, v186, v184
	v_add_f32_e32 v186, v186, v185
	s_nop 1
	v_add_f32_dpp v186, v186, v186 quad_perm:[1,0,3,2] row_mask:0xf bank_mask:0xf
	s_nop 1
	v_add_f32_dpp v186, v186, v186 quad_perm:[2,3,0,1] row_mask:0xf bank_mask:0xf
	s_nop 1
	v_add_f32_dpp v186, v186, v186 row_half_mirror row_mask:0xf bank_mask:0xf
	s_nop 1
	v_add_f32_dpp v186, v186, v186 row_mirror row_mask:0xf bank_mask:0xf
	v_fmamk_f32 v186, v186, 0x3c800000, v173
	v_rsq_f32_e32 v186, v186
	s_nop 0
	v_mul_f32_e32 v187, v178, v186
	v_mul_f32_e32 v188, v179, v186
	v_mul_f32_e32 v189, v180, v186
	v_mul_f32_e32 v190, v181, v186
	v_mul_f32_e32 v182, v62, v187
	v_mul_f32_e32 v183, v58, v188
	v_mul_f32_e32 v184, v54, v189
	v_mul_f32_e32 v185, v50, v190
	v_cvt_pk_bf16_f32 v192, v182, v183
	v_cvt_pk_bf16_f32 v193, v184, v185
	ds_write_b16 v170, v192 offset:0
	ds_write_b16_d16_hi v170, v192 offset:32
	ds_write_b16 v170, v193 offset:64
	ds_write_b16_d16_hi v170, v193 offset:96
	v_mul_f32_e32 v182, v63, v63
	v_mul_f32_e32 v183, v59, v59
	v_mul_f32_e32 v184, v55, v55
	v_mul_f32_e32 v185, v51, v51
	v_add_f32_e32 v186, v182, v183
	v_add_f32_e32 v186, v186, v184
	v_add_f32_e32 v186, v186, v185
	s_nop 1
	v_add_f32_dpp v186, v186, v186 quad_perm:[1,0,3,2] row_mask:0xf bank_mask:0xf
	s_nop 1
	v_add_f32_dpp v186, v186, v186 quad_perm:[2,3,0,1] row_mask:0xf bank_mask:0xf
	s_nop 1
	v_add_f32_dpp v186, v186, v186 row_half_mirror row_mask:0xf bank_mask:0xf
	s_nop 1
	v_add_f32_dpp v186, v186, v186 row_mirror row_mask:0xf bank_mask:0xf
	v_fmamk_f32 v186, v186, 0x3c800000, v173
	v_rsq_f32_e32 v186, v186
	s_nop 0
	v_mul_f32_e32 v187, v178, v186
	v_mul_f32_e32 v188, v179, v186
	v_mul_f32_e32 v189, v180, v186
	v_mul_f32_e32 v190, v181, v186
	v_mul_f32_e32 v182, v63, v187
	v_mul_f32_e32 v183, v59, v188
	v_mul_f32_e32 v184, v55, v189
	v_mul_f32_e32 v185, v51, v190
	v_cvt_pk_bf16_f32 v192, v182, v183
	v_cvt_pk_bf16_f32 v193, v184, v185
	ds_write_b16 v170, v192 offset:144
	ds_write_b16_d16_hi v170, v192 offset:176
; template <int EPI>
; DI void gemm_phase(const P& p, int l, const u16* __restrict__ A, const u16* __restrict__ Bt, int mpx, char* lds) {
;     ...
;             if (donorm) {
;               float ss = v0 * v0 + v1 * v1 + v2 * v2 + v3 * v3;
;               ss += __shfl_xor(ss, 1);
;               ss += __shfl_xor(ss, 2);
;               ss += __shfl_xor(ss, 4);
;               ss += __shfl_xor(ss, 8);
;               const float inv = rsqrtf(ss * (1.f / 64.f) + 1e-6f);
;               v0 *= inv * gv0; v1 *= inv * gv1; v2 *= inv * gv2; v3 *= inv * gv3;
;             }
;             if (dorope) {
;               float sr, cr, sc, cc;
;               sincos_rev((float)(s >> 6) * invf64, sr, cr);
;               sincos_rev((float)(s & 63) * invf64, sc, cc);
;               const float a1 = v0, a2 = v1, b1 = v2, b2 = v3;
;               v0 = a1 * cr - a2 * sr;
;               v1 = a2 * cr + a1 * sr;
;               v2 = b1 * cc - b2 * sc;
;               v3 = b2 * cc + b1 * sc;
;             }
;           } else if (tr == 4) {
;             float sr, cr, sc, cc;
;             sincos_rev((float)(s >> 6) * invf32, sr, cr);
;             sincos_rev((float)(s & 63) * invf32, sc, cc);
;             const float p0 = __shfl_xor(v0, 8), p1 = __shfl_xor(v1, 8), p2 = __shfl_xor(v2, 8), p3 = __shfl_xor(v3, 8);
;             v0 = lo8 ? (v0 * cr - p0 * sr) : (v0 * cr + p0 * sr);
;             v1 = lo8 ? (v1 * cc - p1 * sc) : (v1 * cc + p1 * sc);
;             v2 = lo8 ? (v2 * cr - p2 * sr) : (v2 * cr + p2 * sr);
;             v3 = lo8 ? (v3 * cc - p3 * sc) : (v3 * cc + p3 * sc);
;           }
;           const unsigned u01 = pack2(v0, v1), u23 = pack2(v2, v3);
;           if (kind == 1) {
;             Tl[(0 * 16 + r) * 72 + rowl] = (u16)u01;
;             Tl[(1 * 16 + r) * 72 + rowl] = (u16)(u01 >> 16);
;             Tl[(2 * 16 + r) * 72 + rowl] = (u16)u23;
;             Tl[(3 * 16 + r) * 72 + rowl] = (u16)(u23 >> 16);
;           } else if (tr == 2) {
;             Tl[rowl * 72 + 0 * 16 + r] = f2h(v0);
;             Tl[rowl * 72 + 1 * 16 + r] = f2h(v1);
;             Tl[rowl * 72 + 2 * 16 + r] = f2h(v2);
;             Tl[rowl * 72 + 3 * 16 + r] = f2h(v3);
;           } else {
;             Tl[rowl * 72 + 0 * 16 + r] = (u16)u01;
;             Tl[rowl * 72 + 1 * 16 + r] = (u16)(u01 >> 16);
;             Tl[rowl * 72 + 2 * 16 + r] = (u16)u23;
	ds_write_b16 v170, v193 offset:208
	ds_write_b16_d16_hi v170, v193 offset:240
	v_mul_f32_e32 v182, v64, v64
	v_mul_f32_e32 v183, v60, v60
	v_mul_f32_e32 v184, v56, v56
	v_mul_f32_e32 v185, v52, v52
	v_add_f32_e32 v186, v182, v183
	v_add_f32_e32 v186, v186, v184
	v_add_f32_e32 v186, v186, v185
	s_nop 1
	v_add_f32_dpp v186, v186, v186 quad_perm:[1,0,3,2] row_mask:0xf bank_mask:0xf
	s_nop 1
	v_add_f32_dpp v186, v186, v186 quad_perm:[2,3,0,1] row_mask:0xf bank_mask:0xf
	s_nop 1
	v_add_f32_dpp v186, v186, v186 row_half_mirror row_mask:0xf bank_mask:0xf
	s_nop 1
	v_add_f32_dpp v186, v186, v186 row_mirror row_mask:0xf bank_mask:0xf
	v_fmamk_f32 v186, v186, 0x3c800000, v173
	v_rsq_f32_e32 v186, v186
	s_nop 0
	v_mul_f32_e32 v187, v178, v186
	v_mul_f32_e32 v188, v179, v186
	v_mul_f32_e32 v189, v180, v186
	v_mul_f32_e32 v190, v181, v186
	v_mul_f32_e32 v182, v64, v187
	v_mul_f32_e32 v183, v60, v188
	v_mul_f32_e32 v184, v56, v189
	v_mul_f32_e32 v185, v52, v190
	v_cvt_pk_bf16_f32 v192, v182, v183
	v_cvt_pk_bf16_f32 v193, v184, v185
	ds_write_b16 v170, v192 offset:288
	ds_write_b16_d16_hi v170, v192 offset:320
	ds_write_b16 v170, v193 offset:352
	ds_write_b16_d16_hi v170, v193 offset:384
	v_mul_f32_e32 v182, v65, v65
	v_mul_f32_e32 v183, v61, v61
	v_mul_f32_e32 v184, v57, v57
	v_mul_f32_e32 v185, v53, v53
	v_add_f32_e32 v186, v182, v183
	v_add_f32_e32 v186, v186, v184
	v_add_f32_e32 v186, v186, v185
	s_nop 1
	v_add_f32_dpp v186, v186, v186 quad_perm:[1,0,3,2] row_mask:0xf bank_mask:0xf
	s_nop 1
	v_add_f32_dpp v186, v186, v186 quad_perm:[2,3,0,1] row_mask:0xf bank_mask:0xf
	s_nop 1
	v_add_f32_dpp v186, v186, v186 row_half_mirror row_mask:0xf bank_mask:0xf
	s_nop 1
	v_add_f32_dpp v186, v186, v186 row_mirror row_mask:0xf bank_mask:0xf
	v_fmamk_f32 v186, v186, 0x3c800000, v173
	v_rsq_f32_e32 v186, v186
	s_nop 0
	v_mul_f32_e32 v187, v178, v186
	v_mul_f32_e32 v188, v179, v186
	v_mul_f32_e32 v189, v180, v186
	v_mul_f32_e32 v190, v181, v186
	v_mul_f32_e32 v182, v65, v187
	v_mul_f32_e32 v183, v61, v188
	v_mul_f32_e32 v184, v57, v189
	v_mul_f32_e32 v185, v53, v190
	v_cvt_pk_bf16_f32 v192, v182, v183
	v_cvt_pk_bf16_f32 v193, v184, v185
	ds_write_b16 v170, v192 offset:432
	ds_write_b16_d16_hi v170, v192 offset:464
	ds_write_b16 v170, v193 offset:496
	ds_write_b16_d16_hi v170, v193 offset:528
	v_mul_f32_e32 v182, v46, v46
	v_mul_f32_e32 v183, v42, v42
	v_mul_f32_e32 v184, v38, v38
	v_mul_f32_e32 v185, v34, v34
	v_add_f32_e32 v186, v182, v183
	v_add_f32_e32 v186, v186, v184
	v_add_f32_e32 v186, v186, v185
	s_nop 1
	v_add_f32_dpp v186, v186, v186 quad_perm:[1,0,3,2] row_mask:0xf bank_mask:0xf
	s_nop 1
	v_add_f32_dpp v186, v186, v186 quad_perm:[2,3,0,1] row_mask:0xf bank_mask:0xf
	s_nop 1
	v_add_f32_dpp v186, v186, v186 row_half_mirror row_mask:0xf bank_mask:0xf
	s_nop 1
	v_add_f32_dpp v186, v186, v186 row_mirror row_mask:0xf bank_mask:0xf
	v_fmamk_f32 v186, v186, 0x3c800000, v173
	v_rsq_f32_e32 v186, v186
	s_nop 0
	v_mul_f32_e32 v187, v178, v186
	v_mul_f32_e32 v188, v179, v186
	v_mul_f32_e32 v189, v180, v186
	v_mul_f32_e32 v190, v181, v186
	v_mul_f32_e32 v182, v46, v187
	v_mul_f32_e32 v183, v42, v188
	v_mul_f32_e32 v184, v38, v189
	v_mul_f32_e32 v185, v34, v190
	v_cvt_pk_bf16_f32 v192, v182, v183
	v_cvt_pk_bf16_f32 v193, v184, v185
	ds_write_b16 v170, v192 offset:2304
	ds_write_b16_d16_hi v170, v192 offset:2336
	ds_write_b16 v170, v193 offset:2368
	ds_write_b16_d16_hi v170, v193 offset:2400
	v_mul_f32_e32 v182, v47, v47
	v_mul_f32_e32 v183, v43, v43
	v_mul_f32_e32 v184, v39, v39
	v_mul_f32_e32 v185, v35, v35
	v_add_f32_e32 v186, v182, v183
	v_add_f32_e32 v186, v186, v184
	v_add_f32_e32 v186, v186, v185
	s_nop 1
	v_add_f32_dpp v186, v186, v186 quad_perm:[1,0,3,2] row_mask:0xf bank_mask:0xf
	s_nop 1
	v_add_f32_dpp v186, v186, v186 quad_perm:[2,3,0,1] row_mask:0xf bank_mask:0xf
	s_nop 1
	v_add_f32_dpp v186, v186, v186 row_half_mirror row_mask:0xf bank_mask:0xf
	s_nop 1
	v_add_f32_dpp v186, v186, v186 row_mirror row_mask:0xf bank_mask:0xf
	v_fmamk_f32 v186, v186, 0x3c800000, v173
	v_rsq_f32_e32 v186, v186
	s_nop 0
	v_mul_f32_e32 v187, v178, v186
	v_mul_f32_e32 v188, v179, v186
	v_mul_f32_e32 v189, v180, v186
	v_mul_f32_e32 v190, v181, v186
	v_mul_f32_e32 v182, v47, v187
	v_mul_f32_e32 v183, v43, v188
	v_mul_f32_e32 v184, v39, v189
	v_mul_f32_e32 v185, v35, v190
	v_cvt_pk_bf16_f32 v192, v182, v183
	v_cvt_pk_bf16_f32 v193, v184, v185
	ds_write_b16 v170, v192 offset:2448
	ds_write_b16_d16_hi v170, v192 offset:2480
	ds_write_b16 v170, v193 offset:2512
	ds_write_b16_d16_hi v170, v193 offset:2544
	v_mul_f32_e32 v182, v48, v48
	v_mul_f32_e32 v183, v44, v44
	v_mul_f32_e32 v184, v40, v40
	v_mul_f32_e32 v185, v36, v36
	v_add_f32_e32 v186, v182, v183
	v_add_f32_e32 v186, v186, v184
	v_add_f32_e32 v186, v186, v185
	s_nop 1
	v_add_f32_dpp v186, v186, v186 quad_perm:[1,0,3,2] row_mask:0xf bank_mask:0xf
	s_nop 1
	v_add_f32_dpp v186, v186, v186 quad_perm:[2,3,0,1] row_mask:0xf bank_mask:0xf
	s_nop 1
	v_add_f32_dpp v186, v186, v186 row_half_mirror row_mask:0xf bank_mask:0xf
	s_nop 1
	v_add_f32_dpp v186, v186, v186 row_mirror row_mask:0xf bank_mask:0xf
	v_fmamk_f32 v186, v186, 0x3c800000, v173
	v_rsq_f32_e32 v186, v186
	s_nop 0
	v_mul_f32_e32 v187, v178, v186
	v_mul_f32_e32 v188, v179, v186
	v_mul_f32_e32 v189, v180, v186
	v_mul_f32_e32 v190, v181, v186
	v_mul_f32_e32 v182, v48, v187
	v_mul_f32_e32 v183, v44, v188
	v_mul_f32_e32 v184, v40, v189
	v_mul_f32_e32 v185, v36, v190
	v_cvt_pk_bf16_f32 v192, v182, v183
	v_cvt_pk_bf16_f32 v193, v184, v185
	ds_write_b16 v170, v192 offset:2592
	ds_write_b16_d16_hi v170, v192 offset:2624
	ds_write_b16 v170, v193 offset:2656
	ds_write_b16_d16_hi v170, v193 offset:2688
; template <int EPI>
; DI void gemm_phase(const P& p, int l, const u16* __restrict__ A, const u16* __restrict__ Bt, int mpx, char* lds) {
;     ...
;             if (donorm) {
;               float ss = v0 * v0 + v1 * v1 + v2 * v2 + v3 * v3;
;               ss += __shfl_xor(ss, 1);
;               ss += __shfl_xor(ss, 2);
;               ss += __shfl_xor(ss, 4);
;               ss += __shfl_xor(ss, 8);
;               const float inv = rsqrtf(ss * (1.f / 64.f) + 1e-6f);
;               v0 *= inv * gv0; v1 *= inv * gv1; v2 *= inv * gv2; v3 *= inv * gv3;
;             }
;             if (dorope) {
;               float sr, cr, sc, cc;
;               sincos_rev((float)(s >> 6) * invf64, sr, cr);
;               sincos_rev((float)(s & 63) * invf64, sc, cc);
;               const float a1 = v0, a2 = v1, b1 = v2, b2 = v3;
;               v0 = a1 * cr - a2 * sr;
;               v1 = a2 * cr + a1 * sr;
;               v2 = b1 * cc - b2 * sc;
;               v3 = b2 * cc + b1 * sc;
;             }
;           } else if (tr == 4) {
;             float sr, cr, sc, cc;
;             sincos_rev((float)(s >> 6) * invf32, sr, cr);
;             sincos_rev((float)(s & 63) * invf32, sc, cc);
;             const float p0 = __shfl_xor(v0, 8), p1 = __shfl_xor(v1, 8), p2 = __shfl_xor(v2, 8), p3 = __shfl_xor(v3, 8);
;             v0 = lo8 ? (v0 * cr - p0 * sr) : (v0 * cr + p0 * sr);
;             v1 = lo8 ? (v1 * cc - p1 * sc) : (v1 * cc + p1 * sc);
;             v2 = lo8 ? (v2 * cr - p2 * sr) : (v2 * cr + p2 * sr);
;             v3 = lo8 ? (v3 * cc - p3 * sc) : (v3 * cc + p3 * sc);
;           }
;           const unsigned u01 = pack2(v0, v1), u23 = pack2(v2, v3);
;           if (kind == 1) {
;             Tl[(0 * 16 + r) * 72 + rowl] = (u16)u01;
;             Tl[(1 * 16 + r) * 72 + rowl] = (u16)(u01 >> 16);
;             Tl[(2 * 16 + r) * 72 + rowl] = (u16)u23;
;             Tl[(3 * 16 + r) * 72 + rowl] = (u16)(u23 >> 16);
;           } else if (tr == 2) {
;             Tl[rowl * 72 + 0 * 16 + r] = f2h(v0);
;             Tl[rowl * 72 + 1 * 16 + r] = f2h(v1);
;             Tl[rowl * 72 + 2 * 16 + r] = f2h(v2);
;             Tl[rowl * 72 + 3 * 16 + r] = f2h(v3);
;           } else {
;             Tl[rowl * 72 + 0 * 16 + r] = (u16)u01;
;             Tl[rowl * 72 + 1 * 16 + r] = (u16)(u01 >> 16);
;             Tl[rowl * 72 + 2 * 16 + r] = (u16)u23;
	v_mul_f32_e32 v182, v49, v49
	v_mul_f32_e32 v183, v45, v45
	v_mul_f32_e32 v184, v41, v41
	v_mul_f32_e32 v185, v37, v37
	v_add_f32_e32 v186, v182, v183
	v_add_f32_e32 v186, v186, v184
	v_add_f32_e32 v186, v186, v185
	s_nop 1
	v_add_f32_dpp v186, v186, v186 quad_perm:[1,0,3,2] row_mask:0xf bank_mask:0xf
	s_nop 1
	v_add_f32_dpp v186, v186, v186 quad_perm:[2,3,0,1] row_mask:0xf bank_mask:0xf
	s_nop 1
	v_add_f32_dpp v186, v186, v186 row_half_mirror row_mask:0xf bank_mask:0xf
	s_nop 1
	v_add_f32_dpp v186, v186, v186 row_mirror row_mask:0xf bank_mask:0xf
	v_fmamk_f32 v186, v186, 0x3c800000, v173
	v_rsq_f32_e32 v186, v186
	s_nop 0
	v_mul_f32_e32 v187, v178, v186
	v_mul_f32_e32 v188, v179, v186
	v_mul_f32_e32 v189, v180, v186
	v_mul_f32_e32 v190, v181, v186
	v_mul_f32_e32 v182, v49, v187
	v_mul_f32_e32 v183, v45, v188
	v_mul_f32_e32 v184, v41, v189
	v_mul_f32_e32 v185, v37, v190
	v_cvt_pk_bf16_f32 v192, v182, v183
	v_cvt_pk_bf16_f32 v193, v184, v185
	ds_write_b16 v170, v192 offset:2736
	ds_write_b16_d16_hi v170, v192 offset:2768
	ds_write_b16 v170, v193 offset:2800
	ds_write_b16_d16_hi v170, v193 offset:2832
	v_mul_f32_e32 v182, v30, v30
	v_mul_f32_e32 v183, v26, v26
	v_mul_f32_e32 v184, v22, v22
	v_mul_f32_e32 v185, v18, v18
	v_add_f32_e32 v186, v182, v183
	v_add_f32_e32 v186, v186, v184
	v_add_f32_e32 v186, v186, v185
	s_nop 1
	v_add_f32_dpp v186, v186, v186 quad_perm:[1,0,3,2] row_mask:0xf bank_mask:0xf
	s_nop 1
	v_add_f32_dpp v186, v186, v186 quad_perm:[2,3,0,1] row_mask:0xf bank_mask:0xf
	s_nop 1
	v_add_f32_dpp v186, v186, v186 row_half_mirror row_mask:0xf bank_mask:0xf
	s_nop 1
	v_add_f32_dpp v186, v186, v186 row_mirror row_mask:0xf bank_mask:0xf
	v_fmamk_f32 v186, v186, 0x3c800000, v173
	v_rsq_f32_e32 v186, v186
	s_nop 0
	v_mul_f32_e32 v187, v178, v186
	v_mul_f32_e32 v188, v179, v186
	v_mul_f32_e32 v189, v180, v186
	v_mul_f32_e32 v190, v181, v186
	v_mul_f32_e32 v182, v30, v187
	v_mul_f32_e32 v183, v26, v188
	v_mul_f32_e32 v184, v22, v189
	v_mul_f32_e32 v185, v18, v190
	v_cvt_pk_bf16_f32 v192, v182, v183
	v_cvt_pk_bf16_f32 v193, v184, v185
	ds_write_b16 v170, v192 offset:4608
	ds_write_b16_d16_hi v170, v192 offset:4640
	ds_write_b16 v170, v193 offset:4672
	ds_write_b16_d16_hi v170, v193 offset:4704
	v_mul_f32_e32 v182, v31, v31
	v_mul_f32_e32 v183, v27, v27
	v_mul_f32_e32 v184, v23, v23
	v_mul_f32_e32 v185, v19, v19
	v_add_f32_e32 v186, v182, v183
	v_add_f32_e32 v186, v186, v184
	v_add_f32_e32 v186, v186, v185
	s_nop 1
	v_add_f32_dpp v186, v186, v186 quad_perm:[1,0,3,2] row_mask:0xf bank_mask:0xf
	s_nop 1
	v_add_f32_dpp v186, v186, v186 quad_perm:[2,3,0,1] row_mask:0xf bank_mask:0xf
	s_nop 1
	v_add_f32_dpp v186, v186, v186 row_half_mirror row_mask:0xf bank_mask:0xf
	s_nop 1
	v_add_f32_dpp v186, v186, v186 row_mirror row_mask:0xf bank_mask:0xf
	v_fmamk_f32 v186, v186, 0x3c800000, v173
	v_rsq_f32_e32 v186, v186
	s_nop 0
	v_mul_f32_e32 v187, v178, v186
	v_mul_f32_e32 v188, v179, v186
	v_mul_f32_e32 v189, v180, v186
	v_mul_f32_e32 v190, v181, v186
	v_mul_f32_e32 v182, v31, v187
	v_mul_f32_e32 v183, v27, v188
	v_mul_f32_e32 v184, v23, v189
	v_mul_f32_e32 v185, v19, v190
	v_cvt_pk_bf16_f32 v192, v182, v183
	v_cvt_pk_bf16_f32 v193, v184, v185
	ds_write_b16 v170, v192 offset:4752
	ds_write_b16_d16_hi v170, v192 offset:4784
	ds_write_b16 v170, v193 offset:4816
	ds_write_b16_d16_hi v170, v193 offset:4848
	v_mul_f32_e32 v182, v32, v32
	v_mul_f32_e32 v183, v28, v28
	v_mul_f32_e32 v184, v24, v24
	v_mul_f32_e32 v185, v20, v20
	v_add_f32_e32 v186, v182, v183
	v_add_f32_e32 v186, v186, v184
	v_add_f32_e32 v186, v186, v185
	s_nop 1
	v_add_f32_dpp v186, v186, v186 quad_perm:[1,0,3,2] row_mask:0xf bank_mask:0xf
	s_nop 1
	v_add_f32_dpp v186, v186, v186 quad_perm:[2,3,0,1] row_mask:0xf bank_mask:0xf
	s_nop 1
	v_add_f32_dpp v186, v186, v186 row_half_mirror row_mask:0xf bank_mask:0xf
	s_nop 1
	v_add_f32_dpp v186, v186, v186 row_mirror row_mask:0xf bank_mask:0xf
	v_fmamk_f32 v186, v186, 0x3c800000, v173
	v_rsq_f32_e32 v186, v186
	s_nop 0
	v_mul_f32_e32 v187, v178, v186
	v_mul_f32_e32 v188, v179, v186
	v_mul_f32_e32 v189, v180, v186
	v_mul_f32_e32 v190, v181, v186
	v_mul_f32_e32 v182, v32, v187
	v_mul_f32_e32 v183, v28, v188
	v_mul_f32_e32 v184, v24, v189
	v_mul_f32_e32 v185, v20, v190
	v_cvt_pk_bf16_f32 v192, v182, v183
	v_cvt_pk_bf16_f32 v193, v184, v185
	ds_write_b16 v170, v192 offset:4896
	ds_write_b16_d16_hi v170, v192 offset:4928
	ds_write_b16 v170, v193 offset:4960
	ds_write_b16_d16_hi v170, v193 offset:4992
	v_mul_f32_e32 v182, v33, v33
	v_mul_f32_e32 v183, v29, v29
	v_mul_f32_e32 v184, v25, v25
	v_mul_f32_e32 v185, v21, v21
	v_add_f32_e32 v186, v182, v183
	v_add_f32_e32 v186, v186, v184
	v_add_f32_e32 v186, v186, v185
	s_nop 1
	v_add_f32_dpp v186, v186, v186 quad_perm:[1,0,3,2] row_mask:0xf bank_mask:0xf
	s_nop 1
	v_add_f32_dpp v186, v186, v186 quad_perm:[2,3,0,1] row_mask:0xf bank_mask:0xf
	s_nop 1
	v_add_f32_dpp v186, v186, v186 row_half_mirror row_mask:0xf bank_mask:0xf
	s_nop 1
	v_add_f32_dpp v186, v186, v186 row_mirror row_mask:0xf bank_mask:0xf
	v_fmamk_f32 v186, v186, 0x3c800000, v173
	v_rsq_f32_e32 v186, v186
	s_nop 0
	v_mul_f32_e32 v187, v178, v186
	v_mul_f32_e32 v188, v179, v186
	v_mul_f32_e32 v189, v180, v186
	v_mul_f32_e32 v190, v181, v186
	v_mul_f32_e32 v182, v33, v187
	v_mul_f32_e32 v183, v29, v188
	v_mul_f32_e32 v184, v25, v189
	v_mul_f32_e32 v185, v21, v190
	v_cvt_pk_bf16_f32 v192, v182, v183
	v_cvt_pk_bf16_f32 v193, v184, v185
	ds_write_b16 v170, v192 offset:5040
	ds_write_b16_d16_hi v170, v192 offset:5072
	ds_write_b16 v170, v193 offset:5104
; template <int EPI>
; DI void gemm_phase(const P& p, int l, const u16* __restrict__ A, const u16* __restrict__ Bt, int mpx, char* lds) {
;     ...
;             if (donorm) {
;               float ss = v0 * v0 + v1 * v1 + v2 * v2 + v3 * v3;
;               ss += __shfl_xor(ss, 1);
;               ss += __shfl_xor(ss, 2);
;               ss += __shfl_xor(ss, 4);
;               ss += __shfl_xor(ss, 8);
;               const float inv = rsqrtf(ss * (1.f / 64.f) + 1e-6f);
;               v0 *= inv * gv0; v1 *= inv * gv1; v2 *= inv * gv2; v3 *= inv * gv3;
;             }
;             if (dorope) {
;               float sr, cr, sc, cc;
;               sincos_rev((float)(s >> 6) * invf64, sr, cr);
;               sincos_rev((float)(s & 63) * invf64, sc, cc);
;               const float a1 = v0, a2 = v1, b1 = v2, b2 = v3;
;               v0 = a1 * cr - a2 * sr;
;               v1 = a2 * cr + a1 * sr;
;               v2 = b1 * cc - b2 * sc;
;               v3 = b2 * cc + b1 * sc;
;             }
;           } else if (tr == 4) {
;             float sr, cr, sc, cc;
;             sincos_rev((float)(s >> 6) * invf32, sr, cr);
;             sincos_rev((float)(s & 63) * invf32, sc, cc);
;             const float p0 = __shfl_xor(v0, 8), p1 = __shfl_xor(v1, 8), p2 = __shfl_xor(v2, 8), p3 = __shfl_xor(v3, 8);
;             v0 = lo8 ? (v0 * cr - p0 * sr) : (v0 * cr + p0 * sr);
;             v1 = lo8 ? (v1 * cc - p1 * sc) : (v1 * cc + p1 * sc);
;             v2 = lo8 ? (v2 * cr - p2 * sr) : (v2 * cr + p2 * sr);
;             v3 = lo8 ? (v3 * cc - p3 * sc) : (v3 * cc + p3 * sc);
;           }
;           const unsigned u01 = pack2(v0, v1), u23 = pack2(v2, v3);
;           if (kind == 1) {
;             Tl[(0 * 16 + r) * 72 + rowl] = (u16)u01;
;             Tl[(1 * 16 + r) * 72 + rowl] = (u16)(u01 >> 16);
;             Tl[(2 * 16 + r) * 72 + rowl] = (u16)u23;
;             Tl[(3 * 16 + r) * 72 + rowl] = (u16)(u23 >> 16);
;           } else if (tr == 2) {
;             Tl[rowl * 72 + 0 * 16 + r] = f2h(v0);
;             Tl[rowl * 72 + 1 * 16 + r] = f2h(v1);
;             Tl[rowl * 72 + 2 * 16 + r] = f2h(v2);
;             Tl[rowl * 72 + 3 * 16 + r] = f2h(v3);
;           } else {
;             Tl[rowl * 72 + 0 * 16 + r] = (u16)u01;
;             Tl[rowl * 72 + 1 * 16 + r] = (u16)(u01 >> 16);
;             Tl[rowl * 72 + 2 * 16 + r] = (u16)u23;
	ds_write_b16_d16_hi v170, v193 offset:5136
	v_mul_f32_e32 v182, v166, v166
	v_mul_f32_e32 v183, v162, v162
	v_mul_f32_e32 v184, v2, v2
	v_mul_f32_e32 v185, v6, v6
	v_add_f32_e32 v186, v182, v183
	v_add_f32_e32 v186, v186, v184
	v_add_f32_e32 v186, v186, v185
	s_nop 1
	v_add_f32_dpp v186, v186, v186 quad_perm:[1,0,3,2] row_mask:0xf bank_mask:0xf
	s_nop 1
	v_add_f32_dpp v186, v186, v186 quad_perm:[2,3,0,1] row_mask:0xf bank_mask:0xf
	s_nop 1
	v_add_f32_dpp v186, v186, v186 row_half_mirror row_mask:0xf bank_mask:0xf
	s_nop 1
	v_add_f32_dpp v186, v186, v186 row_mirror row_mask:0xf bank_mask:0xf
	v_fmamk_f32 v186, v186, 0x3c800000, v173
	v_rsq_f32_e32 v186, v186
	s_nop 0
	v_mul_f32_e32 v187, v178, v186
	v_mul_f32_e32 v188, v179, v186
	v_mul_f32_e32 v189, v180, v186
	v_mul_f32_e32 v190, v181, v186
	v_mul_f32_e32 v182, v166, v187
	v_mul_f32_e32 v183, v162, v188
	v_mul_f32_e32 v184, v2, v189
	v_mul_f32_e32 v185, v6, v190
	v_cvt_pk_bf16_f32 v192, v182, v183
	v_cvt_pk_bf16_f32 v193, v184, v185
	ds_write_b16 v170, v192 offset:6912
	ds_write_b16_d16_hi v170, v192 offset:6944
	ds_write_b16 v170, v193 offset:6976
	ds_write_b16_d16_hi v170, v193 offset:7008
	v_mul_f32_e32 v182, v167, v167
	v_mul_f32_e32 v183, v163, v163
	v_mul_f32_e32 v184, v3, v3
	v_mul_f32_e32 v185, v7, v7
	v_add_f32_e32 v186, v182, v183
	v_add_f32_e32 v186, v186, v184
	v_add_f32_e32 v186, v186, v185
	s_nop 1
	v_add_f32_dpp v186, v186, v186 quad_perm:[1,0,3,2] row_mask:0xf bank_mask:0xf
	s_nop 1
	v_add_f32_dpp v186, v186, v186 quad_perm:[2,3,0,1] row_mask:0xf bank_mask:0xf
	s_nop 1
	v_add_f32_dpp v186, v186, v186 row_half_mirror row_mask:0xf bank_mask:0xf
	s_nop 1
	v_add_f32_dpp v186, v186, v186 row_mirror row_mask:0xf bank_mask:0xf
	v_fmamk_f32 v186, v186, 0x3c800000, v173
	v_rsq_f32_e32 v186, v186
	s_nop 0
	v_mul_f32_e32 v187, v178, v186
	v_mul_f32_e32 v188, v179, v186
	v_mul_f32_e32 v189, v180, v186
	v_mul_f32_e32 v190, v181, v186
	v_mul_f32_e32 v182, v167, v187
	v_mul_f32_e32 v183, v163, v188
	v_mul_f32_e32 v184, v3, v189
	v_mul_f32_e32 v185, v7, v190
	v_cvt_pk_bf16_f32 v192, v182, v183
	v_cvt_pk_bf16_f32 v193, v184, v185
	ds_write_b16 v170, v192 offset:7056
	ds_write_b16_d16_hi v170, v192 offset:7088
	ds_write_b16 v170, v193 offset:7120
	ds_write_b16_d16_hi v170, v193 offset:7152
	v_mul_f32_e32 v182, v168, v168
	v_mul_f32_e32 v183, v164, v164
	v_mul_f32_e32 v184, v4, v4
	v_mul_f32_e32 v185, v8, v8
	v_add_f32_e32 v186, v182, v183
	v_add_f32_e32 v186, v186, v184
	v_add_f32_e32 v186, v186, v185
	s_nop 1
	v_add_f32_dpp v186, v186, v186 quad_perm:[1,0,3,2] row_mask:0xf bank_mask:0xf
	s_nop 1
	v_add_f32_dpp v186, v186, v186 quad_perm:[2,3,0,1] row_mask:0xf bank_mask:0xf
	s_nop 1
	v_add_f32_dpp v186, v186, v186 row_half_mirror row_mask:0xf bank_mask:0xf
	s_nop 1
	v_add_f32_dpp v186, v186, v186 row_mirror row_mask:0xf bank_mask:0xf
	v_fmamk_f32 v186, v186, 0x3c800000, v173
	v_rsq_f32_e32 v186, v186
	s_nop 0
	v_mul_f32_e32 v187, v178, v186
	v_mul_f32_e32 v188, v179, v186
	v_mul_f32_e32 v189, v180, v186
	v_mul_f32_e32 v190, v181, v186
	v_mul_f32_e32 v182, v168, v187
	v_mul_f32_e32 v183, v164, v188
	v_mul_f32_e32 v184, v4, v189
	v_mul_f32_e32 v185, v8, v190
	v_cvt_pk_bf16_f32 v192, v182, v183
	v_cvt_pk_bf16_f32 v193, v184, v185
	ds_write_b16 v170, v192 offset:7200
	ds_write_b16_d16_hi v170, v192 offset:7232
	ds_write_b16 v170, v193 offset:7264
	ds_write_b16_d16_hi v170, v193 offset:7296
	v_mul_f32_e32 v182, v169, v169
	v_mul_f32_e32 v183, v165, v165
	v_mul_f32_e32 v184, v5, v5
	v_mul_f32_e32 v185, v9, v9
	v_add_f32_e32 v186, v182, v183
	v_add_f32_e32 v186, v186, v184
	v_add_f32_e32 v186, v186, v185
	s_nop 1
	v_add_f32_dpp v186, v186, v186 quad_perm:[1,0,3,2] row_mask:0xf bank_mask:0xf
	s_nop 1
	v_add_f32_dpp v186, v186, v186 quad_perm:[2,3,0,1] row_mask:0xf bank_mask:0xf
	s_nop 1
	v_add_f32_dpp v186, v186, v186 row_half_mirror row_mask:0xf bank_mask:0xf
	s_nop 1
	v_add_f32_dpp v186, v186, v186 row_mirror row_mask:0xf bank_mask:0xf
	v_fmamk_f32 v186, v186, 0x3c800000, v173
	v_rsq_f32_e32 v186, v186
	s_nop 0
	v_mul_f32_e32 v187, v178, v186
	v_mul_f32_e32 v188, v179, v186
	v_mul_f32_e32 v189, v180, v186
	v_mul_f32_e32 v190, v181, v186
	v_mul_f32_e32 v182, v169, v187
	v_mul_f32_e32 v183, v165, v188
	v_mul_f32_e32 v184, v5, v189
	v_mul_f32_e32 v185, v9, v190
	v_cvt_pk_bf16_f32 v192, v182, v183
	v_cvt_pk_bf16_f32 v193, v184, v185
	ds_write_b16 v170, v192 offset:7344
	ds_write_b16_d16_hi v170, v192 offset:7376
	ds_write_b16 v170, v193 offset:7408
	ds_write_b16_d16_hi v170, v193 offset:7440
	ds_read_b128 v[130:133], v171 offset:0
	ds_read_b128 v[134:137], v171 offset:1152
	ds_read_b128 v[138:141], v171 offset:2304
	ds_read_b128 v[142:145], v171 offset:3456
	ds_read_b128 v[146:149], v171 offset:4608
	ds_read_b128 v[150:153], v171 offset:5760
	ds_read_b128 v[154:157], v171 offset:6912
	ds_read_b128 v[158:161], v171 offset:8064
	s_waitcnt lgkmcnt(7)
	global_store_dwordx4 v172, v[130:133], s[44:45] offset:0 sc1
	s_waitcnt lgkmcnt(6)
	global_store_dwordx4 v172, v[134:137], s[44:45] offset:1024 sc1
	s_waitcnt lgkmcnt(5)
	global_store_dwordx4 v172, v[138:141], s[44:45] offset:2048 sc1
	s_waitcnt lgkmcnt(4)
	global_store_dwordx4 v172, v[142:145], s[44:45] offset:3072 sc1
	s_waitcnt lgkmcnt(3)
	global_store_dwordx4 v172, v[146:149], s[62:63] offset:0 sc1
	s_waitcnt lgkmcnt(2)
	global_store_dwordx4 v172, v[150:153], s[62:63] offset:1024 sc1
	s_waitcnt lgkmcnt(1)
	global_store_dwordx4 v172, v[154:157], s[62:63] offset:2048 sc1
	s_waitcnt lgkmcnt(0)
	global_store_dwordx4 v172, v[158:161], s[62:63] offset:3072 sc1
	s_branch .Lfe_done

; template <int EPI>
; DI void gemm_phase(const P& p, int l, const u16* __restrict__ A, const u16* __restrict__ Bt, int mpx, char* lds) {
;     ...
;           const unsigned u01 = pack2(v0, v1), u23 = pack2(v2, v3);
;           if (kind == 1) {
;             Tl[(0 * 16 + r) * 72 + rowl] = (u16)u01;
;             Tl[(1 * 16 + r) * 72 + rowl] = (u16)(u01 >> 16);
;             Tl[(2 * 16 + r) * 72 + rowl] = (u16)u23;
;             Tl[(3 * 16 + r) * 72 + rowl] = (u16)(u23 >> 16);
;     ...
;       __builtin_amdgcn_fence(__ATOMIC_RELEASE, "wavefront");
;       u16* dh = (kind == 1) ? dst + hf * 64 : dst + (size_t)(hf * 64) * rstride;
; #pragma unroll
;       for (int i = 0; i < 8; ++i) {
;         const int c = lane + i * 64;
;         const int row = c >> 3, cc = c & 7;
;         uint4 v = *(const uint4*)&Tl[row * 72 + cc * 8];
;         *(uint4*)(dh + (size_t)row * rstride + cc * 8) = v;
;       }
.Lfe_k1:
	s_mov_b64 s[62:63], s[44:45]
	v_cvt_pk_bf16_f32 v178, v126, v122
	v_cvt_pk_bf16_f32 v179, v118, v114
	ds_write_b16 v170, v178 offset:0
	ds_write_b16_d16_hi v170, v178 offset:2304
	ds_write_b16 v170, v179 offset:4608
	ds_write_b16_d16_hi v170, v179 offset:6912
	v_cvt_pk_bf16_f32 v184, v127, v123
	v_cvt_pk_bf16_f32 v185, v119, v115
	ds_write_b16 v170, v184 offset:2
	ds_write_b16_d16_hi v170, v184 offset:2306
	ds_write_b16 v170, v185 offset:4610
	ds_write_b16_d16_hi v170, v185 offset:6914
	v_cvt_pk_bf16_f32 v190, v128, v124
	v_cvt_pk_bf16_f32 v191, v120, v116
	ds_write_b16 v170, v190 offset:4
	ds_write_b16_d16_hi v170, v190 offset:2308
	ds_write_b16 v170, v191 offset:4612
	ds_write_b16_d16_hi v170, v191 offset:6916
	v_cvt_pk_bf16_f32 v176, v129, v125
	v_cvt_pk_bf16_f32 v177, v121, v117
	ds_write_b16 v170, v176 offset:6
	ds_write_b16_d16_hi v170, v176 offset:2310
	ds_write_b16 v170, v177 offset:4614
	ds_write_b16_d16_hi v170, v177 offset:6918
	v_cvt_pk_bf16_f32 v182, v110, v106
	v_cvt_pk_bf16_f32 v183, v102, v98
	ds_write_b16 v170, v182 offset:32
	ds_write_b16_d16_hi v170, v182 offset:2336
	ds_write_b16 v170, v183 offset:4640
	ds_write_b16_d16_hi v170, v183 offset:6944
	v_cvt_pk_bf16_f32 v188, v111, v107
	v_cvt_pk_bf16_f32 v189, v103, v99
	ds_write_b16 v170, v188 offset:34
	ds_write_b16_d16_hi v170, v188 offset:2338
	ds_write_b16 v170, v189 offset:4642
	ds_write_b16_d16_hi v170, v189 offset:6946
	v_cvt_pk_bf16_f32 v174, v112, v108
	v_cvt_pk_bf16_f32 v175, v104, v100
	ds_write_b16 v170, v174 offset:36
	ds_write_b16_d16_hi v170, v174 offset:2340
	ds_write_b16 v170, v175 offset:4644
	ds_write_b16_d16_hi v170, v175 offset:6948
	v_cvt_pk_bf16_f32 v180, v113, v109
	v_cvt_pk_bf16_f32 v181, v105, v101
	ds_write_b16 v170, v180 offset:38
	ds_write_b16_d16_hi v170, v180 offset:2342
	ds_write_b16 v170, v181 offset:4646
	ds_write_b16_d16_hi v170, v181 offset:6950
	v_cvt_pk_bf16_f32 v186, v94, v90
	v_cvt_pk_bf16_f32 v187, v86, v82
	ds_write_b16 v170, v186 offset:64
	ds_write_b16_d16_hi v170, v186 offset:2368
	ds_write_b16 v170, v187 offset:4672
	ds_write_b16_d16_hi v170, v187 offset:6976
	v_cvt_pk_bf16_f32 v192, v95, v91
	v_cvt_pk_bf16_f32 v193, v87, v83
	ds_write_b16 v170, v192 offset:66
	ds_write_b16_d16_hi v170, v192 offset:2370
	ds_write_b16 v170, v193 offset:4674
	ds_write_b16_d16_hi v170, v193 offset:6978
	v_cvt_pk_bf16_f32 v178, v96, v92
	v_cvt_pk_bf16_f32 v179, v88, v84
	ds_write_b16 v170, v178 offset:68
	ds_write_b16_d16_hi v170, v178 offset:2372
	ds_write_b16 v170, v179 offset:4676
	ds_write_b16_d16_hi v170, v179 offset:6980
	v_cvt_pk_bf16_f32 v184, v97, v93
	v_cvt_pk_bf16_f32 v185, v89, v85
	ds_write_b16 v170, v184 offset:70
	ds_write_b16_d16_hi v170, v184 offset:2374
	ds_write_b16 v170, v185 offset:4678
	ds_write_b16_d16_hi v170, v185 offset:6982
	v_cvt_pk_bf16_f32 v190, v78, v74
	v_cvt_pk_bf16_f32 v191, v70, v66
	ds_write_b16 v170, v190 offset:96
	ds_write_b16_d16_hi v170, v190 offset:2400
	ds_write_b16 v170, v191 offset:4704
	ds_write_b16_d16_hi v170, v191 offset:7008
	v_cvt_pk_bf16_f32 v176, v79, v75
	v_cvt_pk_bf16_f32 v177, v71, v67
	ds_write_b16 v170, v176 offset:98
	ds_write_b16_d16_hi v170, v176 offset:2402
	ds_write_b16 v170, v177 offset:4706
	ds_write_b16_d16_hi v170, v177 offset:7010
	v_cvt_pk_bf16_f32 v182, v80, v76
	v_cvt_pk_bf16_f32 v183, v72, v68
	ds_write_b16 v170, v182 offset:100
	ds_write_b16_d16_hi v170, v182 offset:2404
	ds_write_b16 v170, v183 offset:4708
	ds_write_b16_d16_hi v170, v183 offset:7012
	v_cvt_pk_bf16_f32 v188, v81, v77
	v_cvt_pk_bf16_f32 v189, v73, v69
	ds_write_b16 v170, v188 offset:102
	ds_write_b16_d16_hi v170, v188 offset:2406
	ds_write_b16 v170, v189 offset:4710
	ds_write_b16_d16_hi v170, v189 offset:7014
	ds_read_b128 v[130:133], v171 offset:0
	ds_read_b128 v[134:137], v171 offset:1152
	ds_read_b128 v[138:141], v171 offset:2304
	ds_read_b128 v[142:145], v171 offset:3456
	ds_read_b128 v[146:149], v171 offset:4608
	ds_read_b128 v[150:153], v171 offset:5760
	ds_read_b128 v[154:157], v171 offset:6912
	ds_read_b128 v[158:161], v171 offset:8064
	s_waitcnt lgkmcnt(7)
	global_store_dwordx4 v172, v[130:133], s[44:45] sc1
	s_add_u32 s44, s44, 0x9000
	s_addc_u32 s45, s45, 0
	s_waitcnt lgkmcnt(6)
	global_store_dwordx4 v172, v[134:137], s[44:45] sc1
	s_add_u32 s44, s44, 0x9000
	s_addc_u32 s45, s45, 0
	s_waitcnt lgkmcnt(5)
	global_store_dwordx4 v172, v[138:141], s[44:45] sc1
	s_add_u32 s44, s44, 0x9000
	s_addc_u32 s45, s45, 0
	s_waitcnt lgkmcnt(4)
	global_store_dwordx4 v172, v[142:145], s[44:45] sc1
	s_add_u32 s44, s44, 0x9000
	s_addc_u32 s45, s45, 0
	s_waitcnt lgkmcnt(3)
	global_store_dwordx4 v172, v[146:149], s[44:45] sc1
	s_add_u32 s44, s44, 0x9000
	s_addc_u32 s45, s45, 0
	s_waitcnt lgkmcnt(2)
	global_store_dwordx4 v172, v[150:153], s[44:45] sc1
	s_add_u32 s44, s44, 0x9000
	s_addc_u32 s45, s45, 0
	s_waitcnt lgkmcnt(1)
	global_store_dwordx4 v172, v[154:157], s[44:45] sc1
	s_add_u32 s44, s44, 0x9000
	s_addc_u32 s45, s45, 0
	s_waitcnt lgkmcnt(0)
; template <int EPI>
; DI void gemm_phase(const P& p, int l, const u16* __restrict__ A, const u16* __restrict__ Bt, int mpx, char* lds) {
;     ...
;           const unsigned u01 = pack2(v0, v1), u23 = pack2(v2, v3);
;           if (kind == 1) {
;             Tl[(0 * 16 + r) * 72 + rowl] = (u16)u01;
;             Tl[(1 * 16 + r) * 72 + rowl] = (u16)(u01 >> 16);
;             Tl[(2 * 16 + r) * 72 + rowl] = (u16)u23;
;             Tl[(3 * 16 + r) * 72 + rowl] = (u16)(u23 >> 16);
;     ...
;       __builtin_amdgcn_fence(__ATOMIC_RELEASE, "wavefront");
;       u16* dh = (kind == 1) ? dst + hf * 64 : dst + (size_t)(hf * 64) * rstride;
; #pragma unroll
;       for (int i = 0; i < 8; ++i) {
;         const int c = lane + i * 64;
;         const int row = c >> 3, cc = c & 7;
;         uint4 v = *(const uint4*)&Tl[row * 72 + cc * 8];
;         *(uint4*)(dh + (size_t)row * rstride + cc * 8) = v;
;       }
	global_store_dwordx4 v172, v[158:161], s[44:45] sc1
	s_add_u32 s44, s62, 0x80
	s_addc_u32 s45, s63, 0
	v_cvt_pk_bf16_f32 v178, v62, v58
	v_cvt_pk_bf16_f32 v179, v54, v50
	ds_write_b16 v170, v178 offset:0
	ds_write_b16_d16_hi v170, v178 offset:2304
	ds_write_b16 v170, v179 offset:4608
	ds_write_b16_d16_hi v170, v179 offset:6912
	v_cvt_pk_bf16_f32 v184, v63, v59
	v_cvt_pk_bf16_f32 v185, v55, v51
	ds_write_b16 v170, v184 offset:2
	ds_write_b16_d16_hi v170, v184 offset:2306
	ds_write_b16 v170, v185 offset:4610
	ds_write_b16_d16_hi v170, v185 offset:6914
	v_cvt_pk_bf16_f32 v190, v64, v60
	v_cvt_pk_bf16_f32 v191, v56, v52
	ds_write_b16 v170, v190 offset:4
	ds_write_b16_d16_hi v170, v190 offset:2308
	ds_write_b16 v170, v191 offset:4612
	ds_write_b16_d16_hi v170, v191 offset:6916
	v_cvt_pk_bf16_f32 v176, v65, v61
	v_cvt_pk_bf16_f32 v177, v57, v53
	ds_write_b16 v170, v176 offset:6
	ds_write_b16_d16_hi v170, v176 offset:2310
	ds_write_b16 v170, v177 offset:4614
	ds_write_b16_d16_hi v170, v177 offset:6918
	v_cvt_pk_bf16_f32 v182, v46, v42
	v_cvt_pk_bf16_f32 v183, v38, v34
	ds_write_b16 v170, v182 offset:32
	ds_write_b16_d16_hi v170, v182 offset:2336
	ds_write_b16 v170, v183 offset:4640
	ds_write_b16_d16_hi v170, v183 offset:6944
	v_cvt_pk_bf16_f32 v188, v47, v43
	v_cvt_pk_bf16_f32 v189, v39, v35
	ds_write_b16 v170, v188 offset:34
	ds_write_b16_d16_hi v170, v188 offset:2338
	ds_write_b16 v170, v189 offset:4642
	ds_write_b16_d16_hi v170, v189 offset:6946
	v_cvt_pk_bf16_f32 v174, v48, v44
	v_cvt_pk_bf16_f32 v175, v40, v36
	ds_write_b16 v170, v174 offset:36
	ds_write_b16_d16_hi v170, v174 offset:2340
	ds_write_b16 v170, v175 offset:4644
	ds_write_b16_d16_hi v170, v175 offset:6948
	v_cvt_pk_bf16_f32 v180, v49, v45
	v_cvt_pk_bf16_f32 v181, v41, v37
	ds_write_b16 v170, v180 offset:38
	ds_write_b16_d16_hi v170, v180 offset:2342
	ds_write_b16 v170, v181 offset:4646
	ds_write_b16_d16_hi v170, v181 offset:6950
	v_cvt_pk_bf16_f32 v186, v30, v26
	v_cvt_pk_bf16_f32 v187, v22, v18
	ds_write_b16 v170, v186 offset:64
	ds_write_b16_d16_hi v170, v186 offset:2368
	ds_write_b16 v170, v187 offset:4672
	ds_write_b16_d16_hi v170, v187 offset:6976
	v_cvt_pk_bf16_f32 v192, v31, v27
	v_cvt_pk_bf16_f32 v193, v23, v19
	ds_write_b16 v170, v192 offset:66
	ds_write_b16_d16_hi v170, v192 offset:2370
	ds_write_b16 v170, v193 offset:4674
	ds_write_b16_d16_hi v170, v193 offset:6978
	v_cvt_pk_bf16_f32 v178, v32, v28
	v_cvt_pk_bf16_f32 v179, v24, v20
	ds_write_b16 v170, v178 offset:68
	ds_write_b16_d16_hi v170, v178 offset:2372
	ds_write_b16 v170, v179 offset:4676
	ds_write_b16_d16_hi v170, v179 offset:6980
	v_cvt_pk_bf16_f32 v184, v33, v29
	v_cvt_pk_bf16_f32 v185, v25, v21
	ds_write_b16 v170, v184 offset:70
	ds_write_b16_d16_hi v170, v184 offset:2374
	ds_write_b16 v170, v185 offset:4678
	ds_write_b16_d16_hi v170, v185 offset:6982
	v_cvt_pk_bf16_f32 v190, v166, v162
	v_cvt_pk_bf16_f32 v191, v2, v6
	ds_write_b16 v170, v190 offset:96
	ds_write_b16_d16_hi v170, v190 offset:2400
	ds_write_b16 v170, v191 offset:4704
	ds_write_b16_d16_hi v170, v191 offset:7008
	v_cvt_pk_bf16_f32 v176, v167, v163
	v_cvt_pk_bf16_f32 v177, v3, v7
	ds_write_b16 v170, v176 offset:98
	ds_write_b16_d16_hi v170, v176 offset:2402
	ds_write_b16 v170, v177 offset:4706
	ds_write_b16_d16_hi v170, v177 offset:7010
	v_cvt_pk_bf16_f32 v182, v168, v164
	v_cvt_pk_bf16_f32 v183, v4, v8
	ds_write_b16 v170, v182 offset:100
	ds_write_b16_d16_hi v170, v182 offset:2404
	ds_write_b16 v170, v183 offset:4708
	ds_write_b16_d16_hi v170, v183 offset:7012
	v_cvt_pk_bf16_f32 v188, v169, v165
	v_cvt_pk_bf16_f32 v189, v5, v9
	ds_write_b16 v170, v188 offset:102
	ds_write_b16_d16_hi v170, v188 offset:2406
	ds_write_b16 v170, v189 offset:4710
	ds_write_b16_d16_hi v170, v189 offset:7014
	ds_read_b128 v[130:133], v171 offset:0
	ds_read_b128 v[134:137], v171 offset:1152
	ds_read_b128 v[138:141], v171 offset:2304
	ds_read_b128 v[142:145], v171 offset:3456
	ds_read_b128 v[146:149], v171 offset:4608
	ds_read_b128 v[150:153], v171 offset:5760
	ds_read_b128 v[154:157], v171 offset:6912
	ds_read_b128 v[158:161], v171 offset:8064
	s_waitcnt lgkmcnt(7)
	global_store_dwordx4 v172, v[130:133], s[44:45] sc1
	s_add_u32 s44, s44, 0x9000
	s_addc_u32 s45, s45, 0
	s_waitcnt lgkmcnt(6)
	global_store_dwordx4 v172, v[134:137], s[44:45] sc1
	s_add_u32 s44, s44, 0x9000
	s_addc_u32 s45, s45, 0
	s_waitcnt lgkmcnt(5)
	global_store_dwordx4 v172, v[138:141], s[44:45] sc1
	s_add_u32 s44, s44, 0x9000
	s_addc_u32 s45, s45, 0
	s_waitcnt lgkmcnt(4)
	global_store_dwordx4 v172, v[142:145], s[44:45] sc1
	s_add_u32 s44, s44, 0x9000
	s_addc_u32 s45, s45, 0
	s_waitcnt lgkmcnt(3)
	global_store_dwordx4 v172, v[146:149], s[44:45] sc1
	s_add_u32 s44, s44, 0x9000
	s_addc_u32 s45, s45, 0
	s_waitcnt lgkmcnt(2)
	global_store_dwordx4 v172, v[150:153], s[44:45] sc1
	s_add_u32 s44, s44, 0x9000
	s_addc_u32 s45, s45, 0
	s_waitcnt lgkmcnt(1)
	global_store_dwordx4 v172, v[154:157], s[44:45] sc1
	s_add_u32 s44, s44, 0x9000
	s_addc_u32 s45, s45, 0
	s_waitcnt lgkmcnt(0)
	global_store_dwordx4 v172, v[158:161], s[44:45] sc1
	s_branch .Lfe_done

; template <int EPI>
; DI void gemm_phase(const P& p, int l, const u16* __restrict__ A, const u16* __restrict__ Bt, int mpx, char* lds) {
;     ...
;           if (tr == 1) {
;             v0 = silu(v0); v1 = silu(v1); v2 = silu(v2); v3 = silu(v3);
;           } else if (tr == 3) {
;             if (donorm) {
;               float ss = v0 * v0 + v1 * v1 + v2 * v2 + v3 * v3;
;               ss += __shfl_xor(ss, 1);
;               ss += __shfl_xor(ss, 2);
;               ss += __shfl_xor(ss, 4);
;               ss += __shfl_xor(ss, 8);
;               const float inv = rsqrtf(ss * (1.f / 64.f) + 1e-6f);
;               v0 *= inv * gv0; v1 *= inv * gv1; v2 *= inv * gv2; v3 *= inv * gv3;
;             }
;             if (dorope) {
;               float sr, cr, sc, cc;
;               sincos_rev((float)(s >> 6) * invf64, sr, cr);
;               sincos_rev((float)(s & 63) * invf64, sc, cc);
;               const float a1 = v0, a2 = v1, b1 = v2, b2 = v3;
;               v0 = a1 * cr - a2 * sr;
;               v1 = a2 * cr + a1 * sr;
;               v2 = b1 * cc - b2 * sc;
;               v3 = b2 * cc + b1 * sc;
;             }
;           } else if (tr == 4) {
;             float sr, cr, sc, cc;
;             sincos_rev((float)(s >> 6) * invf32, sr, cr);
;             sincos_rev((float)(s & 63) * invf32, sc, cc);
;             const float p0 = __shfl_xor(v0, 8), p1 = __shfl_xor(v1, 8), p2 = __shfl_xor(v2, 8), p3 = __shfl_xor(v3, 8);
;             v0 = lo8 ? (v0 * cr - p0 * sr) : (v0 * cr + p0 * sr);
;             v1 = lo8 ? (v1 * cc - p1 * sc) : (v1 * cc + p1 * sc);
;             v2 = lo8 ? (v2 * cr - p2 * sr) : (v2 * cr + p2 * sr);
;             v3 = lo8 ? (v3 * cc - p3 * sc) : (v3 * cc + p3 * sc);
;           }
;           const unsigned u01 = pack2(v0, v1), u23 = pack2(v2, v3);
;           if (kind == 1) {
;             Tl[(0 * 16 + r) * 72 + rowl] = (u16)u01;
;             Tl[(1 * 16 + r) * 72 + rowl] = (u16)(u01 >> 16);
;             Tl[(2 * 16 + r) * 72 + rowl] = (u16)u23;
;             Tl[(3 * 16 + r) * 72 + rowl] = (u16)(u23 >> 16);
;           } else if (tr == 2) {
;             Tl[rowl * 72 + 0 * 16 + r] = f2h(v0);
;             Tl[rowl * 72 + 1 * 16 + r] = f2h(v1);
;             Tl[rowl * 72 + 2 * 16 + r] = f2h(v2);
;             Tl[rowl * 72 + 3 * 16 + r] = f2h(v3);
;           } else {
;             Tl[rowl * 72 + 0 * 16 + r] = (u16)u01;
.Lfe_k2:
	s_mov_b64 s[62:63], s[44:45]
	v_mul_f32_e32 v174, 0xbfb8aa3b, v126
	v_mul_f32_e32 v175, 0xbfb8aa3b, v122
	v_mul_f32_e32 v176, 0xbfb8aa3b, v118
	v_mul_f32_e32 v177, 0xbfb8aa3b, v114
	v_exp_f32_e32 v174, v174
	v_exp_f32_e32 v175, v175
	v_exp_f32_e32 v176, v176
	v_exp_f32_e32 v177, v177
	v_add_f32_e32 v174, 1.0, v174
	v_add_f32_e32 v175, 1.0, v175
	v_add_f32_e32 v176, 1.0, v176
	v_add_f32_e32 v177, 1.0, v177
	v_rcp_f32_e32 v174, v174
	v_rcp_f32_e32 v175, v175
	v_rcp_f32_e32 v176, v176
	v_rcp_f32_e32 v177, v177
	v_mul_f32_e32 v174, v126, v174
	v_mul_f32_e32 v175, v122, v175
	v_mul_f32_e32 v176, v118, v176
	v_mul_f32_e32 v177, v114, v177
	v_cvt_pk_bf16_f32 v178, v174, v175
	v_cvt_pk_bf16_f32 v179, v176, v177
	ds_write_b16 v170, v178 offset:0
	ds_write_b16_d16_hi v170, v178 offset:32
	ds_write_b16 v170, v179 offset:64
	ds_write_b16_d16_hi v170, v179 offset:96
	v_mul_f32_e32 v180, 0xbfb8aa3b, v127
	v_mul_f32_e32 v181, 0xbfb8aa3b, v123
	v_mul_f32_e32 v182, 0xbfb8aa3b, v119
	v_mul_f32_e32 v183, 0xbfb8aa3b, v115
	v_exp_f32_e32 v180, v180
	v_exp_f32_e32 v181, v181
	v_exp_f32_e32 v182, v182
	v_exp_f32_e32 v183, v183
	v_add_f32_e32 v180, 1.0, v180
	v_add_f32_e32 v181, 1.0, v181
	v_add_f32_e32 v182, 1.0, v182
	v_add_f32_e32 v183, 1.0, v183
	v_rcp_f32_e32 v180, v180
	v_rcp_f32_e32 v181, v181
	v_rcp_f32_e32 v182, v182
	v_rcp_f32_e32 v183, v183
	v_mul_f32_e32 v180, v127, v180
	v_mul_f32_e32 v181, v123, v181
	v_mul_f32_e32 v182, v119, v182
	v_mul_f32_e32 v183, v115, v183
	v_cvt_pk_bf16_f32 v184, v180, v181
	v_cvt_pk_bf16_f32 v185, v182, v183
	ds_write_b16 v170, v184 offset:144
	ds_write_b16_d16_hi v170, v184 offset:176
	ds_write_b16 v170, v185 offset:208
	ds_write_b16_d16_hi v170, v185 offset:240
	v_mul_f32_e32 v186, 0xbfb8aa3b, v128
	v_mul_f32_e32 v187, 0xbfb8aa3b, v124
	v_mul_f32_e32 v188, 0xbfb8aa3b, v120
	v_mul_f32_e32 v189, 0xbfb8aa3b, v116
	v_exp_f32_e32 v186, v186
	v_exp_f32_e32 v187, v187
	v_exp_f32_e32 v188, v188
	v_exp_f32_e32 v189, v189
	v_add_f32_e32 v186, 1.0, v186
	v_add_f32_e32 v187, 1.0, v187
	v_add_f32_e32 v188, 1.0, v188
	v_add_f32_e32 v189, 1.0, v189
	v_rcp_f32_e32 v186, v186
	v_rcp_f32_e32 v187, v187
	v_rcp_f32_e32 v188, v188
	v_rcp_f32_e32 v189, v189
	v_mul_f32_e32 v186, v128, v186
	v_mul_f32_e32 v187, v124, v187
	v_mul_f32_e32 v188, v120, v188
	v_mul_f32_e32 v189, v116, v189
	v_cvt_pk_bf16_f32 v190, v186, v187
	v_cvt_pk_bf16_f32 v191, v188, v189
	ds_write_b16 v170, v190 offset:288
	ds_write_b16_d16_hi v170, v190 offset:320
	ds_write_b16 v170, v191 offset:352
	ds_write_b16_d16_hi v170, v191 offset:384
	v_mul_f32_e32 v192, 0xbfb8aa3b, v129
	v_mul_f32_e32 v193, 0xbfb8aa3b, v125
	v_mul_f32_e32 v174, 0xbfb8aa3b, v121
	v_mul_f32_e32 v175, 0xbfb8aa3b, v117
	v_exp_f32_e32 v192, v192
	v_exp_f32_e32 v193, v193
	v_exp_f32_e32 v174, v174
	v_exp_f32_e32 v175, v175
	v_add_f32_e32 v192, 1.0, v192
	v_add_f32_e32 v193, 1.0, v193
	v_add_f32_e32 v174, 1.0, v174
	v_add_f32_e32 v175, 1.0, v175
	v_rcp_f32_e32 v192, v192
	v_rcp_f32_e32 v193, v193
	v_rcp_f32_e32 v174, v174
	v_rcp_f32_e32 v175, v175
	v_mul_f32_e32 v192, v129, v192
	v_mul_f32_e32 v193, v125, v193
	v_mul_f32_e32 v174, v121, v174
	v_mul_f32_e32 v175, v117, v175
	v_cvt_pk_bf16_f32 v176, v192, v193
	v_cvt_pk_bf16_f32 v177, v174, v175
	ds_write_b16 v170, v176 offset:432
	ds_write_b16_d16_hi v170, v176 offset:464
	ds_write_b16 v170, v177 offset:496
	ds_write_b16_d16_hi v170, v177 offset:528
	v_mul_f32_e32 v178, 0xbfb8aa3b, v110
	v_mul_f32_e32 v179, 0xbfb8aa3b, v106
	v_mul_f32_e32 v180, 0xbfb8aa3b, v102
	v_mul_f32_e32 v181, 0xbfb8aa3b, v98
	v_exp_f32_e32 v178, v178
	v_exp_f32_e32 v179, v179
	v_exp_f32_e32 v180, v180
	v_exp_f32_e32 v181, v181
	v_add_f32_e32 v178, 1.0, v178
	v_add_f32_e32 v179, 1.0, v179
	v_add_f32_e32 v180, 1.0, v180
	v_add_f32_e32 v181, 1.0, v181
	v_rcp_f32_e32 v178, v178
	v_rcp_f32_e32 v179, v179
	v_rcp_f32_e32 v180, v180
	v_rcp_f32_e32 v181, v181
	v_mul_f32_e32 v178, v110, v178
	v_mul_f32_e32 v179, v106, v179
	v_mul_f32_e32 v180, v102, v180
	v_mul_f32_e32 v181, v98, v181
	v_cvt_pk_bf16_f32 v182, v178, v179
	v_cvt_pk_bf16_f32 v183, v180, v181
	ds_write_b16 v170, v182 offset:2304
	ds_write_b16_d16_hi v170, v182 offset:2336
	ds_write_b16 v170, v183 offset:2368
	ds_write_b16_d16_hi v170, v183 offset:2400
	v_mul_f32_e32 v184, 0xbfb8aa3b, v111
	v_mul_f32_e32 v185, 0xbfb8aa3b, v107
	v_mul_f32_e32 v186, 0xbfb8aa3b, v103
	v_mul_f32_e32 v187, 0xbfb8aa3b, v99
	v_exp_f32_e32 v184, v184
	v_exp_f32_e32 v185, v185
	v_exp_f32_e32 v186, v186
	v_exp_f32_e32 v187, v187
	v_add_f32_e32 v184, 1.0, v184
	v_add_f32_e32 v185, 1.0, v185
	v_add_f32_e32 v186, 1.0, v186
	v_add_f32_e32 v187, 1.0, v187
	v_rcp_f32_e32 v184, v184
	v_rcp_f32_e32 v185, v185
	v_rcp_f32_e32 v186, v186
	v_rcp_f32_e32 v187, v187
	v_mul_f32_e32 v184, v111, v184
	v_mul_f32_e32 v185, v107, v185
	v_mul_f32_e32 v186, v103, v186
	v_mul_f32_e32 v187, v99, v187
	v_cvt_pk_bf16_f32 v188, v184, v185
	v_cvt_pk_bf16_f32 v189, v186, v187
	ds_write_b16 v170, v188 offset:2448
	ds_write_b16_d16_hi v170, v188 offset:2480
	ds_write_b16 v170, v189 offset:2512
	ds_write_b16_d16_hi v170, v189 offset:2544
	v_mul_f32_e32 v190, 0xbfb8aa3b, v112
	v_mul_f32_e32 v191, 0xbfb8aa3b, v108
	v_mul_f32_e32 v192, 0xbfb8aa3b, v104
	v_mul_f32_e32 v193, 0xbfb8aa3b, v100
	v_exp_f32_e32 v190, v190
	v_exp_f32_e32 v191, v191
	v_exp_f32_e32 v192, v192
	v_exp_f32_e32 v193, v193
	v_add_f32_e32 v190, 1.0, v190
	v_add_f32_e32 v191, 1.0, v191
	v_add_f32_e32 v192, 1.0, v192
	v_add_f32_e32 v193, 1.0, v193
	v_rcp_f32_e32 v190, v190
	v_rcp_f32_e32 v191, v191
	v_rcp_f32_e32 v192, v192
	v_rcp_f32_e32 v193, v193
	v_mul_f32_e32 v190, v112, v190
	v_mul_f32_e32 v191, v108, v191
; template <int EPI>
; DI void gemm_phase(const P& p, int l, const u16* __restrict__ A, const u16* __restrict__ Bt, int mpx, char* lds) {
;     ...
;           if (tr == 1) {
;             v0 = silu(v0); v1 = silu(v1); v2 = silu(v2); v3 = silu(v3);
;           } else if (tr == 3) {
;             if (donorm) {
;               float ss = v0 * v0 + v1 * v1 + v2 * v2 + v3 * v3;
;               ss += __shfl_xor(ss, 1);
;               ss += __shfl_xor(ss, 2);
;               ss += __shfl_xor(ss, 4);
;               ss += __shfl_xor(ss, 8);
;               const float inv = rsqrtf(ss * (1.f / 64.f) + 1e-6f);
;               v0 *= inv * gv0; v1 *= inv * gv1; v2 *= inv * gv2; v3 *= inv * gv3;
;             }
;             if (dorope) {
;               float sr, cr, sc, cc;
;               sincos_rev((float)(s >> 6) * invf64, sr, cr);
;               sincos_rev((float)(s & 63) * invf64, sc, cc);
;               const float a1 = v0, a2 = v1, b1 = v2, b2 = v3;
;               v0 = a1 * cr - a2 * sr;
;               v1 = a2 * cr + a1 * sr;
;               v2 = b1 * cc - b2 * sc;
;               v3 = b2 * cc + b1 * sc;
;             }
;           } else if (tr == 4) {
;             float sr, cr, sc, cc;
;             sincos_rev((float)(s >> 6) * invf32, sr, cr);
;             sincos_rev((float)(s & 63) * invf32, sc, cc);
;             const float p0 = __shfl_xor(v0, 8), p1 = __shfl_xor(v1, 8), p2 = __shfl_xor(v2, 8), p3 = __shfl_xor(v3, 8);
;             v0 = lo8 ? (v0 * cr - p0 * sr) : (v0 * cr + p0 * sr);
;             v1 = lo8 ? (v1 * cc - p1 * sc) : (v1 * cc + p1 * sc);
;             v2 = lo8 ? (v2 * cr - p2 * sr) : (v2 * cr + p2 * sr);
;             v3 = lo8 ? (v3 * cc - p3 * sc) : (v3 * cc + p3 * sc);
;           }
;           const unsigned u01 = pack2(v0, v1), u23 = pack2(v2, v3);
;           if (kind == 1) {
;             Tl[(0 * 16 + r) * 72 + rowl] = (u16)u01;
;             Tl[(1 * 16 + r) * 72 + rowl] = (u16)(u01 >> 16);
;             Tl[(2 * 16 + r) * 72 + rowl] = (u16)u23;
;             Tl[(3 * 16 + r) * 72 + rowl] = (u16)(u23 >> 16);
;           } else if (tr == 2) {
;             Tl[rowl * 72 + 0 * 16 + r] = f2h(v0);
;             Tl[rowl * 72 + 1 * 16 + r] = f2h(v1);
;             Tl[rowl * 72 + 2 * 16 + r] = f2h(v2);
;             Tl[rowl * 72 + 3 * 16 + r] = f2h(v3);
;           } else {
;             Tl[rowl * 72 + 0 * 16 + r] = (u16)u01;
	v_mul_f32_e32 v192, v104, v192
	v_mul_f32_e32 v193, v100, v193
	v_cvt_pk_bf16_f32 v174, v190, v191
	v_cvt_pk_bf16_f32 v175, v192, v193
	ds_write_b16 v170, v174 offset:2592
	ds_write_b16_d16_hi v170, v174 offset:2624
	ds_write_b16 v170, v175 offset:2656
	ds_write_b16_d16_hi v170, v175 offset:2688
	v_mul_f32_e32 v176, 0xbfb8aa3b, v113
	v_mul_f32_e32 v177, 0xbfb8aa3b, v109
	v_mul_f32_e32 v178, 0xbfb8aa3b, v105
	v_mul_f32_e32 v179, 0xbfb8aa3b, v101
	v_exp_f32_e32 v176, v176
	v_exp_f32_e32 v177, v177
	v_exp_f32_e32 v178, v178
	v_exp_f32_e32 v179, v179
	v_add_f32_e32 v176, 1.0, v176
	v_add_f32_e32 v177, 1.0, v177
	v_add_f32_e32 v178, 1.0, v178
	v_add_f32_e32 v179, 1.0, v179
	v_rcp_f32_e32 v176, v176
	v_rcp_f32_e32 v177, v177
	v_rcp_f32_e32 v178, v178
	v_rcp_f32_e32 v179, v179
	v_mul_f32_e32 v176, v113, v176
	v_mul_f32_e32 v177, v109, v177
	v_mul_f32_e32 v178, v105, v178
	v_mul_f32_e32 v179, v101, v179
	v_cvt_pk_bf16_f32 v180, v176, v177
	v_cvt_pk_bf16_f32 v181, v178, v179
	ds_write_b16 v170, v180 offset:2736
	ds_write_b16_d16_hi v170, v180 offset:2768
	ds_write_b16 v170, v181 offset:2800
	ds_write_b16_d16_hi v170, v181 offset:2832
	v_mul_f32_e32 v182, 0xbfb8aa3b, v94
	v_mul_f32_e32 v183, 0xbfb8aa3b, v90
	v_mul_f32_e32 v184, 0xbfb8aa3b, v86
	v_mul_f32_e32 v185, 0xbfb8aa3b, v82
	v_exp_f32_e32 v182, v182
	v_exp_f32_e32 v183, v183
	v_exp_f32_e32 v184, v184
	v_exp_f32_e32 v185, v185
	v_add_f32_e32 v182, 1.0, v182
	v_add_f32_e32 v183, 1.0, v183
	v_add_f32_e32 v184, 1.0, v184
	v_add_f32_e32 v185, 1.0, v185
	v_rcp_f32_e32 v182, v182
	v_rcp_f32_e32 v183, v183
	v_rcp_f32_e32 v184, v184
	v_rcp_f32_e32 v185, v185
	v_mul_f32_e32 v182, v94, v182
	v_mul_f32_e32 v183, v90, v183
	v_mul_f32_e32 v184, v86, v184
	v_mul_f32_e32 v185, v82, v185
	v_cvt_pk_bf16_f32 v186, v182, v183
	v_cvt_pk_bf16_f32 v187, v184, v185
	ds_write_b16 v170, v186 offset:4608
	ds_write_b16_d16_hi v170, v186 offset:4640
	ds_write_b16 v170, v187 offset:4672
	ds_write_b16_d16_hi v170, v187 offset:4704
	v_mul_f32_e32 v188, 0xbfb8aa3b, v95
	v_mul_f32_e32 v189, 0xbfb8aa3b, v91
	v_mul_f32_e32 v190, 0xbfb8aa3b, v87
	v_mul_f32_e32 v191, 0xbfb8aa3b, v83
	v_exp_f32_e32 v188, v188
	v_exp_f32_e32 v189, v189
	v_exp_f32_e32 v190, v190
	v_exp_f32_e32 v191, v191
	v_add_f32_e32 v188, 1.0, v188
	v_add_f32_e32 v189, 1.0, v189
	v_add_f32_e32 v190, 1.0, v190
	v_add_f32_e32 v191, 1.0, v191
	v_rcp_f32_e32 v188, v188
	v_rcp_f32_e32 v189, v189
	v_rcp_f32_e32 v190, v190
	v_rcp_f32_e32 v191, v191
	v_mul_f32_e32 v188, v95, v188
	v_mul_f32_e32 v189, v91, v189
	v_mul_f32_e32 v190, v87, v190
	v_mul_f32_e32 v191, v83, v191
	v_cvt_pk_bf16_f32 v192, v188, v189
	v_cvt_pk_bf16_f32 v193, v190, v191
	ds_write_b16 v170, v192 offset:4752
	ds_write_b16_d16_hi v170, v192 offset:4784
	ds_write_b16 v170, v193 offset:4816
	ds_write_b16_d16_hi v170, v193 offset:4848
	v_mul_f32_e32 v174, 0xbfb8aa3b, v96
	v_mul_f32_e32 v175, 0xbfb8aa3b, v92
	v_mul_f32_e32 v176, 0xbfb8aa3b, v88
	v_mul_f32_e32 v177, 0xbfb8aa3b, v84
	v_exp_f32_e32 v174, v174
	v_exp_f32_e32 v175, v175
	v_exp_f32_e32 v176, v176
	v_exp_f32_e32 v177, v177
	v_add_f32_e32 v174, 1.0, v174
	v_add_f32_e32 v175, 1.0, v175
	v_add_f32_e32 v176, 1.0, v176
	v_add_f32_e32 v177, 1.0, v177
	v_rcp_f32_e32 v174, v174
	v_rcp_f32_e32 v175, v175
	v_rcp_f32_e32 v176, v176
	v_rcp_f32_e32 v177, v177
	v_mul_f32_e32 v174, v96, v174
	v_mul_f32_e32 v175, v92, v175
	v_mul_f32_e32 v176, v88, v176
	v_mul_f32_e32 v177, v84, v177
	v_cvt_pk_bf16_f32 v178, v174, v175
	v_cvt_pk_bf16_f32 v179, v176, v177
	ds_write_b16 v170, v178 offset:4896
	ds_write_b16_d16_hi v170, v178 offset:4928
	ds_write_b16 v170, v179 offset:4960
	ds_write_b16_d16_hi v170, v179 offset:4992
	v_mul_f32_e32 v180, 0xbfb8aa3b, v97
	v_mul_f32_e32 v181, 0xbfb8aa3b, v93
	v_mul_f32_e32 v182, 0xbfb8aa3b, v89
	v_mul_f32_e32 v183, 0xbfb8aa3b, v85
	v_exp_f32_e32 v180, v180
	v_exp_f32_e32 v181, v181
	v_exp_f32_e32 v182, v182
	v_exp_f32_e32 v183, v183
	v_add_f32_e32 v180, 1.0, v180
	v_add_f32_e32 v181, 1.0, v181
	v_add_f32_e32 v182, 1.0, v182
	v_add_f32_e32 v183, 1.0, v183
	v_rcp_f32_e32 v180, v180
	v_rcp_f32_e32 v181, v181
	v_rcp_f32_e32 v182, v182
	v_rcp_f32_e32 v183, v183
	v_mul_f32_e32 v180, v97, v180
	v_mul_f32_e32 v181, v93, v181
	v_mul_f32_e32 v182, v89, v182
	v_mul_f32_e32 v183, v85, v183
	v_cvt_pk_bf16_f32 v184, v180, v181
	v_cvt_pk_bf16_f32 v185, v182, v183
	ds_write_b16 v170, v184 offset:5040
	ds_write_b16_d16_hi v170, v184 offset:5072
	ds_write_b16 v170, v185 offset:5104
	ds_write_b16_d16_hi v170, v185 offset:5136
	v_mul_f32_e32 v186, 0xbfb8aa3b, v78
	v_mul_f32_e32 v187, 0xbfb8aa3b, v74
	v_mul_f32_e32 v188, 0xbfb8aa3b, v70
	v_mul_f32_e32 v189, 0xbfb8aa3b, v66
	v_exp_f32_e32 v186, v186
	v_exp_f32_e32 v187, v187
	v_exp_f32_e32 v188, v188
	v_exp_f32_e32 v189, v189
	v_add_f32_e32 v186, 1.0, v186
	v_add_f32_e32 v187, 1.0, v187
	v_add_f32_e32 v188, 1.0, v188
	v_add_f32_e32 v189, 1.0, v189
	v_rcp_f32_e32 v186, v186
	v_rcp_f32_e32 v187, v187
	v_rcp_f32_e32 v188, v188
	v_rcp_f32_e32 v189, v189
	v_mul_f32_e32 v186, v78, v186
	v_mul_f32_e32 v187, v74, v187
	v_mul_f32_e32 v188, v70, v188
	v_mul_f32_e32 v189, v66, v189
	v_cvt_pk_bf16_f32 v190, v186, v187
	v_cvt_pk_bf16_f32 v191, v188, v189
	ds_write_b16 v170, v190 offset:6912
	ds_write_b16_d16_hi v170, v190 offset:6944
	ds_write_b16 v170, v191 offset:6976
	ds_write_b16_d16_hi v170, v191 offset:7008
	v_mul_f32_e32 v192, 0xbfb8aa3b, v79
	v_mul_f32_e32 v193, 0xbfb8aa3b, v75
	v_mul_f32_e32 v174, 0xbfb8aa3b, v71
	v_mul_f32_e32 v175, 0xbfb8aa3b, v67
	v_exp_f32_e32 v192, v192
	v_exp_f32_e32 v193, v193
	v_exp_f32_e32 v174, v174
	v_exp_f32_e32 v175, v175
	v_add_f32_e32 v192, 1.0, v192
	v_add_f32_e32 v193, 1.0, v193
; template <int EPI>
; DI void gemm_phase(const P& p, int l, const u16* __restrict__ A, const u16* __restrict__ Bt, int mpx, char* lds) {
;     ...
;           if (tr == 1) {
;             v0 = silu(v0); v1 = silu(v1); v2 = silu(v2); v3 = silu(v3);
;           } else if (tr == 3) {
;             if (donorm) {
;               float ss = v0 * v0 + v1 * v1 + v2 * v2 + v3 * v3;
;               ss += __shfl_xor(ss, 1);
;               ss += __shfl_xor(ss, 2);
;               ss += __shfl_xor(ss, 4);
;               ss += __shfl_xor(ss, 8);
;               const float inv = rsqrtf(ss * (1.f / 64.f) + 1e-6f);
;               v0 *= inv * gv0; v1 *= inv * gv1; v2 *= inv * gv2; v3 *= inv * gv3;
;             }
;             if (dorope) {
;               float sr, cr, sc, cc;
;               sincos_rev((float)(s >> 6) * invf64, sr, cr);
;               sincos_rev((float)(s & 63) * invf64, sc, cc);
;               const float a1 = v0, a2 = v1, b1 = v2, b2 = v3;
;               v0 = a1 * cr - a2 * sr;
;               v1 = a2 * cr + a1 * sr;
;               v2 = b1 * cc - b2 * sc;
;               v3 = b2 * cc + b1 * sc;
;             }
;           } else if (tr == 4) {
;             float sr, cr, sc, cc;
;             sincos_rev((float)(s >> 6) * invf32, sr, cr);
;             sincos_rev((float)(s & 63) * invf32, sc, cc);
;             const float p0 = __shfl_xor(v0, 8), p1 = __shfl_xor(v1, 8), p2 = __shfl_xor(v2, 8), p3 = __shfl_xor(v3, 8);
;             v0 = lo8 ? (v0 * cr - p0 * sr) : (v0 * cr + p0 * sr);
;             v1 = lo8 ? (v1 * cc - p1 * sc) : (v1 * cc + p1 * sc);
;             v2 = lo8 ? (v2 * cr - p2 * sr) : (v2 * cr + p2 * sr);
;             v3 = lo8 ? (v3 * cc - p3 * sc) : (v3 * cc + p3 * sc);
;           }
;           const unsigned u01 = pack2(v0, v1), u23 = pack2(v2, v3);
;           if (kind == 1) {
;             Tl[(0 * 16 + r) * 72 + rowl] = (u16)u01;
;             Tl[(1 * 16 + r) * 72 + rowl] = (u16)(u01 >> 16);
;             Tl[(2 * 16 + r) * 72 + rowl] = (u16)u23;
;             Tl[(3 * 16 + r) * 72 + rowl] = (u16)(u23 >> 16);
;           } else if (tr == 2) {
;             Tl[rowl * 72 + 0 * 16 + r] = f2h(v0);
;             Tl[rowl * 72 + 1 * 16 + r] = f2h(v1);
;             Tl[rowl * 72 + 2 * 16 + r] = f2h(v2);
;             Tl[rowl * 72 + 3 * 16 + r] = f2h(v3);
;           } else {
;             Tl[rowl * 72 + 0 * 16 + r] = (u16)u01;
	v_add_f32_e32 v174, 1.0, v174
	v_add_f32_e32 v175, 1.0, v175
	v_rcp_f32_e32 v192, v192
	v_rcp_f32_e32 v193, v193
	v_rcp_f32_e32 v174, v174
	v_rcp_f32_e32 v175, v175
	v_mul_f32_e32 v192, v79, v192
	v_mul_f32_e32 v193, v75, v193
	v_mul_f32_e32 v174, v71, v174
	v_mul_f32_e32 v175, v67, v175
	v_cvt_pk_bf16_f32 v176, v192, v193
	v_cvt_pk_bf16_f32 v177, v174, v175
	ds_write_b16 v170, v176 offset:7056
	ds_write_b16_d16_hi v170, v176 offset:7088
	ds_write_b16 v170, v177 offset:7120
	ds_write_b16_d16_hi v170, v177 offset:7152
	v_mul_f32_e32 v178, 0xbfb8aa3b, v80
	v_mul_f32_e32 v179, 0xbfb8aa3b, v76
	v_mul_f32_e32 v180, 0xbfb8aa3b, v72
	v_mul_f32_e32 v181, 0xbfb8aa3b, v68
	v_exp_f32_e32 v178, v178
	v_exp_f32_e32 v179, v179
	v_exp_f32_e32 v180, v180
	v_exp_f32_e32 v181, v181
	v_add_f32_e32 v178, 1.0, v178
	v_add_f32_e32 v179, 1.0, v179
	v_add_f32_e32 v180, 1.0, v180
	v_add_f32_e32 v181, 1.0, v181
	v_rcp_f32_e32 v178, v178
	v_rcp_f32_e32 v179, v179
	v_rcp_f32_e32 v180, v180
	v_rcp_f32_e32 v181, v181
	v_mul_f32_e32 v178, v80, v178
	v_mul_f32_e32 v179, v76, v179
	v_mul_f32_e32 v180, v72, v180
	v_mul_f32_e32 v181, v68, v181
	v_cvt_pk_bf16_f32 v182, v178, v179
	v_cvt_pk_bf16_f32 v183, v180, v181
	ds_write_b16 v170, v182 offset:7200
	ds_write_b16_d16_hi v170, v182 offset:7232
	ds_write_b16 v170, v183 offset:7264
	ds_write_b16_d16_hi v170, v183 offset:7296
	v_mul_f32_e32 v184, 0xbfb8aa3b, v81
	v_mul_f32_e32 v185, 0xbfb8aa3b, v77
	v_mul_f32_e32 v186, 0xbfb8aa3b, v73
	v_mul_f32_e32 v187, 0xbfb8aa3b, v69
	v_exp_f32_e32 v184, v184
	v_exp_f32_e32 v185, v185
	v_exp_f32_e32 v186, v186
	v_exp_f32_e32 v187, v187
	v_add_f32_e32 v184, 1.0, v184
	v_add_f32_e32 v185, 1.0, v185
	v_add_f32_e32 v186, 1.0, v186
	v_add_f32_e32 v187, 1.0, v187
	v_rcp_f32_e32 v184, v184
	v_rcp_f32_e32 v185, v185
	v_rcp_f32_e32 v186, v186
	v_rcp_f32_e32 v187, v187
	v_mul_f32_e32 v184, v81, v184
	v_mul_f32_e32 v185, v77, v185
	v_mul_f32_e32 v186, v73, v186
	v_mul_f32_e32 v187, v69, v187
	v_cvt_pk_bf16_f32 v188, v184, v185
	v_cvt_pk_bf16_f32 v189, v186, v187
	ds_write_b16 v170, v188 offset:7344
	ds_write_b16_d16_hi v170, v188 offset:7376
	ds_write_b16 v170, v189 offset:7408
	ds_write_b16_d16_hi v170, v189 offset:7440
	ds_read_b128 v[130:133], v171 offset:0
	ds_read_b128 v[134:137], v171 offset:1152
	ds_read_b128 v[138:141], v171 offset:2304
	ds_read_b128 v[142:145], v171 offset:3456
	ds_read_b128 v[146:149], v171 offset:4608
	ds_read_b128 v[150:153], v171 offset:5760
	ds_read_b128 v[154:157], v171 offset:6912
	ds_read_b128 v[158:161], v171 offset:8064
	s_waitcnt lgkmcnt(7)
	global_store_dwordx4 v172, v[130:133], s[44:45] sc1
	s_add_u32 s44, s44, 0x4000
	s_addc_u32 s45, s45, 0
	s_waitcnt lgkmcnt(6)
	global_store_dwordx4 v172, v[134:137], s[44:45] sc1
	s_add_u32 s44, s44, 0x4000
	s_addc_u32 s45, s45, 0
	s_waitcnt lgkmcnt(5)
	global_store_dwordx4 v172, v[138:141], s[44:45] sc1
	s_add_u32 s44, s44, 0x4000
	s_addc_u32 s45, s45, 0
	s_waitcnt lgkmcnt(4)
	global_store_dwordx4 v172, v[142:145], s[44:45] sc1
	s_add_u32 s44, s44, 0x4000
	s_addc_u32 s45, s45, 0
	s_waitcnt lgkmcnt(3)
	global_store_dwordx4 v172, v[146:149], s[44:45] sc1
	s_add_u32 s44, s44, 0x4000
	s_addc_u32 s45, s45, 0
	s_waitcnt lgkmcnt(2)
	global_store_dwordx4 v172, v[150:153], s[44:45] sc1
	s_add_u32 s44, s44, 0x4000
	s_addc_u32 s45, s45, 0
	s_waitcnt lgkmcnt(1)
	global_store_dwordx4 v172, v[154:157], s[44:45] sc1
	s_add_u32 s44, s44, 0x4000
	s_addc_u32 s45, s45, 0
	s_waitcnt lgkmcnt(0)
	global_store_dwordx4 v172, v[158:161], s[44:45] sc1
	s_add_u32 s44, s62, 0x20000
	s_addc_u32 s45, s63, 0
	v_mul_f32_e32 v174, 0xbfb8aa3b, v62
	v_mul_f32_e32 v175, 0xbfb8aa3b, v58
	v_mul_f32_e32 v176, 0xbfb8aa3b, v54
	v_mul_f32_e32 v177, 0xbfb8aa3b, v50
	v_exp_f32_e32 v174, v174
	v_exp_f32_e32 v175, v175
	v_exp_f32_e32 v176, v176
	v_exp_f32_e32 v177, v177
	v_add_f32_e32 v174, 1.0, v174
	v_add_f32_e32 v175, 1.0, v175
	v_add_f32_e32 v176, 1.0, v176
	v_add_f32_e32 v177, 1.0, v177
	v_rcp_f32_e32 v174, v174
	v_rcp_f32_e32 v175, v175
	v_rcp_f32_e32 v176, v176
	v_rcp_f32_e32 v177, v177
	v_mul_f32_e32 v174, v62, v174
	v_mul_f32_e32 v175, v58, v175
	v_mul_f32_e32 v176, v54, v176
	v_mul_f32_e32 v177, v50, v177
	v_cvt_pk_bf16_f32 v178, v174, v175
	v_cvt_pk_bf16_f32 v179, v176, v177
	ds_write_b16 v170, v178 offset:0
	ds_write_b16_d16_hi v170, v178 offset:32
	ds_write_b16 v170, v179 offset:64
	ds_write_b16_d16_hi v170, v179 offset:96
	v_mul_f32_e32 v180, 0xbfb8aa3b, v63
	v_mul_f32_e32 v181, 0xbfb8aa3b, v59
	v_mul_f32_e32 v182, 0xbfb8aa3b, v55
	v_mul_f32_e32 v183, 0xbfb8aa3b, v51
	v_exp_f32_e32 v180, v180
	v_exp_f32_e32 v181, v181
	v_exp_f32_e32 v182, v182
	v_exp_f32_e32 v183, v183
	v_add_f32_e32 v180, 1.0, v180
	v_add_f32_e32 v181, 1.0, v181
	v_add_f32_e32 v182, 1.0, v182
	v_add_f32_e32 v183, 1.0, v183
	v_rcp_f32_e32 v180, v180
	v_rcp_f32_e32 v181, v181
	v_rcp_f32_e32 v182, v182
	v_rcp_f32_e32 v183, v183
	v_mul_f32_e32 v180, v63, v180
	v_mul_f32_e32 v181, v59, v181
	v_mul_f32_e32 v182, v55, v182
	v_mul_f32_e32 v183, v51, v183
	v_cvt_pk_bf16_f32 v184, v180, v181
	v_cvt_pk_bf16_f32 v185, v182, v183
	ds_write_b16 v170, v184 offset:144
	ds_write_b16_d16_hi v170, v184 offset:176
	ds_write_b16 v170, v185 offset:208
	ds_write_b16_d16_hi v170, v185 offset:240
	v_mul_f32_e32 v186, 0xbfb8aa3b, v64
	v_mul_f32_e32 v187, 0xbfb8aa3b, v60
	v_mul_f32_e32 v188, 0xbfb8aa3b, v56
	v_mul_f32_e32 v189, 0xbfb8aa3b, v52
	v_exp_f32_e32 v186, v186
	v_exp_f32_e32 v187, v187
	v_exp_f32_e32 v188, v188
	v_exp_f32_e32 v189, v189
	v_add_f32_e32 v186, 1.0, v186
	v_add_f32_e32 v187, 1.0, v187
	v_add_f32_e32 v188, 1.0, v188
	v_add_f32_e32 v189, 1.0, v189
	v_rcp_f32_e32 v186, v186
	v_rcp_f32_e32 v187, v187
; template <int EPI>
; DI void gemm_phase(const P& p, int l, const u16* __restrict__ A, const u16* __restrict__ Bt, int mpx, char* lds) {
;     ...
;           float v0 = acc[hf * 4 + mi][0][j], v1 = acc[hf * 4 + mi][1][j], v2 = acc[hf * 4 + mi][2][j], v3 = acc[hf * 4 + mi][3][j];
;           const int rowl = mi * 16 + g * 4 + j;
;           const int s = tokw + hf * 64 + rowl;
;           if (tr == 1) {
;             v0 = silu(v0); v1 = silu(v1); v2 = silu(v2); v3 = silu(v3);
;           } else if (tr == 3) {
;             if (donorm) {
;               float ss = v0 * v0 + v1 * v1 + v2 * v2 + v3 * v3;
;               ss += __shfl_xor(ss, 1);
;               ss += __shfl_xor(ss, 2);
;               ss += __shfl_xor(ss, 4);
;               ss += __shfl_xor(ss, 8);
;               const float inv = rsqrtf(ss * (1.f / 64.f) + 1e-6f);
;               v0 *= inv * gv0; v1 *= inv * gv1; v2 *= inv * gv2; v3 *= inv * gv3;
;             }
;             if (dorope) {
;               float sr, cr, sc, cc;
;               sincos_rev((float)(s >> 6) * invf64, sr, cr);
;               sincos_rev((float)(s & 63) * invf64, sc, cc);
;               const float a1 = v0, a2 = v1, b1 = v2, b2 = v3;
;               v0 = a1 * cr - a2 * sr;
;               v1 = a2 * cr + a1 * sr;
;               v2 = b1 * cc - b2 * sc;
;               v3 = b2 * cc + b1 * sc;
;             }
;           } else if (tr == 4) {
;             float sr, cr, sc, cc;
;             sincos_rev((float)(s >> 6) * invf32, sr, cr);
;             sincos_rev((float)(s & 63) * invf32, sc, cc);
;             const float p0 = __shfl_xor(v0, 8), p1 = __shfl_xor(v1, 8), p2 = __shfl_xor(v2, 8), p3 = __shfl_xor(v3, 8);
;             v0 = lo8 ? (v0 * cr - p0 * sr) : (v0 * cr + p0 * sr);
;             v1 = lo8 ? (v1 * cc - p1 * sc) : (v1 * cc + p1 * sc);
;             v2 = lo8 ? (v2 * cr - p2 * sr) : (v2 * cr + p2 * sr);
;             v3 = lo8 ? (v3 * cc - p3 * sc) : (v3 * cc + p3 * sc);
;           }
;           const unsigned u01 = pack2(v0, v1), u23 = pack2(v2, v3);
;           if (kind == 1) {
;             Tl[(0 * 16 + r) * 72 + rowl] = (u16)u01;
;             Tl[(1 * 16 + r) * 72 + rowl] = (u16)(u01 >> 16);
;             Tl[(2 * 16 + r) * 72 + rowl] = (u16)u23;
;             Tl[(3 * 16 + r) * 72 + rowl] = (u16)(u23 >> 16);
;           } else if (tr == 2) {
;             Tl[rowl * 72 + 0 * 16 + r] = f2h(v0);
	v_rcp_f32_e32 v188, v188
	v_rcp_f32_e32 v189, v189
	v_mul_f32_e32 v186, v64, v186
	v_mul_f32_e32 v187, v60, v187
	v_mul_f32_e32 v188, v56, v188
	v_mul_f32_e32 v189, v52, v189
	v_cvt_pk_bf16_f32 v190, v186, v187
	v_cvt_pk_bf16_f32 v191, v188, v189
	ds_write_b16 v170, v190 offset:288
	ds_write_b16_d16_hi v170, v190 offset:320
	ds_write_b16 v170, v191 offset:352
	ds_write_b16_d16_hi v170, v191 offset:384
	v_mul_f32_e32 v192, 0xbfb8aa3b, v65
	v_mul_f32_e32 v193, 0xbfb8aa3b, v61
	v_mul_f32_e32 v174, 0xbfb8aa3b, v57
	v_mul_f32_e32 v175, 0xbfb8aa3b, v53
	v_exp_f32_e32 v192, v192
	v_exp_f32_e32 v193, v193
	v_exp_f32_e32 v174, v174
	v_exp_f32_e32 v175, v175
	v_add_f32_e32 v192, 1.0, v192
	v_add_f32_e32 v193, 1.0, v193
	v_add_f32_e32 v174, 1.0, v174
	v_add_f32_e32 v175, 1.0, v175
	v_rcp_f32_e32 v192, v192
	v_rcp_f32_e32 v193, v193
	v_rcp_f32_e32 v174, v174
	v_rcp_f32_e32 v175, v175
	v_mul_f32_e32 v192, v65, v192
	v_mul_f32_e32 v193, v61, v193
	v_mul_f32_e32 v174, v57, v174
	v_mul_f32_e32 v175, v53, v175
	v_cvt_pk_bf16_f32 v176, v192, v193
	v_cvt_pk_bf16_f32 v177, v174, v175
	ds_write_b16 v170, v176 offset:432
	ds_write_b16_d16_hi v170, v176 offset:464
	ds_write_b16 v170, v177 offset:496
	ds_write_b16_d16_hi v170, v177 offset:528
	v_mul_f32_e32 v178, 0xbfb8aa3b, v46
	v_mul_f32_e32 v179, 0xbfb8aa3b, v42
	v_mul_f32_e32 v180, 0xbfb8aa3b, v38
	v_mul_f32_e32 v181, 0xbfb8aa3b, v34
	v_exp_f32_e32 v178, v178
	v_exp_f32_e32 v179, v179
	v_exp_f32_e32 v180, v180
	v_exp_f32_e32 v181, v181
	v_add_f32_e32 v178, 1.0, v178
	v_add_f32_e32 v179, 1.0, v179
	v_add_f32_e32 v180, 1.0, v180
	v_add_f32_e32 v181, 1.0, v181
	v_rcp_f32_e32 v178, v178
	v_rcp_f32_e32 v179, v179
	v_rcp_f32_e32 v180, v180
	v_rcp_f32_e32 v181, v181
	v_mul_f32_e32 v178, v46, v178
	v_mul_f32_e32 v179, v42, v179
	v_mul_f32_e32 v180, v38, v180
	v_mul_f32_e32 v181, v34, v181
	v_cvt_pk_bf16_f32 v182, v178, v179
	v_cvt_pk_bf16_f32 v183, v180, v181
	ds_write_b16 v170, v182 offset:2304
	ds_write_b16_d16_hi v170, v182 offset:2336
	ds_write_b16 v170, v183 offset:2368
	ds_write_b16_d16_hi v170, v183 offset:2400
	v_mul_f32_e32 v184, 0xbfb8aa3b, v47
	v_mul_f32_e32 v185, 0xbfb8aa3b, v43
	v_mul_f32_e32 v186, 0xbfb8aa3b, v39
	v_mul_f32_e32 v187, 0xbfb8aa3b, v35
	v_exp_f32_e32 v184, v184
	v_exp_f32_e32 v185, v185
	v_exp_f32_e32 v186, v186
	v_exp_f32_e32 v187, v187
	v_add_f32_e32 v184, 1.0, v184
	v_add_f32_e32 v185, 1.0, v185
	v_add_f32_e32 v186, 1.0, v186
	v_add_f32_e32 v187, 1.0, v187
	v_rcp_f32_e32 v184, v184
	v_rcp_f32_e32 v185, v185
	v_rcp_f32_e32 v186, v186
	v_rcp_f32_e32 v187, v187
	v_mul_f32_e32 v184, v47, v184
	v_mul_f32_e32 v185, v43, v185
	v_mul_f32_e32 v186, v39, v186
	v_mul_f32_e32 v187, v35, v187
	v_cvt_pk_bf16_f32 v188, v184, v185
	v_cvt_pk_bf16_f32 v189, v186, v187
	ds_write_b16 v170, v188 offset:2448
	ds_write_b16_d16_hi v170, v188 offset:2480
	ds_write_b16 v170, v189 offset:2512
	ds_write_b16_d16_hi v170, v189 offset:2544
	v_mul_f32_e32 v190, 0xbfb8aa3b, v48
	v_mul_f32_e32 v191, 0xbfb8aa3b, v44
	v_mul_f32_e32 v192, 0xbfb8aa3b, v40
	v_mul_f32_e32 v193, 0xbfb8aa3b, v36
	v_exp_f32_e32 v190, v190
	v_exp_f32_e32 v191, v191
	v_exp_f32_e32 v192, v192
	v_exp_f32_e32 v193, v193
	v_add_f32_e32 v190, 1.0, v190
	v_add_f32_e32 v191, 1.0, v191
	v_add_f32_e32 v192, 1.0, v192
	v_add_f32_e32 v193, 1.0, v193
	v_rcp_f32_e32 v190, v190
	v_rcp_f32_e32 v191, v191
	v_rcp_f32_e32 v192, v192
	v_rcp_f32_e32 v193, v193
	v_mul_f32_e32 v190, v48, v190
	v_mul_f32_e32 v191, v44, v191
	v_mul_f32_e32 v192, v40, v192
	v_mul_f32_e32 v193, v36, v193
	v_cvt_pk_bf16_f32 v174, v190, v191
	v_cvt_pk_bf16_f32 v175, v192, v193
	ds_write_b16 v170, v174 offset:2592
	ds_write_b16_d16_hi v170, v174 offset:2624
	ds_write_b16 v170, v175 offset:2656
	ds_write_b16_d16_hi v170, v175 offset:2688
	v_mul_f32_e32 v176, 0xbfb8aa3b, v49
	v_mul_f32_e32 v177, 0xbfb8aa3b, v45
	v_mul_f32_e32 v178, 0xbfb8aa3b, v41
	v_mul_f32_e32 v179, 0xbfb8aa3b, v37
	v_exp_f32_e32 v176, v176
	v_exp_f32_e32 v177, v177
	v_exp_f32_e32 v178, v178
	v_exp_f32_e32 v179, v179
	v_add_f32_e32 v176, 1.0, v176
	v_add_f32_e32 v177, 1.0, v177
	v_add_f32_e32 v178, 1.0, v178
	v_add_f32_e32 v179, 1.0, v179
	v_rcp_f32_e32 v176, v176
	v_rcp_f32_e32 v177, v177
	v_rcp_f32_e32 v178, v178
	v_rcp_f32_e32 v179, v179
	v_mul_f32_e32 v176, v49, v176
	v_mul_f32_e32 v177, v45, v177
	v_mul_f32_e32 v178, v41, v178
	v_mul_f32_e32 v179, v37, v179
	v_cvt_pk_bf16_f32 v180, v176, v177
	v_cvt_pk_bf16_f32 v181, v178, v179
	ds_write_b16 v170, v180 offset:2736
	ds_write_b16_d16_hi v170, v180 offset:2768
	ds_write_b16 v170, v181 offset:2800
	ds_write_b16_d16_hi v170, v181 offset:2832
	v_mul_f32_e32 v182, 0xbfb8aa3b, v30
	v_mul_f32_e32 v183, 0xbfb8aa3b, v26
	v_mul_f32_e32 v184, 0xbfb8aa3b, v22
	v_mul_f32_e32 v185, 0xbfb8aa3b, v18
	v_exp_f32_e32 v182, v182
	v_exp_f32_e32 v183, v183
	v_exp_f32_e32 v184, v184
	v_exp_f32_e32 v185, v185
	v_add_f32_e32 v182, 1.0, v182
	v_add_f32_e32 v183, 1.0, v183
	v_add_f32_e32 v184, 1.0, v184
	v_add_f32_e32 v185, 1.0, v185
	v_rcp_f32_e32 v182, v182
	v_rcp_f32_e32 v183, v183
	v_rcp_f32_e32 v184, v184
	v_rcp_f32_e32 v185, v185
	v_mul_f32_e32 v182, v30, v182
	v_mul_f32_e32 v183, v26, v183
	v_mul_f32_e32 v184, v22, v184
	v_mul_f32_e32 v185, v18, v185
	v_cvt_pk_bf16_f32 v186, v182, v183
	v_cvt_pk_bf16_f32 v187, v184, v185
	ds_write_b16 v170, v186 offset:4608
	ds_write_b16_d16_hi v170, v186 offset:4640
	ds_write_b16 v170, v187 offset:4672
	ds_write_b16_d16_hi v170, v187 offset:4704
	v_mul_f32_e32 v188, 0xbfb8aa3b, v31
	v_mul_f32_e32 v189, 0xbfb8aa3b, v27
	v_mul_f32_e32 v190, 0xbfb8aa3b, v23
	v_mul_f32_e32 v191, 0xbfb8aa3b, v19
	v_exp_f32_e32 v188, v188
	v_exp_f32_e32 v189, v189
; template <int EPI>
; DI void gemm_phase(const P& p, int l, const u16* __restrict__ A, const u16* __restrict__ Bt, int mpx, char* lds) {
;     ...
;           if (tr == 1) {
;             v0 = silu(v0); v1 = silu(v1); v2 = silu(v2); v3 = silu(v3);
;           } else if (tr == 3) {
;             if (donorm) {
;               float ss = v0 * v0 + v1 * v1 + v2 * v2 + v3 * v3;
;               ss += __shfl_xor(ss, 1);
;               ss += __shfl_xor(ss, 2);
;               ss += __shfl_xor(ss, 4);
;               ss += __shfl_xor(ss, 8);
;               const float inv = rsqrtf(ss * (1.f / 64.f) + 1e-6f);
;               v0 *= inv * gv0; v1 *= inv * gv1; v2 *= inv * gv2; v3 *= inv * gv3;
;             }
;             if (dorope) {
;               float sr, cr, sc, cc;
;               sincos_rev((float)(s >> 6) * invf64, sr, cr);
;               sincos_rev((float)(s & 63) * invf64, sc, cc);
;               const float a1 = v0, a2 = v1, b1 = v2, b2 = v3;
;               v0 = a1 * cr - a2 * sr;
;               v1 = a2 * cr + a1 * sr;
;               v2 = b1 * cc - b2 * sc;
;               v3 = b2 * cc + b1 * sc;
;             }
;           } else if (tr == 4) {
;             float sr, cr, sc, cc;
;             sincos_rev((float)(s >> 6) * invf32, sr, cr);
;             sincos_rev((float)(s & 63) * invf32, sc, cc);
;             const float p0 = __shfl_xor(v0, 8), p1 = __shfl_xor(v1, 8), p2 = __shfl_xor(v2, 8), p3 = __shfl_xor(v3, 8);
;             v0 = lo8 ? (v0 * cr - p0 * sr) : (v0 * cr + p0 * sr);
;             v1 = lo8 ? (v1 * cc - p1 * sc) : (v1 * cc + p1 * sc);
;             v2 = lo8 ? (v2 * cr - p2 * sr) : (v2 * cr + p2 * sr);
;             v3 = lo8 ? (v3 * cc - p3 * sc) : (v3 * cc + p3 * sc);
;           }
;           const unsigned u01 = pack2(v0, v1), u23 = pack2(v2, v3);
;           if (kind == 1) {
;             Tl[(0 * 16 + r) * 72 + rowl] = (u16)u01;
;             Tl[(1 * 16 + r) * 72 + rowl] = (u16)(u01 >> 16);
;             Tl[(2 * 16 + r) * 72 + rowl] = (u16)u23;
;             Tl[(3 * 16 + r) * 72 + rowl] = (u16)(u23 >> 16);
;           } else if (tr == 2) {
;             Tl[rowl * 72 + 0 * 16 + r] = f2h(v0);
;             Tl[rowl * 72 + 1 * 16 + r] = f2h(v1);
;             Tl[rowl * 72 + 2 * 16 + r] = f2h(v2);
;             Tl[rowl * 72 + 3 * 16 + r] = f2h(v3);
;           } else {
;             Tl[rowl * 72 + 0 * 16 + r] = (u16)u01;
	v_exp_f32_e32 v190, v190
	v_exp_f32_e32 v191, v191
	v_add_f32_e32 v188, 1.0, v188
	v_add_f32_e32 v189, 1.0, v189
	v_add_f32_e32 v190, 1.0, v190
	v_add_f32_e32 v191, 1.0, v191
	v_rcp_f32_e32 v188, v188
	v_rcp_f32_e32 v189, v189
	v_rcp_f32_e32 v190, v190
	v_rcp_f32_e32 v191, v191
	v_mul_f32_e32 v188, v31, v188
	v_mul_f32_e32 v189, v27, v189
	v_mul_f32_e32 v190, v23, v190
	v_mul_f32_e32 v191, v19, v191
	v_cvt_pk_bf16_f32 v192, v188, v189
	v_cvt_pk_bf16_f32 v193, v190, v191
	ds_write_b16 v170, v192 offset:4752
	ds_write_b16_d16_hi v170, v192 offset:4784
	ds_write_b16 v170, v193 offset:4816
	ds_write_b16_d16_hi v170, v193 offset:4848
	v_mul_f32_e32 v174, 0xbfb8aa3b, v32
	v_mul_f32_e32 v175, 0xbfb8aa3b, v28
	v_mul_f32_e32 v176, 0xbfb8aa3b, v24
	v_mul_f32_e32 v177, 0xbfb8aa3b, v20
	v_exp_f32_e32 v174, v174
	v_exp_f32_e32 v175, v175
	v_exp_f32_e32 v176, v176
	v_exp_f32_e32 v177, v177
	v_add_f32_e32 v174, 1.0, v174
	v_add_f32_e32 v175, 1.0, v175
	v_add_f32_e32 v176, 1.0, v176
	v_add_f32_e32 v177, 1.0, v177
	v_rcp_f32_e32 v174, v174
	v_rcp_f32_e32 v175, v175
	v_rcp_f32_e32 v176, v176
	v_rcp_f32_e32 v177, v177
	v_mul_f32_e32 v174, v32, v174
	v_mul_f32_e32 v175, v28, v175
	v_mul_f32_e32 v176, v24, v176
	v_mul_f32_e32 v177, v20, v177
	v_cvt_pk_bf16_f32 v178, v174, v175
	v_cvt_pk_bf16_f32 v179, v176, v177
	ds_write_b16 v170, v178 offset:4896
	ds_write_b16_d16_hi v170, v178 offset:4928
	ds_write_b16 v170, v179 offset:4960
	ds_write_b16_d16_hi v170, v179 offset:4992
	v_mul_f32_e32 v180, 0xbfb8aa3b, v33
	v_mul_f32_e32 v181, 0xbfb8aa3b, v29
	v_mul_f32_e32 v182, 0xbfb8aa3b, v25
	v_mul_f32_e32 v183, 0xbfb8aa3b, v21
	v_exp_f32_e32 v180, v180
	v_exp_f32_e32 v181, v181
	v_exp_f32_e32 v182, v182
	v_exp_f32_e32 v183, v183
	v_add_f32_e32 v180, 1.0, v180
	v_add_f32_e32 v181, 1.0, v181
	v_add_f32_e32 v182, 1.0, v182
	v_add_f32_e32 v183, 1.0, v183
	v_rcp_f32_e32 v180, v180
	v_rcp_f32_e32 v181, v181
	v_rcp_f32_e32 v182, v182
	v_rcp_f32_e32 v183, v183
	v_mul_f32_e32 v180, v33, v180
	v_mul_f32_e32 v181, v29, v181
	v_mul_f32_e32 v182, v25, v182
	v_mul_f32_e32 v183, v21, v183
	v_cvt_pk_bf16_f32 v184, v180, v181
	v_cvt_pk_bf16_f32 v185, v182, v183
	ds_write_b16 v170, v184 offset:5040
	ds_write_b16_d16_hi v170, v184 offset:5072
	ds_write_b16 v170, v185 offset:5104
	ds_write_b16_d16_hi v170, v185 offset:5136
	v_mul_f32_e32 v186, 0xbfb8aa3b, v166
	v_mul_f32_e32 v187, 0xbfb8aa3b, v162
	v_mul_f32_e32 v188, 0xbfb8aa3b, v2
	v_mul_f32_e32 v189, 0xbfb8aa3b, v6
	v_exp_f32_e32 v186, v186
	v_exp_f32_e32 v187, v187
	v_exp_f32_e32 v188, v188
	v_exp_f32_e32 v189, v189
	v_add_f32_e32 v186, 1.0, v186
	v_add_f32_e32 v187, 1.0, v187
	v_add_f32_e32 v188, 1.0, v188
	v_add_f32_e32 v189, 1.0, v189
	v_rcp_f32_e32 v186, v186
	v_rcp_f32_e32 v187, v187
	v_rcp_f32_e32 v188, v188
	v_rcp_f32_e32 v189, v189
	v_mul_f32_e32 v186, v166, v186
	v_mul_f32_e32 v187, v162, v187
	v_mul_f32_e32 v188, v2, v188
	v_mul_f32_e32 v189, v6, v189
	v_cvt_pk_bf16_f32 v190, v186, v187
	v_cvt_pk_bf16_f32 v191, v188, v189
	ds_write_b16 v170, v190 offset:6912
	ds_write_b16_d16_hi v170, v190 offset:6944
	ds_write_b16 v170, v191 offset:6976
	ds_write_b16_d16_hi v170, v191 offset:7008
	v_mul_f32_e32 v192, 0xbfb8aa3b, v167
	v_mul_f32_e32 v193, 0xbfb8aa3b, v163
	v_mul_f32_e32 v174, 0xbfb8aa3b, v3
	v_mul_f32_e32 v175, 0xbfb8aa3b, v7
	v_exp_f32_e32 v192, v192
	v_exp_f32_e32 v193, v193
	v_exp_f32_e32 v174, v174
	v_exp_f32_e32 v175, v175
	v_add_f32_e32 v192, 1.0, v192
	v_add_f32_e32 v193, 1.0, v193
	v_add_f32_e32 v174, 1.0, v174
	v_add_f32_e32 v175, 1.0, v175
	v_rcp_f32_e32 v192, v192
	v_rcp_f32_e32 v193, v193
	v_rcp_f32_e32 v174, v174
	v_rcp_f32_e32 v175, v175
	v_mul_f32_e32 v192, v167, v192
	v_mul_f32_e32 v193, v163, v193
	v_mul_f32_e32 v174, v3, v174
	v_mul_f32_e32 v175, v7, v175
	v_cvt_pk_bf16_f32 v176, v192, v193
	v_cvt_pk_bf16_f32 v177, v174, v175
	ds_write_b16 v170, v176 offset:7056
	ds_write_b16_d16_hi v170, v176 offset:7088
	ds_write_b16 v170, v177 offset:7120
	ds_write_b16_d16_hi v170, v177 offset:7152
	v_mul_f32_e32 v178, 0xbfb8aa3b, v168
	v_mul_f32_e32 v179, 0xbfb8aa3b, v164
	v_mul_f32_e32 v180, 0xbfb8aa3b, v4
	v_mul_f32_e32 v181, 0xbfb8aa3b, v8
	v_exp_f32_e32 v178, v178
	v_exp_f32_e32 v179, v179
	v_exp_f32_e32 v180, v180
	v_exp_f32_e32 v181, v181
	v_add_f32_e32 v178, 1.0, v178
	v_add_f32_e32 v179, 1.0, v179
	v_add_f32_e32 v180, 1.0, v180
	v_add_f32_e32 v181, 1.0, v181
	v_rcp_f32_e32 v178, v178
	v_rcp_f32_e32 v179, v179
	v_rcp_f32_e32 v180, v180
	v_rcp_f32_e32 v181, v181
	v_mul_f32_e32 v178, v168, v178
	v_mul_f32_e32 v179, v164, v179
	v_mul_f32_e32 v180, v4, v180
	v_mul_f32_e32 v181, v8, v181
	v_cvt_pk_bf16_f32 v182, v178, v179
	v_cvt_pk_bf16_f32 v183, v180, v181
	ds_write_b16 v170, v182 offset:7200
	ds_write_b16_d16_hi v170, v182 offset:7232
	ds_write_b16 v170, v183 offset:7264
	ds_write_b16_d16_hi v170, v183 offset:7296
	v_mul_f32_e32 v184, 0xbfb8aa3b, v169
	v_mul_f32_e32 v185, 0xbfb8aa3b, v165
	v_mul_f32_e32 v186, 0xbfb8aa3b, v5
	v_mul_f32_e32 v187, 0xbfb8aa3b, v9
	v_exp_f32_e32 v184, v184
	v_exp_f32_e32 v185, v185
	v_exp_f32_e32 v186, v186
	v_exp_f32_e32 v187, v187
	v_add_f32_e32 v184, 1.0, v184
	v_add_f32_e32 v185, 1.0, v185
	v_add_f32_e32 v186, 1.0, v186
	v_add_f32_e32 v187, 1.0, v187
	v_rcp_f32_e32 v184, v184
	v_rcp_f32_e32 v185, v185
	v_rcp_f32_e32 v186, v186
	v_rcp_f32_e32 v187, v187
	v_mul_f32_e32 v184, v169, v184
	v_mul_f32_e32 v185, v165, v185
	v_mul_f32_e32 v186, v5, v186
	v_mul_f32_e32 v187, v9, v187
	v_cvt_pk_bf16_f32 v188, v184, v185
	v_cvt_pk_bf16_f32 v189, v186, v187
	ds_write_b16 v170, v188 offset:7344
	ds_write_b16_d16_hi v170, v188 offset:7376
	ds_write_b16 v170, v189 offset:7408
	ds_write_b16_d16_hi v170, v189 offset:7440
	ds_read_b128 v[130:133], v171 offset:0
	ds_read_b128 v[134:137], v171 offset:1152
	ds_read_b128 v[138:141], v171 offset:2304
	ds_read_b128 v[142:145], v171 offset:3456
	ds_read_b128 v[146:149], v171 offset:4608
	ds_read_b128 v[150:153], v171 offset:5760
	ds_read_b128 v[154:157], v171 offset:6912
	ds_read_b128 v[158:161], v171 offset:8064
	s_waitcnt lgkmcnt(7)
	global_store_dwordx4 v172, v[130:133], s[44:45] sc1
	s_add_u32 s44, s44, 0x4000
	s_addc_u32 s45, s45, 0
	s_waitcnt lgkmcnt(6)
	global_store_dwordx4 v172, v[134:137], s[44:45] sc1
	s_add_u32 s44, s44, 0x4000
	s_addc_u32 s45, s45, 0
	s_waitcnt lgkmcnt(5)
	global_store_dwordx4 v172, v[138:141], s[44:45] sc1
	s_add_u32 s44, s44, 0x4000
	s_addc_u32 s45, s45, 0
	s_waitcnt lgkmcnt(4)
	global_store_dwordx4 v172, v[142:145], s[44:45] sc1
	s_add_u32 s44, s44, 0x4000
	s_addc_u32 s45, s45, 0
	s_waitcnt lgkmcnt(3)
	global_store_dwordx4 v172, v[146:149], s[44:45] sc1
	s_add_u32 s44, s44, 0x4000
	s_addc_u32 s45, s45, 0
	s_waitcnt lgkmcnt(2)
	global_store_dwordx4 v172, v[150:153], s[44:45] sc1
	s_add_u32 s44, s44, 0x4000
	s_addc_u32 s45, s45, 0
	s_waitcnt lgkmcnt(1)
	global_store_dwordx4 v172, v[154:157], s[44:45] sc1
	s_add_u32 s44, s44, 0x4000
	s_addc_u32 s45, s45, 0
	s_waitcnt lgkmcnt(0)
	global_store_dwordx4 v172, v[158:161], s[44:45] sc1
	s_branch .Lfe_done
